# packed f32 VALU ops split into single f32 ops in every phase (bit-identical), on top of v017
# baseline (speedup 1.0000x reference)
; __device__ __forceinline__ unsigned pk2(float lo, float hi) { const bfx2 b = __builtin_convertvector((f32x2){lo, hi}, bfx2); return __builtin_bit_cast(unsigned, b); }
; __device__ __forceinline__ void rms_row_to_bf16(const float* xrow, const float* g, bf16* orow, int lane) {
;     f32x4 v[8]; float s = 0.f;
; #pragma unroll
;     for (int j = 0; j < 4; ++j) { const float* p = xrow + (j * 64 + lane) * 8; v[2 * j] = __builtin_nontemporal_load((const f32x4*)p); v[2 * j + 1] = __builtin_nontemporal_load((const f32x4*)(p + 4));
;         s += (v[2*j].x * v[2*j].x + v[2*j].y * v[2*j].y) + (v[2*j].z * v[2*j].z + v[2*j].w * v[2*j].w) + (v[2*j+1].x * v[2*j+1].x + v[2*j+1].y * v[2*j+1].y) + (v[2*j+1].z * v[2*j+1].z + v[2*j+1].w * v[2*j+1].w); }
;     const float r = 1.0f / sqrtf(wave_sum(s) * (1.0f / D) + RMS_EPS);
; #pragma unroll
;     for (int j = 0; j < 4; ++j) { const int c = (j * 64 + lane) * 8; const f32x4 g0 = *(const f32x4*)(g + c), g1 = *(const f32x4*)(g + c + 4); const f32x4 a = v[2 * j] * r * g0, b = v[2 * j + 1] * r * g1;
;         u32x4 o; o.x = pk2(a.x, a.y); o.y = pk2(a.z, a.w); o.z = pk2(b.x, b.y); o.w = pk2(b.z, b.w); *(u32x4*)(orow + c) = o; }
; }
.LBB0_251:
	global_load_dwordx4 v[14:17], v42, s[10:11] nt
	global_load_dwordx4 v[10:13], v42, s[10:11] offset:16 nt
	global_load_dwordx4 v[26:29], v42, s[10:11] offset:2048 nt
	global_load_dwordx4 v[18:21], v42, s[10:11] offset:2064 nt
	global_load_dwordx4 v[6:9], v44, s[10:11] nt
	global_load_dwordx4 v[22:25], v43, s[10:11] offset:16 nt
	global_load_dwordx4 v[30:33], v43, s[10:11] nt
	global_load_dwordx4 v[2:5], v44, s[10:11] offset:16 nt
	global_load_dwordx4 v[48:51], v[34:35], off offset:16
	global_load_dwordx4 v[52:55], v[34:35], off
	s_waitcnt vmcnt(9)
	v_mul_f32_e32 v56, v16, v16
	v_mul_f32_e32 v57, v17, v17
	v_mul_f32_e32 v58, v14, v14
	v_mul_f32_e32 v59, v15, v15
	s_waitcnt vmcnt(8)
	v_mul_f32_e32 v60, v12, v12
	v_mul_f32_e32 v61, v13, v13
	v_mul_f32_e32 v62, v10, v10
	v_mul_f32_e32 v63, v11, v11
	s_waitcnt vmcnt(7)
	v_mul_f32_e32 v64, v28, v28
	v_mul_f32_e32 v65, v29, v29
	v_mul_f32_e32 v66, v26, v26
	v_mul_f32_e32 v67, v27, v27
	s_waitcnt vmcnt(6)
	v_mul_f32_e32 v68, v20, v20
	v_mul_f32_e32 v69, v21, v21
	v_mul_f32_e32 v70, v18, v18
	v_mul_f32_e32 v71, v19, v19
	v_pk_mov_b32 v[84:85], v[58:59], v[56:57] op_sel:[1,0]
	v_mov_b32_e32 v59, v57
	v_mov_b32_e32 v56, v60
	v_mov_b32_e32 v57, v62
	v_mov_b32_e32 v62, v61
	v_pk_mov_b32 v[60:61], v[66:67], v[64:65] op_sel:[1,0]
	v_mov_b32_e32 v67, v65
	s_waitcnt vmcnt(4)
	v_mov_b32_e32 v74, v23
	v_mov_b32_e32 v75, v7
	s_waitcnt vmcnt(3)
	v_mul_f32_e32 v76, v31, v31
	v_mul_f32_e32 v78, v33, v33
	v_mov_b32_e32 v64, v68
	v_mov_b32_e32 v65, v70
	v_mov_b32_e32 v70, v69
	v_add_f32_e32 v58, v84, v58
	v_add_f32_e32 v59, v85, v59
	v_add_f32_e32 v60, v60, v66
	v_add_f32_e32 v61, v61, v67
	v_mul_f32_e32 v47, v8, v8
	v_mul_f32_e32 v86, v9, v9
	v_mul_f32_e32 v68, v74, v74
	v_mul_f32_e32 v69, v75, v75
	v_fma_f32 v74, v30, v30, v76
	v_fma_f32 v75, v31, v31, v76
	v_fma_f32 v76, v32, v32, v78
	v_fma_f32 v77, v33, v33, v78
	v_add_f32_e32 v56, v56, v62
	v_add_f32_e32 v57, v57, v63
	v_add_f32_e32 v62, v64, v70
	v_add_f32_e32 v63, v65, v71
	v_pk_add_f32 v[58:59], v[58:59], v[58:59] op_sel:[0,1] op_sel_hi:[1,0]
	v_pk_add_f32 v[60:61], v[60:61], v[60:61] op_sel:[0,1] op_sel_hi:[1,0]
	v_mov_b32_e32 v72, v22
	v_mov_b32_e32 v73, v6
	v_mov_b32_e32 v82, v25
	s_waitcnt vmcnt(2)
	v_mov_b32_e32 v83, v3
	v_mov_b32_e32 v75, v47
	v_mov_b32_e32 v77, v86
	v_add_f32_e32 v58, v57, v58
	v_add_f32_e32 v59, v56, v59
	v_add_f32_e32 v60, v63, v60
	v_add_f32_e32 v61, v62, v61
	v_mov_b32_e32 v80, v24
	v_mov_b32_e32 v81, v2
	v_mul_f32_e32 v78, v82, v82
	v_mul_f32_e32 v79, v83, v83
	v_fma_f32 v64, v72, v72, v68
	v_fma_f32 v65, v73, v73, v69
	v_add_f32_e32 v68, v74, v76
	v_add_f32_e32 v69, v75, v77
	v_add_f32_e32 v56, v56, v58
	v_add_f32_e32 v57, v57, v59
	v_add_f32_e32 v58, v62, v60
	v_add_f32_e32 v59, v63, v61
	v_fma_f32 v66, v80, v80, v78
	v_fma_f32 v67, v81, v81, v79
	v_add_f32_e32 v64, v64, v68
	v_add_f32_e32 v65, v65, v69
	v_mul_f32_e32 v57, v4, v4
	v_mul_f32_e32 v59, v5, v5
	v_add_f32_e32 v60, v66, v64
	v_add_f32_e32 v61, v67, v65
	v_add_f32_e32 v56, v56, v58
	v_add_f32_e32 v57, v57, v59
	s_nop 0
	v_add_f32_e32 v56, v56, v60
	v_add_f32_e32 v57, v57, v61
	s_nop 0
	v_add_f32_e32 v47, v56, v57
	s_nop 1
	v_add_f32_dpp v47, v47, v47 quad_perm:[1,0,3,2] row_mask:0xf bank_mask:0xf bound_ctrl:1
	s_nop 1
	v_add_f32_dpp v47, v47, v47 quad_perm:[2,3,0,1] row_mask:0xf bank_mask:0xf bound_ctrl:1
	s_nop 1
	v_add_f32_dpp v47, v47, v47 row_half_mirror row_mask:0xf bank_mask:0xf bound_ctrl:1
	s_nop 1
	v_add_f32_dpp v47, v47, v47 row_mirror row_mask:0xf bank_mask:0xf bound_ctrl:1
	s_nop 0
	v_readlane_b32 s3, v47, 16
	v_readlane_b32 s8, v47, 48
	v_readlane_b32 s10, v47, 0
	v_readlane_b32 s11, v47, 32
	v_mov_b32_e32 v56, s3
	v_mov_b32_e32 v57, s8
	v_add_f32_e32 v56, s10, v56
	v_add_f32_e32 v57, s11, v57
	s_lshl_b64 s[10:11], s[4:5], 12
	v_add_f32_e32 v47, v56, v57
	v_fmamk_f32 v47, v47, 0x3a000000, v45
	v_mul_f32_e32 v56, 0x4f800000, v47
	v_cmp_gt_f32_e32 vcc, s2, v47
	s_nop 1
	v_cndmask_b32_e32 v47, v47, v56, vcc
	v_sqrt_f32_e32 v56, v47
	s_nop 0
	v_add_u32_e32 v57, -1, v56
	v_add_u32_e32 v58, 1, v56
	v_fma_f32 v59, -v57, v56, v47
	v_fma_f32 v60, -v58, v56, v47
	v_cmp_ge_f32_e64 s[4:5], 0, v59
	s_nop 1
	v_cndmask_b32_e64 v56, v56, v57, s[4:5]
	v_cmp_lt_f32_e64 s[4:5], 0, v60
	s_nop 1
	v_cndmask_b32_e64 v56, v56, v58, s[4:5]
	v_mul_f32_e32 v57, 0x37800000, v56
	v_cndmask_b32_e32 v56, v56, v57, vcc
	v_cmp_class_f32_e32 vcc, v47, v46
	s_nop 1
	v_cndmask_b32_e32 v47, v56, v47, vcc
	v_div_scale_f32 v58, s[4:5], v47, v47, 1.0
	v_rcp_f32_e32 v59, v58
	v_div_scale_f32 v60, vcc, 1.0, v47, 1.0
	v_lshl_add_u64 v[56:57], v[40:41], 0, s[10:11]
	v_fma_f32 v61, -v58, v59, 1.0
	v_fmac_f32_e32 v59, v61, v59
	v_mul_f32_e32 v61, v60, v59
	v_fma_f32 v62, -v58, v61, v60
	v_fmac_f32_e32 v61, v62, v59
	v_fma_f32 v58, -v58, v61, v60
	v_div_fmas_f32 v58, v58, v59, v61
	v_div_fixup_f32 v58, v58, v47, 1.0
	v_mul_f32_e32 v14, v14, v58
	v_mul_f32_e32 v15, v15, v58
	v_mul_f32_e32 v16, v16, v58
	v_mul_f32_e32 v17, v17, v58
	v_mul_f32_e32 v10, v10, v58
	v_mul_f32_e32 v11, v11, v58
	v_mul_f32_e32 v12, v12, v58
	v_mul_f32_e32 v13, v13, v58
	s_waitcnt vmcnt(0)
; __device__ __forceinline__ unsigned pk2(float lo, float hi) { const bfx2 b = __builtin_convertvector((f32x2){lo, hi}, bfx2); return __builtin_bit_cast(unsigned, b); }
; __device__ __forceinline__ void rms_row_to_bf16(const float* xrow, const float* g, bf16* orow, int lane) {
;     ...
; #pragma unroll
;     for (int j = 0; j < 4; ++j) { const int c = (j * 64 + lane) * 8; const f32x4 g0 = *(const f32x4*)(g + c), g1 = *(const f32x4*)(g + c + 4); const f32x4 a = v[2 * j] * r * g0, b = v[2 * j + 1] * r * g1;
;         u32x4 o; o.x = pk2(a.x, a.y); o.y = pk2(a.z, a.w); o.z = pk2(b.x, b.y); o.w = pk2(b.z, b.w); *(u32x4*)(orow + c) = o; }
	v_mul_f32_e32 v16, v54, v16
	v_mul_f32_e32 v17, v55, v17
	v_mul_f32_e32 v14, v52, v14
	v_mul_f32_e32 v15, v53, v15
	v_mul_f32_e32 v50, v50, v12
	v_mul_f32_e32 v51, v51, v13
	v_mul_f32_e32 v12, v48, v10
	v_mul_f32_e32 v13, v49, v11
	v_cvt_pk_bf16_f32 v10, v14, v15
	v_cvt_pk_bf16_f32 v11, v16, v17
	v_cvt_pk_bf16_f32 v12, v12, v13
	v_cvt_pk_bf16_f32 v13, v50, v51
	global_store_dwordx4 v[56:57], v[10:13], off
	s_nop 0
	s_nop 0
	s_nop 0
	v_mul_f32_e32 v26, v26, v58
	v_mul_f32_e32 v27, v27, v58
	v_mul_f32_e32 v28, v28, v58
	v_mul_f32_e32 v29, v29, v58
	v_mul_f32_e32 v18, v18, v58
	v_mul_f32_e32 v19, v19, v58
	v_mul_f32_e32 v20, v20, v58
	v_mul_f32_e32 v21, v21, v58
	v_mul_f32_e32 v22, v22, v58
	v_mul_f32_e32 v23, v23, v58
	v_mul_f32_e32 v24, v24, v58
	v_mul_f32_e32 v25, v25, v58
	v_mul_f32_e32 v6, v6, v58
	v_mul_f32_e32 v7, v7, v58
	v_mul_f32_e32 v8, v8, v58
	v_mul_f32_e32 v9, v9, v58
	v_mul_f32_e32 v2, v2, v58
	v_mul_f32_e32 v3, v3, v58
	v_mul_f32_e32 v4, v4, v58
	v_mul_f32_e32 v5, v5, v58
	s_nop 1
	v_mov_b64_e32 v[10:11], v[90:91]
	v_mov_b64_e32 v[12:13], v[92:93]
	v_mov_b64_e32 v[14:15], v[94:95]
	v_mov_b64_e32 v[16:17], v[96:97]
	v_mul_f32_e32 v12, v12, v28
	v_mul_f32_e32 v13, v13, v29
	v_mul_f32_e32 v10, v10, v26
	v_mul_f32_e32 v11, v11, v27
	s_nop 0
	v_mul_f32_e32 v16, v16, v20
	v_mul_f32_e32 v17, v17, v21
	v_mul_f32_e32 v14, v14, v18
	v_mul_f32_e32 v15, v15, v19
	v_cvt_pk_bf16_f32 v10, v10, v11
	v_cvt_pk_bf16_f32 v11, v12, v13
	v_cvt_pk_bf16_f32 v12, v14, v15
	v_cvt_pk_bf16_f32 v13, v16, v17
	global_store_dwordx4 v[56:57], v[10:13], off offset:1024
	s_nop 0
	s_nop 0
	s_nop 0
	v_mul_f32_e32 v18, v30, v58
	v_mul_f32_e32 v19, v31, v58
	v_mul_f32_e32 v20, v32, v58
	v_mul_f32_e32 v21, v33, v58
	s_nop 1
	v_mov_b64_e32 v[10:11], v[98:99]
	v_mov_b64_e32 v[12:13], v[100:101]
	v_mov_b64_e32 v[14:15], v[102:103]
	v_mov_b64_e32 v[16:17], v[104:105]
	v_mul_f32_e32 v10, v10, v18
	v_mul_f32_e32 v11, v11, v19
	v_mul_f32_e32 v12, v12, v20
	v_mul_f32_e32 v13, v13, v21
	s_nop 0
	v_mul_f32_e32 v16, v16, v24
	v_mul_f32_e32 v17, v17, v25
	v_mul_f32_e32 v14, v14, v22
	v_mul_f32_e32 v15, v15, v23
	v_cvt_pk_bf16_f32 v10, v10, v11
	v_cvt_pk_bf16_f32 v11, v12, v13
	v_cvt_pk_bf16_f32 v12, v14, v15
	v_cvt_pk_bf16_f32 v13, v16, v17
	global_store_dwordx4 v[56:57], v[10:13], off offset:2048
	s_nop 0
	s_nop 0
	s_nop 0
	s_nop 1
	v_mov_b64_e32 v[10:11], v[106:107]
	v_mov_b64_e32 v[12:13], v[108:109]
	v_mov_b64_e32 v[14:15], v[110:111]
	v_mov_b64_e32 v[16:17], v[112:113]
	v_mul_f32_e32 v8, v8, v12
	v_mul_f32_e32 v9, v9, v13
	v_mul_f32_e32 v6, v6, v10
	v_mul_f32_e32 v7, v7, v11
	s_nop 0
	v_mul_f32_e32 v10, v4, v16
	v_mul_f32_e32 v11, v5, v17
	v_mul_f32_e32 v4, v2, v14
	v_mul_f32_e32 v5, v3, v15
	v_cvt_pk_bf16_f32 v2, v6, v7
	v_cvt_pk_bf16_f32 v3, v8, v9
	v_cvt_pk_bf16_f32 v4, v4, v5
	v_cvt_pk_bf16_f32 v5, v10, v11
	global_store_dwordx4 v[56:57], v[2:5], off offset:3072

; __device__ __forceinline__ u32x4 pack8(const f32x4 a, const f32x4 b) { u32x4 o; o.x = pk2(a.x, a.y); o.y = pk2(a.z, a.w); o.z = pk2(b.x, b.y); o.w = pk2(b.z, b.w); return o; }
; __device__ __forceinline__ f32x4 sig4(const f32x4 v) { f32x4 r; r.x = sigmoidf_(v.x); r.y = sigmoidf_(v.y); r.z = sigmoidf_(v.z); r.w = sigmoidf_(v.w); return r; }
;     __device__ __forceinline__ void operator()(const pg8::f32x4 (&acc)[2][2][4][2], const pg8::Unit& u, int wr, int wc, int fr, int fq) const {
;         EPI_REMAP(); const int row0 = u.pm * 256 + wr * 64 + fr2, col0 = u.pn * 128 + wc * 32 + 8 * fq2;
; #pragma unroll
;         for (int ai = 0; ai < 2; ++ai)
; #pragma unroll
;             for (int m = 0; m < 4; ++m) { bf16* rowp = O + (size_t)(row0 + ai * 128 + m * 16) * DFF + col0;
;                 const f32x4 a0 = acc[ai][0][m][0], a1 = acc[ai][0][m][1], b0 = acc[ai][1][m][0], b1 = acc[ai][1][m][1];
;                 *(u32x4*)rowp = epi_perm(pack8(a0 * sig4(a0) * b0, a1 * sig4(a1) * b1), src4); }
;     }
.LBB0_354:
	v_mul_f32_e32 v160, 0xbfb8aa3b, v126
	v_mul_f32_e32 v161, 0xbfb8aa3b, v127
	v_mul_f32_e32 v162, 0xbfb8aa3b, v128
	v_mul_f32_e32 v163, 0xbfb8aa3b, v129
	v_exp_f32_e32 v160, v160
	v_exp_f32_e32 v161, v161
	v_exp_f32_e32 v162, v162
	v_exp_f32_e32 v163, v163
	v_add_f32_e32 v160, 1.0, v160
	v_add_f32_e32 v161, 1.0, v161
	v_add_f32_e32 v162, 1.0, v162
	v_add_f32_e32 v163, 1.0, v163
	v_rcp_f32_e32 v160, v160
	v_rcp_f32_e32 v161, v161
	v_rcp_f32_e32 v162, v162
	v_rcp_f32_e32 v163, v163
	v_lshl_or_b32 v148, s42, 7, v153
	v_mul_f32_e32 v126, v126, v160
	v_mul_f32_e32 v127, v127, v161
	v_mul_f32_e32 v160, 0xbfb8aa3b, v122
	v_mul_f32_e32 v161, 0xbfb8aa3b, v123
	v_mul_f32_e32 v128, v128, v162
	v_mul_f32_e32 v129, v129, v163
	v_mul_f32_e32 v162, 0xbfb8aa3b, v124
	v_mul_f32_e32 v163, 0xbfb8aa3b, v125
	v_exp_f32_e32 v160, v160
	v_exp_f32_e32 v161, v161
	v_exp_f32_e32 v162, v162
	v_exp_f32_e32 v163, v163
	v_add_f32_e32 v160, 1.0, v160
	v_add_f32_e32 v161, 1.0, v161
	v_add_f32_e32 v162, 1.0, v162
	v_add_f32_e32 v163, 1.0, v163
	v_rcp_f32_e32 v160, v160
	v_rcp_f32_e32 v161, v161
	v_rcp_f32_e32 v162, v162
	v_rcp_f32_e32 v163, v163
	v_mul_f32_e32 v120, v128, v120
	v_mul_f32_e32 v121, v129, v121
	v_mul_f32_e32 v122, v122, v160
	v_mul_f32_e32 v123, v123, v161
	v_mul_f32_e32 v118, v126, v118
	v_mul_f32_e32 v119, v127, v119
	v_mul_f32_e32 v124, v124, v162
	v_mul_f32_e32 v125, v125, v163
	v_mul_f32_e32 v114, v122, v114
	v_mul_f32_e32 v115, v123, v115
	v_mul_f32_e32 v116, v124, v116
	v_mul_f32_e32 v117, v125, v117
	v_cvt_pk_bf16_f32 v118, v118, v119
	v_cvt_pk_bf16_f32 v119, v120, v121
	v_cvt_pk_bf16_f32 v120, v114, v115
	v_cvt_pk_bf16_f32 v117, v116, v117
	ds_bpermute_b32 v114, v151, v118
	ds_bpermute_b32 v115, v151, v119
	ds_bpermute_b32 v116, v151, v120
	ds_bpermute_b32 v117, v151, v117
	v_lshl_add_u32 v157, s18, 8, v152
	v_ashrrev_i32_e32 v149, 31, v148
	v_mov_b64_e32 v[146:147], s[58:59]
	v_mad_i64_i32 v[158:159], s[20:21], v157, s39, v[146:147]
	v_lshlrev_b64 v[148:149], 1, v[148:149]
	v_lshl_add_u64 v[158:159], v[158:159], 0, v[148:149]
	v_mul_f32_e32 v118, 0xbfb8aa3b, v110
	v_mul_f32_e32 v119, 0xbfb8aa3b, v111
	s_waitcnt lgkmcnt(0)
	global_store_dwordx4 v[158:159], v[114:117], off
	v_exp_f32_e32 v118, v118
	v_exp_f32_e32 v119, v119
	v_mul_f32_e32 v116, 0xbfb8aa3b, v112
	v_mul_f32_e32 v117, 0xbfb8aa3b, v113
	v_exp_f32_e32 v116, v116
	v_exp_f32_e32 v117, v117
	v_add_f32_e32 v114, 1.0, v118
	v_add_f32_e32 v115, 1.0, v119
	v_add_f32_e32 v116, 1.0, v116
	v_add_f32_e32 v117, 1.0, v117
	v_rcp_f32_e32 v114, v114
	v_rcp_f32_e32 v115, v115
	v_rcp_f32_e32 v116, v116
	v_rcp_f32_e32 v117, v117
	s_andn2_b64 vcc, exec, s[0:1]
	v_mul_f32_e32 v110, v110, v114
	v_mul_f32_e32 v111, v111, v115
	v_mul_f32_e32 v114, 0xbfb8aa3b, v106
	v_mul_f32_e32 v115, 0xbfb8aa3b, v107
	v_mul_f32_e32 v112, v112, v116
	v_mul_f32_e32 v113, v113, v117
	v_mul_f32_e32 v116, 0xbfb8aa3b, v108
	v_mul_f32_e32 v117, 0xbfb8aa3b, v109
	v_exp_f32_e32 v114, v114
	v_exp_f32_e32 v115, v115
	v_exp_f32_e32 v116, v116
	v_exp_f32_e32 v117, v117
	v_add_f32_e32 v114, 1.0, v114
	v_add_f32_e32 v115, 1.0, v115
	v_add_f32_e32 v116, 1.0, v116
	v_add_f32_e32 v117, 1.0, v117
	v_rcp_f32_e32 v114, v114
	v_rcp_f32_e32 v115, v115
	v_rcp_f32_e32 v116, v116
	v_rcp_f32_e32 v117, v117
	v_mul_f32_e32 v104, v112, v104
	v_mul_f32_e32 v105, v113, v105
	v_mul_f32_e32 v106, v106, v114
	v_mul_f32_e32 v107, v107, v115
	v_mul_f32_e32 v102, v110, v102
	v_mul_f32_e32 v103, v111, v103
	v_mul_f32_e32 v108, v108, v116
	v_mul_f32_e32 v109, v109, v117
	v_mul_f32_e32 v98, v106, v98
	v_mul_f32_e32 v99, v107, v99
	v_mul_f32_e32 v100, v108, v100
	v_mul_f32_e32 v101, v109, v101
	v_cvt_pk_bf16_f32 v102, v102, v103
	v_cvt_pk_bf16_f32 v103, v104, v105
	v_cvt_pk_bf16_f32 v104, v98, v99
	v_cvt_pk_bf16_f32 v101, v100, v101
	ds_bpermute_b32 v98, v151, v102
	ds_bpermute_b32 v99, v151, v103
	ds_bpermute_b32 v100, v151, v104
	ds_bpermute_b32 v101, v151, v101
	v_or_b32_e32 v102, 16, v157
	v_mad_i64_i32 v[102:103], s[20:21], v102, s39, v[146:147]
	v_lshl_add_u64 v[102:103], v[102:103], 0, v[148:149]
	s_waitcnt lgkmcnt(0)
	global_store_dwordx4 v[102:103], v[98:101], off
	v_mul_f32_e32 v102, 0xbfb8aa3b, v96
	v_mul_f32_e32 v103, 0xbfb8aa3b, v97
	v_mul_f32_e32 v100, 0xbfb8aa3b, v94
	v_mul_f32_e32 v101, 0xbfb8aa3b, v95
	v_exp_f32_e32 v100, v100
	v_exp_f32_e32 v101, v101
	v_exp_f32_e32 v102, v102
	v_exp_f32_e32 v103, v103
	v_add_f32_e32 v100, 1.0, v100
	v_add_f32_e32 v101, 1.0, v101
	v_add_f32_e32 v102, 1.0, v102
	v_add_f32_e32 v103, 1.0, v103
	v_rcp_f32_e32 v100, v100
	v_rcp_f32_e32 v101, v101
	v_rcp_f32_e32 v102, v102
	v_rcp_f32_e32 v103, v103
	v_or_b32_e32 v98, 32, v157
	v_mul_f32_e32 v94, v94, v100
	v_mul_f32_e32 v95, v95, v101
	v_mul_f32_e32 v100, 0xbfb8aa3b, v90
	v_mul_f32_e32 v101, 0xbfb8aa3b, v91
	v_mul_f32_e32 v96, v96, v102
	v_mul_f32_e32 v97, v97, v103
	v_mul_f32_e32 v102, 0xbfb8aa3b, v92
	v_mul_f32_e32 v103, 0xbfb8aa3b, v93
	v_exp_f32_e32 v100, v100
	v_exp_f32_e32 v101, v101
	v_exp_f32_e32 v102, v102
	v_exp_f32_e32 v103, v103
	v_add_f32_e32 v100, 1.0, v100
	v_add_f32_e32 v101, 1.0, v101
	v_add_f32_e32 v102, 1.0, v102
	v_add_f32_e32 v103, 1.0, v103
	v_rcp_f32_e32 v100, v100
	v_rcp_f32_e32 v101, v101
	v_rcp_f32_e32 v102, v102
	v_rcp_f32_e32 v103, v103
	v_mul_f32_e32 v88, v96, v88
	v_mul_f32_e32 v89, v97, v89
	v_mul_f32_e32 v90, v90, v100
	v_mul_f32_e32 v91, v91, v101
	v_mul_f32_e32 v86, v94, v86
	v_mul_f32_e32 v87, v95, v87
	v_mul_f32_e32 v92, v92, v102
	v_mul_f32_e32 v93, v93, v103
	v_mul_f32_e32 v82, v90, v82
	v_mul_f32_e32 v83, v91, v83
	v_mul_f32_e32 v84, v92, v84
	v_mul_f32_e32 v85, v93, v85
	v_cvt_pk_bf16_f32 v86, v86, v87
	v_cvt_pk_bf16_f32 v87, v88, v89
	v_cvt_pk_bf16_f32 v88, v82, v83
	v_cvt_pk_bf16_f32 v85, v84, v85
	ds_bpermute_b32 v82, v151, v86
	ds_bpermute_b32 v83, v151, v87
	ds_bpermute_b32 v84, v151, v88
	ds_bpermute_b32 v85, v151, v85
	v_mad_i64_i32 v[98:99], s[20:21], v98, s39, v[146:147]
	v_lshl_add_u64 v[98:99], v[98:99], 0, v[148:149]
	v_mul_f32_e32 v86, 0xbfb8aa3b, v78
	v_mul_f32_e32 v87, 0xbfb8aa3b, v79
	s_waitcnt lgkmcnt(0)
; __device__ __forceinline__ u32x4 pack8(const f32x4 a, const f32x4 b) { u32x4 o; o.x = pk2(a.x, a.y); o.y = pk2(a.z, a.w); o.z = pk2(b.x, b.y); o.w = pk2(b.z, b.w); return o; }
; __device__ __forceinline__ f32x4 sig4(const f32x4 v) { f32x4 r; r.x = sigmoidf_(v.x); r.y = sigmoidf_(v.y); r.z = sigmoidf_(v.z); r.w = sigmoidf_(v.w); return r; }
;     __device__ __forceinline__ void operator()(const pg8::f32x4 (&acc)[2][2][4][2], const pg8::Unit& u, int wr, int wc, int fr, int fq) const {
;     ...
;         for (int ai = 0; ai < 2; ++ai)
; #pragma unroll
;             for (int m = 0; m < 4; ++m) { bf16* rowp = O + (size_t)(row0 + ai * 128 + m * 16) * DFF + col0;
;                 const f32x4 a0 = acc[ai][0][m][0], a1 = acc[ai][0][m][1], b0 = acc[ai][1][m][0], b1 = acc[ai][1][m][1];
;                 *(u32x4*)rowp = epi_perm(pack8(a0 * sig4(a0) * b0, a1 * sig4(a1) * b1), src4); }
;     }
	global_store_dwordx4 v[98:99], v[82:85], off
	v_exp_f32_e32 v86, v86
	v_exp_f32_e32 v87, v87
	v_mul_f32_e32 v84, 0xbfb8aa3b, v80
	v_mul_f32_e32 v85, 0xbfb8aa3b, v81
	v_exp_f32_e32 v84, v84
	v_exp_f32_e32 v85, v85
	v_add_f32_e32 v82, 1.0, v86
	v_add_f32_e32 v83, 1.0, v87
	v_add_f32_e32 v84, 1.0, v84
	v_add_f32_e32 v85, 1.0, v85
	v_rcp_f32_e32 v82, v82
	v_rcp_f32_e32 v83, v83
	v_rcp_f32_e32 v84, v84
	v_rcp_f32_e32 v85, v85
	s_mov_b64 s[0:1], -1
	v_mul_f32_e32 v78, v78, v82
	v_mul_f32_e32 v79, v79, v83
	v_mul_f32_e32 v82, 0xbfb8aa3b, v74
	v_mul_f32_e32 v83, 0xbfb8aa3b, v75
	v_mul_f32_e32 v80, v80, v84
	v_mul_f32_e32 v81, v81, v85
	v_mul_f32_e32 v84, 0xbfb8aa3b, v76
	v_mul_f32_e32 v85, 0xbfb8aa3b, v77
	v_exp_f32_e32 v82, v82
	v_exp_f32_e32 v83, v83
	v_exp_f32_e32 v84, v84
	v_exp_f32_e32 v85, v85
	v_add_f32_e32 v82, 1.0, v82
	v_add_f32_e32 v83, 1.0, v83
	v_add_f32_e32 v84, 1.0, v84
	v_add_f32_e32 v85, 1.0, v85
	v_rcp_f32_e32 v82, v82
	v_rcp_f32_e32 v83, v83
	v_rcp_f32_e32 v84, v84
	v_rcp_f32_e32 v85, v85
	v_mul_f32_e32 v72, v80, v72
	v_mul_f32_e32 v73, v81, v73
	v_mul_f32_e32 v74, v74, v82
	v_mul_f32_e32 v75, v75, v83
	v_mul_f32_e32 v70, v78, v70
	v_mul_f32_e32 v71, v79, v71
	v_mul_f32_e32 v76, v76, v84
	v_mul_f32_e32 v77, v77, v85
	v_mul_f32_e32 v66, v74, v66
	v_mul_f32_e32 v67, v75, v67
	v_mul_f32_e32 v68, v76, v68
	v_mul_f32_e32 v69, v77, v69
	v_cvt_pk_bf16_f32 v70, v70, v71
	v_cvt_pk_bf16_f32 v71, v72, v73
	v_cvt_pk_bf16_f32 v72, v66, v67
	v_cvt_pk_bf16_f32 v69, v68, v69
	ds_bpermute_b32 v66, v151, v70
	ds_bpermute_b32 v67, v151, v71
	ds_bpermute_b32 v68, v151, v72
	ds_bpermute_b32 v69, v151, v69
	v_or_b32_e32 v70, 48, v157
	v_mad_i64_i32 v[70:71], s[20:21], v70, s39, v[146:147]
	v_lshl_add_u64 v[70:71], v[70:71], 0, v[148:149]
	s_waitcnt lgkmcnt(0)
	global_store_dwordx4 v[70:71], v[66:69], off
	v_mul_f32_e32 v70, 0xbfb8aa3b, v64
	v_mul_f32_e32 v71, 0xbfb8aa3b, v65
	v_mul_f32_e32 v68, 0xbfb8aa3b, v62
	v_mul_f32_e32 v69, 0xbfb8aa3b, v63
	v_exp_f32_e32 v68, v68
	v_exp_f32_e32 v69, v69
	v_exp_f32_e32 v70, v70
	v_exp_f32_e32 v71, v71
	v_add_f32_e32 v68, 1.0, v68
	v_add_f32_e32 v69, 1.0, v69
	v_add_f32_e32 v70, 1.0, v70
	v_add_f32_e32 v71, 1.0, v71
	v_rcp_f32_e32 v68, v68
	v_rcp_f32_e32 v69, v69
	v_rcp_f32_e32 v70, v70
	v_rcp_f32_e32 v71, v71
	v_add_u32_e32 v66, 0x80, v157
	v_mul_f32_e32 v62, v62, v68
	v_mul_f32_e32 v63, v63, v69
	v_mul_f32_e32 v68, 0xbfb8aa3b, v58
	v_mul_f32_e32 v69, 0xbfb8aa3b, v59
	v_mul_f32_e32 v64, v64, v70
	v_mul_f32_e32 v65, v65, v71
	v_mul_f32_e32 v70, 0xbfb8aa3b, v60
	v_mul_f32_e32 v71, 0xbfb8aa3b, v61
	v_exp_f32_e32 v68, v68
	v_exp_f32_e32 v69, v69
	v_exp_f32_e32 v70, v70
	v_exp_f32_e32 v71, v71
	v_add_f32_e32 v68, 1.0, v68
	v_add_f32_e32 v69, 1.0, v69
	v_add_f32_e32 v70, 1.0, v70
	v_add_f32_e32 v71, 1.0, v71
	v_rcp_f32_e32 v68, v68
	v_rcp_f32_e32 v69, v69
	v_rcp_f32_e32 v70, v70
	v_rcp_f32_e32 v71, v71
	v_mul_f32_e32 v56, v64, v56
	v_mul_f32_e32 v57, v65, v57
	v_mul_f32_e32 v58, v58, v68
	v_mul_f32_e32 v59, v59, v69
	v_mul_f32_e32 v54, v62, v54
	v_mul_f32_e32 v55, v63, v55
	v_mul_f32_e32 v60, v60, v70
	v_mul_f32_e32 v61, v61, v71
	v_mul_f32_e32 v50, v58, v50
	v_mul_f32_e32 v51, v59, v51
	v_mul_f32_e32 v52, v60, v52
	v_mul_f32_e32 v53, v61, v53
	v_cvt_pk_bf16_f32 v54, v54, v55
	v_cvt_pk_bf16_f32 v55, v56, v57
	v_cvt_pk_bf16_f32 v56, v50, v51
	v_cvt_pk_bf16_f32 v53, v52, v53
	ds_bpermute_b32 v50, v151, v54
	ds_bpermute_b32 v51, v151, v55
	ds_bpermute_b32 v52, v151, v56
	ds_bpermute_b32 v53, v151, v53
	v_mad_i64_i32 v[66:67], s[20:21], v66, s39, v[146:147]
	v_lshl_add_u64 v[66:67], v[66:67], 0, v[148:149]
	v_mul_f32_e32 v54, 0xbfb8aa3b, v46
	v_mul_f32_e32 v55, 0xbfb8aa3b, v47
	s_waitcnt lgkmcnt(0)
	global_store_dwordx4 v[66:67], v[50:53], off
	v_exp_f32_e32 v54, v54
	v_exp_f32_e32 v55, v55
	v_mul_f32_e32 v52, 0xbfb8aa3b, v48
	v_mul_f32_e32 v53, 0xbfb8aa3b, v49
	v_exp_f32_e32 v52, v52
	v_exp_f32_e32 v53, v53
	v_add_f32_e32 v50, 1.0, v54
	v_add_f32_e32 v51, 1.0, v55
	v_add_f32_e32 v52, 1.0, v52
	v_add_f32_e32 v53, 1.0, v53
	v_rcp_f32_e32 v50, v50
	v_rcp_f32_e32 v51, v51
	v_rcp_f32_e32 v52, v52
	v_rcp_f32_e32 v53, v53
	v_mul_f32_e32 v46, v46, v50
	v_mul_f32_e32 v47, v47, v51
	v_mul_f32_e32 v50, 0xbfb8aa3b, v42
	v_mul_f32_e32 v51, 0xbfb8aa3b, v43
	v_mul_f32_e32 v48, v48, v52
	v_mul_f32_e32 v49, v49, v53
	v_mul_f32_e32 v52, 0xbfb8aa3b, v44
	v_mul_f32_e32 v53, 0xbfb8aa3b, v45
	v_exp_f32_e32 v50, v50
	v_exp_f32_e32 v51, v51
	v_exp_f32_e32 v52, v52
	v_exp_f32_e32 v53, v53
	v_add_f32_e32 v50, 1.0, v50
	v_add_f32_e32 v51, 1.0, v51
	v_add_f32_e32 v52, 1.0, v52
	v_add_f32_e32 v53, 1.0, v53
	v_rcp_f32_e32 v50, v50
	v_rcp_f32_e32 v51, v51
	v_rcp_f32_e32 v52, v52
	v_rcp_f32_e32 v53, v53
	v_mul_f32_e32 v40, v48, v40
	v_mul_f32_e32 v41, v49, v41
	v_mul_f32_e32 v42, v42, v50
	v_mul_f32_e32 v43, v43, v51
	v_mul_f32_e32 v38, v46, v38
	v_mul_f32_e32 v39, v47, v39
	v_mul_f32_e32 v44, v44, v52
	v_mul_f32_e32 v45, v45, v53
	v_mul_f32_e32 v34, v42, v34
	v_mul_f32_e32 v35, v43, v35
	v_mul_f32_e32 v36, v44, v36
	v_mul_f32_e32 v37, v45, v37
	v_cvt_pk_bf16_f32 v38, v38, v39
	v_cvt_pk_bf16_f32 v39, v40, v41
	v_cvt_pk_bf16_f32 v40, v34, v35
	v_cvt_pk_bf16_f32 v37, v36, v37
	ds_bpermute_b32 v34, v151, v38
	ds_bpermute_b32 v35, v151, v39
	ds_bpermute_b32 v36, v151, v40
	ds_bpermute_b32 v37, v151, v37
	v_add_u32_e32 v38, 0x90, v157
	v_mad_i64_i32 v[38:39], s[20:21], v38, s39, v[146:147]
	v_lshl_add_u64 v[38:39], v[38:39], 0, v[148:149]
	s_waitcnt lgkmcnt(0)
; #define PG8_BAR __builtin_amdgcn_s_barrier()
; __device__ __forceinline__ u32x4 pack8(const f32x4 a, const f32x4 b) { u32x4 o; o.x = pk2(a.x, a.y); o.y = pk2(a.z, a.w); o.z = pk2(b.x, b.y); o.w = pk2(b.z, b.w); return o; }
; __device__ __forceinline__ f32x4 sig4(const f32x4 v) { f32x4 r; r.x = sigmoidf_(v.x); r.y = sigmoidf_(v.y); r.z = sigmoidf_(v.z); r.w = sigmoidf_(v.w); return r; }
; template <class Epi, class Sched, bool ALIGN_EPI = false, bool SP2 = false>
; __device__ __forceinline__ void gemm_phase(PG8_LAS unsigned char* lds, const Gemm g, const Sched& S, const Epi& E) {
;     ...
;         if constexpr (ALIGN_EPI) { if (wr == 0) PG8_BAR; }
;         if constexpr (!Epi::AFTER_DRAIN) { E(acc, cur, wr, wc, fr, fq); S.done(cur); }
;         if (!has_next) break;
; #pragma unroll
;         for (int a = 0; a < 2; ++a)
; #pragma unroll
;             for (int b = 0; b < 2; ++b)
; #pragma unroll
;                 for (int m = 0; m < 4; ++m)
; #pragma unroll
;                     for (int n = 0; n < 2; ++n) acc[a][b][m][n] = (f32x4){0.f, 0.f, 0.f, 0.f};
;         cur = nxt; cA = nA; cB = nB; ++ui;
;         if constexpr (ALIGN_EPI) { if (wr == 1) PG8_BAR; }
;     }
;     __device__ __forceinline__ void operator()(const pg8::f32x4 (&acc)[2][2][4][2], const pg8::Unit& u, int wr, int wc, int fr, int fq) const {
;     ...
;         for (int ai = 0; ai < 2; ++ai)
; #pragma unroll
;             for (int m = 0; m < 4; ++m) { bf16* rowp = O + (size_t)(row0 + ai * 128 + m * 16) * DFF + col0;
;                 const f32x4 a0 = acc[ai][0][m][0], a1 = acc[ai][0][m][1], b0 = acc[ai][1][m][0], b1 = acc[ai][1][m][1];
;                 *(u32x4*)rowp = epi_perm(pack8(a0 * sig4(a0) * b0, a1 * sig4(a1) * b1), src4); }
;     }
	global_store_dwordx4 v[38:39], v[34:37], off
	v_mul_f32_e32 v38, 0xbfb8aa3b, v32
	v_mul_f32_e32 v39, 0xbfb8aa3b, v33
	v_mul_f32_e32 v36, 0xbfb8aa3b, v30
	v_mul_f32_e32 v37, 0xbfb8aa3b, v31
	v_exp_f32_e32 v36, v36
	v_exp_f32_e32 v37, v37
	v_exp_f32_e32 v38, v38
	v_exp_f32_e32 v39, v39
	v_add_f32_e32 v36, 1.0, v36
	v_add_f32_e32 v37, 1.0, v37
	v_add_f32_e32 v38, 1.0, v38
	v_add_f32_e32 v39, 1.0, v39
	v_rcp_f32_e32 v36, v36
	v_rcp_f32_e32 v37, v37
	v_rcp_f32_e32 v38, v38
	v_rcp_f32_e32 v39, v39
	v_add_u32_e32 v34, 0xa0, v157
	v_mul_f32_e32 v30, v30, v36
	v_mul_f32_e32 v31, v31, v37
	v_mul_f32_e32 v36, 0xbfb8aa3b, v26
	v_mul_f32_e32 v37, 0xbfb8aa3b, v27
	v_mul_f32_e32 v32, v32, v38
	v_mul_f32_e32 v33, v33, v39
	v_mul_f32_e32 v38, 0xbfb8aa3b, v28
	v_mul_f32_e32 v39, 0xbfb8aa3b, v29
	v_exp_f32_e32 v36, v36
	v_exp_f32_e32 v37, v37
	v_exp_f32_e32 v38, v38
	v_exp_f32_e32 v39, v39
	v_add_f32_e32 v36, 1.0, v36
	v_add_f32_e32 v37, 1.0, v37
	v_add_f32_e32 v38, 1.0, v38
	v_add_f32_e32 v39, 1.0, v39
	v_rcp_f32_e32 v36, v36
	v_rcp_f32_e32 v37, v37
	v_rcp_f32_e32 v38, v38
	v_rcp_f32_e32 v39, v39
	v_mul_f32_e32 v24, v32, v24
	v_mul_f32_e32 v25, v33, v25
	v_mul_f32_e32 v26, v26, v36
	v_mul_f32_e32 v27, v27, v37
	v_mul_f32_e32 v22, v30, v22
	v_mul_f32_e32 v23, v31, v23
	v_mul_f32_e32 v28, v28, v38
	v_mul_f32_e32 v29, v29, v39
	v_mul_f32_e32 v18, v26, v18
	v_mul_f32_e32 v19, v27, v19
	v_mul_f32_e32 v20, v28, v20
	v_mul_f32_e32 v21, v29, v21
	v_cvt_pk_bf16_f32 v22, v22, v23
	v_cvt_pk_bf16_f32 v23, v24, v25
	v_cvt_pk_bf16_f32 v24, v18, v19
	v_cvt_pk_bf16_f32 v21, v20, v21
	ds_bpermute_b32 v18, v151, v22
	ds_bpermute_b32 v19, v151, v23
	ds_bpermute_b32 v20, v151, v24
	ds_bpermute_b32 v21, v151, v21
	v_mad_i64_i32 v[34:35], s[20:21], v34, s39, v[146:147]
	v_lshl_add_u64 v[34:35], v[34:35], 0, v[148:149]
	v_mul_f32_e32 v22, 0xbfb8aa3b, v14
	v_mul_f32_e32 v23, 0xbfb8aa3b, v15
	s_waitcnt lgkmcnt(0)
	global_store_dwordx4 v[34:35], v[18:21], off
	v_exp_f32_e32 v22, v22
	v_exp_f32_e32 v23, v23
	v_mul_f32_e32 v20, 0xbfb8aa3b, v16
	v_mul_f32_e32 v21, 0xbfb8aa3b, v17
	v_exp_f32_e32 v20, v20
	v_exp_f32_e32 v21, v21
	v_add_f32_e32 v18, 1.0, v22
	v_add_f32_e32 v19, 1.0, v23
	v_add_f32_e32 v20, 1.0, v20
	v_add_f32_e32 v21, 1.0, v21
	v_rcp_f32_e32 v18, v18
	v_rcp_f32_e32 v19, v19
	v_rcp_f32_e32 v20, v20
	v_rcp_f32_e32 v21, v21
	v_mul_f32_e32 v14, v14, v18
	v_mul_f32_e32 v15, v15, v19
	v_mul_f32_e32 v18, 0xbfb8aa3b, v10
	v_mul_f32_e32 v19, 0xbfb8aa3b, v11
	v_mul_f32_e32 v16, v16, v20
	v_mul_f32_e32 v17, v17, v21
	v_mul_f32_e32 v20, 0xbfb8aa3b, v12
	v_mul_f32_e32 v21, 0xbfb8aa3b, v13
	v_exp_f32_e32 v18, v18
	v_exp_f32_e32 v19, v19
	v_exp_f32_e32 v20, v20
	v_exp_f32_e32 v21, v21
	v_add_f32_e32 v18, 1.0, v18
	v_add_f32_e32 v19, 1.0, v19
	v_add_f32_e32 v20, 1.0, v20
	v_add_f32_e32 v21, 1.0, v21
	v_rcp_f32_e32 v18, v18
	v_rcp_f32_e32 v19, v19
	v_rcp_f32_e32 v20, v20
	v_rcp_f32_e32 v21, v21
	v_mul_f32_e32 v8, v16, v8
	v_mul_f32_e32 v9, v17, v9
	v_mul_f32_e32 v10, v10, v18
	v_mul_f32_e32 v11, v11, v19
	v_mul_f32_e32 v6, v14, v6
	v_mul_f32_e32 v7, v15, v7
	v_mul_f32_e32 v12, v12, v20
	v_mul_f32_e32 v13, v13, v21
	v_mul_f32_e32 v2, v10, v2
	v_mul_f32_e32 v3, v11, v3
	v_mul_f32_e32 v4, v12, v4
	v_mul_f32_e32 v5, v13, v5
	v_cvt_pk_bf16_f32 v6, v6, v7
	v_cvt_pk_bf16_f32 v7, v8, v9
	v_cvt_pk_bf16_f32 v8, v2, v3
	v_cvt_pk_bf16_f32 v5, v4, v5
	ds_bpermute_b32 v2, v151, v6
	ds_bpermute_b32 v3, v151, v7
	ds_bpermute_b32 v4, v151, v8
	ds_bpermute_b32 v5, v151, v5
	v_add_u32_e32 v6, 0xb0, v157
	v_mad_i64_i32 v[6:7], s[20:21], v6, s39, v[146:147]
	v_lshl_add_u64 v[6:7], v[6:7], 0, v[148:149]
	s_waitcnt lgkmcnt(0)
	global_store_dwordx4 v[6:7], v[2:5], off
	s_cbranch_vccnz .LBB0_347
	s_andn2_b64 vcc, exec, s[4:5]
	s_cbranch_vccnz .LBB0_346
	s_barrier
	s_branch .LBB0_346

; __device__ __forceinline__ unsigned pk2(float lo, float hi) { const bfx2 b = __builtin_convertvector((f32x2){lo, hi}, bfx2); return __builtin_bit_cast(unsigned, b); }
; __device__ __forceinline__ f32x4 sig4(const f32x4 v) { f32x4 r; r.x = sigmoidf_(v.x); r.y = sigmoidf_(v.y); r.z = sigmoidf_(v.z); r.w = sigmoidf_(v.w); return r; }
; template <int CW, int NB, int NS, class Epi>
; __device__ __forceinline__ void skinny_gemm(Frame& F, const bf16* A, int K, const bf16* Bt, int nchunks, const Epi& E) {
;     ...
;         if (ks == 0) {
; #pragma unroll
;             for (int i = 0; i < 2; ++i)
; #pragma unroll
;                 for (int j = 0; j < NT; ++j) {
; #pragma unroll
;                     for (int nb = 0; nb < NB; ++nb) acc[i][j][nb] += red[((i * NT + j) * NB + nb) * 256 + rg * 64 + lane];
;                     if (16 * j + 4 * lq < CW) E(32 * rg + 16 * i + lr, c0 + 16 * j + 4 * lq, acc[i][j][0], acc[i][j][NB - 1]); }
;         }
;     __device__ __forceinline__ void operator()(int r, int c, const pg8::f32x4 a, const pg8::f32x4 b) const {
;         const f32x4 v = a * sig4(a) * b; u32x2 w; w.x = pk2(v.x, v.y); w.y = pk2(v.z, v.w); *(u32x2*)(ACT + (size_t)(MP + r) * DFF + c) = w; }
.LBB0_373:
	s_andn2_b64 vcc, exec, s[4:5]
	s_waitcnt lgkmcnt(0)
	s_barrier
	s_cbranch_vccnz .LBB0_360
	s_waitcnt vmcnt(10)
	ds_read_b128 v[82:85], v162
	v_or_b32_e32 v86, s21, v147
	v_ashrrev_i32_e32 v87, 31, v86
	s_waitcnt lgkmcnt(0)
	v_add_f32_e32 v84, v80, v84
	v_add_f32_e32 v85, v81, v85
	v_add_f32_e32 v82, v78, v82
	v_add_f32_e32 v83, v79, v83
	ds_read_b128 v[78:81], v162 offset:4096
	s_waitcnt lgkmcnt(0)
	v_add_f32_e32 v74, v74, v78
	v_add_f32_e32 v75, v75, v79
	v_mul_f32_e32 v78, 0xbfb8aa3b, v82
	v_mul_f32_e32 v79, 0xbfb8aa3b, v83
	v_add_f32_e32 v76, v76, v80
	v_add_f32_e32 v77, v77, v81
	v_exp_f32_e32 v78, v78
	v_exp_f32_e32 v79, v79
	v_mul_f32_e32 v80, 0xbfb8aa3b, v84
	v_mul_f32_e32 v81, 0xbfb8aa3b, v85
	v_exp_f32_e32 v80, v80
	v_exp_f32_e32 v81, v81
	v_add_f32_e32 v78, 1.0, v78
	v_add_f32_e32 v79, 1.0, v79
	v_rcp_f32_e32 v78, v78
	v_rcp_f32_e32 v79, v79
	v_add_f32_e32 v80, 1.0, v80
	v_add_f32_e32 v81, 1.0, v81
	v_rcp_f32_e32 v80, v80
	v_rcp_f32_e32 v81, v81
	v_mul_f32_e32 v78, v82, v78
	v_mul_f32_e32 v79, v83, v79
	v_mul_f32_e32 v80, v84, v80
	v_mul_f32_e32 v81, v85, v81
	v_mul_f32_e32 v74, v74, v78
	v_mul_f32_e32 v75, v75, v79
	v_mul_f32_e32 v76, v76, v80
	v_mul_f32_e32 v77, v77, v81
	v_cvt_pk_bf16_f32 v78, v74, v75
	v_lshlrev_b64 v[74:75], 1, v[86:87]
	v_cvt_pk_bf16_f32 v79, v76, v77
	v_lshl_add_u64 v[80:81], v[140:141], 0, v[74:75]
	global_store_dwordx2 v[80:81], v[78:79], off
	ds_read_b128 v[76:79], v162 offset:8192
	s_waitcnt lgkmcnt(0)
	v_add_f32_e32 v78, v72, v78
	v_add_f32_e32 v79, v73, v79
	v_add_f32_e32 v76, v70, v76
	v_add_f32_e32 v77, v71, v77
	ds_read_b128 v[70:73], v162 offset:12288
	s_waitcnt lgkmcnt(0)
	v_add_f32_e32 v68, v68, v72
	v_add_f32_e32 v69, v69, v73
	v_add_f32_e32 v66, v66, v70
	v_add_f32_e32 v67, v67, v71
	v_mul_f32_e32 v70, 0xbfb8aa3b, v76
	v_mul_f32_e32 v71, 0xbfb8aa3b, v77
	v_mul_f32_e32 v72, 0xbfb8aa3b, v78
	v_mul_f32_e32 v73, 0xbfb8aa3b, v79
	v_exp_f32_e32 v70, v70
	v_exp_f32_e32 v71, v71
	v_exp_f32_e32 v72, v72
	v_exp_f32_e32 v73, v73
	v_add_f32_e32 v70, 1.0, v70
	v_add_f32_e32 v71, 1.0, v71
	v_add_f32_e32 v72, 1.0, v72
	v_add_f32_e32 v73, 1.0, v73
	v_rcp_f32_e32 v70, v70
	v_rcp_f32_e32 v71, v71
	v_rcp_f32_e32 v72, v72
	v_rcp_f32_e32 v73, v73
	v_mul_f32_e32 v70, v76, v70
	v_mul_f32_e32 v71, v77, v71
	s_nop 0
	v_mul_f32_e32 v66, v66, v70
	v_mul_f32_e32 v67, v67, v71
	v_mul_f32_e32 v72, v78, v72
	v_mul_f32_e32 v73, v79, v73
	v_cvt_pk_bf16_f32 v66, v66, v67
	v_mul_f32_e32 v68, v68, v72
	v_mul_f32_e32 v69, v69, v73
	s_nop 0
	v_cvt_pk_bf16_f32 v67, v68, v69
	global_store_dwordx2 v[80:81], v[66:67], off offset:32
	ds_read_b128 v[66:69], v162 offset:16384
	s_waitcnt lgkmcnt(0)
	v_add_f32_e32 v68, v64, v68
	v_add_f32_e32 v69, v65, v69
	v_add_f32_e32 v66, v62, v66
	v_add_f32_e32 v67, v63, v67
	ds_read_b128 v[62:65], v162 offset:20480
	s_waitcnt lgkmcnt(0)
	v_add_f32_e32 v60, v60, v64
	v_add_f32_e32 v61, v61, v65
	v_add_f32_e32 v58, v58, v62
	v_add_f32_e32 v59, v59, v63
	v_mul_f32_e32 v62, 0xbfb8aa3b, v66
	v_mul_f32_e32 v63, 0xbfb8aa3b, v67
	v_mul_f32_e32 v64, 0xbfb8aa3b, v68
	v_mul_f32_e32 v65, 0xbfb8aa3b, v69
	v_exp_f32_e32 v62, v62
	v_exp_f32_e32 v63, v63
	v_exp_f32_e32 v64, v64
	v_exp_f32_e32 v65, v65
	v_add_f32_e32 v62, 1.0, v62
	v_add_f32_e32 v63, 1.0, v63
	v_add_f32_e32 v64, 1.0, v64
	v_add_f32_e32 v65, 1.0, v65
	v_rcp_f32_e32 v62, v62
	v_rcp_f32_e32 v63, v63
	v_rcp_f32_e32 v64, v64
	v_rcp_f32_e32 v65, v65
	v_mul_f32_e32 v62, v66, v62
	v_mul_f32_e32 v63, v67, v63
	s_nop 0
	v_mul_f32_e32 v58, v58, v62
	v_mul_f32_e32 v59, v59, v63
	v_mul_f32_e32 v64, v68, v64
	v_mul_f32_e32 v65, v69, v65
	v_cvt_pk_bf16_f32 v58, v58, v59
	v_mul_f32_e32 v60, v60, v64
	v_mul_f32_e32 v61, v61, v65
	v_lshl_add_u64 v[62:63], v[142:143], 0, v[74:75]
	v_cvt_pk_bf16_f32 v59, v60, v61
	global_store_dwordx2 v[62:63], v[58:59], off
	ds_read_b128 v[58:61], v162 offset:24576
	s_waitcnt lgkmcnt(0)
	v_add_f32_e32 v60, v56, v60
	v_add_f32_e32 v61, v57, v61
	v_add_f32_e32 v58, v54, v58
	v_add_f32_e32 v59, v55, v59
	ds_read_b128 v[54:57], v162 offset:28672
	s_waitcnt lgkmcnt(0)
	v_add_f32_e32 v52, v52, v56
	v_add_f32_e32 v53, v53, v57
	v_add_f32_e32 v50, v50, v54
	v_add_f32_e32 v51, v51, v55
	v_mul_f32_e32 v54, 0xbfb8aa3b, v58
	v_mul_f32_e32 v55, 0xbfb8aa3b, v59
	v_mul_f32_e32 v56, 0xbfb8aa3b, v60
	v_mul_f32_e32 v57, 0xbfb8aa3b, v61
	v_exp_f32_e32 v54, v54
	v_exp_f32_e32 v55, v55
	v_exp_f32_e32 v56, v56
	v_exp_f32_e32 v57, v57
	v_add_f32_e32 v54, 1.0, v54
	v_add_f32_e32 v55, 1.0, v55
	v_add_f32_e32 v56, 1.0, v56
	v_add_f32_e32 v57, 1.0, v57
	v_rcp_f32_e32 v54, v54
	v_rcp_f32_e32 v55, v55
	v_rcp_f32_e32 v56, v56
	v_rcp_f32_e32 v57, v57
	v_mul_f32_e32 v54, v58, v54
	v_mul_f32_e32 v55, v59, v55
	s_nop 0
	v_mul_f32_e32 v50, v50, v54
	v_mul_f32_e32 v51, v51, v55
	v_mul_f32_e32 v56, v60, v56
	v_mul_f32_e32 v57, v61, v57
	v_cvt_pk_bf16_f32 v50, v50, v51
	v_mul_f32_e32 v52, v52, v56
	v_mul_f32_e32 v53, v53, v57
	s_nop 0
	v_cvt_pk_bf16_f32 v51, v52, v53
	global_store_dwordx2 v[62:63], v[50:51], off offset:32
	s_branch .LBB0_360

; __device__ __forceinline__ unsigned pk2(float lo, float hi) { const bfx2 b = __builtin_convertvector((f32x2){lo, hi}, bfx2); return __builtin_bit_cast(unsigned, b); }
; template <int NS, class Epi>
; __device__ __forceinline__ void skinny_gemm2d(Frame& F, const bf16* A, int K, const bf16* Bt, const Epi& E) {
;     ...
;         if (ks == 1) red[(mt * 2 + nt) * 64 + lane] = acc;
;         __syncthreads();
;         if (ks == 0) { acc += red[(mt * 2 + nt) * 64 + lane]; E(r0 + lr, c0 + 4 * lq, acc, acc); }
;         __syncthreads();
;     __device__ __forceinline__ void operator()(int r, int c, const pg8::f32x4 a, const pg8::f32x4) const {
;         u32x2 w; w.x = pk2(a.x, a.y); w.y = pk2(a.z, a.w); *(u32x2*)(O + (size_t)(MP + r) * ldc + c) = w; }
.LBB0_460:
	s_and_b64 vcc, exec, s[4:5]
	s_waitcnt lgkmcnt(0)
	s_barrier
	s_cbranch_vccnz .LBB0_457
	ds_read_b128 v[6:9], v207
	s_waitcnt lgkmcnt(0)
	s_nop 0
	v_add_f32_e32 v4, v4, v8
	v_add_f32_e32 v5, v5, v9
	v_add_f32_e32 v2, v2, v6
	v_add_f32_e32 v3, v3, v7
	v_or_b32_e32 v6, s12, v208
	v_cvt_pk_bf16_f32 v2, v2, v3
	v_cvt_pk_bf16_f32 v3, v4, v5
	v_or_b32_e32 v4, s11, v211
	v_readlane_b32 s12, v254, 8
	v_lshlrev_b32_e32 v190, 12, v4
	v_readlane_b32 s13, v254, 9
	v_ashrrev_i32_e32 v7, 31, v6
	s_nop 0
	v_lshl_add_u64 v[4:5], s[12:13], 0, v[190:191]
	v_lshl_add_u64 v[4:5], v[6:7], 1, v[4:5]
	global_store_dwordx2 v[4:5], v[2:3], off
	s_branch .LBB0_457

; __device__ __forceinline__ float bflo(unsigned w) { return __uint_as_float(w << 16); }
; __device__ __forceinline__ float bfhi(unsigned w) { return __uint_as_float(w & 0xffff0000u); }
; template <bool INB, bool OUTB>
; __device__ __forceinline__ void thin_phase(Frame& F, const bf16* Fb, const void* xin_p, const void* xin_s, const float* post_g, float half, void* xout, const float* next_g, bf16* H) {
;     ...
;     for (int m0 = 2 * gw; m0 < MT; m0 += 2 * NGW) {
;         f32x4 f[2][8], x[2][8]; float s[2] = {0.f, 0.f};
; #pragma unroll
;         for (int r = 0; r < 2; ++r) { const int m = m0 + r;
; #pragma unroll
;             for (int j = 0; j < 4; ++j) { const int c = (j * 64 + lane) * 8; const u32x4 w = *(const u32x4*)(Fb + (size_t)m * D + c);
;                 f[r][2 * j] = (f32x4){bflo(w.x), bfhi(w.x), bflo(w.y), bfhi(w.y)}; f[r][2 * j + 1] = (f32x4){bflo(w.z), bfhi(w.z), bflo(w.w), bfhi(w.w)};
;                 if (INB) { const bf16* xr = m < MP ? (const bf16*)xin_p + (size_t)m * D : (const bf16*)xin_s + (size_t)(m - MP) * D; const u32x4 xw = *(const u32x4*)(xr + c);
;                     x[r][2 * j] = (f32x4){bflo(xw.x), bfhi(xw.x), bflo(xw.y), bfhi(xw.y)}; x[r][2 * j + 1] = (f32x4){bflo(xw.z), bfhi(xw.z), bflo(xw.w), bfhi(xw.w)}; }
;                 else { const float* xr = m < MP ? (const float*)xin_p + (size_t)m * D : (const float*)xin_s + (size_t)(m - MP) * D; x[r][2 * j] = *(const f32x4*)(xr + c); x[r][2 * j + 1] = *(const f32x4*)(xr + c + 4); } } }
; #pragma unroll
;         for (int r = 0; r < 2; ++r)
; #pragma unroll
;             for (int q = 0; q < 8; ++q) s[r] += (f[r][q].x * f[r][q].x + f[r][q].y * f[r][q].y) + (f[r][q].z * f[r][q].z + f[r][q].w * f[r][q].w);
;         const float r0 = half / sqrtf(wave_sum(s[0]) * (1.0f / D) + RMS_EPS), r1 = half / sqrtf(wave_sum(s[1]) * (1.0f / D) + RMS_EPS);
.LBB0_517:
	s_add_i32 s14, s6, 0xffffc000
	s_lshl_b64 s[4:5], s[14:15], 13
	s_mov_b32 s9, 0xfbeff000
	s_add_u32 s4, s62, s4
	v_add_co_u32_e32 v2, vcc, s9, v106
	s_addc_u32 s5, s63, s5
	s_nop 0
	v_addc_co_u32_e32 v3, vcc, -1, v107, vcc
	s_mov_b32 s9, 0xfbf00000
	s_cmpk_lt_i32 s6, 0x4000
	v_add_co_u32_e32 v58, vcc, s9, v106
	s_cselect_b32 s5, s3, s5
	s_cselect_b32 s4, s2, s4
	v_addc_co_u32_e32 v59, vcc, -1, v107, vcc
	global_load_dwordx4 v[76:79], v[2:3], off offset:-3072
	global_load_dwordx4 v[26:29], v158, s[4:5] offset:16
	global_load_dwordx4 v[30:33], v158, s[4:5]
	global_load_dwordx4 v[68:71], v[2:3], off offset:-2048
	global_load_dwordx4 v[14:17], v158, s[4:5] offset:2064
	global_load_dwordx4 v[18:21], v158, s[4:5] offset:2048
	global_load_dwordx4 v[64:67], v[2:3], off offset:-1024
	s_nop 0
	global_load_dwordx4 v[2:5], v159, s[4:5] offset:16
	global_load_dwordx4 v[6:9], v159, s[4:5]
	global_load_dwordx4 v[80:83], v[58:59], off offset:-4096
	s_add_i32 s9, s6, 1
	s_add_u32 s16, s2, 0x2000
	s_addc_u32 s17, s3, 0
	s_add_i32 s14, s6, 0xffffc001
	global_load_dwordx4 v[10:13], v160, s[4:5] offset:16
	global_load_dwordx4 v[22:25], v160, s[4:5]
	s_lshl_b64 s[4:5], s[14:15], 13
	s_add_u32 s4, s62, s4
	s_addc_u32 s5, s63, s5
	s_cmpk_lt_i32 s9, 0x4000
	s_cselect_b32 s5, s17, s5
	s_cselect_b32 s4, s16, s4
	global_load_dwordx4 v[72:75], v[58:59], off offset:-3072
	global_load_dwordx4 v[42:45], v158, s[4:5] offset:16
	global_load_dwordx4 v[46:49], v158, s[4:5]
	global_load_dwordx4 v[86:89], v[58:59], off offset:-2048
	s_waitcnt vmcnt(15)
	v_and_b32_e32 v137, 0xffff0000, v78
	v_and_b32_e32 v136, 0xffff0000, v76
	v_and_b32_e32 v141, 0xffff0000, v79
	v_and_b32_e32 v140, 0xffff0000, v77
	s_waitcnt vmcnt(12)
	v_lshlrev_b32_e32 v116, 16, v70
	v_lshlrev_b32_e32 v139, 16, v78
	s_waitcnt vmcnt(6)
	v_lshlrev_b32_e32 v114, 16, v82
	v_and_b32_e32 v115, 0xffff0000, v82
	v_lshlrev_b32_e32 v118, 16, v83
	v_and_b32_e32 v119, 0xffff0000, v83
	global_load_dwordx4 v[50:53], v158, s[4:5] offset:2064
	global_load_dwordx4 v[54:57], v158, s[4:5] offset:2048
	global_load_dwordx4 v[82:85], v[58:59], off offset:-1024
	global_load_dwordx4 v[34:37], v159, s[4:5] offset:16
	global_load_dwordx4 v[38:41], v159, s[4:5]
	global_load_dwordx4 v[90:93], v[58:59], off
	v_lshlrev_b32_e32 v138, 16, v76
	v_lshlrev_b32_e32 v143, 16, v79
	v_lshlrev_b32_e32 v142, 16, v77
	v_mul_f32_e32 v76, v136, v136
	v_mul_f32_e32 v77, v137, v137
	v_mul_f32_e32 v78, v140, v140
	v_mul_f32_e32 v79, v141, v141
	v_and_b32_e32 v117, 0xffff0000, v70
	v_lshlrev_b32_e32 v111, 16, v64
	v_fma_f32 v76, v138, v138, v76
	v_fma_f32 v77, v139, v139, v77
	v_fma_f32 v78, v142, v142, v78
	v_fma_f32 v79, v143, v143, v79
	v_and_b32_e32 v133, 0xffff0000, v69
	v_and_b32_e32 v132, 0xffff0000, v68
	v_mul_f32_e32 v110, v116, v116
	v_add_f32_e32 v76, v76, v78
	v_add_f32_e32 v77, v77, v79
	v_lshlrev_b32_e32 v131, 16, v69
	v_lshlrev_b32_e32 v130, 16, v68
	v_mul_f32_e32 v68, v132, v132
	v_mul_f32_e32 v69, v133, v133
	v_mul_f32_e32 v70, v117, v117
	v_lshlrev_b32_e32 v134, 16, v71
	v_and_b32_e32 v135, 0xffff0000, v71
	v_mov_b32_e32 v71, v111
	v_mul_f32_e32 v78, v110, v110
	v_mul_f32_e32 v79, v111, v111
	v_and_b32_e32 v109, 0xffff0000, v64
	v_lshlrev_b32_e32 v112, 16, v65
	v_and_b32_e32 v113, 0xffff0000, v65
	v_fma_f32 v68, v130, v130, v68
	v_fma_f32 v69, v131, v131, v69
	v_add_f32_e32 v70, v110, v70
	v_add_f32_e32 v71, v111, v71
	v_mul_f32_e32 v78, v135, v135
	s_waitcnt vmcnt(6)
	v_lshlrev_b32_e32 v126, 16, v88
	v_and_b32_e32 v127, 0xffff0000, v88
	v_mul_f32_e32 v88, v109, v109
	v_mul_f32_e32 v108, v112, v112
	v_mul_f32_e32 v120, v113, v113
	v_mov_b32_e32 v71, v79
	v_fma_f32 v79, v135, v135, v78
	v_fma_f32 v78, v134, v134, v78
	v_pk_add_f32 v[76:77], v[76:77], v[76:77] op_sel:[0,1] op_sel_hi:[1,0]
	v_pk_add_f32 v[68:69], v[68:69], v[68:69] op_sel:[0,1] op_sel_hi:[1,0]
	v_mov_b32_e32 v79, v88
	v_mov_b32_e32 v77, v108
	v_mov_b32_e32 v69, v120
	v_add_f32_e32 v70, v70, v78
	v_add_f32_e32 v71, v71, v79
	v_add_f32_e32 v68, v76, v68
	v_add_f32_e32 v69, v77, v69
	v_lshlrev_b32_e32 v76, 16, v66
	v_add_f32_e32 v68, v70, v68
	v_add_f32_e32 v69, v71, v69
	v_and_b32_e32 v77, 0xffff0000, v66
	v_add_f32_e32 v69, v68, v69
	v_add_f32_e32 v68, v68, v68
	v_mul_f32_e32 v66, v76, v76
	v_lshlrev_b32_e32 v128, 16, v67
	v_lshlrev_b32_e32 v78, 16, v80
	v_fma_f32 v70, v76, v76, v66
	v_fma_f32 v71, v77, v77, v66
	v_and_b32_e32 v129, 0xffff0000, v67
	v_mul_f32_e32 v66, v128, v128
	v_and_b32_e32 v79, 0xffff0000, v80
	v_mul_f32_e32 v68, v78, v78
	v_lshlrev_b32_e32 v80, 16, v81
	v_fma_f32 v67, v129, v129, v66
	v_fma_f32 v66, v128, v128, v66
	v_fma_f32 v144, v78, v78, v68
	v_fma_f32 v145, v79, v79, v68
	v_and_b32_e32 v81, 0xffff0000, v81
	v_mul_f32_e32 v68, v80, v80
	v_fma_f32 v146, v80, v80, v68
	v_fma_f32 v147, v81, v81, v68
	v_add_f32_e32 v66, v70, v66
	v_add_f32_e32 v67, v71, v67
	v_mul_f32_e32 v68, v115, v115
	v_mul_f32_e32 v144, v118, v118
	v_mul_f32_e32 v146, v119, v119
	v_mul_f32_e32 v148, v114, v114
	v_mov_b32_e32 v149, v67
	v_add_f32_e32 v66, v148, v68
	v_add_f32_e32 v67, v149, v69
	v_add_f32_e32 v68, v144, v146
	v_add_f32_e32 v69, v145, v147
	v_and_b32_e32 v151, 0xffff0000, v74
	v_add_f32_e32 v66, v66, v68
	v_add_f32_e32 v67, v67, v69
	v_and_b32_e32 v150, 0xffff0000, v72
	v_and_b32_e32 v155, 0xffff0000, v75
	v_and_b32_e32 v154, 0xffff0000, v73
	v_add_f32_e32 v108, v66, v67
	v_lshlrev_b32_e32 v153, 16, v74
	v_lshlrev_b32_e32 v152, 16, v72
	v_lshlrev_b32_e32 v157, 16, v75
	v_lshlrev_b32_e32 v156, 16, v73
	v_mul_f32_e32 v66, v150, v150
	v_mul_f32_e32 v67, v151, v151
	v_mul_f32_e32 v68, v154, v154
	v_mul_f32_e32 v69, v155, v155
	s_waitcnt vmcnt(3)
; template <bool INB, bool OUTB>
; __device__ __forceinline__ void thin_phase(Frame& F, const bf16* Fb, const void* xin_p, const void* xin_s, const float* post_g, float half, void* xout, const float* next_g, bf16* H) {
;     ...
;         for (int r = 0; r < 2; ++r)
; #pragma unroll
;             for (int q = 0; q < 8; ++q) s[r] += (f[r][q].x * f[r][q].x + f[r][q].y * f[r][q].y) + (f[r][q].z * f[r][q].z + f[r][q].w * f[r][q].w);
;         const float r0 = half / sqrtf(wave_sum(s[0]) * (1.0f / D) + RMS_EPS), r1 = half / sqrtf(wave_sum(s[1]) * (1.0f / D) + RMS_EPS);
	v_lshlrev_b32_e32 v123, 16, v82
	v_fma_f32 v66, v152, v152, v66
	v_fma_f32 v67, v153, v153, v67
	v_fma_f32 v68, v156, v156, v68
	v_fma_f32 v69, v157, v157, v69
	v_and_b32_e32 v147, 0xffff0000, v87
	v_and_b32_e32 v146, 0xffff0000, v86
	v_mul_f32_e32 v122, v126, v126
	v_add_f32_e32 v66, v66, v68
	v_add_f32_e32 v67, v67, v69
	v_lshlrev_b32_e32 v75, 16, v87
	v_lshlrev_b32_e32 v74, 16, v86
	v_mul_f32_e32 v68, v146, v146
	v_mul_f32_e32 v69, v147, v147
	v_mul_f32_e32 v70, v127, v127
	v_and_b32_e32 v149, 0xffff0000, v89
	v_mov_b32_e32 v71, v123
	v_mul_f32_e32 v72, v122, v122
	v_mul_f32_e32 v73, v123, v123
	v_and_b32_e32 v121, 0xffff0000, v82
	v_lshlrev_b32_e32 v124, 16, v83
	v_and_b32_e32 v125, 0xffff0000, v83
	v_fma_f32 v68, v74, v74, v68
	v_fma_f32 v69, v75, v75, v69
	v_lshlrev_b32_e32 v148, 16, v89
	v_add_f32_e32 v70, v122, v70
	v_add_f32_e32 v71, v123, v71
	v_mul_f32_e32 v72, v149, v149
	v_mul_f32_e32 v86, v121, v121
	v_mul_f32_e32 v87, v124, v124
	v_mul_f32_e32 v88, v125, v125
	v_mov_b32_e32 v71, v73
	v_fma_f32 v73, v149, v149, v72
	v_fma_f32 v72, v148, v148, v72
	v_pk_add_f32 v[66:67], v[66:67], v[66:67] op_sel:[0,1] op_sel_hi:[1,0]
	v_pk_add_f32 v[68:69], v[68:69], v[68:69] op_sel:[0,1] op_sel_hi:[1,0]
	v_mov_b32_e32 v73, v86
	v_mov_b32_e32 v67, v87
	v_mov_b32_e32 v69, v88
	v_add_f32_e32 v70, v70, v72
	v_add_f32_e32 v71, v71, v73
	v_add_f32_e32 v66, v66, v68
	v_add_f32_e32 v67, v67, v69
	v_lshlrev_b32_e32 v88, 16, v84
	v_add_f32_e32 v66, v70, v66
	v_add_f32_e32 v67, v71, v67
	v_and_b32_e32 v89, 0xffff0000, v84
	v_add_f32_e32 v67, v66, v67
	v_add_f32_e32 v66, v66, v66
	v_mul_f32_e32 v66, v88, v88
	v_lshlrev_b32_e32 v144, 16, v85
	v_fma_f32 v68, v88, v88, v66
	v_fma_f32 v69, v89, v89, v66
	v_and_b32_e32 v145, 0xffff0000, v85
	v_mul_f32_e32 v66, v144, v144
	s_waitcnt vmcnt(0)
	v_lshlrev_b32_e32 v84, 16, v90
	v_fma_f32 v70, v144, v144, v66
	v_fma_f32 v71, v145, v145, v66
	v_and_b32_e32 v85, 0xffff0000, v90
	v_mul_f32_e32 v66, v84, v84
	v_lshlrev_b32_e32 v86, 16, v91
	v_fma_f32 v72, v84, v84, v66
	v_fma_f32 v73, v85, v85, v66
	v_and_b32_e32 v87, 0xffff0000, v91
	v_mul_f32_e32 v66, v86, v86
	v_lshlrev_b32_e32 v82, 16, v92
	v_and_b32_e32 v83, 0xffff0000, v92
	v_lshlrev_b32_e32 v92, 16, v93
	v_and_b32_e32 v93, 0xffff0000, v93
	v_fma_f32 v90, v86, v86, v66
	v_fma_f32 v91, v87, v87, v66
	v_add_f32_e32 v68, v68, v70
	v_add_f32_e32 v69, v69, v71
	v_mul_f32_e32 v66, v83, v83
	v_mul_f32_e32 v72, v92, v92
	v_mul_f32_e32 v90, v93, v93
	v_mul_f32_e32 v164, v82, v82
	v_mov_b32_e32 v165, v69
	v_add_f32_e32 v66, v164, v66
	v_add_f32_e32 v67, v165, v67
	v_add_f32_e32 v68, v72, v90
	v_add_f32_e32 v69, v73, v91
	global_load_dwordx4 v[58:61], v160, s[4:5] offset:16
	global_load_dwordx4 v[62:65], v160, s[4:5]
	v_add_f32_e32 v66, v66, v68
	v_add_f32_e32 v67, v67, v69
	v_mov_b32_e32 v167, v140
	v_add_f32_e32 v68, v66, v67
	v_add_f32_dpp v66, v108, v108 quad_perm:[1,0,3,2] row_mask:0xf bank_mask:0xf bound_ctrl:1
	v_mov_b32_e32 v140, v143
	v_mov_b32_e32 v164, v138
	v_add_f32_dpp v66, v66, v66 quad_perm:[2,3,0,1] row_mask:0xf bank_mask:0xf bound_ctrl:1
	v_mov_b32_e32 v165, v136
	v_mov_b32_e32 v166, v142
	v_add_f32_dpp v66, v66, v66 row_half_mirror row_mask:0xf bank_mask:0xf bound_ctrl:1
	v_mov_b32_e32 v136, v139
	s_nop 0
	v_add_f32_dpp v66, v66, v66 row_mirror row_mask:0xf bank_mask:0xf bound_ctrl:1
	s_nop 0
	v_readlane_b32 s9, v66, 16
	v_readlane_b32 s14, v66, 48
	v_readlane_b32 s4, v66, 0
	v_readlane_b32 s5, v66, 32
	v_mov_b32_e32 v66, s9
	v_mov_b32_e32 v67, s14
	v_add_f32_e32 v66, s4, v66
	v_add_f32_e32 v67, s5, v67
	s_nop 0
	v_add_f32_e32 v66, v66, v67
	v_fmamk_f32 v66, v66, 0x3a000000, v161
	v_cmp_gt_f32_e32 vcc, s7, v66
	v_mul_f32_e32 v67, 0x4f800000, v66
	s_nop 0
	v_cndmask_b32_e32 v66, v66, v67, vcc
	v_sqrt_f32_e32 v67, v66
	s_nop 0
	v_add_u32_e32 v69, -1, v67
	v_fma_f32 v70, -v69, v67, v66
	v_cmp_ge_f32_e64 s[4:5], 0, v70
	v_add_u32_e32 v70, 1, v67
	s_nop 0
	v_cndmask_b32_e64 v69, v67, v69, s[4:5]
	v_fma_f32 v67, -v70, v67, v66
	v_cmp_lt_f32_e64 s[4:5], 0, v67
	s_nop 1
	v_cndmask_b32_e64 v67, v69, v70, s[4:5]
	v_mul_f32_e32 v69, 0x37800000, v67
	v_cndmask_b32_e32 v67, v67, v69, vcc
	v_cmp_class_f32_e32 vcc, v66, v162
	s_nop 1
	v_cndmask_b32_e32 v90, v67, v66, vcc
	v_add_f32_dpp v66, v68, v68 quad_perm:[1,0,3,2] row_mask:0xf bank_mask:0xf bound_ctrl:1
	s_nop 1
	v_add_f32_dpp v66, v66, v66 quad_perm:[2,3,0,1] row_mask:0xf bank_mask:0xf bound_ctrl:1
	s_nop 1
	v_add_f32_dpp v66, v66, v66 row_half_mirror row_mask:0xf bank_mask:0xf bound_ctrl:1
	s_nop 1
	v_add_f32_dpp v66, v66, v66 row_mirror row_mask:0xf bank_mask:0xf bound_ctrl:1
	s_nop 0
	v_readlane_b32 s9, v66, 16
	v_readlane_b32 s14, v66, 48
	v_readlane_b32 s4, v66, 0
	v_readlane_b32 s5, v66, 32
	v_mov_b32_e32 v66, s9
	v_mov_b32_e32 v67, s14
	v_add_f32_e32 v66, s4, v66
	v_add_f32_e32 v67, s5, v67
	s_nop 0
	v_add_f32_e32 v66, v66, v67
	v_fmamk_f32 v66, v66, 0x3a000000, v161
	v_cmp_gt_f32_e32 vcc, s7, v66
	v_mul_f32_e32 v67, 0x4f800000, v66
	s_nop 0
	v_cndmask_b32_e32 v66, v66, v67, vcc
	v_sqrt_f32_e32 v67, v66
	s_nop 0
	v_add_u32_e32 v68, -1, v67
	v_fma_f32 v69, -v68, v67, v66
	v_cmp_ge_f32_e64 s[4:5], 0, v69
	v_add_u32_e32 v69, 1, v67
	s_nop 0
	v_cndmask_b32_e64 v68, v67, v68, s[4:5]
	v_fma_f32 v67, -v69, v67, v66
	v_cmp_lt_f32_e64 s[4:5], 0, v67
	s_nop 1
	v_cndmask_b32_e64 v67, v68, v69, s[4:5]
	v_mul_f32_e32 v68, 0x37800000, v67
	v_cndmask_b32_e32 v67, v67, v68, vcc
	v_cmp_class_f32_e32 vcc, v66, v162
	v_div_scale_f32 v108, s[4:5], v90, v90, 0.5
	s_nop 0
	v_cndmask_b32_e32 v91, v67, v66, vcc
	s_nop 0
	s_nop 0
	v_rcp_f32_e32 v110, v108
	s_nop 0
	v_fma_f32 v120, -v108, v110, 1.0
	v_fmac_f32_e32 v110, v120, v110
; #define NT_ST4(ptr_, val_) __builtin_nontemporal_store((val_), (f32x4*)(ptr_))
; __device__ __forceinline__ u32x4 pack8(const f32x4 a, const f32x4 b) { u32x4 o; o.x = pk2(a.x, a.y); o.y = pk2(a.z, a.w); o.z = pk2(b.x, b.y); o.w = pk2(b.z, b.w); return o; }
; template <bool INB, bool OUTB>
; __device__ __forceinline__ void thin_phase(Frame& F, const bf16* Fb, const void* xin_p, const void* xin_s, const float* post_g, float half, void* xout, const float* next_g, bf16* H) {
;     ...
;         for (int j = 0; j < 4; ++j) { const int c = (j * 64 + lane) * 8; const f32x4 g0 = *(const f32x4*)(post_g + c), g1 = *(const f32x4*)(post_g + c + 4);
; #pragma unroll
;             for (int r = 0; r < 2; ++r) { const f32x4 o0 = x[r][2 * j] + f[r][2 * j] * (r == 0 ? r0 : r1) * g0, o1 = x[r][2 * j + 1] + f[r][2 * j + 1] * (r == 0 ? r0 : r1) * g1; f[r][2 * j] = o0; f[r][2 * j + 1] = o1;
;                 if (OUTB) __builtin_nontemporal_store(pack8(o0, o1), (u32x4*)((bf16*)xout + (size_t)(m0 + r) * D + c));
;                 else { NT_ST4((float*)xout + (size_t)(m0 + r) * D + c, o0); NT_ST4((float*)xout + (size_t)(m0 + r) * D + c + 4, o1); }
;                 s2[r] += ((o0.x * o0.x + o0.y * o0.y) + (o0.z * o0.z + o0.w * o0.w)) + ((o1.x * o1.x + o1.y * o1.y) + (o1.z * o1.z + o1.w * o1.w)); } }
	v_div_scale_f32 v120, vcc, 0.5, v90, 0.5
	v_mul_f32_e32 v122, v120, v110
	v_fma_f32 v163, -v108, v122, v120
	v_fmac_f32_e32 v122, v163, v110
	v_fma_f32 v108, -v108, v122, v120
	v_div_fmas_f32 v108, v108, v110, v122
	v_div_fixup_f32 v90, v108, v90, 0.5
	v_div_scale_f32 v108, s[4:5], v91, v91, 0.5
	v_rcp_f32_e32 v110, v108
	v_mul_f32_e32 v138, v90, v140
	v_mul_f32_e32 v139, v90, v141
	v_add_co_u32_e32 v140, vcc, 0xfffff000, v106
	v_mul_f32_e32 v164, v90, v164
	v_mul_f32_e32 v165, v90, v165
	v_mul_f32_e32 v166, v90, v166
	v_mul_f32_e32 v167, v90, v167
	v_mul_f32_e32 v136, v90, v136
	v_mul_f32_e32 v137, v90, v137
	v_addc_co_u32_e32 v141, vcc, -1, v107, vcc
	v_fma_f32 v120, -v108, v110, 1.0
	v_fmac_f32_e32 v110, v120, v110
	v_div_scale_f32 v120, vcc, 0.5, v91, 0.5
	v_mul_f32_e32 v122, v120, v110
	s_nop 1
	v_mov_b64_e32 v[66:67], v[168:169]
	v_mov_b64_e32 v[68:69], v[170:171]
	v_mov_b64_e32 v[70:71], v[172:173]
	v_mov_b64_e32 v[72:73], v[174:175]
	v_fma_f32 v28, v68, v138, v28
	v_fma_f32 v29, v69, v139, v29
	s_nop 0
	v_fma_f32 v32, v72, v166, v32
	v_fma_f32 v33, v73, v167, v33
	v_fma_f32 v30, v70, v164, v30
	v_fma_f32 v31, v71, v165, v31
	v_fma_f32 v26, v66, v136, v26
	v_fma_f32 v27, v67, v137, v27
	v_cvt_pk_bf16_f32 v136, v30, v31
	v_cvt_pk_bf16_f32 v137, v32, v33
	v_cvt_pk_bf16_f32 v138, v26, v27
	v_cvt_pk_bf16_f32 v139, v28, v29
	global_store_dwordx4 v[140:141], v[136:139], off offset:-3072 nt
	s_nop 1
	v_fma_f32 v136, -v108, v122, v120
	v_fmac_f32_e32 v122, v136, v110
	v_fma_f32 v108, -v108, v122, v120
	v_div_fmas_f32 v108, v108, v110, v122
	v_div_fixup_f32 v110, v108, v91, 0.5
	v_mov_b32_e32 v136, v152
	v_mov_b32_e32 v137, v150
	v_mov_b32_e32 v138, v156
	v_mov_b32_e32 v139, v154
	v_mul_f32_e32 v136, v110, v136
	v_mul_f32_e32 v137, v110, v137
	v_mul_f32_e32 v138, v110, v138
	v_mul_f32_e32 v139, v110, v139
	v_mov_b32_e32 v150, v153
	v_mov_b32_e32 v154, v157
	v_fma_f32 v48, v72, v138, v48
	v_fma_f32 v49, v73, v139, v49
	v_fma_f32 v46, v70, v136, v46
	v_fma_f32 v47, v71, v137, v47
	v_mul_f32_e32 v70, v110, v150
	v_mul_f32_e32 v71, v110, v151
	v_mul_f32_e32 v72, v110, v154
	v_mul_f32_e32 v73, v110, v155
	v_fma_f32 v44, v68, v72, v44
	v_fma_f32 v45, v69, v73, v45
	v_fma_f32 v42, v66, v70, v42
	v_fma_f32 v43, v67, v71, v43
	v_cvt_pk_bf16_f32 v66, v46, v47
	v_cvt_pk_bf16_f32 v67, v48, v49
	v_cvt_pk_bf16_f32 v68, v42, v43
	v_cvt_pk_bf16_f32 v69, v44, v45
	global_store_dwordx4 v[106:107], v[66:69], off offset:-3072 nt
	s_nop 0
	s_nop 0
	v_mov_b32_e32 v66, v131
	v_mov_b32_e32 v67, v133
	v_mov_b32_e32 v131, v132
	v_mul_f32_e32 v66, v90, v66
	v_mul_f32_e32 v67, v90, v67
	v_mul_f32_e32 v68, v90, v130
	v_mul_f32_e32 v69, v90, v131
	v_mov_b32_e32 v108, v111
	v_mov_b32_e32 v120, v123
	s_and_b64 vcc, exec, s[0:1]
	s_nop 1
	v_mov_b64_e32 v[70:71], v[176:177]
	v_mov_b64_e32 v[72:73], v[178:179]
	v_mov_b64_e32 v[136:137], v[180:181]
	v_mov_b64_e32 v[138:139], v[182:183]
	v_fma_f32 v18, v68, v136, v18
	v_fma_f32 v19, v69, v137, v19
	v_fma_f32 v20, v66, v138, v20
	v_fma_f32 v21, v67, v139, v21
	v_mul_f32_e32 v68, v90, v134
	v_mul_f32_e32 v69, v90, v135
	v_mul_f32_e32 v66, v90, v116
	v_mul_f32_e32 v67, v90, v117
	v_fma_f32 v66, v66, v70, v14
	v_fma_f32 v67, v67, v71, v15
	v_fma_f32 v68, v68, v72, v16
	v_fma_f32 v69, v69, v73, v17
	v_cvt_pk_bf16_f32 v14, v18, v19
	v_cvt_pk_bf16_f32 v15, v20, v21
	v_cvt_pk_bf16_f32 v16, v66, v67
	v_cvt_pk_bf16_f32 v17, v68, v69
	global_store_dwordx4 v[140:141], v[14:17], off offset:-2048 nt
	s_nop 1
	v_mov_b32_e32 v14, v75
	v_mov_b32_e32 v15, v147
	v_mov_b32_e32 v75, v146
	v_mul_f32_e32 v14, v110, v14
	v_mul_f32_e32 v15, v110, v15
	v_mul_f32_e32 v16, v110, v74
	v_mul_f32_e32 v17, v110, v75
	v_fma_f32 v54, v136, v16, v54
	v_fma_f32 v55, v137, v17, v55
	v_fma_f32 v56, v138, v14, v56
	v_fma_f32 v57, v139, v15, v57
	v_mul_f32_e32 v14, v110, v148
	v_mul_f32_e32 v15, v110, v149
	v_mul_f32_e32 v16, v110, v126
	v_mul_f32_e32 v17, v110, v127
	v_fma_f32 v50, v70, v16, v50
	v_fma_f32 v51, v71, v17, v51
	v_fma_f32 v52, v72, v14, v52
	v_fma_f32 v53, v73, v15, v53
	v_cvt_pk_bf16_f32 v14, v54, v55
	v_cvt_pk_bf16_f32 v15, v56, v57
	v_cvt_pk_bf16_f32 v16, v50, v51
	v_cvt_pk_bf16_f32 v17, v52, v53
	global_store_dwordx4 v[106:107], v[14:17], off offset:-2048 nt
	s_nop 0
	s_nop 0
	s_nop 0
	v_mul_f32_e32 v72, v90, v112
	v_mul_f32_e32 v73, v90, v113
	v_mul_f32_e32 v70, v90, v108
	v_mul_f32_e32 v71, v90, v109
	s_nop 1
	v_mov_b64_e32 v[14:15], v[184:185]
	v_mov_b64_e32 v[16:17], v[186:187]
	v_mov_b64_e32 v[130:131], v[188:189]
	v_mov_b64_e32 v[132:133], v[190:191]
	v_fma_f32 v70, v70, v130, v6
	v_fma_f32 v71, v71, v131, v7
	v_fma_f32 v74, v72, v132, v8
	v_fma_f32 v75, v73, v133, v9
	v_mul_f32_e32 v6, v90, v128
	v_mul_f32_e32 v7, v90, v129
	v_mul_f32_e32 v8, v90, v76
	v_mul_f32_e32 v9, v90, v77
	v_fma_f32 v72, v8, v14, v2
	v_fma_f32 v73, v9, v15, v3
	v_fma_f32 v76, v6, v16, v4
	v_fma_f32 v77, v7, v17, v5
	v_cvt_pk_bf16_f32 v2, v70, v71
	v_cvt_pk_bf16_f32 v3, v74, v75
	v_cvt_pk_bf16_f32 v4, v72, v73
	v_cvt_pk_bf16_f32 v5, v76, v77
	global_store_dwordx4 v[140:141], v[2:5], off offset:-1024 nt
	s_nop 1
	v_mul_f32_e32 v2, v110, v124
	v_mul_f32_e32 v3, v110, v125
	v_mul_f32_e32 v4, v110, v120
	v_mul_f32_e32 v5, v110, v121
	v_fma_f32 v38, v130, v4, v38
	v_fma_f32 v39, v131, v5, v39
	v_fma_f32 v40, v132, v2, v40
	v_fma_f32 v41, v133, v3, v41
	v_mul_f32_e32 v2, v110, v144
	v_mul_f32_e32 v3, v110, v145
	v_mul_f32_e32 v4, v110, v88
	v_mul_f32_e32 v5, v110, v89
	v_fma_f32 v34, v14, v4, v34
	v_fma_f32 v35, v15, v5, v35
	v_fma_f32 v36, v16, v2, v36
	v_fma_f32 v37, v17, v3, v37
	v_cvt_pk_bf16_f32 v2, v38, v39
	v_cvt_pk_bf16_f32 v3, v40, v41
	v_cvt_pk_bf16_f32 v4, v34, v35
	v_cvt_pk_bf16_f32 v5, v36, v37
	global_store_dwordx4 v[106:107], v[2:5], off offset:-1024 nt
	s_nop 0
	s_nop 0
	s_nop 0
	v_mul_f32_e32 v14, v90, v80
	v_mul_f32_e32 v15, v90, v81
	v_mul_f32_e32 v16, v90, v78
	v_mul_f32_e32 v17, v90, v79
	s_nop 1
	v_mov_b64_e32 v[2:3], v[192:193]
	v_mov_b64_e32 v[4:5], v[194:195]
	v_mov_b64_e32 v[6:7], v[196:197]
	v_mov_b64_e32 v[8:9], v[198:199]
	v_fma_f32 v78, v16, v6, v22
	v_fma_f32 v79, v17, v7, v23
	v_fma_f32 v80, v14, v8, v24
	v_fma_f32 v81, v15, v9, v25
	v_mul_f32_e32 v14, v90, v118
	v_mul_f32_e32 v15, v90, v119
	v_mul_f32_e32 v16, v90, v114
	v_mul_f32_e32 v17, v90, v115
	v_fma_f32 v22, v16, v2, v10
	v_fma_f32 v23, v17, v3, v11
	v_fma_f32 v24, v14, v4, v12
	v_fma_f32 v25, v15, v5, v13
	v_cvt_pk_bf16_f32 v10, v78, v79
	v_cvt_pk_bf16_f32 v11, v80, v81
	v_cvt_pk_bf16_f32 v12, v22, v23
	v_cvt_pk_bf16_f32 v13, v24, v25
	global_store_dwordx4 v[106:107], v[10:13], off offset:-4096 nt
	s_nop 1
	v_mul_f32_e32 v10, v110, v86
	v_mul_f32_e32 v11, v110, v87
	v_mul_f32_e32 v12, v110, v84
	v_mul_f32_e32 v13, v110, v85
	s_waitcnt vmcnt(7)
; #define NT_ST4(ptr_, val_) __builtin_nontemporal_store((val_), (f32x4*)(ptr_))
; __device__ __forceinline__ u32x4 pack8(const f32x4 a, const f32x4 b) { u32x4 o; o.x = pk2(a.x, a.y); o.y = pk2(a.z, a.w); o.z = pk2(b.x, b.y); o.w = pk2(b.z, b.w); return o; }
; template <bool INB, bool OUTB>
; __device__ __forceinline__ void thin_phase(Frame& F, const bf16* Fb, const void* xin_p, const void* xin_s, const float* post_g, float half, void* xout, const float* next_g, bf16* H) {
;     ...
;             for (int r = 0; r < 2; ++r) { const f32x4 o0 = x[r][2 * j] + f[r][2 * j] * (r == 0 ? r0 : r1) * g0, o1 = x[r][2 * j + 1] + f[r][2 * j + 1] * (r == 0 ? r0 : r1) * g1; f[r][2 * j] = o0; f[r][2 * j + 1] = o1;
;                 if (OUTB) __builtin_nontemporal_store(pack8(o0, o1), (u32x4*)((bf16*)xout + (size_t)(m0 + r) * D + c));
;                 else { NT_ST4((float*)xout + (size_t)(m0 + r) * D + c, o0); NT_ST4((float*)xout + (size_t)(m0 + r) * D + c + 4, o1); }
;                 s2[r] += ((o0.x * o0.x + o0.y * o0.y) + (o0.z * o0.z + o0.w * o0.w)) + ((o1.x * o1.x + o1.y * o1.y) + (o1.z * o1.z + o1.w * o1.w)); } }
;         if (next_g) { const float q0 = 1.0f / sqrtf(wave_sum(s2[0]) * (1.0f / D) + RMS_EPS), q1 = 1.0f / sqrtf(wave_sum(s2[1]) * (1.0f / D) + RMS_EPS);
	v_fma_f32 v16, v12, v6, v62
	v_fma_f32 v17, v13, v7, v63
	v_fma_f32 v14, v10, v8, v64
	v_fma_f32 v15, v11, v9, v65
	v_mul_f32_e32 v6, v110, v92
	v_mul_f32_e32 v7, v110, v93
	v_mul_f32_e32 v8, v110, v82
	v_mul_f32_e32 v9, v110, v83
	v_fma_f32 v12, v8, v2, v58
	v_fma_f32 v13, v9, v3, v59
	v_fma_f32 v10, v6, v4, v60
	v_fma_f32 v11, v7, v5, v61
	v_cvt_pk_bf16_f32 v2, v16, v17
	v_cvt_pk_bf16_f32 v3, v14, v15
	v_cvt_pk_bf16_f32 v4, v12, v13
	v_cvt_pk_bf16_f32 v5, v10, v11
	global_store_dwordx4 v[106:107], v[2:5], off nt
	s_cbranch_vccnz .LBB0_516
	s_nop 0
	v_mul_f32_e32 v2, v48, v48
	v_mul_f32_e32 v3, v49, v49
	v_mul_f32_e32 v4, v46, v46
	v_mul_f32_e32 v5, v47, v47
	v_mul_f32_e32 v62, v17, v17
	v_pk_mov_b32 v[6:7], v[4:5], v[2:3] op_sel:[1,0]
	v_mov_b32_e32 v5, v3
	v_add_f32_e32 v2, v6, v4
	v_add_f32_e32 v3, v7, v5
	v_mul_f32_e32 v4, v44, v44
	v_mul_f32_e32 v5, v45, v45
	v_mul_f32_e32 v6, v42, v42
	v_mul_f32_e32 v7, v43, v43
	v_mul_f32_e32 v65, v12, v12
	v_pk_mov_b32 v[8:9], v[6:7], v[4:5] op_sel:[1,0]
	v_mov_b32_e32 v7, v5
	v_add_f32_e32 v4, v8, v6
	v_add_f32_e32 v5, v9, v7
	v_mul_f32_e32 v6, v56, v56
	v_mul_f32_e32 v7, v57, v57
	v_mul_f32_e32 v8, v54, v54
	v_mul_f32_e32 v9, v55, v55
	v_mul_f32_e32 v82, v13, v13
	v_pk_mov_b32 v[58:59], v[8:9], v[6:7] op_sel:[1,0]
	v_mov_b32_e32 v9, v7
	v_add_f32_e32 v6, v58, v8
	v_add_f32_e32 v7, v59, v9
	v_mul_f32_e32 v8, v52, v52
	v_mul_f32_e32 v9, v53, v53
	v_mul_f32_e32 v58, v50, v50
	v_mul_f32_e32 v59, v51, v51
	v_pk_add_f32 v[2:3], v[2:3], v[2:3] op_sel:[0,1] op_sel_hi:[1,0]
	v_pk_mov_b32 v[60:61], v[58:59], v[8:9] op_sel:[1,0]
	v_mov_b32_e32 v59, v9
	v_add_f32_e32 v8, v60, v58
	v_add_f32_e32 v9, v61, v59
	v_mul_f32_e32 v58, v39, v39
	v_mul_f32_e32 v60, v16, v16
	v_fma_f32 v59, v39, v39, v58
	v_fma_f32 v58, v38, v38, v58
	v_pk_add_f32 v[4:5], v[4:5], v[4:5] op_sel:[0,1] op_sel_hi:[1,0]
	v_mov_b32_e32 v59, v60
	v_mul_f32_e32 v60, v41, v41
	v_fma_f32 v61, v41, v41, v60
	v_fma_f32 v60, v40, v40, v60
	v_mul_f32_e32 v63, v14, v14
	v_mov_b32_e32 v61, v62
	v_add_f32_e32 v58, v58, v60
	v_add_f32_e32 v59, v59, v61
	v_mul_f32_e32 v60, v35, v35
	v_fma_f32 v61, v35, v35, v60
	v_fma_f32 v60, v34, v34, v60
	v_mul_f32_e32 v62, v37, v37
	v_mov_b32_e32 v3, v65
	v_mov_b32_e32 v5, v82
	v_mul_f32_e32 v64, v15, v15
	v_mul_f32_e32 v83, v10, v10
	v_mul_f32_e32 v84, v11, v11
	v_mov_b32_e32 v61, v63
	v_fma_f32 v63, v37, v37, v62
	v_fma_f32 v62, v36, v36, v62
	v_add_f32_e32 v2, v2, v4
	v_add_f32_e32 v3, v3, v5
	v_add_f32_e32 v4, v6, v7
	v_add_f32_e32 v5, v7, v6
	v_add_f32_e32 v6, v8, v9
	v_add_f32_e32 v7, v9, v8
	v_mov_b32_e32 v63, v64
	v_mov_b32_e32 v5, v83
	v_mov_b32_e32 v7, v84
	v_add_f32_e32 v60, v60, v62
	v_add_f32_e32 v61, v61, v63
	v_add_f32_e32 v4, v4, v6
	v_add_f32_e32 v5, v5, v7
	v_add_f32_e32 v58, v58, v60
	v_add_f32_e32 v59, v59, v61
	v_add_f32_e32 v2, v2, v4
	v_add_f32_e32 v3, v3, v5
	v_mul_f32_e32 v4, v30, v30
	v_mul_f32_e32 v5, v31, v31
	v_add_f32_e32 v2, v58, v2
	v_add_f32_e32 v3, v59, v3
	v_mul_f32_e32 v63, v22, v22
	v_add_f32_e32 v62, v2, v3
	v_mul_f32_e32 v2, v32, v32
	v_mul_f32_e32 v3, v33, v33
	v_mul_f32_e32 v64, v23, v23
	v_pk_mov_b32 v[6:7], v[4:5], v[2:3] op_sel:[1,0]
	v_mov_b32_e32 v5, v3
	v_add_f32_e32 v2, v6, v4
	v_add_f32_e32 v3, v7, v5
	v_mul_f32_e32 v4, v28, v28
	v_mul_f32_e32 v5, v29, v29
	v_mul_f32_e32 v6, v26, v26
	v_mul_f32_e32 v7, v27, v27
	v_pk_add_f32 v[2:3], v[2:3], v[2:3] op_sel:[0,1] op_sel_hi:[1,0]
	v_pk_mov_b32 v[8:9], v[6:7], v[4:5] op_sel:[1,0]
	v_mov_b32_e32 v7, v5
	v_add_f32_e32 v4, v8, v6
	v_add_f32_e32 v5, v9, v7
	v_mul_f32_e32 v6, v20, v20
	v_mul_f32_e32 v7, v21, v21
	v_mul_f32_e32 v8, v18, v18
	v_mul_f32_e32 v9, v19, v19
	v_pk_add_f32 v[4:5], v[4:5], v[4:5] op_sel:[0,1] op_sel_hi:[1,0]
	v_pk_mov_b32 v[58:59], v[8:9], v[6:7] op_sel:[1,0]
	v_mov_b32_e32 v9, v7
	v_add_f32_e32 v6, v58, v8
	v_add_f32_e32 v7, v59, v9
	v_mul_f32_e32 v8, v68, v68
	v_mul_f32_e32 v9, v69, v69
	v_mul_f32_e32 v58, v66, v66
	v_mul_f32_e32 v59, v67, v67
	v_mul_f32_e32 v65, v24, v24
	v_pk_mov_b32 v[60:61], v[58:59], v[8:9] op_sel:[1,0]
	v_mov_b32_e32 v59, v9
	v_add_f32_e32 v8, v60, v58
	v_add_f32_e32 v9, v61, v59
	v_mul_f32_e32 v58, v78, v78
	v_mul_f32_e32 v59, v79, v79
	v_mov_b32_e32 v3, v58
	v_mov_b32_e32 v5, v59
	v_mul_f32_e32 v60, v80, v80
	v_mul_f32_e32 v61, v81, v81
	v_add_f32_e32 v2, v2, v4
	v_add_f32_e32 v3, v3, v5
	v_add_f32_e32 v4, v6, v7
	v_add_f32_e32 v5, v7, v6
	v_add_f32_e32 v6, v8, v9
	v_add_f32_e32 v7, v9, v8
	v_mov_b32_e32 v5, v60
	v_mov_b32_e32 v7, v61
	v_add_f32_e32 v4, v4, v6
	v_add_f32_e32 v5, v5, v7
	v_mul_f32_e32 v6, v75, v75
	v_add_f32_e32 v2, v2, v4
	v_add_f32_e32 v3, v3, v5
	v_mul_f32_e32 v4, v71, v71
	v_fma_f32 v5, v71, v71, v4
	v_fma_f32 v4, v70, v70, v4
	v_fma_f32 v7, v75, v75, v6
	v_fma_f32 v6, v74, v74, v6
	v_mov_b32_e32 v5, v63
	v_mov_b32_e32 v7, v64
	v_add_f32_e32 v4, v4, v6
	v_add_f32_e32 v5, v5, v7
	v_mul_f32_e32 v6, v73, v73
	v_mul_f32_e32 v8, v77, v77
	v_mul_f32_e32 v82, v25, v25
	v_fma_f32 v7, v73, v73, v6
	v_fma_f32 v6, v72, v72, v6
	v_fma_f32 v9, v77, v77, v8
	v_fma_f32 v8, v76, v76, v8
	v_mov_b32_e32 v7, v65
	v_mov_b32_e32 v9, v82
	v_add_f32_e32 v6, v6, v8
	v_add_f32_e32 v7, v7, v9
	s_nop 0
	v_add_f32_e32 v4, v4, v6
	v_add_f32_e32 v5, v5, v7
	s_nop 0
	v_add_f32_e32 v2, v2, v4
	v_add_f32_e32 v3, v3, v5
	s_nop 0
	v_add_f32_e32 v2, v2, v3
	s_nop 1
	v_add_f32_dpp v2, v2, v2 quad_perm:[1,0,3,2] row_mask:0xf bank_mask:0xf bound_ctrl:1
	s_nop 1
	v_add_f32_dpp v2, v2, v2 quad_perm:[2,3,0,1] row_mask:0xf bank_mask:0xf bound_ctrl:1
	s_nop 1
	v_add_f32_dpp v2, v2, v2 row_half_mirror row_mask:0xf bank_mask:0xf bound_ctrl:1
	s_nop 1
	v_add_f32_dpp v2, v2, v2 row_mirror row_mask:0xf bank_mask:0xf bound_ctrl:1
; __device__ __forceinline__ u32x4 pack8(const f32x4 a, const f32x4 b) { u32x4 o; o.x = pk2(a.x, a.y); o.y = pk2(a.z, a.w); o.z = pk2(b.x, b.y); o.w = pk2(b.z, b.w); return o; }
; template <bool INB, bool OUTB>
; __device__ __forceinline__ void thin_phase(Frame& F, const bf16* Fb, const void* xin_p, const void* xin_s, const float* post_g, float half, void* xout, const float* next_g, bf16* H) {
;     ...
;         if (next_g) { const float q0 = 1.0f / sqrtf(wave_sum(s2[0]) * (1.0f / D) + RMS_EPS), q1 = 1.0f / sqrtf(wave_sum(s2[1]) * (1.0f / D) + RMS_EPS);
; #pragma unroll
;             for (int j = 0; j < 4; ++j) { const int c = (j * 64 + lane) * 8; const f32x4 g0 = *(const f32x4*)(next_g + c), g1 = *(const f32x4*)(next_g + c + 4);
; #pragma unroll
;                 for (int r = 0; r < 2; ++r) *(u32x4*)(H + (size_t)(m0 + r) * D + c) = pack8(f[r][2 * j] * (r == 0 ? q0 : q1) * g0, f[r][2 * j + 1] * (r == 0 ? q0 : q1) * g1); } }
	s_nop 0
	v_readlane_b32 s9, v2, 16
	v_readlane_b32 s14, v2, 48
	v_readlane_b32 s4, v2, 0
	v_readlane_b32 s5, v2, 32
	v_mov_b32_e32 v2, s9
	v_mov_b32_e32 v3, s14
	v_add_f32_e32 v2, s4, v2
	v_add_f32_e32 v3, s5, v3
	s_nop 0
	v_add_f32_e32 v2, v2, v3
	v_fmamk_f32 v2, v2, 0x3a000000, v161
	v_cmp_gt_f32_e32 vcc, s7, v2
	v_mul_f32_e32 v3, 0x4f800000, v2
	s_nop 0
	v_cndmask_b32_e32 v2, v2, v3, vcc
	v_sqrt_f32_e32 v3, v2
	s_nop 0
	v_add_u32_e32 v4, -1, v3
	v_fma_f32 v5, -v4, v3, v2
	v_cmp_ge_f32_e64 s[4:5], 0, v5
	v_add_u32_e32 v5, 1, v3
	s_nop 0
	v_cndmask_b32_e64 v4, v3, v4, s[4:5]
	v_fma_f32 v3, -v5, v3, v2
	v_cmp_lt_f32_e64 s[4:5], 0, v3
	s_nop 1
	v_cndmask_b32_e64 v3, v4, v5, s[4:5]
	v_mul_f32_e32 v4, 0x37800000, v3
	v_cndmask_b32_e32 v3, v3, v4, vcc
	v_cmp_class_f32_e32 vcc, v2, v162
	s_nop 1
	v_cndmask_b32_e32 v59, v3, v2, vcc
	v_add_f32_dpp v2, v62, v62 quad_perm:[1,0,3,2] row_mask:0xf bank_mask:0xf bound_ctrl:1
	s_nop 1
	v_add_f32_dpp v2, v2, v2 quad_perm:[2,3,0,1] row_mask:0xf bank_mask:0xf bound_ctrl:1
	s_nop 1
	v_add_f32_dpp v2, v2, v2 row_half_mirror row_mask:0xf bank_mask:0xf bound_ctrl:1
	s_nop 1
	v_add_f32_dpp v2, v2, v2 row_mirror row_mask:0xf bank_mask:0xf bound_ctrl:1
	s_nop 0
	v_readlane_b32 s9, v2, 16
	v_readlane_b32 s14, v2, 48
	v_readlane_b32 s4, v2, 0
	v_readlane_b32 s5, v2, 32
	v_mov_b32_e32 v2, s9
	v_mov_b32_e32 v3, s14
	v_add_f32_e32 v2, s4, v2
	v_add_f32_e32 v3, s5, v3
	s_nop 0
	v_add_f32_e32 v2, v2, v3
	v_fmamk_f32 v2, v2, 0x3a000000, v161
	v_cmp_gt_f32_e32 vcc, s7, v2
	v_mul_f32_e32 v3, 0x4f800000, v2
	s_nop 0
	v_cndmask_b32_e32 v2, v2, v3, vcc
	v_sqrt_f32_e32 v3, v2
	s_nop 0
	v_add_u32_e32 v4, -1, v3
	v_fma_f32 v5, -v4, v3, v2
	v_cmp_ge_f32_e64 s[4:5], 0, v5
	v_add_u32_e32 v5, 1, v3
	s_nop 0
	v_cndmask_b32_e64 v4, v3, v4, s[4:5]
	v_fma_f32 v3, -v5, v3, v2
	v_cmp_lt_f32_e64 s[4:5], 0, v3
	s_nop 1
	v_cndmask_b32_e64 v3, v4, v5, s[4:5]
	v_mul_f32_e32 v4, 0x37800000, v3
	v_cndmask_b32_e32 v3, v3, v4, vcc
	v_cmp_class_f32_e32 vcc, v2, v162
	v_div_scale_f32 v60, s[4:5], v59, v59, 1.0
	s_nop 0
	v_cndmask_b32_e32 v58, v3, v2, vcc
	s_nop 0
	s_nop 0
	v_rcp_f32_e32 v61, v60
	s_mov_b32 s4, 0xecb3f000
	v_fma_f32 v62, -v60, v61, 1.0
	v_fmac_f32_e32 v61, v62, v61
	v_div_scale_f32 v62, vcc, 1.0, v59, 1.0
	v_mul_f32_e32 v63, v62, v61
	v_fma_f32 v64, -v60, v63, v62
	v_fmac_f32_e32 v63, v64, v61
	v_fma_f32 v60, -v60, v63, v62
	v_div_fmas_f32 v60, v60, v61, v63
	v_div_fixup_f32 v60, v60, v59, 1.0
	v_mul_f32_e32 v30, v30, v60
	v_mul_f32_e32 v31, v31, v60
	v_mul_f32_e32 v32, v32, v60
	v_mul_f32_e32 v33, v33, v60
	v_mul_f32_e32 v26, v26, v60
	v_mul_f32_e32 v27, v27, v60
	v_mul_f32_e32 v28, v28, v60
	v_mul_f32_e32 v29, v29, v60
	v_mul_f32_e32 v18, v18, v60
	v_mul_f32_e32 v19, v19, v60
	v_mul_f32_e32 v20, v20, v60
	v_mul_f32_e32 v21, v21, v60
	v_mul_f32_e32 v22, v22, v60
	v_mul_f32_e32 v23, v23, v60
	v_mul_f32_e32 v24, v24, v60
	v_mul_f32_e32 v25, v25, v60
	s_nop 1
	v_mov_b64_e32 v[2:3], v[200:201]
	v_mov_b64_e32 v[4:5], v[202:203]
	v_mov_b64_e32 v[6:7], v[204:205]
	v_mov_b64_e32 v[8:9], v[206:207]
	v_mul_f32_e32 v62, v4, v28
	v_mul_f32_e32 v63, v5, v29
	s_nop 0
	v_mul_f32_e32 v30, v6, v30
	v_mul_f32_e32 v31, v7, v31
	v_mul_f32_e32 v32, v8, v32
	v_mul_f32_e32 v33, v9, v33
	v_mul_f32_e32 v28, v2, v26
	v_mul_f32_e32 v29, v3, v27
	v_cvt_pk_bf16_f32 v26, v30, v31
	v_add_co_u32_e32 v30, vcc, s4, v106
	v_cvt_pk_bf16_f32 v27, v32, v33
	v_cvt_pk_bf16_f32 v28, v28, v29
	v_cvt_pk_bf16_f32 v29, v62, v63
	v_addc_co_u32_e32 v31, vcc, -1, v107, vcc
	global_store_dwordx4 v[30:31], v[26:29], off offset:-3072
	s_nop 1
	v_div_scale_f32 v26, s[4:5], v58, v58, 1.0
	v_rcp_f32_e32 v27, v26
	s_mov_b32 s4, 0xecb40000
	v_fma_f32 v28, -v26, v27, 1.0
	v_fmac_f32_e32 v27, v28, v27
	v_div_scale_f32 v28, vcc, 1.0, v58, 1.0
	v_mul_f32_e32 v29, v28, v27
	v_fma_f32 v32, -v26, v29, v28
	v_fmac_f32_e32 v29, v32, v27
	v_fma_f32 v26, -v26, v29, v28
	v_div_fmas_f32 v26, v26, v27, v29
	v_div_fixup_f32 v26, v26, v58, 1.0
	v_mul_f32_e32 v28, v46, v26
	v_mul_f32_e32 v29, v47, v26
	v_mul_f32_e32 v32, v48, v26
	v_mul_f32_e32 v33, v49, v26
	v_mul_f32_e32 v6, v6, v28
	v_mul_f32_e32 v7, v7, v29
	v_mul_f32_e32 v8, v8, v32
	v_mul_f32_e32 v9, v9, v33
	v_mul_f32_e32 v28, v42, v26
	v_mul_f32_e32 v29, v43, v26
	v_mul_f32_e32 v32, v44, v26
	v_mul_f32_e32 v33, v45, v26
	v_mul_f32_e32 v42, v68, v60
	v_mul_f32_e32 v43, v69, v60
	v_mul_f32_e32 v32, v4, v32
	v_mul_f32_e32 v33, v5, v33
; __device__ __forceinline__ u32x4 pack8(const f32x4 a, const f32x4 b) { u32x4 o; o.x = pk2(a.x, a.y); o.y = pk2(a.z, a.w); o.z = pk2(b.x, b.y); o.w = pk2(b.z, b.w); return o; }
; template <bool INB, bool OUTB>
; __device__ __forceinline__ void thin_phase(Frame& F, const bf16* Fb, const void* xin_p, const void* xin_s, const float* post_g, float half, void* xout, const float* next_g, bf16* H) {
;     ...
;             for (int j = 0; j < 4; ++j) { const int c = (j * 64 + lane) * 8; const f32x4 g0 = *(const f32x4*)(next_g + c), g1 = *(const f32x4*)(next_g + c + 4);
; #pragma unroll
;                 for (int r = 0; r < 2; ++r) *(u32x4*)(H + (size_t)(m0 + r) * D + c) = pack8(f[r][2 * j] * (r == 0 ? q0 : q1) * g0, f[r][2 * j + 1] * (r == 0 ? q0 : q1) * g1); } }
	v_mul_f32_e32 v4, v2, v28
	v_mul_f32_e32 v5, v3, v29
	v_add_co_u32_e32 v28, vcc, s4, v106
	v_cvt_pk_bf16_f32 v2, v6, v7
	v_cvt_pk_bf16_f32 v3, v8, v9
	v_cvt_pk_bf16_f32 v4, v4, v5
	v_cvt_pk_bf16_f32 v5, v32, v33
	v_addc_co_u32_e32 v29, vcc, -1, v107, vcc
	global_store_dwordx4 v[28:29], v[2:5], off offset:-3072
	s_nop 0
	s_nop 0
	s_nop 0
	v_mul_f32_e32 v32, v66, v60
	v_mul_f32_e32 v33, v67, v60
	v_mul_f32_e32 v16, v16, v26
	v_mul_f32_e32 v17, v17, v26
	v_mul_f32_e32 v14, v14, v26
	v_mul_f32_e32 v15, v15, v26
	v_mul_f32_e32 v12, v12, v26
	v_mul_f32_e32 v13, v13, v26
	v_mul_f32_e32 v10, v10, v26
	v_mul_f32_e32 v11, v11, v26
	s_nop 1
	v_mov_b64_e32 v[2:3], v[208:209]
	v_mov_b64_e32 v[4:5], v[210:211]
	v_mov_b64_e32 v[6:7], v[212:213]
	v_mov_b64_e32 v[8:9], v[214:215]
	v_mul_f32_e32 v42, v42, v4
	v_mul_f32_e32 v43, v43, v5
	s_nop 0
	v_mul_f32_e32 v20, v20, v8
	v_mul_f32_e32 v21, v21, v9
	v_mul_f32_e32 v18, v18, v6
	v_mul_f32_e32 v19, v19, v7
	v_mul_f32_e32 v32, v32, v2
	v_mul_f32_e32 v33, v33, v3
	v_cvt_pk_bf16_f32 v18, v18, v19
	v_cvt_pk_bf16_f32 v19, v20, v21
	v_cvt_pk_bf16_f32 v20, v32, v33
	v_cvt_pk_bf16_f32 v21, v42, v43
	global_store_dwordx4 v[30:31], v[18:21], off offset:-2048
	v_mul_f32_e32 v32, v72, v60
	v_mul_f32_e32 v33, v73, v60
	v_mul_f32_e32 v42, v76, v60
	v_mul_f32_e32 v43, v77, v60
	v_mul_f32_e32 v18, v54, v26
	v_mul_f32_e32 v19, v55, v26
	v_mul_f32_e32 v20, v56, v26
	v_mul_f32_e32 v21, v57, v26
	v_mul_f32_e32 v6, v6, v18
	v_mul_f32_e32 v7, v7, v19
	v_mul_f32_e32 v8, v8, v20
	v_mul_f32_e32 v9, v9, v21
	v_mul_f32_e32 v18, v50, v26
	v_mul_f32_e32 v19, v51, v26
	v_mul_f32_e32 v20, v52, v26
	v_mul_f32_e32 v21, v53, v26
	s_nop 0
	v_mul_f32_e32 v20, v4, v20
	v_mul_f32_e32 v21, v5, v21
	v_mul_f32_e32 v4, v2, v18
	v_mul_f32_e32 v5, v3, v19
	v_cvt_pk_bf16_f32 v2, v6, v7
	v_cvt_pk_bf16_f32 v3, v8, v9
	v_cvt_pk_bf16_f32 v4, v4, v5
	v_cvt_pk_bf16_f32 v5, v20, v21
	global_store_dwordx4 v[28:29], v[2:5], off offset:-2048
	s_nop 0
	s_nop 0
	s_nop 0
	v_mul_f32_e32 v18, v70, v60
	v_mul_f32_e32 v19, v71, v60
	v_mul_f32_e32 v20, v74, v60
	v_mul_f32_e32 v21, v75, v60
	s_nop 1
	v_mov_b64_e32 v[2:3], v[216:217]
	v_mov_b64_e32 v[4:5], v[218:219]
	v_mov_b64_e32 v[6:7], v[220:221]
	v_mov_b64_e32 v[8:9], v[222:223]
	v_mul_f32_e32 v42, v42, v4
	v_mul_f32_e32 v43, v43, v5
	s_nop 0
	v_mul_f32_e32 v20, v20, v8
	v_mul_f32_e32 v21, v21, v9
	v_mul_f32_e32 v18, v18, v6
	v_mul_f32_e32 v19, v19, v7
	v_mul_f32_e32 v32, v32, v2
	v_mul_f32_e32 v33, v33, v3
	v_cvt_pk_bf16_f32 v18, v18, v19
	v_cvt_pk_bf16_f32 v19, v20, v21
	v_cvt_pk_bf16_f32 v20, v32, v33
	v_cvt_pk_bf16_f32 v21, v42, v43
	global_store_dwordx4 v[30:31], v[18:21], off offset:-1024
	s_nop 1
	v_mul_f32_e32 v18, v38, v26
	v_mul_f32_e32 v19, v39, v26
	v_mul_f32_e32 v20, v40, v26
	v_mul_f32_e32 v21, v41, v26
	v_mul_f32_e32 v6, v6, v18
	v_mul_f32_e32 v7, v7, v19
	v_mul_f32_e32 v8, v8, v20
	v_mul_f32_e32 v9, v9, v21
	v_mul_f32_e32 v18, v34, v26
	v_mul_f32_e32 v19, v35, v26
	v_mul_f32_e32 v20, v36, v26
	v_mul_f32_e32 v21, v37, v26
	s_nop 0
	v_mul_f32_e32 v20, v4, v20
	v_mul_f32_e32 v21, v5, v21
	v_mul_f32_e32 v4, v2, v18
	v_mul_f32_e32 v5, v3, v19
	v_cvt_pk_bf16_f32 v2, v6, v7
	v_cvt_pk_bf16_f32 v3, v8, v9
	v_cvt_pk_bf16_f32 v4, v4, v5
	v_cvt_pk_bf16_f32 v5, v20, v21
	global_store_dwordx4 v[28:29], v[2:5], off offset:-1024
	s_nop 0
	s_nop 0
	s_nop 0
	v_mul_f32_e32 v18, v78, v60
	v_mul_f32_e32 v19, v79, v60
	v_mul_f32_e32 v20, v80, v60
	v_mul_f32_e32 v21, v81, v60
	s_nop 1
	v_mov_b64_e32 v[2:3], v[224:225]
	v_mov_b64_e32 v[4:5], v[226:227]
	v_mov_b64_e32 v[6:7], v[228:229]
	v_mov_b64_e32 v[8:9], v[230:231]
	v_mul_f32_e32 v24, v24, v4
	v_mul_f32_e32 v25, v25, v5
	s_nop 0
	v_mul_f32_e32 v20, v20, v8
	v_mul_f32_e32 v21, v21, v9
	v_mul_f32_e32 v18, v18, v6
	v_mul_f32_e32 v19, v19, v7
	v_mul_f32_e32 v22, v22, v2
	v_mul_f32_e32 v23, v23, v3
	v_mul_f32_e32 v8, v14, v8
	v_mul_f32_e32 v9, v15, v9
	v_mul_f32_e32 v6, v16, v6
	v_mul_f32_e32 v7, v17, v7
	v_mul_f32_e32 v10, v10, v4
	v_mul_f32_e32 v11, v11, v5
	v_mul_f32_e32 v4, v12, v2
	v_mul_f32_e32 v5, v13, v3
	v_cvt_pk_bf16_f32 v18, v18, v19
	v_cvt_pk_bf16_f32 v19, v20, v21
	v_cvt_pk_bf16_f32 v20, v22, v23
	v_cvt_pk_bf16_f32 v21, v24, v25
	v_cvt_pk_bf16_f32 v2, v6, v7
	v_cvt_pk_bf16_f32 v3, v8, v9
	v_cvt_pk_bf16_f32 v4, v4, v5
	v_cvt_pk_bf16_f32 v5, v10, v11
	global_store_dwordx4 v[28:29], v[18:21], off offset:-4096
	global_store_dwordx4 v[28:29], v[2:5], off
	s_branch .LBB0_516

; __device__ __forceinline__ unsigned pk2(float lo, float hi) { const bfx2 b = __builtin_convertvector((f32x2){lo, hi}, bfx2); return __builtin_bit_cast(unsigned, b); }
; __device__ __forceinline__ f32x4 sig4(const f32x4 v) { f32x4 r; r.x = sigmoidf_(v.x); r.y = sigmoidf_(v.y); r.z = sigmoidf_(v.z); r.w = sigmoidf_(v.w); return r; }
; template <int CW, int NB, int NS, class Epi>
; __device__ __forceinline__ void skinny_gemm(Frame& F, const bf16* A, int K, const bf16* Bt, int nchunks, const Epi& E) {
;     ...
;         if (ks == 0) {
; #pragma unroll
;             for (int i = 0; i < 2; ++i)
; #pragma unroll
;                 for (int j = 0; j < NT; ++j) {
; #pragma unroll
;                     for (int nb = 0; nb < NB; ++nb) acc[i][j][nb] += red[((i * NT + j) * NB + nb) * 256 + rg * 64 + lane];
;                     if (16 * j + 4 * lq < CW) E(32 * rg + 16 * i + lr, c0 + 16 * j + 4 * lq, acc[i][j][0], acc[i][j][NB - 1]); }
;     __device__ __forceinline__ void operator()(int r, int n, const pg8::f32x4 a, const pg8::f32x4) const {
;         const int row = MP + r, b = r >> 2, t = r & 3;
;         u32x2 w; w.x = pk2(a.x, a.y); w.y = pk2(a.z, a.w);
;         if (n < 3328) { *(u32x2*)(PRW + (size_t)row * RWP + n) = w; if (t == 3) *(f32x4*)(out + O_SS + (size_t)b * RWP + n) = a; }
;         else if (n < 4352) { *(u32x2*)(Q + (size_t)row * 1024 + (n - 3328)) = w; }
;         else if (n < 5376) { *(u32x2*)(KVN + (size_t)row * 1024 + (n - 4352)) = w; *(f32x4*)(out + O_KV + (size_t)row * 1024 + (n - 4352)) = a; }
;         else if (n < 5888) { *(u32x2*)(WINN + (size_t)row * 512 + (n - 5376)) = w; *(f32x4*)(out + O_WS + ((size_t)b * 512 + 508 + t) * 512 + (n - 5376)) = a; }
;         else if (n < 7936) { const f32x4 s = sig4(a); u32x2 x; x.x = pk2(s.x, s.y); x.y = pk2(s.z, s.w); *(u32x2*)(GRW + (size_t)row * D + (n - 5888)) = x; }
;         else if (n < 9984) { const f32x4 s = sig4(a); u32x2 x; x.x = pk2(s.x, s.y); x.y = pk2(s.z, s.w); *(u32x2*)(GNSA + (size_t)row * D + (n - 7936)) = x; }
;         else if (n < 10008) { *(f32x4*)(NG + (size_t)row * 32 + (n - 9984)) = sig4(a); }
;     }
.LBB0_1121:
	s_andn2_b64 vcc, exec, s[14:15]
	s_waitcnt lgkmcnt(0)
	s_barrier
	s_cbranch_vccnz .LBB0_1104
	s_waitcnt vmcnt(8)
	ds_read_b128 v[66:69], v225
	v_add_u32_e32 v4, s10, v209
	s_movk_i32 s8, 0xcff
	v_cmp_lt_i32_e64 s[8:9], s8, v4
	s_waitcnt lgkmcnt(0)
	v_add_f32_e32 v68, v148, v68
	v_add_f32_e32 v69, v149, v69
	v_add_f32_e32 v66, v146, v66
	v_add_f32_e32 v67, v147, v67
	v_cvt_pk_bf16_f32 v71, v68, v69
	v_cvt_pk_bf16_f32 v70, v66, v67
	s_and_saveexec_b64 s[10:11], s[8:9]
	s_xor_b64 s[10:11], exec, s[10:11]
	s_cbranch_execz .LBB0_1146
	v_cmp_lt_u32_e32 vcc, s45, v4
	s_and_saveexec_b64 s[18:19], vcc
	s_xor_b64 s[18:19], exec, s[18:19]
	s_cbranch_execz .LBB0_1143
	v_cmp_lt_u32_e32 vcc, s52, v4
	s_and_saveexec_b64 s[20:21], vcc
	s_xor_b64 s[20:21], exec, s[20:21]
	s_cbranch_execz .LBB0_1140
	v_cmp_lt_u32_e32 vcc, s53, v4
	s_and_saveexec_b64 s[22:23], vcc
	s_xor_b64 s[22:23], exec, s[22:23]
	s_cbranch_execz .LBB0_1137
	v_cmp_lt_u32_e32 vcc, s54, v4
	s_and_saveexec_b64 s[24:25], vcc
	s_xor_b64 s[24:25], exec, s[24:25]
	s_cbranch_execz .LBB0_1134
	v_cmp_lt_u32_e32 vcc, s55, v4
	s_and_saveexec_b64 s[26:27], vcc
	s_xor_b64 s[26:27], exec, s[26:27]
	s_cbranch_execz .LBB0_1131
	v_cmp_gt_u32_e32 vcc, s56, v4
	s_and_saveexec_b64 s[28:29], vcc
	s_cbranch_execz .LBB0_1130
	v_mul_f32_e32 v2, 0xbfb8aa3b, v66
	v_exp_f32_e32 v2, v2
	v_mul_f32_e32 v5, 0xbfb8aa3b, v67
	v_mul_f32_e32 v67, 0xbfb8aa3b, v69
	v_exp_f32_e32 v5, v5
	v_add_f32_e32 v2, 1.0, v2
	v_rcp_f32_e32 v66, v2
	v_mul_f32_e32 v2, 0xbfb8aa3b, v68
	v_exp_f32_e32 v2, v2
	v_exp_f32_e32 v69, v67
	v_add_f32_e32 v5, 1.0, v5
	v_rcp_f32_e32 v67, v5
	v_add_f32_e32 v2, 1.0, v2
	v_rcp_f32_e32 v68, v2
	v_add_f32_e32 v2, 1.0, v69
	v_rcp_f32_e32 v69, v2
	v_mov_b32_e32 v5, v3
	v_lshl_add_u64 v[70:71], v[4:5], 2, v[168:169]
	v_add_co_u32_e32 v70, vcc, 0xffff7000, v70
	s_nop 1
	v_addc_co_u32_e32 v71, vcc, -1, v71, vcc
	global_store_dwordx4 v[70:71], v[66:69], off offset:-3072

; __device__ __forceinline__ unsigned pk2(float lo, float hi) { const bfx2 b = __builtin_convertvector((f32x2){lo, hi}, bfx2); return __builtin_bit_cast(unsigned, b); }
; __device__ __forceinline__ f32x4 sig4(const f32x4 v) { f32x4 r; r.x = sigmoidf_(v.x); r.y = sigmoidf_(v.y); r.z = sigmoidf_(v.z); r.w = sigmoidf_(v.w); return r; }
; template <int CW, int NB, int NS, class Epi>
; __device__ __forceinline__ void skinny_gemm(Frame& F, const bf16* A, int K, const bf16* Bt, int nchunks, const Epi& E) {
;     ...
;                     for (int nb = 0; nb < NB; ++nb) acc[i][j][nb] += red[((i * NT + j) * NB + nb) * 256 + rg * 64 + lane];
;                     if (16 * j + 4 * lq < CW) E(32 * rg + 16 * i + lr, c0 + 16 * j + 4 * lq, acc[i][j][0], acc[i][j][NB - 1]); }
;     __device__ __forceinline__ void operator()(int r, int n, const pg8::f32x4 a, const pg8::f32x4) const {
;         const int row = MP + r, b = r >> 2, t = r & 3;
;         u32x2 w; w.x = pk2(a.x, a.y); w.y = pk2(a.z, a.w);
;         if (n < 3328) { *(u32x2*)(PRW + (size_t)row * RWP + n) = w; if (t == 3) *(f32x4*)(out + O_SS + (size_t)b * RWP + n) = a; }
;         else if (n < 4352) { *(u32x2*)(Q + (size_t)row * 1024 + (n - 3328)) = w; }
;         else if (n < 5376) { *(u32x2*)(KVN + (size_t)row * 1024 + (n - 4352)) = w; *(f32x4*)(out + O_KV + (size_t)row * 1024 + (n - 4352)) = a; }
;         else if (n < 5888) { *(u32x2*)(WINN + (size_t)row * 512 + (n - 5376)) = w; *(f32x4*)(out + O_WS + ((size_t)b * 512 + 508 + t) * 512 + (n - 5376)) = a; }
;         else if (n < 7936) { const f32x4 s = sig4(a); u32x2 x; x.x = pk2(s.x, s.y); x.y = pk2(s.z, s.w); *(u32x2*)(GRW + (size_t)row * D + (n - 5888)) = x; }
;         else if (n < 9984) { const f32x4 s = sig4(a); u32x2 x; x.x = pk2(s.x, s.y); x.y = pk2(s.z, s.w); *(u32x2*)(GNSA + (size_t)row * D + (n - 7936)) = x; }
;         else if (n < 10008) { *(f32x4*)(NG + (size_t)row * 32 + (n - 9984)) = sig4(a); }
;     }
.LBB0_1150:
	s_or_b64 exec, exec, s[10:11]
	ds_read_b128 v[66:69], v225 offset:4096
	s_movk_i32 s10, 0xcef
	v_add_u32_e32 v2, 16, v4
	v_cmp_lt_i32_e64 s[10:11], s10, v4
	s_waitcnt lgkmcnt(0)
	v_add_f32_e32 v64, v64, v68
	v_add_f32_e32 v65, v65, v69
	v_add_f32_e32 v62, v62, v66
	v_add_f32_e32 v63, v63, v67
	v_cvt_pk_bf16_f32 v67, v64, v65
	v_cvt_pk_bf16_f32 v66, v62, v63
	s_and_saveexec_b64 s[18:19], s[10:11]
	s_xor_b64 s[18:19], exec, s[18:19]
	s_cbranch_execz .LBB0_1175
	v_cmp_lt_u32_e32 vcc, s45, v2
	s_and_saveexec_b64 s[20:21], vcc
	s_xor_b64 s[20:21], exec, s[20:21]
	s_cbranch_execz .LBB0_1171
	v_cmp_lt_u32_e32 vcc, s52, v2
	s_and_saveexec_b64 s[22:23], vcc
	s_xor_b64 s[22:23], exec, s[22:23]
	s_cbranch_execz .LBB0_1168
	v_cmp_lt_u32_e32 vcc, s53, v2
	s_and_saveexec_b64 s[24:25], vcc
	s_xor_b64 s[24:25], exec, s[24:25]
	s_cbranch_execz .LBB0_1165
	v_cmp_lt_u32_e32 vcc, s54, v2
	s_and_saveexec_b64 s[26:27], vcc
	s_xor_b64 s[26:27], exec, s[26:27]
	s_cbranch_execz .LBB0_1162
	v_cmp_lt_u32_e32 vcc, s55, v2
	s_and_saveexec_b64 s[28:29], vcc
	s_xor_b64 s[28:29], exec, s[28:29]
	s_cbranch_execz .LBB0_1159
	v_cmp_gt_u32_e32 vcc, s56, v2
	s_and_saveexec_b64 s[30:31], vcc
	s_cbranch_execz .LBB0_1158
	v_mul_f32_e32 v5, 0xbfb8aa3b, v62
	v_exp_f32_e32 v5, v5
	v_mul_f32_e32 v62, 0xbfb8aa3b, v63
	v_exp_f32_e32 v62, v62
	v_lshl_add_u64 v[66:67], v[2:3], 2, v[168:169]
	v_add_f32_e32 v5, 1.0, v5
	v_add_co_u32_e32 v66, vcc, 0xffff7000, v66
	v_add_f32_e32 v63, 1.0, v62
	v_rcp_f32_e32 v62, v5
	v_mul_f32_e32 v5, 0xbfb8aa3b, v64
	v_exp_f32_e32 v5, v5
	v_mul_f32_e32 v64, 0xbfb8aa3b, v65
	v_exp_f32_e32 v65, v64
	v_rcp_f32_e32 v63, v63
	v_add_f32_e32 v5, 1.0, v5
	v_rcp_f32_e32 v64, v5
	v_add_f32_e32 v5, 1.0, v65
	v_rcp_f32_e32 v65, v5
	v_addc_co_u32_e32 v67, vcc, -1, v67, vcc
	global_store_dwordx4 v[66:67], v[62:65], off offset:-3072

; __device__ __forceinline__ unsigned pk2(float lo, float hi) { const bfx2 b = __builtin_convertvector((f32x2){lo, hi}, bfx2); return __builtin_bit_cast(unsigned, b); }
; __device__ __forceinline__ f32x4 sig4(const f32x4 v) { f32x4 r; r.x = sigmoidf_(v.x); r.y = sigmoidf_(v.y); r.z = sigmoidf_(v.z); r.w = sigmoidf_(v.w); return r; }
; template <int CW, int NB, int NS, class Epi>
; __device__ __forceinline__ void skinny_gemm(Frame& F, const bf16* A, int K, const bf16* Bt, int nchunks, const Epi& E) {
;     ...
;                     for (int nb = 0; nb < NB; ++nb) acc[i][j][nb] += red[((i * NT + j) * NB + nb) * 256 + rg * 64 + lane];
;                     if (16 * j + 4 * lq < CW) E(32 * rg + 16 * i + lr, c0 + 16 * j + 4 * lq, acc[i][j][0], acc[i][j][NB - 1]); }
;     __device__ __forceinline__ void operator()(int r, int n, const pg8::f32x4 a, const pg8::f32x4) const {
;         const int row = MP + r, b = r >> 2, t = r & 3;
;         u32x2 w; w.x = pk2(a.x, a.y); w.y = pk2(a.z, a.w);
;         if (n < 3328) { *(u32x2*)(PRW + (size_t)row * RWP + n) = w; if (t == 3) *(f32x4*)(out + O_SS + (size_t)b * RWP + n) = a; }
;         else if (n < 4352) { *(u32x2*)(Q + (size_t)row * 1024 + (n - 3328)) = w; }
;         else if (n < 5376) { *(u32x2*)(KVN + (size_t)row * 1024 + (n - 4352)) = w; *(f32x4*)(out + O_KV + (size_t)row * 1024 + (n - 4352)) = a; }
;         else if (n < 5888) { *(u32x2*)(WINN + (size_t)row * 512 + (n - 5376)) = w; *(f32x4*)(out + O_WS + ((size_t)b * 512 + 508 + t) * 512 + (n - 5376)) = a; }
;         else if (n < 7936) { const f32x4 s = sig4(a); u32x2 x; x.x = pk2(s.x, s.y); x.y = pk2(s.z, s.w); *(u32x2*)(GRW + (size_t)row * D + (n - 5888)) = x; }
;         else if (n < 9984) { const f32x4 s = sig4(a); u32x2 x; x.x = pk2(s.x, s.y); x.y = pk2(s.z, s.w); *(u32x2*)(GNSA + (size_t)row * D + (n - 7936)) = x; }
;         else if (n < 10008) { *(f32x4*)(NG + (size_t)row * 32 + (n - 9984)) = sig4(a); }
;     }
.LBB0_1179:
	ds_read_b128 v[62:65], v225 offset:8192
	v_cmp_lt_i32_e32 vcc, s57, v4
	s_waitcnt lgkmcnt(0)
	v_add_f32_e32 v60, v60, v64
	v_add_f32_e32 v61, v61, v65
	v_add_f32_e32 v58, v58, v62
	v_add_f32_e32 v59, v59, v63
	v_cvt_pk_bf16_f32 v65, v60, v61
	v_cvt_pk_bf16_f32 v64, v58, v59
	s_and_saveexec_b64 s[20:21], vcc
	s_xor_b64 s[20:21], exec, s[20:21]
	s_cbranch_execz .LBB0_1203
	v_add_u32_e32 v62, 32, v4
	v_cmp_lt_u32_e32 vcc, s45, v62
	s_and_saveexec_b64 s[22:23], vcc
	s_xor_b64 s[22:23], exec, s[22:23]
	s_cbranch_execz .LBB0_1200
	v_cmp_lt_u32_e32 vcc, s52, v62
	s_and_saveexec_b64 s[24:25], vcc
	s_xor_b64 s[24:25], exec, s[24:25]
	s_cbranch_execz .LBB0_1197
	v_cmp_lt_u32_e32 vcc, s53, v62
	s_and_saveexec_b64 s[26:27], vcc
	s_xor_b64 s[26:27], exec, s[26:27]
	s_cbranch_execz .LBB0_1194
	v_cmp_lt_u32_e32 vcc, s54, v62
	s_and_saveexec_b64 s[28:29], vcc
	s_xor_b64 s[28:29], exec, s[28:29]
	s_cbranch_execz .LBB0_1191
	v_cmp_lt_u32_e32 vcc, s55, v62
	s_and_saveexec_b64 s[30:31], vcc
	s_xor_b64 s[30:31], exec, s[30:31]
	s_cbranch_execz .LBB0_1188
	v_cmp_gt_u32_e32 vcc, s56, v62
	s_and_saveexec_b64 s[38:39], vcc
	s_cbranch_execz .LBB0_1187
	v_mul_f32_e32 v5, 0xbfb8aa3b, v58
	v_exp_f32_e32 v5, v5
	v_mul_f32_e32 v58, 0xbfb8aa3b, v59
	v_exp_f32_e32 v58, v58
	v_mov_b32_e32 v63, v3
	v_add_f32_e32 v5, 1.0, v5
	v_lshl_add_u64 v[62:63], v[62:63], 2, v[168:169]
	v_add_f32_e32 v59, 1.0, v58
	v_rcp_f32_e32 v58, v5
	v_mul_f32_e32 v5, 0xbfb8aa3b, v60
	v_exp_f32_e32 v5, v5
	v_mul_f32_e32 v60, 0xbfb8aa3b, v61
	v_exp_f32_e32 v61, v60
	v_rcp_f32_e32 v59, v59
	v_add_f32_e32 v5, 1.0, v5
	v_rcp_f32_e32 v60, v5
	v_add_f32_e32 v5, 1.0, v61
	v_rcp_f32_e32 v61, v5
	v_add_co_u32_e32 v62, vcc, 0xffff7000, v62
	s_nop 1
	v_addc_co_u32_e32 v63, vcc, -1, v63, vcc
	global_store_dwordx4 v[62:63], v[58:61], off offset:-3072

; __device__ __forceinline__ unsigned pk2(float lo, float hi) { const bfx2 b = __builtin_convertvector((f32x2){lo, hi}, bfx2); return __builtin_bit_cast(unsigned, b); }
; __device__ __forceinline__ f32x4 sig4(const f32x4 v) { f32x4 r; r.x = sigmoidf_(v.x); r.y = sigmoidf_(v.y); r.z = sigmoidf_(v.z); r.w = sigmoidf_(v.w); return r; }
; template <int CW, int NB, int NS, class Epi>
; __device__ __forceinline__ void skinny_gemm(Frame& F, const bf16* A, int K, const bf16* Bt, int nchunks, const Epi& E) {
;     ...
;                     for (int nb = 0; nb < NB; ++nb) acc[i][j][nb] += red[((i * NT + j) * NB + nb) * 256 + rg * 64 + lane];
;                     if (16 * j + 4 * lq < CW) E(32 * rg + 16 * i + lr, c0 + 16 * j + 4 * lq, acc[i][j][0], acc[i][j][NB - 1]); }
;     __device__ __forceinline__ void operator()(int r, int n, const pg8::f32x4 a, const pg8::f32x4) const {
;         const int row = MP + r, b = r >> 2, t = r & 3;
;         u32x2 w; w.x = pk2(a.x, a.y); w.y = pk2(a.z, a.w);
;         if (n < 3328) { *(u32x2*)(PRW + (size_t)row * RWP + n) = w; if (t == 3) *(f32x4*)(out + O_SS + (size_t)b * RWP + n) = a; }
;         else if (n < 4352) { *(u32x2*)(Q + (size_t)row * 1024 + (n - 3328)) = w; }
;         else if (n < 5376) { *(u32x2*)(KVN + (size_t)row * 1024 + (n - 4352)) = w; *(f32x4*)(out + O_KV + (size_t)row * 1024 + (n - 4352)) = a; }
;         else if (n < 5888) { *(u32x2*)(WINN + (size_t)row * 512 + (n - 5376)) = w; *(f32x4*)(out + O_WS + ((size_t)b * 512 + 508 + t) * 512 + (n - 5376)) = a; }
;         else if (n < 7936) { const f32x4 s = sig4(a); u32x2 x; x.x = pk2(s.x, s.y); x.y = pk2(s.z, s.w); *(u32x2*)(GRW + (size_t)row * D + (n - 5888)) = x; }
;         else if (n < 9984) { const f32x4 s = sig4(a); u32x2 x; x.x = pk2(s.x, s.y); x.y = pk2(s.z, s.w); *(u32x2*)(GNSA + (size_t)row * D + (n - 7936)) = x; }
;         else if (n < 10008) { *(f32x4*)(NG + (size_t)row * 32 + (n - 9984)) = sig4(a); }
;     }
.LBB0_1206:
	s_or_b64 exec, exec, s[18:19]
	ds_read_b128 v[58:61], v225 offset:12288
	s_waitcnt lgkmcnt(0)
	v_add_f32_e32 v56, v56, v60
	v_add_f32_e32 v57, v57, v61
	v_add_f32_e32 v54, v54, v58
	v_add_f32_e32 v55, v55, v59
	v_cvt_pk_bf16_f32 v59, v56, v57
	v_cvt_pk_bf16_f32 v58, v54, v55
	s_and_saveexec_b64 s[18:19], s[8:9]
	s_xor_b64 s[8:9], exec, s[18:19]
	s_cbranch_execz .LBB0_1230
	v_cmp_lt_u32_e32 vcc, s45, v4
	s_and_saveexec_b64 s[18:19], vcc
	s_xor_b64 s[18:19], exec, s[18:19]
	s_cbranch_execz .LBB0_1227
	v_cmp_lt_u32_e32 vcc, s52, v4
	s_and_saveexec_b64 s[20:21], vcc
	s_xor_b64 s[20:21], exec, s[20:21]
	s_cbranch_execz .LBB0_1224
	v_cmp_lt_u32_e32 vcc, s53, v4
	s_and_saveexec_b64 s[22:23], vcc
	s_xor_b64 s[22:23], exec, s[22:23]
	s_cbranch_execz .LBB0_1221
	v_cmp_lt_u32_e32 vcc, s54, v4
	s_and_saveexec_b64 s[24:25], vcc
	s_xor_b64 s[24:25], exec, s[24:25]
	s_cbranch_execz .LBB0_1218
	v_cmp_lt_u32_e32 vcc, s55, v4
	s_and_saveexec_b64 s[26:27], vcc
	s_xor_b64 s[26:27], exec, s[26:27]
	s_cbranch_execz .LBB0_1215
	v_cmp_gt_u32_e32 vcc, s56, v4
	s_and_saveexec_b64 s[28:29], vcc
	s_cbranch_execz .LBB0_1214
	v_mul_f32_e32 v5, 0xbfb8aa3b, v54
	v_exp_f32_e32 v5, v5
	v_mul_f32_e32 v54, 0xbfb8aa3b, v55
	v_exp_f32_e32 v54, v54
	v_add_f32_e32 v5, 1.0, v5
	v_add_f32_e32 v55, 1.0, v54
	v_rcp_f32_e32 v54, v5
	v_mul_f32_e32 v5, 0xbfb8aa3b, v56
	v_exp_f32_e32 v5, v5
	v_mul_f32_e32 v56, 0xbfb8aa3b, v57
	v_exp_f32_e32 v57, v56
	v_rcp_f32_e32 v55, v55
	v_add_f32_e32 v5, 1.0, v5
	v_rcp_f32_e32 v56, v5
	v_add_f32_e32 v5, 1.0, v57
	v_rcp_f32_e32 v57, v5
	v_mov_b32_e32 v5, v3
	v_lshl_add_u64 v[58:59], v[4:5], 2, v[188:189]
	v_add_co_u32_e32 v58, vcc, 0xffff7000, v58
	s_nop 1
	v_addc_co_u32_e32 v59, vcc, -1, v59, vcc
	global_store_dwordx4 v[58:59], v[54:57], off offset:-3072

; __device__ __forceinline__ unsigned pk2(float lo, float hi) { const bfx2 b = __builtin_convertvector((f32x2){lo, hi}, bfx2); return __builtin_bit_cast(unsigned, b); }
; __device__ __forceinline__ f32x4 sig4(const f32x4 v) { f32x4 r; r.x = sigmoidf_(v.x); r.y = sigmoidf_(v.y); r.z = sigmoidf_(v.z); r.w = sigmoidf_(v.w); return r; }
; template <int CW, int NB, int NS, class Epi>
; __device__ __forceinline__ void skinny_gemm(Frame& F, const bf16* A, int K, const bf16* Bt, int nchunks, const Epi& E) {
;     ...
;                     for (int nb = 0; nb < NB; ++nb) acc[i][j][nb] += red[((i * NT + j) * NB + nb) * 256 + rg * 64 + lane];
;                     if (16 * j + 4 * lq < CW) E(32 * rg + 16 * i + lr, c0 + 16 * j + 4 * lq, acc[i][j][0], acc[i][j][NB - 1]); }
;     __device__ __forceinline__ void operator()(int r, int n, const pg8::f32x4 a, const pg8::f32x4) const {
;         const int row = MP + r, b = r >> 2, t = r & 3;
;         u32x2 w; w.x = pk2(a.x, a.y); w.y = pk2(a.z, a.w);
;         if (n < 3328) { *(u32x2*)(PRW + (size_t)row * RWP + n) = w; if (t == 3) *(f32x4*)(out + O_SS + (size_t)b * RWP + n) = a; }
;         else if (n < 4352) { *(u32x2*)(Q + (size_t)row * 1024 + (n - 3328)) = w; }
;         else if (n < 5376) { *(u32x2*)(KVN + (size_t)row * 1024 + (n - 4352)) = w; *(f32x4*)(out + O_KV + (size_t)row * 1024 + (n - 4352)) = a; }
;         else if (n < 5888) { *(u32x2*)(WINN + (size_t)row * 512 + (n - 5376)) = w; *(f32x4*)(out + O_WS + ((size_t)b * 512 + 508 + t) * 512 + (n - 5376)) = a; }
;         else if (n < 7936) { const f32x4 s = sig4(a); u32x2 x; x.x = pk2(s.x, s.y); x.y = pk2(s.z, s.w); *(u32x2*)(GRW + (size_t)row * D + (n - 5888)) = x; }
;         else if (n < 9984) { const f32x4 s = sig4(a); u32x2 x; x.x = pk2(s.x, s.y); x.y = pk2(s.z, s.w); *(u32x2*)(GNSA + (size_t)row * D + (n - 7936)) = x; }
;         else if (n < 10008) { *(f32x4*)(NG + (size_t)row * 32 + (n - 9984)) = sig4(a); }
;     }
.LBB0_1234:
	s_or_b64 exec, exec, s[8:9]
	ds_read_b128 v[54:57], v225 offset:16384
	s_waitcnt lgkmcnt(0)
	v_add_f32_e32 v52, v52, v56
	v_add_f32_e32 v53, v53, v57
	v_add_f32_e32 v50, v50, v54
	v_add_f32_e32 v51, v51, v55
	v_cvt_pk_bf16_f32 v55, v52, v53
	v_cvt_pk_bf16_f32 v54, v50, v51
	s_and_saveexec_b64 s[8:9], s[10:11]
	s_xor_b64 s[8:9], exec, s[8:9]
	s_cbranch_execz .LBB0_1259
	v_cmp_lt_u32_e32 vcc, s45, v2
	s_and_saveexec_b64 s[10:11], vcc
	s_xor_b64 s[10:11], exec, s[10:11]
	s_cbranch_execz .LBB0_1255
	v_cmp_lt_u32_e32 vcc, s52, v2
	s_and_saveexec_b64 s[18:19], vcc
	s_xor_b64 s[18:19], exec, s[18:19]
	s_cbranch_execz .LBB0_1252
	v_cmp_lt_u32_e32 vcc, s53, v2
	s_and_saveexec_b64 s[20:21], vcc
	s_xor_b64 s[20:21], exec, s[20:21]
	s_cbranch_execz .LBB0_1249
	v_cmp_lt_u32_e32 vcc, s54, v2
	s_and_saveexec_b64 s[22:23], vcc
	s_xor_b64 s[22:23], exec, s[22:23]
	s_cbranch_execz .LBB0_1246
	v_cmp_lt_u32_e32 vcc, s55, v2
	s_and_saveexec_b64 s[24:25], vcc
	s_xor_b64 s[24:25], exec, s[24:25]
	s_cbranch_execz .LBB0_1243
	v_cmp_gt_u32_e32 vcc, s56, v2
	s_and_saveexec_b64 s[26:27], vcc
	s_cbranch_execz .LBB0_1242
	v_mul_f32_e32 v5, 0xbfb8aa3b, v50
	v_exp_f32_e32 v5, v5
	v_mul_f32_e32 v50, 0xbfb8aa3b, v51
	v_exp_f32_e32 v50, v50
	v_lshl_add_u64 v[54:55], v[2:3], 2, v[188:189]
	v_add_f32_e32 v5, 1.0, v5
	v_add_co_u32_e32 v54, vcc, 0xffff7000, v54
	v_add_f32_e32 v51, 1.0, v50
	v_rcp_f32_e32 v50, v5
	v_mul_f32_e32 v5, 0xbfb8aa3b, v52
	v_exp_f32_e32 v5, v5
	v_mul_f32_e32 v52, 0xbfb8aa3b, v53
	v_exp_f32_e32 v53, v52
	v_rcp_f32_e32 v51, v51
	v_add_f32_e32 v5, 1.0, v5
	v_rcp_f32_e32 v52, v5
	v_add_f32_e32 v5, 1.0, v53
	v_rcp_f32_e32 v53, v5
	v_addc_co_u32_e32 v55, vcc, -1, v55, vcc
	global_store_dwordx4 v[54:55], v[50:53], off offset:-3072

; __device__ __forceinline__ unsigned pk2(float lo, float hi) { const bfx2 b = __builtin_convertvector((f32x2){lo, hi}, bfx2); return __builtin_bit_cast(unsigned, b); }
; __device__ __forceinline__ f32x4 sig4(const f32x4 v) { f32x4 r; r.x = sigmoidf_(v.x); r.y = sigmoidf_(v.y); r.z = sigmoidf_(v.z); r.w = sigmoidf_(v.w); return r; }
; template <int CW, int NB, int NS, class Epi>
; __device__ __forceinline__ void skinny_gemm(Frame& F, const bf16* A, int K, const bf16* Bt, int nchunks, const Epi& E) {
;     ...
;                     for (int nb = 0; nb < NB; ++nb) acc[i][j][nb] += red[((i * NT + j) * NB + nb) * 256 + rg * 64 + lane];
;                     if (16 * j + 4 * lq < CW) E(32 * rg + 16 * i + lr, c0 + 16 * j + 4 * lq, acc[i][j][0], acc[i][j][NB - 1]); }
;     __device__ __forceinline__ void operator()(int r, int n, const pg8::f32x4 a, const pg8::f32x4) const {
;         const int row = MP + r, b = r >> 2, t = r & 3;
;         u32x2 w; w.x = pk2(a.x, a.y); w.y = pk2(a.z, a.w);
;         if (n < 3328) { *(u32x2*)(PRW + (size_t)row * RWP + n) = w; if (t == 3) *(f32x4*)(out + O_SS + (size_t)b * RWP + n) = a; }
;         else if (n < 4352) { *(u32x2*)(Q + (size_t)row * 1024 + (n - 3328)) = w; }
;         else if (n < 5376) { *(u32x2*)(KVN + (size_t)row * 1024 + (n - 4352)) = w; *(f32x4*)(out + O_KV + (size_t)row * 1024 + (n - 4352)) = a; }
;         else if (n < 5888) { *(u32x2*)(WINN + (size_t)row * 512 + (n - 5376)) = w; *(f32x4*)(out + O_WS + ((size_t)b * 512 + 508 + t) * 512 + (n - 5376)) = a; }
;         else if (n < 7936) { const f32x4 s = sig4(a); u32x2 x; x.x = pk2(s.x, s.y); x.y = pk2(s.z, s.w); *(u32x2*)(GRW + (size_t)row * D + (n - 5888)) = x; }
;         else if (n < 9984) { const f32x4 s = sig4(a); u32x2 x; x.x = pk2(s.x, s.y); x.y = pk2(s.z, s.w); *(u32x2*)(GNSA + (size_t)row * D + (n - 7936)) = x; }
;         else if (n < 10008) { *(f32x4*)(NG + (size_t)row * 32 + (n - 9984)) = sig4(a); }
;     }
.LBB0_1263:
	ds_read_b128 v[50:53], v225 offset:20480
	v_cmp_lt_i32_e32 vcc, s57, v4
	s_waitcnt lgkmcnt(0)
	v_add_f32_e32 v48, v48, v52
	v_add_f32_e32 v49, v49, v53
	v_add_f32_e32 v46, v46, v50
	v_add_f32_e32 v47, v47, v51
	v_cvt_pk_bf16_f32 v51, v48, v49
	v_cvt_pk_bf16_f32 v50, v46, v47
	s_and_saveexec_b64 s[10:11], vcc
	s_xor_b64 s[10:11], exec, s[10:11]
	s_cbranch_execz .LBB0_1287
	v_add_u32_e32 v2, 32, v4
	v_cmp_lt_u32_e32 vcc, s45, v2
	s_and_saveexec_b64 s[18:19], vcc
	s_xor_b64 s[18:19], exec, s[18:19]
	s_cbranch_execz .LBB0_1284
	v_cmp_lt_u32_e32 vcc, s52, v2
	s_and_saveexec_b64 s[20:21], vcc
	s_xor_b64 s[20:21], exec, s[20:21]
	s_cbranch_execz .LBB0_1281
	v_cmp_lt_u32_e32 vcc, s53, v2
	s_and_saveexec_b64 s[22:23], vcc
	s_xor_b64 s[22:23], exec, s[22:23]
	s_cbranch_execz .LBB0_1278
	v_cmp_lt_u32_e32 vcc, s54, v2
	s_and_saveexec_b64 s[24:25], vcc
	s_xor_b64 s[24:25], exec, s[24:25]
	s_cbranch_execz .LBB0_1275
	v_cmp_lt_u32_e32 vcc, s55, v2
	s_and_saveexec_b64 s[26:27], vcc
	s_xor_b64 s[26:27], exec, s[26:27]
	s_cbranch_execz .LBB0_1272
	v_cmp_gt_u32_e32 vcc, s56, v2
	s_and_saveexec_b64 s[28:29], vcc
	s_cbranch_execz .LBB0_1271
	v_mul_f32_e32 v4, 0xbfb8aa3b, v46
	v_exp_f32_e32 v4, v4
	v_mul_f32_e32 v5, 0xbfb8aa3b, v47
	v_mul_f32_e32 v47, 0xbfb8aa3b, v49
	v_exp_f32_e32 v5, v5
	v_add_f32_e32 v4, 1.0, v4
	v_rcp_f32_e32 v46, v4
	v_mul_f32_e32 v4, 0xbfb8aa3b, v48
	v_exp_f32_e32 v4, v4
	v_exp_f32_e32 v49, v47
	v_add_f32_e32 v5, 1.0, v5
	v_rcp_f32_e32 v47, v5
	v_add_f32_e32 v4, 1.0, v4
	v_rcp_f32_e32 v48, v4
	v_add_f32_e32 v4, 1.0, v49
	v_rcp_f32_e32 v49, v4
	v_lshl_add_u64 v[4:5], v[2:3], 2, v[188:189]
	v_add_co_u32_e32 v4, vcc, 0xffff7000, v4
	s_nop 1
	v_addc_co_u32_e32 v5, vcc, -1, v5, vcc
	global_store_dwordx4 v[4:5], v[46:49], off offset:-3072

; __device__ __forceinline__ unsigned pk2(float lo, float hi) { const bfx2 b = __builtin_convertvector((f32x2){lo, hi}, bfx2); return __builtin_bit_cast(unsigned, b); }
; __device__ __forceinline__ f32x4 bf4(const u32x2 w) { return (f32x4){bflo(w.x), bfhi(w.x), bflo(w.y), bfhi(w.y)}; }
; __device__ __forceinline__ void rwkv_post(const P& p, Frame& F) {
;     const bf16* YRAW = (const bf16*)(p.ws + WS_YRAW); const bf16* VVB = (const bf16*)(p.ws + WS_VV); const float* CB = (const float*)(p.ws + WS_CB); const bf16* GG = (const bf16*)(p.ws + WS_GG);
;     bf16* YRW = (bf16*)(p.ws + WS_YRW);
;     const int gw = F.bid * NWAVES + F.wave, NGW = F.G * NWAVES, q = F.lane >> 4, c = F.lane & 15;
;     for (int it = gw; it < MT * 4; it += NGW) { const int m = it >> 2, h = 4 * (it & 3) + q, c0 = h * 64 + 4 * c;
;         size_t sr; if (m < MP) sr = (size_t)((m >> 11) * RWH + h) * TP + (m & (TP - 1)); else { const int x = m - MP; sr = (size_t)NSEQ_P * TP + (size_t)((x >> 2) * RWH + h) * TS + (x & 3); }
;         const f32x4 y = bf4(*(const u32x2*)(YRAW + (size_t)m * 1024 + c0)), vv = bf4(*(const u32x2*)(VVB + sr * 64 + 4 * c)), g = bf4(*(const u32x2*)(GG + (size_t)m * 1024 + c0));
;         const float cb = CB[(size_t)m * 16 + h];
;         const float mean = red16((y.x + y.y) + (y.z + y.w)) * (1.0f / 64.0f); const f32x4 dd = y - mean;
;         const float var = red16((dd.x * dd.x + dd.y * dd.y) + (dd.z * dd.z + dd.w * dd.w)) * (1.0f / 64.0f);
;         const f32x4 yn = dd * (1.0f / sqrtf(var + RW_LN_EPS)) * *(const f32x4*)(p.in[I_LNW] + c0) + *(const f32x4*)(p.in[I_LNB] + c0);
;         const f32x4 o = (yn + vv * cb) * g;
;         u32x2 w; w.x = pk2(o.x, o.y); w.y = pk2(o.z, o.w); *(u32x2*)(YRW + (size_t)m * 1024 + c0) = w; }
; }
.LBB0_2454:
	s_and_b32 s6, s0, s8
	s_ashr_i32 s9, s8, 31
	v_lshl_add_u64 v[8:9], v[8:9], 0, s[6:7]
	s_lshl_b64 s[0:1], s[8:9], 11
	v_lshl_or_b32 v14, v13, 6, v10
	v_lshlrev_b64 v[8:9], 7, v[8:9]
	s_add_u32 s14, s5, s0
	v_lshl_add_u64 v[8:9], v[4:5], 0, v[8:9]
	s_addc_u32 s15, s10, s1
	v_lshlrev_b32_e32 v36, 1, v14
	global_load_dwordx2 v[8:9], v[8:9], off
	v_readlane_b32 s16, v254, 31
	global_load_dwordx2 v[22:23], v36, s[14:15]
	v_readlane_b32 s14, v252, 3
	v_readlane_b32 s15, v252, 4
	s_add_u32 s14, s14, s0
	s_addc_u32 s15, s15, s1
	s_lshl_b64 s[8:9], s[8:9], 6
	s_add_u32 s8, s64, s8
	v_lshlrev_b32_e32 v2, 2, v13
	s_addc_u32 s9, s65, s9
	v_lshlrev_b32_e32 v13, 2, v14
	v_readlane_b32 s17, v254, 32
	global_load_dword v2, v2, s[8:9]
	s_nop 0
	global_load_dwordx2 v[24:25], v36, s[14:15]
	v_readlane_b32 s18, v254, 33
	v_readlane_b32 s19, v254, 34
	global_load_dwordx4 v[14:17], v13, s[16:17]
	s_nop 3
	global_load_dwordx4 v[18:21], v13, s[18:19]
	s_add_u32 s8, s2, s0
	s_addc_u32 s9, s3, s1
	s_add_i32 s4, s4, s50
	s_add_i32 s11, s11, s12
	s_cmp_lt_i32 s4, 0x10200
	v_readlane_b32 s20, v254, 35
	v_readlane_b32 s21, v254, 36
	v_readlane_b32 s22, v254, 37
	v_readlane_b32 s23, v254, 38
	v_readlane_b32 s24, v254, 39
	v_readlane_b32 s25, v254, 40
	v_readlane_b32 s26, v254, 41
	v_readlane_b32 s27, v254, 42
	v_readlane_b32 s28, v254, 43
	v_readlane_b32 s29, v254, 44
	v_readlane_b32 s30, v254, 45
	v_readlane_b32 s31, v254, 46
	s_waitcnt vmcnt(5)
	v_lshlrev_b32_e32 v26, 16, v8
	v_and_b32_e32 v27, 0xffff0000, v8
	s_waitcnt vmcnt(4)
	v_lshlrev_b32_e32 v29, 16, v23
	v_lshlrev_b32_e32 v28, 16, v22
	v_and_b32_e32 v23, 0xffff0000, v23
	v_and_b32_e32 v22, 0xffff0000, v22
	v_add_f32_e32 v30, v28, v22
	v_add_f32_e32 v31, v29, v23
	v_lshlrev_b32_e32 v8, 16, v9
	v_add_f32_e32 v13, v30, v31
	v_and_b32_e32 v9, 0xffff0000, v9
	s_nop 0
	v_add_f32_dpp v13, v13, v13 quad_perm:[1,0,3,2] row_mask:0xf bank_mask:0xf bound_ctrl:1
	s_nop 1
	v_add_f32_dpp v13, v13, v13 quad_perm:[2,3,0,1] row_mask:0xf bank_mask:0xf bound_ctrl:1
	s_nop 1
	v_add_f32_dpp v13, v13, v13 row_half_mirror row_mask:0xf bank_mask:0xf bound_ctrl:1
	s_nop 1
	v_add_f32_dpp v13, v13, v13 row_mirror row_mask:0xf bank_mask:0xf bound_ctrl:1
	v_fmac_f32_e32 v22, 0xbc800000, v13
	v_fmac_f32_e32 v23, 0xbc800000, v13
	v_fmac_f32_e32 v29, 0xbc800000, v13
	v_fmac_f32_e32 v28, 0xbc800000, v13
	v_mov_b32_e32 v30, v29
	v_mov_b32_e32 v31, v23
	v_mov_b32_e32 v29, v22
	v_mul_f32_e32 v22, v30, v30
	v_mul_f32_e32 v23, v31, v31
	v_mul_f32_e32 v32, v28, v28
	v_mul_f32_e32 v33, v29, v29
	s_nop 0
	v_pk_mov_b32 v[34:35], v[32:33], v[22:23] op_sel:[1,0]
	v_mov_b32_e32 v33, v23
	v_add_f32_e32 v22, v34, v32
	v_add_f32_e32 v23, v35, v33
	s_nop 0
	v_add_f32_e32 v13, v22, v23
	s_waitcnt vmcnt(2)
	v_and_b32_e32 v23, 0xffff0000, v24
	v_add_f32_dpp v13, v13, v13 quad_perm:[1,0,3,2] row_mask:0xf bank_mask:0xf bound_ctrl:1
	s_nop 1
	v_add_f32_dpp v13, v13, v13 quad_perm:[2,3,0,1] row_mask:0xf bank_mask:0xf bound_ctrl:1
	s_nop 1
	v_add_f32_dpp v13, v13, v13 row_half_mirror row_mask:0xf bank_mask:0xf bound_ctrl:1
	s_nop 1
	v_add_f32_dpp v13, v13, v13 row_mirror row_mask:0xf bank_mask:0xf bound_ctrl:1
	v_fmamk_f32 v13, v13, 0x3c800000, v11
	v_mul_f32_e32 v22, 0x4f800000, v13
	v_cmp_gt_f32_e32 vcc, s13, v13
	s_nop 1
	v_cndmask_b32_e32 v13, v13, v22, vcc
	v_sqrt_f32_e32 v32, v13
	v_lshlrev_b32_e32 v22, 16, v24
	v_lshlrev_b32_e32 v24, 16, v25
	v_and_b32_e32 v25, 0xffff0000, v25
	v_add_u32_e32 v33, -1, v32
	v_add_u32_e32 v34, 1, v32
	v_fma_f32 v35, -v33, v32, v13
	v_fma_f32 v37, -v34, v32, v13
	v_cmp_ge_f32_e64 s[0:1], 0, v35
	s_nop 1
	v_cndmask_b32_e64 v32, v32, v33, s[0:1]
	v_cmp_lt_f32_e64 s[0:1], 0, v37
	s_nop 1
	v_cndmask_b32_e64 v32, v32, v34, s[0:1]
	v_mul_f32_e32 v33, 0x37800000, v32
	v_cndmask_b32_e32 v32, v32, v33, vcc
	v_cmp_class_f32_e32 vcc, v13, v12
	s_nop 1
	v_cndmask_b32_e32 v13, v32, v13, vcc
	v_div_scale_f32 v32, s[0:1], v13, v13, 1.0
	v_rcp_f32_e32 v33, v32
	v_div_scale_f32 v34, vcc, 1.0, v13, 1.0
	v_fma_f32 v35, -v32, v33, 1.0
	v_fmac_f32_e32 v33, v35, v33
	v_mul_f32_e32 v35, v34, v33
	v_fma_f32 v37, -v32, v35, v34
	v_fmac_f32_e32 v35, v37, v33
	v_fma_f32 v32, -v32, v35, v34
	v_div_fmas_f32 v32, v32, v33, v35
	v_div_fixup_f32 v32, v32, v13, 1.0
	v_mul_f32_e32 v28, v28, v32
	v_mul_f32_e32 v29, v29, v32
	v_mul_f32_e32 v30, v30, v32
	v_mul_f32_e32 v31, v31, v32
	s_waitcnt vmcnt(0)
	v_fma_f32 v14, v14, v28, v18
	v_fma_f32 v15, v15, v29, v19
	v_fma_f32 v16, v16, v30, v20
	v_fma_f32 v17, v17, v31, v21
	v_fma_f32 v14, v2, v26, v14
	v_fma_f32 v15, v2, v27, v15
	v_fma_f32 v8, v2, v8, v16
	v_fma_f32 v9, v2, v9, v17
	v_mul_f32_e32 v8, v8, v24
	v_mul_f32_e32 v9, v9, v25
	v_mul_f32_e32 v14, v14, v22
	v_mul_f32_e32 v15, v15, v23
	s_nop 0
	v_cvt_pk_bf16_f32 v14, v14, v15
	v_cvt_pk_bf16_f32 v15, v8, v9
	global_store_dwordx2 v36, v[14:15], s[8:9]
	s_cbranch_scc0 .LBB0_2459

; __device__ __forceinline__ float bflo(unsigned w) { return __uint_as_float(w << 16); }
; __device__ __forceinline__ float bfhi(unsigned w) { return __uint_as_float(w & 0xffff0000u); }
; __device__ __forceinline__ u32x4 pack8(const f32x4 a, const f32x4 b) { u32x4 o; o.x = pk2(a.x, a.y); o.y = pk2(a.z, a.w); o.z = pk2(b.x, b.y); o.w = pk2(b.z, b.w); return o; }
; __device__ __forceinline__ size_t tile_native(int pm, int pt, int wr, int wc, int fr, int fq) { return ((size_t)((pm * 8 + pt) * 8 + wr * 4 + wc)) * 8192 + (size_t)(fr + 16 * fq) * 8; }
;     __device__ __forceinline__ void operator()(const pg8::f32x4 (&acc)[2][2][4][2], const pg8::Unit& u, int wr, int wc, int fr, int fq) const {
;         EPI_REMAP(); const int row0 = u.pm * 256 + wr * 64 + fr2, col0 = u.pn * 256 + wc * 32 + 8 * fq2; const size_t nat = tile_native(u.pm, u.pn, wr, wc, fr, fq);
; #pragma unroll
;         for (int ai = 0; ai < 2; ++ai)
; #pragma unroll
;             for (int m = 0; m < 4; ++m) { const size_t off = (size_t)(row0 + ai * 128 + m * 16) * D + col0;
; #pragma unroll
;                 for (int bj = 0; bj < 2; ++bj) { const size_t no = nat + (size_t)(((ai * 2 + bj) * 4 + m) * 512); const u32x4 gw = *(const u32x4*)(GATE + no);
;                     f32x4 a = acc[ai][bj][m][0] * (f32x4){bflo(gw.x), bfhi(gw.x), bflo(gw.y), bfhi(gw.y)}, b = acc[ai][bj][m][1] * (f32x4){bflo(gw.z), bfhi(gw.z), bflo(gw.w), bfhi(gw.w)};
;                     if (STAGE == 0) *(u32x4*)(PART + no) = pack8(a, b);
;                     else { const u32x4 pw = *(const u32x4*)(PART + no); a += (f32x4){bflo(pw.x), bfhi(pw.x), bflo(pw.y), bfhi(pw.y)}; b += (f32x4){bflo(pw.z), bfhi(pw.z), bflo(pw.w), bfhi(pw.w)};
;                         *(u32x4*)(MRG + off + bj * 128) = epi_perm(pack8(a, b), src4); } } }
;     }
.LBB0_2531:
	s_lshl_b32 s15, s39, 3
	s_lshl_b32 s13, s20, 6
	s_add_i32 s15, s36, s15
	s_add_i32 s22, s15, s13
	s_ashr_i32 s23, s22, 31
	s_lshl_b64 s[22:23], s[22:23], 14
	v_lshl_or_b32 v156, v146, 1, s22
	v_mov_b32_e32 v157, s23
	v_or_b32_e32 v188, 0x800, v156
	v_mov_b32_e32 v189, v157
	v_lshl_add_u64 v[130:131], s[58:59], 0, v[156:157]
	v_lshl_add_u64 v[176:177], s[58:59], 0, v[188:189]
	global_load_dwordx4 v[134:137], v[130:131], off
	v_or_b32_e32 v184, 0x1400, v156
	global_load_dwordx4 v[176:179], v[176:177], off
	v_or_b32_e32 v130, 0x1000, v156
	v_mov_b32_e32 v131, s23
	v_lshl_add_u64 v[132:133], s[58:59], 0, v[130:131]
	global_load_dwordx4 v[164:167], v[132:133], off
	v_or_b32_e32 v132, 0x400, v156
	v_mov_b32_e32 v133, s23
	v_lshl_add_u64 v[158:159], s[58:59], 0, v[132:133]
	global_load_dwordx4 v[168:171], v[158:159], off
	v_mov_b32_e32 v185, s23
	v_lshl_add_u64 v[158:159], s[58:59], 0, v[184:185]
	global_load_dwordx4 v[172:175], v[158:159], off
	v_readlane_b32 s22, v254, 49
	v_readlane_b32 s23, v254, 50
	v_or_b32_e32 v160, 0x1800, v156
	v_mov_b32_e32 v161, v157
	v_or_b32_e32 v158, 0xc00, v156
	v_mov_b32_e32 v159, v157
	v_lshl_add_u64 v[190:191], s[22:23], 0, v[130:131]
	v_lshl_add_u64 v[192:193], s[22:23], 0, v[132:133]
	v_lshl_add_u64 v[130:131], s[58:59], 0, v[160:161]
	v_lshl_add_u64 v[132:133], s[58:59], 0, v[158:159]
	global_load_dwordx4 v[180:183], v[130:131], off
	s_nop 0
	global_load_dwordx4 v[130:133], v[132:133], off
	v_lshl_add_u64 v[186:187], s[22:23], 0, v[156:157]
	s_andn2_b64 vcc, exec, s[0:1]
	s_mov_b64 s[0:1], -1
	s_waitcnt vmcnt(0)
	v_lshlrev_b32_e32 v194, 16, v134
	v_and_b32_e32 v195, 0xffff0000, v134
	v_lshlrev_b32_e32 v134, 16, v135
	v_and_b32_e32 v135, 0xffff0000, v135
	v_lshlrev_b32_e32 v196, 16, v136
	v_and_b32_e32 v197, 0xffff0000, v136
	v_lshlrev_b32_e32 v136, 16, v137
	v_and_b32_e32 v137, 0xffff0000, v137
	v_mul_f32_e32 v128, v128, v134
	v_mul_f32_e32 v129, v129, v135
	v_mul_f32_e32 v126, v126, v194
	v_mul_f32_e32 v127, v127, v195
	v_mul_f32_e32 v134, v124, v136
	v_mul_f32_e32 v135, v125, v137
	v_mul_f32_e32 v124, v122, v196
	v_mul_f32_e32 v125, v123, v197
	v_lshlrev_b32_e32 v136, 16, v164
	v_and_b32_e32 v137, 0xffff0000, v164
	v_lshlrev_b32_e32 v164, 16, v165
	v_and_b32_e32 v165, 0xffff0000, v165
	v_lshlrev_b32_e32 v194, 16, v166
	v_and_b32_e32 v195, 0xffff0000, v166
	v_lshlrev_b32_e32 v166, 16, v167
	v_and_b32_e32 v167, 0xffff0000, v167
	v_lshlrev_b32_e32 v196, 16, v168
	v_and_b32_e32 v197, 0xffff0000, v168
	v_lshlrev_b32_e32 v168, 16, v169
	v_and_b32_e32 v169, 0xffff0000, v169
	v_lshlrev_b32_e32 v198, 16, v170
	v_and_b32_e32 v199, 0xffff0000, v170
	v_lshlrev_b32_e32 v170, 16, v171
	v_and_b32_e32 v171, 0xffff0000, v171
	v_cvt_pk_bf16_f32 v122, v126, v127
	v_mul_f32_e32 v112, v112, v164
	v_mul_f32_e32 v113, v113, v165
	v_mul_f32_e32 v110, v110, v136
	v_mul_f32_e32 v111, v111, v137
	v_mul_f32_e32 v126, v108, v166
	v_mul_f32_e32 v127, v109, v167
	v_mul_f32_e32 v108, v106, v194
	v_mul_f32_e32 v109, v107, v195
	v_mul_f32_e32 v120, v120, v168
	v_mul_f32_e32 v121, v121, v169
	v_mul_f32_e32 v118, v118, v196
	v_mul_f32_e32 v119, v119, v197
	v_mul_f32_e32 v116, v116, v170
	v_mul_f32_e32 v117, v117, v171
	v_mul_f32_e32 v114, v114, v198
	v_mul_f32_e32 v115, v115, v199
	v_cvt_pk_bf16_f32 v123, v128, v129
	v_cvt_pk_bf16_f32 v124, v124, v125
	v_cvt_pk_bf16_f32 v125, v134, v135
	v_cvt_pk_bf16_f32 v106, v110, v111
	v_cvt_pk_bf16_f32 v107, v112, v113
	v_cvt_pk_bf16_f32 v108, v108, v109
	v_cvt_pk_bf16_f32 v109, v126, v127
	v_cvt_pk_bf16_f32 v110, v118, v119
	v_cvt_pk_bf16_f32 v111, v120, v121
	v_cvt_pk_bf16_f32 v112, v114, v115
	v_cvt_pk_bf16_f32 v113, v116, v117
	v_lshlrev_b32_e32 v200, 16, v172
	v_and_b32_e32 v201, 0xffff0000, v172
	v_lshlrev_b32_e32 v172, 16, v173
	v_and_b32_e32 v173, 0xffff0000, v173
	global_store_dwordx4 v[186:187], v[122:125], off
	global_store_dwordx4 v[190:191], v[106:109], off
	global_store_dwordx4 v[192:193], v[110:113], off
	v_lshlrev_b32_e32 v114, 16, v175
	v_and_b32_e32 v115, 0xffff0000, v175
	v_or_b32_e32 v110, 0x1c00, v156
	v_mov_b32_e32 v111, v157
	v_lshlrev_b32_e32 v112, 16, v174
	v_and_b32_e32 v113, 0xffff0000, v174
	v_mul_f32_e32 v108, v104, v172
	v_mul_f32_e32 v109, v105, v173
	v_lshl_add_u64 v[104:105], s[58:59], 0, v[110:111]
	v_mul_f32_e32 v102, v102, v200
	v_mul_f32_e32 v103, v103, v201
	v_mul_f32_e32 v114, v100, v114
	v_mul_f32_e32 v115, v101, v115
	v_mul_f32_e32 v100, v98, v112
	v_mul_f32_e32 v101, v99, v113
	global_load_dwordx4 v[104:107], v[104:105], off
	v_cvt_pk_bf16_f32 v98, v102, v103
	v_cvt_pk_bf16_f32 v99, v108, v109
	v_cvt_pk_bf16_f32 v100, v100, v101
	v_cvt_pk_bf16_f32 v101, v114, v115
	v_lshl_add_u64 v[102:103], s[22:23], 0, v[184:185]
	global_store_dwordx4 v[102:103], v[98:101], off
	v_or_b32_e32 v108, 0x2000, v156
	v_mov_b32_e32 v109, v157
	v_lshlrev_b32_e32 v98, 16, v177
	v_and_b32_e32 v99, 0xffff0000, v177
	v_lshlrev_b32_e32 v100, 16, v176
	v_and_b32_e32 v101, 0xffff0000, v176
	v_mul_f32_e32 v102, v96, v98
	v_mul_f32_e32 v103, v97, v99
	v_lshl_add_u64 v[96:97], s[58:59], 0, v[108:109]
	global_load_dwordx4 v[96:99], v[96:97], off
	v_mul_f32_e32 v94, v94, v100
	v_mul_f32_e32 v95, v95, v101
	v_lshlrev_b32_e32 v100, 16, v178
	v_and_b32_e32 v101, 0xffff0000, v178
	v_lshlrev_b32_e32 v112, 16, v179
	v_and_b32_e32 v113, 0xffff0000, v179
	v_mul_f32_e32 v112, v92, v112
	v_mul_f32_e32 v113, v93, v113
	v_mul_f32_e32 v92, v90, v100
	v_mul_f32_e32 v93, v91, v101
	v_cvt_pk_bf16_f32 v90, v94, v95
	v_cvt_pk_bf16_f32 v91, v102, v103
	v_cvt_pk_bf16_f32 v92, v92, v93
	v_cvt_pk_bf16_f32 v93, v112, v113
	v_lshl_add_u64 v[94:95], s[22:23], 0, v[188:189]
	global_store_dwordx4 v[94:95], v[90:93], off
; __device__ __forceinline__ float bflo(unsigned w) { return __uint_as_float(w << 16); }
; __device__ __forceinline__ float bfhi(unsigned w) { return __uint_as_float(w & 0xffff0000u); }
; __device__ __forceinline__ u32x4 pack8(const f32x4 a, const f32x4 b) { u32x4 o; o.x = pk2(a.x, a.y); o.y = pk2(a.z, a.w); o.z = pk2(b.x, b.y); o.w = pk2(b.z, b.w); return o; }
;     __device__ __forceinline__ void operator()(const pg8::f32x4 (&acc)[2][2][4][2], const pg8::Unit& u, int wr, int wc, int fr, int fq) const {
;     ...
;             for (int m = 0; m < 4; ++m) { const size_t off = (size_t)(row0 + ai * 128 + m * 16) * D + col0;
; #pragma unroll
;                 for (int bj = 0; bj < 2; ++bj) { const size_t no = nat + (size_t)(((ai * 2 + bj) * 4 + m) * 512); const u32x4 gw = *(const u32x4*)(GATE + no);
;                     f32x4 a = acc[ai][bj][m][0] * (f32x4){bflo(gw.x), bfhi(gw.x), bflo(gw.y), bfhi(gw.y)}, b = acc[ai][bj][m][1] * (f32x4){bflo(gw.z), bfhi(gw.z), bflo(gw.w), bfhi(gw.w)};
;                     if (STAGE == 0) *(u32x4*)(PART + no) = pack8(a, b);
	v_lshlrev_b32_e32 v100, 16, v182
	v_and_b32_e32 v101, 0xffff0000, v182
	v_lshlrev_b32_e32 v90, 16, v180
	v_and_b32_e32 v91, 0xffff0000, v180
	v_lshlrev_b32_e32 v92, 16, v181
	v_and_b32_e32 v93, 0xffff0000, v181
	v_mul_f32_e32 v94, v86, v90
	v_mul_f32_e32 v95, v87, v91
	v_lshlrev_b32_e32 v102, 16, v183
	v_or_b32_e32 v86, 0x3000, v156
	v_mov_b32_e32 v87, v157
	v_and_b32_e32 v103, 0xffff0000, v183
	v_mul_f32_e32 v92, v88, v92
	v_mul_f32_e32 v93, v89, v93
	v_lshl_add_u64 v[88:89], s[58:59], 0, v[86:87]
	v_mul_f32_e32 v102, v80, v102
	v_mul_f32_e32 v103, v81, v103
	v_mul_f32_e32 v80, v78, v100
	v_mul_f32_e32 v81, v79, v101
	global_load_dwordx4 v[88:91], v[88:89], off
	v_cvt_pk_bf16_f32 v78, v94, v95
	v_cvt_pk_bf16_f32 v79, v92, v93
	v_cvt_pk_bf16_f32 v80, v80, v81
	v_cvt_pk_bf16_f32 v81, v102, v103
	v_lshl_add_u64 v[92:93], s[22:23], 0, v[160:161]
	global_store_dwordx4 v[92:93], v[78:81], off
	v_lshlrev_b32_e32 v94, 16, v132
	v_and_b32_e32 v95, 0xffff0000, v132
	v_lshlrev_b32_e32 v78, 16, v130
	v_and_b32_e32 v79, 0xffff0000, v130
	v_lshlrev_b32_e32 v80, 16, v131
	v_and_b32_e32 v81, 0xffff0000, v131
	v_mul_f32_e32 v92, v82, v78
	v_mul_f32_e32 v93, v83, v79
	v_or_b32_e32 v78, 0x2400, v156
	v_mov_b32_e32 v79, v157
	v_mul_f32_e32 v84, v84, v80
	v_mul_f32_e32 v85, v85, v81
	v_lshl_add_u64 v[80:81], s[58:59], 0, v[78:79]
	global_load_dwordx4 v[80:83], v[80:81], off
	v_lshlrev_b32_e32 v100, 16, v133
	v_and_b32_e32 v101, 0xffff0000, v133
	v_mul_f32_e32 v100, v76, v100
	v_mul_f32_e32 v101, v77, v101
	v_mul_f32_e32 v76, v74, v94
	v_mul_f32_e32 v77, v75, v95
	v_cvt_pk_bf16_f32 v74, v92, v93
	v_cvt_pk_bf16_f32 v75, v84, v85
	v_cvt_pk_bf16_f32 v76, v76, v77
	v_cvt_pk_bf16_f32 v77, v100, v101
	v_lshl_add_u64 v[84:85], s[22:23], 0, v[158:159]
	global_store_dwordx4 v[84:85], v[74:77], off
	v_or_b32_e32 v92, 0x3400, v156
	v_mov_b32_e32 v93, v157
	s_waitcnt vmcnt(7)
	v_lshlrev_b32_e32 v74, 16, v104
	v_and_b32_e32 v75, 0xffff0000, v104
	v_lshlrev_b32_e32 v76, 16, v105
	v_and_b32_e32 v77, 0xffff0000, v105
	v_lshlrev_b32_e32 v84, 16, v106
	v_and_b32_e32 v85, 0xffff0000, v106
	v_lshlrev_b32_e32 v94, 16, v107
	v_and_b32_e32 v95, 0xffff0000, v107
	v_mul_f32_e32 v76, v72, v76
	v_mul_f32_e32 v77, v73, v77
	v_mul_f32_e32 v74, v70, v74
	v_mul_f32_e32 v75, v71, v75
	v_lshl_add_u64 v[70:71], s[58:59], 0, v[92:93]
	v_mul_f32_e32 v94, v68, v94
	v_mul_f32_e32 v95, v69, v95
	v_mul_f32_e32 v68, v66, v84
	v_mul_f32_e32 v69, v67, v85
	global_load_dwordx4 v[70:73], v[70:71], off
	v_cvt_pk_bf16_f32 v66, v74, v75
	v_cvt_pk_bf16_f32 v67, v76, v77
	v_cvt_pk_bf16_f32 v68, v68, v69
	v_cvt_pk_bf16_f32 v69, v94, v95
	v_lshl_add_u64 v[74:75], s[22:23], 0, v[110:111]
	global_store_dwordx4 v[74:75], v[66:69], off
	s_waitcnt vmcnt(7)
	v_lshlrev_b32_e32 v74, 16, v96
	v_and_b32_e32 v75, 0xffff0000, v96
	v_lshlrev_b32_e32 v76, 16, v97
	v_and_b32_e32 v77, 0xffff0000, v97
	v_or_b32_e32 v84, 0x2800, v156
	v_mov_b32_e32 v85, v157
	v_mul_f32_e32 v64, v64, v76
	v_mul_f32_e32 v65, v65, v77
	v_mul_f32_e32 v62, v62, v74
	v_mul_f32_e32 v63, v63, v75
	v_lshlrev_b32_e32 v74, 16, v98
	v_and_b32_e32 v75, 0xffff0000, v98
	v_lshlrev_b32_e32 v76, 16, v99
	v_and_b32_e32 v77, 0xffff0000, v99
	v_lshl_add_u64 v[66:67], s[58:59], 0, v[84:85]
	v_mul_f32_e32 v76, v60, v76
	v_mul_f32_e32 v77, v61, v77
	v_mul_f32_e32 v60, v58, v74
	v_mul_f32_e32 v61, v59, v75
	global_load_dwordx4 v[66:69], v[66:67], off
	v_cvt_pk_bf16_f32 v58, v62, v63
	v_cvt_pk_bf16_f32 v59, v64, v65
	v_cvt_pk_bf16_f32 v60, v60, v61
	v_cvt_pk_bf16_f32 v61, v76, v77
	v_lshl_add_u64 v[62:63], s[22:23], 0, v[108:109]
	global_store_dwordx4 v[62:63], v[58:61], off
	v_or_b32_e32 v62, 0x3800, v156
	v_mov_b32_e32 v63, v157
	v_lshl_add_u64 v[58:59], s[58:59], 0, v[62:63]
	global_load_dwordx4 v[58:61], v[58:59], off
	s_waitcnt vmcnt(8)
	v_lshlrev_b32_e32 v64, 16, v88
	v_and_b32_e32 v65, 0xffff0000, v88
	v_lshlrev_b32_e32 v74, 16, v89
	v_and_b32_e32 v75, 0xffff0000, v89
	v_mul_f32_e32 v56, v56, v74
	v_mul_f32_e32 v57, v57, v75
	v_mul_f32_e32 v54, v54, v64
	v_mul_f32_e32 v55, v55, v65
	v_lshlrev_b32_e32 v64, 16, v90
	v_and_b32_e32 v65, 0xffff0000, v90
	v_lshlrev_b32_e32 v74, 16, v91
	v_and_b32_e32 v75, 0xffff0000, v91
	v_mul_f32_e32 v74, v52, v74
	v_mul_f32_e32 v75, v53, v75
	v_mul_f32_e32 v52, v50, v64
	v_mul_f32_e32 v53, v51, v65
	v_or_b32_e32 v64, 0x2c00, v156
	v_mov_b32_e32 v65, v157
	v_cvt_pk_bf16_f32 v50, v54, v55
	v_cvt_pk_bf16_f32 v51, v56, v57
	v_lshl_add_u64 v[54:55], s[58:59], 0, v[64:65]
	v_cvt_pk_bf16_f32 v52, v52, v53
	v_cvt_pk_bf16_f32 v53, v74, v75
	v_lshl_add_u64 v[74:75], s[22:23], 0, v[86:87]
	global_load_dwordx4 v[54:57], v[54:55], off
	v_or_b32_e32 v156, 0x3c00, v156
	global_store_dwordx4 v[74:75], v[50:53], off
	s_waitcnt vmcnt(8)
; #define PG8_BAR __builtin_amdgcn_s_barrier()
; __device__ __forceinline__ float bflo(unsigned w) { return __uint_as_float(w << 16); }
; __device__ __forceinline__ float bfhi(unsigned w) { return __uint_as_float(w & 0xffff0000u); }
; __device__ __forceinline__ u32x4 pack8(const f32x4 a, const f32x4 b) { u32x4 o; o.x = pk2(a.x, a.y); o.y = pk2(a.z, a.w); o.z = pk2(b.x, b.y); o.w = pk2(b.z, b.w); return o; }
; template <class Epi, class Sched, bool ALIGN_EPI = false, bool SP2 = false>
; __device__ __forceinline__ void gemm_phase(PG8_LAS unsigned char* lds, const Gemm g, const Sched& S, const Epi& E) {
;     ...
;         if constexpr (ALIGN_EPI) { if (wr == 0) PG8_BAR; }
;         if constexpr (!Epi::AFTER_DRAIN) { E(acc, cur, wr, wc, fr, fq); S.done(cur); }
;         if (!has_next) break;
; #pragma unroll
;         for (int a = 0; a < 2; ++a)
; #pragma unroll
;             for (int b = 0; b < 2; ++b)
; #pragma unroll
;                 for (int m = 0; m < 4; ++m)
; #pragma unroll
;                     for (int n = 0; n < 2; ++n) acc[a][b][m][n] = (f32x4){0.f, 0.f, 0.f, 0.f};
;         cur = nxt; cA = nA; cB = nB; ++ui;
;         if constexpr (ALIGN_EPI) { if (wr == 1) PG8_BAR; }
;     }
;     __device__ __forceinline__ void operator()(const pg8::f32x4 (&acc)[2][2][4][2], const pg8::Unit& u, int wr, int wc, int fr, int fq) const {
;     ...
;             for (int m = 0; m < 4; ++m) { const size_t off = (size_t)(row0 + ai * 128 + m * 16) * D + col0;
; #pragma unroll
;                 for (int bj = 0; bj < 2; ++bj) { const size_t no = nat + (size_t)(((ai * 2 + bj) * 4 + m) * 512); const u32x4 gw = *(const u32x4*)(GATE + no);
;                     f32x4 a = acc[ai][bj][m][0] * (f32x4){bflo(gw.x), bfhi(gw.x), bflo(gw.y), bfhi(gw.y)}, b = acc[ai][bj][m][1] * (f32x4){bflo(gw.z), bfhi(gw.z), bflo(gw.w), bfhi(gw.w)};
;                     if (STAGE == 0) *(u32x4*)(PART + no) = pack8(a, b);
	s_nop 0
	v_lshlrev_b32_e32 v50, 16, v80
	v_and_b32_e32 v51, 0xffff0000, v80
	v_lshlrev_b32_e32 v52, 16, v81
	v_and_b32_e32 v53, 0xffff0000, v81
	v_mul_f32_e32 v52, v48, v52
	v_mul_f32_e32 v53, v49, v53
	v_mul_f32_e32 v48, v46, v50
	v_mul_f32_e32 v49, v47, v51
	v_lshlrev_b32_e32 v46, 16, v83
	v_and_b32_e32 v47, 0xffff0000, v83
	v_mul_f32_e32 v74, v44, v46
	v_mul_f32_e32 v75, v45, v47
	v_lshl_add_u64 v[44:45], s[58:59], 0, v[156:157]
	global_load_dwordx4 v[44:47], v[44:45], off
	v_lshlrev_b32_e32 v50, 16, v82
	v_and_b32_e32 v51, 0xffff0000, v82
	v_mul_f32_e32 v42, v42, v50
	v_mul_f32_e32 v43, v43, v51
	v_cvt_pk_bf16_f32 v48, v48, v49
	v_cvt_pk_bf16_f32 v49, v52, v53
	v_cvt_pk_bf16_f32 v50, v42, v43
	v_cvt_pk_bf16_f32 v51, v74, v75
	v_lshl_add_u64 v[42:43], s[22:23], 0, v[78:79]
	global_store_dwordx4 v[42:43], v[48:51], off
	s_waitcnt vmcnt(8)
	v_lshlrev_b32_e32 v42, 16, v70
	v_and_b32_e32 v43, 0xffff0000, v70
	v_lshlrev_b32_e32 v48, 16, v71
	v_and_b32_e32 v49, 0xffff0000, v71
	v_mul_f32_e32 v36, v36, v48
	v_mul_f32_e32 v37, v37, v49
	v_mul_f32_e32 v34, v34, v42
	v_mul_f32_e32 v35, v35, v43
	v_lshlrev_b32_e32 v42, 16, v72
	v_and_b32_e32 v43, 0xffff0000, v72
	v_lshlrev_b32_e32 v48, 16, v73
	v_and_b32_e32 v49, 0xffff0000, v73
	v_mul_f32_e32 v48, v28, v48
	v_mul_f32_e32 v49, v29, v49
	v_mul_f32_e32 v28, v26, v42
	v_mul_f32_e32 v29, v27, v43
	v_cvt_pk_bf16_f32 v26, v34, v35
	v_cvt_pk_bf16_f32 v27, v36, v37
	v_cvt_pk_bf16_f32 v28, v28, v29
	v_cvt_pk_bf16_f32 v29, v48, v49
	v_lshl_add_u64 v[34:35], s[22:23], 0, v[92:93]
	global_store_dwordx4 v[34:35], v[26:29], off
	s_waitcnt vmcnt(7)
	v_lshlrev_b32_e32 v34, 16, v68
	v_lshlrev_b32_e32 v26, 16, v66
	v_and_b32_e32 v27, 0xffff0000, v66
	v_lshlrev_b32_e32 v28, 16, v67
	v_and_b32_e32 v29, 0xffff0000, v67
	v_and_b32_e32 v35, 0xffff0000, v68
	v_lshlrev_b32_e32 v36, 16, v69
	v_and_b32_e32 v37, 0xffff0000, v69
	v_mul_f32_e32 v28, v40, v28
	v_mul_f32_e32 v29, v41, v29
	v_mul_f32_e32 v26, v38, v26
	v_mul_f32_e32 v27, v39, v27
	v_mul_f32_e32 v32, v32, v36
	v_mul_f32_e32 v33, v33, v37
	v_mul_f32_e32 v30, v30, v34
	v_mul_f32_e32 v31, v31, v35
	v_cvt_pk_bf16_f32 v26, v26, v27
	v_cvt_pk_bf16_f32 v27, v28, v29
	v_cvt_pk_bf16_f32 v28, v30, v31
	v_cvt_pk_bf16_f32 v29, v32, v33
	v_lshl_add_u64 v[30:31], s[22:23], 0, v[84:85]
	global_store_dwordx4 v[30:31], v[26:29], off
	s_waitcnt vmcnt(6)
	s_nop 0
	v_lshlrev_b32_e32 v26, 16, v58
	v_and_b32_e32 v27, 0xffff0000, v58
	v_lshlrev_b32_e32 v28, 16, v59
	v_and_b32_e32 v29, 0xffff0000, v59
	v_mul_f32_e32 v20, v20, v28
	v_mul_f32_e32 v21, v21, v29
	v_mul_f32_e32 v18, v18, v26
	v_mul_f32_e32 v19, v19, v27
	v_lshlrev_b32_e32 v26, 16, v60
	v_and_b32_e32 v27, 0xffff0000, v60
	v_lshlrev_b32_e32 v28, 16, v61
	v_and_b32_e32 v29, 0xffff0000, v61
	v_mul_f32_e32 v28, v12, v28
	v_mul_f32_e32 v29, v13, v29
	v_mul_f32_e32 v12, v10, v26
	v_mul_f32_e32 v13, v11, v27
	v_cvt_pk_bf16_f32 v10, v18, v19
	v_cvt_pk_bf16_f32 v11, v20, v21
	v_cvt_pk_bf16_f32 v12, v12, v13
	v_cvt_pk_bf16_f32 v13, v28, v29
	v_lshl_add_u64 v[18:19], s[22:23], 0, v[62:63]
	global_store_dwordx4 v[18:19], v[10:13], off
	s_waitcnt vmcnt(6)
	v_lshlrev_b32_e32 v18, 16, v56
	v_and_b32_e32 v19, 0xffff0000, v56
	v_lshlrev_b32_e32 v10, 16, v54
	v_and_b32_e32 v11, 0xffff0000, v54
	v_lshlrev_b32_e32 v12, 16, v55
	v_and_b32_e32 v13, 0xffff0000, v55
	v_lshlrev_b32_e32 v20, 16, v57
	v_and_b32_e32 v21, 0xffff0000, v57
	v_mul_f32_e32 v12, v24, v12
	v_mul_f32_e32 v13, v25, v13
	v_mul_f32_e32 v10, v22, v10
	v_mul_f32_e32 v11, v23, v11
	v_mul_f32_e32 v16, v16, v20
	v_mul_f32_e32 v17, v17, v21
	v_mul_f32_e32 v14, v14, v18
	v_mul_f32_e32 v15, v15, v19
	v_cvt_pk_bf16_f32 v10, v10, v11
	v_cvt_pk_bf16_f32 v11, v12, v13
	v_cvt_pk_bf16_f32 v12, v14, v15
	v_cvt_pk_bf16_f32 v13, v16, v17
	v_lshl_add_u64 v[14:15], s[22:23], 0, v[64:65]
	global_store_dwordx4 v[14:15], v[10:13], off
	s_waitcnt vmcnt(5)
	s_nop 0
	v_lshlrev_b32_e32 v10, 16, v44
	v_and_b32_e32 v11, 0xffff0000, v44
	v_lshlrev_b32_e32 v12, 16, v45
	v_and_b32_e32 v13, 0xffff0000, v45
	v_mul_f32_e32 v8, v8, v12
	v_mul_f32_e32 v9, v9, v13
	v_mul_f32_e32 v6, v6, v10
	v_mul_f32_e32 v7, v7, v11
	v_lshlrev_b32_e32 v10, 16, v46
	v_and_b32_e32 v11, 0xffff0000, v46
	v_lshlrev_b32_e32 v12, 16, v47
	v_and_b32_e32 v13, 0xffff0000, v47
	v_mul_f32_e32 v12, v4, v12
	v_mul_f32_e32 v13, v5, v13
	v_mul_f32_e32 v4, v2, v10
	v_mul_f32_e32 v5, v3, v11
	v_cvt_pk_bf16_f32 v2, v6, v7
	v_cvt_pk_bf16_f32 v3, v8, v9
	v_cvt_pk_bf16_f32 v4, v4, v5
	v_cvt_pk_bf16_f32 v5, v12, v13
	v_lshl_add_u64 v[6:7], s[22:23], 0, v[156:157]
	global_store_dwordx4 v[6:7], v[2:5], off
	s_cbranch_vccnz .LBB0_2520
	s_andn2_b64 vcc, exec, s[4:5]
	s_cbranch_vccnz .LBB0_2519
	s_barrier
	s_branch .LBB0_2519

; __device__ __forceinline__ unsigned pk2(float lo, float hi) { const bfx2 b = __builtin_convertvector((f32x2){lo, hi}, bfx2); return __builtin_bit_cast(unsigned, b); }
; __device__ __forceinline__ float bflo(unsigned w) { return __uint_as_float(w << 16); }
; __device__ __forceinline__ float bfhi(unsigned w) { return __uint_as_float(w & 0xffff0000u); }
; template <int NS, class Epi>
; __device__ __forceinline__ void skinny_gemm2d(Frame& F, const bf16* A, int K, const bf16* Bt, const Epi& E) {
;     ...
;         if (ks == 1) red[(mt * 2 + nt) * 64 + lane] = acc;
;         __syncthreads();
;         if (ks == 0) { acc += red[(mt * 2 + nt) * 64 + lane]; E(r0 + lr, c0 + 4 * lq, acc, acc); }
;         __syncthreads();
;     __device__ __forceinline__ void operator()(int r, int c, const pg8::f32x4 a, const pg8::f32x4) const {
;         const size_t off = (size_t)(MP + r) * D + c; const u32x2 gw = *(const u32x2*)(GATE + off);
;         f32x4 v = a * (f32x4){bflo(gw.x), bfhi(gw.x), bflo(gw.y), bfhi(gw.y)};
;         if (STAGE == 1) { const u32x2 pw = *(const u32x2*)(MRG + off); v += (f32x4){bflo(pw.x), bfhi(pw.x), bflo(pw.y), bfhi(pw.y)}; }
;         u32x2 w; w.x = pk2(v.x, v.y); w.y = pk2(v.z, v.w); *(u32x2*)(MRG + off) = w; }
.LBB0_2540:
	s_and_b64 vcc, exec, s[8:9]
	s_waitcnt lgkmcnt(0)
	s_barrier
	s_cbranch_vccnz .LBB0_2537
	v_or_b32_e32 v6, s14, v1
	v_or_b32_e32 v18, s15, v14
	v_lshl_or_b32 v6, v6, 11, v17
	v_ashrrev_i32_e32 v19, 31, v18
	v_lshl_add_u64 v[18:19], v[6:7], 0, v[18:19]
	v_lshlrev_b64 v[22:23], 1, v[18:19]
	v_lshl_add_u64 v[18:19], s[58:59], 0, v[22:23]
	global_load_dwordx2 v[24:25], v[18:19], off
	ds_read_b128 v[18:21], v13
	s_waitcnt lgkmcnt(0)
	v_add_f32_e32 v4, v4, v20
	v_add_f32_e32 v5, v5, v21
	v_add_f32_e32 v2, v2, v18
	v_add_f32_e32 v3, v3, v19
	s_waitcnt vmcnt(0)
	v_lshlrev_b32_e32 v18, 16, v24
	v_and_b32_e32 v19, 0xffff0000, v24
	v_lshlrev_b32_e32 v20, 16, v25
	v_and_b32_e32 v21, 0xffff0000, v25
	v_mul_f32_e32 v4, v4, v20
	v_mul_f32_e32 v5, v5, v21
	v_mul_f32_e32 v2, v2, v18
	v_mul_f32_e32 v3, v3, v19
	s_nop 0
	v_cvt_pk_bf16_f32 v2, v2, v3
	v_cvt_pk_bf16_f32 v3, v4, v5
	v_lshl_add_u64 v[4:5], s[4:5], 0, v[22:23]
	global_store_dwordx2 v[4:5], v[2:3], off
	s_branch .LBB0_2537

; __device__ __forceinline__ float bflo(unsigned w) { return __uint_as_float(w << 16); }
; __device__ __forceinline__ float bfhi(unsigned w) { return __uint_as_float(w & 0xffff0000u); }
; __device__ __forceinline__ u32x4 pack8(const f32x4 a, const f32x4 b) { u32x4 o; o.x = pk2(a.x, a.y); o.y = pk2(a.z, a.w); o.z = pk2(b.x, b.y); o.w = pk2(b.z, b.w); return o; }
;     __device__ __forceinline__ void operator()(const pg8::f32x4 (&acc)[2][2][4][2], const pg8::Unit& u, int wr, int wc, int fr, int fq) const {
;     ...
;                 for (int bj = 0; bj < 2; ++bj) { const size_t no = nat + (size_t)(((ai * 2 + bj) * 4 + m) * 512); const u32x4 gw = *(const u32x4*)(GATE + no);
;                     f32x4 a = acc[ai][bj][m][0] * (f32x4){bflo(gw.x), bfhi(gw.x), bflo(gw.y), bfhi(gw.y)}, b = acc[ai][bj][m][1] * (f32x4){bflo(gw.z), bfhi(gw.z), bflo(gw.w), bfhi(gw.w)};
;                     if (STAGE == 0) *(u32x4*)(PART + no) = pack8(a, b);
;                     else { const u32x4 pw = *(const u32x4*)(PART + no); a += (f32x4){bflo(pw.x), bfhi(pw.x), bflo(pw.y), bfhi(pw.y)}; b += (f32x4){bflo(pw.z), bfhi(pw.z), bflo(pw.w), bfhi(pw.w)};
;                         *(u32x4*)(MRG + off + bj * 128) = epi_perm(pack8(a, b), src4); } } }
.LBB0_2562:
	s_lshl_b32 s17, s23, 3
	s_lshl_b32 s15, s22, 6
	s_add_i32 s17, s37, s17
	s_add_i32 s24, s17, s15
	s_ashr_i32 s25, s24, 31
	s_lshl_b64 s[24:25], s[24:25], 14
	v_lshl_or_b32 v148, v138, 1, s24
	v_mov_b32_e32 v149, s25
	v_readlane_b32 s24, v254, 49
	v_lshl_add_u64 v[150:151], s[56:57], 0, v[148:149]
	v_readlane_b32 s25, v254, 50
	global_load_dwordx4 v[160:163], v[150:151], off
	v_lshl_add_u32 v152, s22, 8, v154
	v_lshl_add_u64 v[150:151], s[24:25], 0, v[148:149]
	global_load_dwordx4 v[164:167], v[150:151], off
	v_lshl_or_b32 v150, s23, 8, v155
	v_ashrrev_i32_e32 v153, 31, v152
	v_ashrrev_i32_e32 v151, 31, v150
	v_lshlrev_b64 v[168:169], 12, v[152:153]
	v_lshlrev_b64 v[150:151], 1, v[150:151]
	v_lshl_add_u64 v[168:169], s[4:5], 0, v[168:169]
	s_mov_b32 s15, 0x80000
	s_mov_b64 s[22:23], 0x80000
	s_waitcnt vmcnt(0)
	v_lshlrev_b32_e32 v170, 16, v160
	v_and_b32_e32 v171, 0xffff0000, v160
	v_lshlrev_b32_e32 v160, 16, v161
	v_and_b32_e32 v161, 0xffff0000, v161
	v_lshlrev_b32_e32 v172, 16, v162
	v_and_b32_e32 v173, 0xffff0000, v162
	v_lshlrev_b32_e32 v162, 16, v163
	v_and_b32_e32 v163, 0xffff0000, v163
	v_lshlrev_b32_e32 v174, 16, v164
	v_and_b32_e32 v175, 0xffff0000, v164
	v_lshlrev_b32_e32 v164, 16, v165
	v_and_b32_e32 v165, 0xffff0000, v165
	v_lshlrev_b32_e32 v176, 16, v166
	v_and_b32_e32 v177, 0xffff0000, v166
	v_lshlrev_b32_e32 v166, 16, v167
	v_and_b32_e32 v167, 0xffff0000, v167
	v_fma_f32 v128, v128, v160, v164
	v_fma_f32 v129, v129, v161, v165
	v_fma_f32 v126, v126, v170, v174
	v_fma_f32 v127, v127, v171, v175
	v_fma_f32 v124, v124, v162, v166
	v_fma_f32 v125, v125, v163, v167
	v_fma_f32 v122, v122, v172, v176
	v_fma_f32 v123, v123, v173, v177
	v_cvt_pk_bf16_f32 v126, v126, v127
	v_cvt_pk_bf16_f32 v127, v128, v129
	v_cvt_pk_bf16_f32 v122, v122, v123
	v_cvt_pk_bf16_f32 v123, v124, v125
	ds_bpermute_b32 v124, v139, v126
	ds_bpermute_b32 v125, v139, v127
	ds_bpermute_b32 v126, v139, v122
	ds_bpermute_b32 v127, v139, v123
	v_lshl_add_u64 v[122:123], v[168:169], 0, v[150:151]
	v_or_b32_e32 v128, 0x1000, v148
	v_mov_b32_e32 v129, v149
	v_lshl_add_u64 v[160:161], s[56:57], 0, v[128:129]
	s_waitcnt lgkmcnt(0)
	global_store_dwordx4 v[122:123], v[124:127], off
	v_lshl_add_u64 v[128:129], s[24:25], 0, v[128:129]
	global_load_dwordx4 v[124:127], v[160:161], off
	s_waitcnt vmcnt(0)
	v_lshlrev_b32_e32 v164, 16, v126
	global_load_dwordx4 v[160:163], v[128:129], off
	v_lshlrev_b32_e32 v128, 16, v124
	v_and_b32_e32 v129, 0xffff0000, v124
	v_lshlrev_b32_e32 v124, 16, v125
	v_and_b32_e32 v125, 0xffff0000, v125
	v_and_b32_e32 v165, 0xffff0000, v126
	v_lshlrev_b32_e32 v126, 16, v127
	v_and_b32_e32 v127, 0xffff0000, v127
	s_waitcnt vmcnt(0)
	v_lshlrev_b32_e32 v166, 16, v160
	v_and_b32_e32 v167, 0xffff0000, v160
	v_lshlrev_b32_e32 v160, 16, v161
	v_and_b32_e32 v161, 0xffff0000, v161
	v_lshlrev_b32_e32 v168, 16, v162
	v_and_b32_e32 v169, 0xffff0000, v162
	v_lshlrev_b32_e32 v162, 16, v163
	v_and_b32_e32 v163, 0xffff0000, v163
	v_fma_f32 v120, v120, v124, v160
	v_fma_f32 v121, v121, v125, v161
	v_fma_f32 v118, v118, v128, v166
	v_fma_f32 v119, v119, v129, v167
	v_fma_f32 v116, v116, v126, v162
	v_fma_f32 v117, v117, v127, v163
	v_fma_f32 v114, v114, v164, v168
	v_fma_f32 v115, v115, v165, v169
	v_cvt_pk_bf16_f32 v118, v118, v119
	v_cvt_pk_bf16_f32 v119, v120, v121
	v_cvt_pk_bf16_f32 v120, v114, v115
	v_cvt_pk_bf16_f32 v117, v116, v117
	ds_bpermute_b32 v114, v139, v118
	ds_bpermute_b32 v115, v139, v119
	ds_bpermute_b32 v116, v139, v120
	ds_bpermute_b32 v117, v139, v117
	v_or_b32_e32 v118, 0x400, v148
	v_mov_b32_e32 v119, v149
	v_lshl_add_u64 v[120:121], s[56:57], 0, v[118:119]
	v_lshl_add_u64 v[118:119], s[24:25], 0, v[118:119]
	s_waitcnt lgkmcnt(0)
	global_store_dwordx4 v[122:123], v[114:117], off offset:256
	global_load_dwordx4 v[114:117], v[120:121], off
	v_or_b32_e32 v124, 16, v152
	global_load_dwordx4 v[118:121], v[118:119], off
	v_ashrrev_i32_e32 v125, 31, v124
	v_lshlrev_b64 v[124:125], 12, v[124:125]
	v_lshl_add_u64 v[124:125], s[4:5], 0, v[124:125]
	s_waitcnt vmcnt(1)
	v_lshlrev_b32_e32 v126, 16, v114
	v_and_b32_e32 v127, 0xffff0000, v114
	v_lshlrev_b32_e32 v114, 16, v115
	v_and_b32_e32 v115, 0xffff0000, v115
	v_lshlrev_b32_e32 v128, 16, v116
	v_and_b32_e32 v129, 0xffff0000, v116
	v_lshlrev_b32_e32 v116, 16, v117
	v_and_b32_e32 v117, 0xffff0000, v117
	s_waitcnt vmcnt(0)
	v_lshlrev_b32_e32 v160, 16, v118
	v_and_b32_e32 v161, 0xffff0000, v118
	v_lshlrev_b32_e32 v118, 16, v119
	v_and_b32_e32 v119, 0xffff0000, v119
	v_lshlrev_b32_e32 v162, 16, v120
	v_and_b32_e32 v163, 0xffff0000, v120
	v_lshlrev_b32_e32 v120, 16, v121
	v_and_b32_e32 v121, 0xffff0000, v121
	v_fma_f32 v112, v112, v114, v118
	v_fma_f32 v113, v113, v115, v119
	v_fma_f32 v110, v110, v126, v160
	v_fma_f32 v111, v111, v127, v161
	v_fma_f32 v108, v108, v116, v120
	v_fma_f32 v109, v109, v117, v121
	v_fma_f32 v106, v106, v128, v162
	v_fma_f32 v107, v107, v129, v163
	v_cvt_pk_bf16_f32 v110, v110, v111
	v_cvt_pk_bf16_f32 v111, v112, v113
	v_cvt_pk_bf16_f32 v112, v106, v107
	v_cvt_pk_bf16_f32 v109, v108, v109
	ds_bpermute_b32 v106, v139, v110
	ds_bpermute_b32 v107, v139, v111
	ds_bpermute_b32 v108, v139, v112
	ds_bpermute_b32 v109, v139, v109
	v_lshl_add_u64 v[114:115], v[124:125], 0, v[150:151]
	v_or_b32_e32 v110, 0x1400, v148
	v_mov_b32_e32 v111, v149
	v_lshl_add_u64 v[112:113], s[56:57], 0, v[110:111]
	s_waitcnt lgkmcnt(0)
	global_store_dwordx4 v[114:115], v[106:109], off
	v_lshl_add_u64 v[110:111], s[24:25], 0, v[110:111]
	global_load_dwordx4 v[106:109], v[112:113], off
	s_waitcnt vmcnt(0)
; __device__ __forceinline__ float bflo(unsigned w) { return __uint_as_float(w << 16); }
; __device__ __forceinline__ float bfhi(unsigned w) { return __uint_as_float(w & 0xffff0000u); }
; __device__ __forceinline__ u32x4 pack8(const f32x4 a, const f32x4 b) { u32x4 o; o.x = pk2(a.x, a.y); o.y = pk2(a.z, a.w); o.z = pk2(b.x, b.y); o.w = pk2(b.z, b.w); return o; }
; __device__ __forceinline__ size_t tile_native(int pm, int pt, int wr, int wc, int fr, int fq) { return ((size_t)((pm * 8 + pt) * 8 + wr * 4 + wc)) * 8192 + (size_t)(fr + 16 * fq) * 8; }
;     __device__ __forceinline__ void operator()(const pg8::f32x4 (&acc)[2][2][4][2], const pg8::Unit& u, int wr, int wc, int fr, int fq) const {
;         EPI_REMAP(); const int row0 = u.pm * 256 + wr * 64 + fr2, col0 = u.pn * 256 + wc * 32 + 8 * fq2; const size_t nat = tile_native(u.pm, u.pn, wr, wc, fr, fq);
; #pragma unroll
;         for (int ai = 0; ai < 2; ++ai)
; #pragma unroll
;             for (int m = 0; m < 4; ++m) { const size_t off = (size_t)(row0 + ai * 128 + m * 16) * D + col0;
; #pragma unroll
;                 for (int bj = 0; bj < 2; ++bj) { const size_t no = nat + (size_t)(((ai * 2 + bj) * 4 + m) * 512); const u32x4 gw = *(const u32x4*)(GATE + no);
;                     f32x4 a = acc[ai][bj][m][0] * (f32x4){bflo(gw.x), bfhi(gw.x), bflo(gw.y), bfhi(gw.y)}, b = acc[ai][bj][m][1] * (f32x4){bflo(gw.z), bfhi(gw.z), bflo(gw.w), bfhi(gw.w)};
;                     if (STAGE == 0) *(u32x4*)(PART + no) = pack8(a, b);
;                     else { const u32x4 pw = *(const u32x4*)(PART + no); a += (f32x4){bflo(pw.x), bfhi(pw.x), bflo(pw.y), bfhi(pw.y)}; b += (f32x4){bflo(pw.z), bfhi(pw.z), bflo(pw.w), bfhi(pw.w)};
;                         *(u32x4*)(MRG + off + bj * 128) = epi_perm(pack8(a, b), src4); } } }
	v_lshlrev_b32_e32 v116, 16, v106
	global_load_dwordx4 v[110:113], v[110:111], off
	v_and_b32_e32 v117, 0xffff0000, v106
	v_lshlrev_b32_e32 v106, 16, v107
	v_and_b32_e32 v107, 0xffff0000, v107
	v_lshlrev_b32_e32 v118, 16, v108
	v_and_b32_e32 v119, 0xffff0000, v108
	v_lshlrev_b32_e32 v108, 16, v109
	v_and_b32_e32 v109, 0xffff0000, v109
	s_waitcnt vmcnt(0)
	v_lshlrev_b32_e32 v120, 16, v110
	v_and_b32_e32 v121, 0xffff0000, v110
	v_lshlrev_b32_e32 v110, 16, v111
	v_and_b32_e32 v111, 0xffff0000, v111
	v_lshlrev_b32_e32 v124, 16, v112
	v_and_b32_e32 v125, 0xffff0000, v112
	v_lshlrev_b32_e32 v112, 16, v113
	v_and_b32_e32 v113, 0xffff0000, v113
	v_fma_f32 v104, v104, v106, v110
	v_fma_f32 v105, v105, v107, v111
	v_fma_f32 v102, v102, v116, v120
	v_fma_f32 v103, v103, v117, v121
	v_fma_f32 v100, v100, v108, v112
	v_fma_f32 v101, v101, v109, v113
	v_fma_f32 v98, v98, v118, v124
	v_fma_f32 v99, v99, v119, v125
	v_cvt_pk_bf16_f32 v102, v102, v103
	v_cvt_pk_bf16_f32 v103, v104, v105
	v_cvt_pk_bf16_f32 v104, v98, v99
	v_cvt_pk_bf16_f32 v101, v100, v101
	ds_bpermute_b32 v98, v139, v102
	ds_bpermute_b32 v99, v139, v103
	ds_bpermute_b32 v100, v139, v104
	ds_bpermute_b32 v101, v139, v101
	v_or_b32_e32 v102, 0x800, v148
	v_mov_b32_e32 v103, v149
	v_lshl_add_u64 v[104:105], s[56:57], 0, v[102:103]
	v_lshl_add_u64 v[102:103], s[24:25], 0, v[102:103]
	s_waitcnt lgkmcnt(0)
	global_store_dwordx4 v[114:115], v[98:101], off offset:256
	global_load_dwordx4 v[98:101], v[104:105], off
	v_or_b32_e32 v106, 32, v152
	global_load_dwordx4 v[102:105], v[102:103], off
	v_ashrrev_i32_e32 v107, 31, v106
	v_lshlrev_b64 v[106:107], 12, v[106:107]
	v_lshl_add_u64 v[106:107], s[4:5], 0, v[106:107]
	s_waitcnt vmcnt(1)
	v_lshlrev_b32_e32 v108, 16, v98
	v_and_b32_e32 v109, 0xffff0000, v98
	v_lshlrev_b32_e32 v98, 16, v99
	v_and_b32_e32 v99, 0xffff0000, v99
	v_lshlrev_b32_e32 v110, 16, v100
	v_and_b32_e32 v111, 0xffff0000, v100
	v_lshlrev_b32_e32 v100, 16, v101
	v_and_b32_e32 v101, 0xffff0000, v101
	s_waitcnt vmcnt(0)
	v_lshlrev_b32_e32 v112, 16, v102
	v_and_b32_e32 v113, 0xffff0000, v102
	v_lshlrev_b32_e32 v102, 16, v103
	v_and_b32_e32 v103, 0xffff0000, v103
	v_lshlrev_b32_e32 v114, 16, v104
	v_and_b32_e32 v115, 0xffff0000, v104
	v_lshlrev_b32_e32 v104, 16, v105
	v_and_b32_e32 v105, 0xffff0000, v105
	v_fma_f32 v96, v96, v98, v102
	v_fma_f32 v97, v97, v99, v103
	v_fma_f32 v94, v94, v108, v112
	v_fma_f32 v95, v95, v109, v113
	v_fma_f32 v92, v92, v100, v104
	v_fma_f32 v93, v93, v101, v105
	v_fma_f32 v90, v90, v110, v114
	v_fma_f32 v91, v91, v111, v115
	v_cvt_pk_bf16_f32 v94, v94, v95
	v_cvt_pk_bf16_f32 v95, v96, v97
	v_cvt_pk_bf16_f32 v96, v90, v91
	v_cvt_pk_bf16_f32 v93, v92, v93
	ds_bpermute_b32 v90, v139, v94
	ds_bpermute_b32 v91, v139, v95
	ds_bpermute_b32 v92, v139, v96
	ds_bpermute_b32 v93, v139, v93
	v_lshl_add_u64 v[98:99], v[106:107], 0, v[150:151]
	v_or_b32_e32 v94, 0x1800, v148
	v_mov_b32_e32 v95, v149
	v_lshl_add_u64 v[96:97], s[56:57], 0, v[94:95]
	s_waitcnt lgkmcnt(0)
	global_store_dwordx4 v[98:99], v[90:93], off
	v_lshl_add_u64 v[94:95], s[24:25], 0, v[94:95]
	global_load_dwordx4 v[90:93], v[96:97], off
	s_waitcnt vmcnt(0)
	v_lshlrev_b32_e32 v100, 16, v90
	global_load_dwordx4 v[94:97], v[94:95], off
	v_and_b32_e32 v101, 0xffff0000, v90
	v_lshlrev_b32_e32 v90, 16, v91
	v_and_b32_e32 v91, 0xffff0000, v91
	v_lshlrev_b32_e32 v102, 16, v92
	v_and_b32_e32 v103, 0xffff0000, v92
	v_lshlrev_b32_e32 v92, 16, v93
	v_and_b32_e32 v93, 0xffff0000, v93
	s_waitcnt vmcnt(0)
	v_lshlrev_b32_e32 v104, 16, v94
	v_and_b32_e32 v105, 0xffff0000, v94
	v_lshlrev_b32_e32 v94, 16, v95
	v_and_b32_e32 v95, 0xffff0000, v95
	v_lshlrev_b32_e32 v106, 16, v96
	v_and_b32_e32 v107, 0xffff0000, v96
	v_lshlrev_b32_e32 v96, 16, v97
	v_and_b32_e32 v97, 0xffff0000, v97
	v_fma_f32 v88, v88, v90, v94
	v_fma_f32 v89, v89, v91, v95
	v_fma_f32 v86, v86, v100, v104
	v_fma_f32 v87, v87, v101, v105
	v_fma_f32 v84, v84, v92, v96
	v_fma_f32 v85, v85, v93, v97
	v_fma_f32 v82, v82, v102, v106
	v_fma_f32 v83, v83, v103, v107
	v_cvt_pk_bf16_f32 v86, v86, v87
	v_cvt_pk_bf16_f32 v87, v88, v89
	v_cvt_pk_bf16_f32 v88, v82, v83
	v_cvt_pk_bf16_f32 v85, v84, v85
	ds_bpermute_b32 v82, v139, v86
	ds_bpermute_b32 v83, v139, v87
	ds_bpermute_b32 v84, v139, v88
	ds_bpermute_b32 v85, v139, v85
	v_or_b32_e32 v86, 0xc00, v148
	v_mov_b32_e32 v87, v149
	v_lshl_add_u64 v[88:89], s[56:57], 0, v[86:87]
	v_lshl_add_u64 v[86:87], s[24:25], 0, v[86:87]
	s_waitcnt lgkmcnt(0)
	global_store_dwordx4 v[98:99], v[82:85], off offset:256
	global_load_dwordx4 v[82:85], v[88:89], off
	v_or_b32_e32 v90, 48, v152
	global_load_dwordx4 v[86:89], v[86:87], off
	v_ashrrev_i32_e32 v91, 31, v90
	v_lshlrev_b64 v[90:91], 12, v[90:91]
	v_lshl_add_u64 v[90:91], s[4:5], 0, v[90:91]
	s_waitcnt vmcnt(1)
	v_lshlrev_b32_e32 v92, 16, v82
	v_and_b32_e32 v93, 0xffff0000, v82
	v_lshlrev_b32_e32 v82, 16, v83
	v_and_b32_e32 v83, 0xffff0000, v83
	v_lshlrev_b32_e32 v94, 16, v84
	v_and_b32_e32 v95, 0xffff0000, v84
	v_lshlrev_b32_e32 v84, 16, v85
	v_and_b32_e32 v85, 0xffff0000, v85
	s_waitcnt vmcnt(0)
	v_lshlrev_b32_e32 v96, 16, v86
	v_and_b32_e32 v97, 0xffff0000, v86
	v_lshlrev_b32_e32 v86, 16, v87
	v_and_b32_e32 v87, 0xffff0000, v87
	v_lshlrev_b32_e32 v98, 16, v88
	v_and_b32_e32 v99, 0xffff0000, v88
	v_lshlrev_b32_e32 v88, 16, v89
	v_and_b32_e32 v89, 0xffff0000, v89
	v_fma_f32 v80, v80, v82, v86
	v_fma_f32 v81, v81, v83, v87
	v_fma_f32 v78, v78, v92, v96
	v_fma_f32 v79, v79, v93, v97
	v_fma_f32 v76, v76, v84, v88
	v_fma_f32 v77, v77, v85, v89
	v_fma_f32 v74, v74, v94, v98
	v_fma_f32 v75, v75, v95, v99
	v_cvt_pk_bf16_f32 v78, v78, v79
	v_cvt_pk_bf16_f32 v79, v80, v81
	v_cvt_pk_bf16_f32 v80, v74, v75
	v_cvt_pk_bf16_f32 v77, v76, v77
	ds_bpermute_b32 v74, v139, v78
	ds_bpermute_b32 v75, v139, v79
	ds_bpermute_b32 v76, v139, v80
	ds_bpermute_b32 v77, v139, v77
	v_lshl_add_u64 v[82:83], v[90:91], 0, v[150:151]
	v_or_b32_e32 v78, 0x1c00, v148
	v_mov_b32_e32 v79, v149
	v_lshl_add_u64 v[80:81], s[56:57], 0, v[78:79]
	s_waitcnt lgkmcnt(0)
; __device__ __forceinline__ float bflo(unsigned w) { return __uint_as_float(w << 16); }
; __device__ __forceinline__ float bfhi(unsigned w) { return __uint_as_float(w & 0xffff0000u); }
; __device__ __forceinline__ u32x4 pack8(const f32x4 a, const f32x4 b) { u32x4 o; o.x = pk2(a.x, a.y); o.y = pk2(a.z, a.w); o.z = pk2(b.x, b.y); o.w = pk2(b.z, b.w); return o; }
; __device__ __forceinline__ size_t tile_native(int pm, int pt, int wr, int wc, int fr, int fq) { return ((size_t)((pm * 8 + pt) * 8 + wr * 4 + wc)) * 8192 + (size_t)(fr + 16 * fq) * 8; }
;     __device__ __forceinline__ void operator()(const pg8::f32x4 (&acc)[2][2][4][2], const pg8::Unit& u, int wr, int wc, int fr, int fq) const {
;         EPI_REMAP(); const int row0 = u.pm * 256 + wr * 64 + fr2, col0 = u.pn * 256 + wc * 32 + 8 * fq2; const size_t nat = tile_native(u.pm, u.pn, wr, wc, fr, fq);
; #pragma unroll
;         for (int ai = 0; ai < 2; ++ai)
; #pragma unroll
;             for (int m = 0; m < 4; ++m) { const size_t off = (size_t)(row0 + ai * 128 + m * 16) * D + col0;
; #pragma unroll
;                 for (int bj = 0; bj < 2; ++bj) { const size_t no = nat + (size_t)(((ai * 2 + bj) * 4 + m) * 512); const u32x4 gw = *(const u32x4*)(GATE + no);
;                     f32x4 a = acc[ai][bj][m][0] * (f32x4){bflo(gw.x), bfhi(gw.x), bflo(gw.y), bfhi(gw.y)}, b = acc[ai][bj][m][1] * (f32x4){bflo(gw.z), bfhi(gw.z), bflo(gw.w), bfhi(gw.w)};
;                     if (STAGE == 0) *(u32x4*)(PART + no) = pack8(a, b);
;                     else { const u32x4 pw = *(const u32x4*)(PART + no); a += (f32x4){bflo(pw.x), bfhi(pw.x), bflo(pw.y), bfhi(pw.y)}; b += (f32x4){bflo(pw.z), bfhi(pw.z), bflo(pw.w), bfhi(pw.w)};
;                         *(u32x4*)(MRG + off + bj * 128) = epi_perm(pack8(a, b), src4); } } }
	global_store_dwordx4 v[82:83], v[74:77], off
	v_lshl_add_u64 v[78:79], s[24:25], 0, v[78:79]
	global_load_dwordx4 v[74:77], v[80:81], off
	s_waitcnt vmcnt(0)
	v_lshlrev_b32_e32 v84, 16, v74
	global_load_dwordx4 v[78:81], v[78:79], off
	v_and_b32_e32 v85, 0xffff0000, v74
	v_lshlrev_b32_e32 v74, 16, v75
	v_and_b32_e32 v75, 0xffff0000, v75
	v_lshlrev_b32_e32 v86, 16, v76
	v_and_b32_e32 v87, 0xffff0000, v76
	v_lshlrev_b32_e32 v76, 16, v77
	v_and_b32_e32 v77, 0xffff0000, v77
	s_waitcnt vmcnt(0)
	v_lshlrev_b32_e32 v88, 16, v78
	v_and_b32_e32 v89, 0xffff0000, v78
	v_lshlrev_b32_e32 v78, 16, v79
	v_and_b32_e32 v79, 0xffff0000, v79
	v_lshlrev_b32_e32 v90, 16, v80
	v_and_b32_e32 v91, 0xffff0000, v80
	v_lshlrev_b32_e32 v80, 16, v81
	v_and_b32_e32 v81, 0xffff0000, v81
	v_fma_f32 v72, v72, v74, v78
	v_fma_f32 v73, v73, v75, v79
	v_fma_f32 v70, v70, v84, v88
	v_fma_f32 v71, v71, v85, v89
	v_fma_f32 v68, v68, v76, v80
	v_fma_f32 v69, v69, v77, v81
	v_fma_f32 v66, v66, v86, v90
	v_fma_f32 v67, v67, v87, v91
	v_cvt_pk_bf16_f32 v70, v70, v71
	v_cvt_pk_bf16_f32 v71, v72, v73
	v_cvt_pk_bf16_f32 v72, v66, v67
	v_cvt_pk_bf16_f32 v69, v68, v69
	ds_bpermute_b32 v66, v139, v70
	ds_bpermute_b32 v67, v139, v71
	ds_bpermute_b32 v68, v139, v72
	ds_bpermute_b32 v69, v139, v69
	v_or_b32_e32 v70, 0x2000, v148
	v_mov_b32_e32 v71, v149
	v_lshl_add_u64 v[72:73], s[56:57], 0, v[70:71]
	v_lshl_add_u64 v[70:71], s[24:25], 0, v[70:71]
	s_waitcnt lgkmcnt(0)
	global_store_dwordx4 v[82:83], v[66:69], off offset:256
	global_load_dwordx4 v[66:69], v[72:73], off
	s_waitcnt vmcnt(0)
	v_lshlrev_b32_e32 v74, 16, v66
	global_load_dwordx4 v[70:73], v[70:71], off
	v_and_b32_e32 v75, 0xffff0000, v66
	v_lshlrev_b32_e32 v66, 16, v67
	v_and_b32_e32 v67, 0xffff0000, v67
	v_lshlrev_b32_e32 v76, 16, v68
	v_and_b32_e32 v77, 0xffff0000, v68
	v_lshlrev_b32_e32 v68, 16, v69
	v_and_b32_e32 v69, 0xffff0000, v69
	s_waitcnt vmcnt(0)
	v_lshlrev_b32_e32 v78, 16, v70
	v_and_b32_e32 v79, 0xffff0000, v70
	v_lshlrev_b32_e32 v70, 16, v71
	v_and_b32_e32 v71, 0xffff0000, v71
	v_lshlrev_b32_e32 v80, 16, v72
	v_and_b32_e32 v81, 0xffff0000, v72
	v_lshlrev_b32_e32 v72, 16, v73
	v_and_b32_e32 v73, 0xffff0000, v73
	v_fma_f32 v64, v64, v66, v70
	v_fma_f32 v65, v65, v67, v71
	v_fma_f32 v62, v62, v74, v78
	v_fma_f32 v63, v63, v75, v79
	v_fma_f32 v60, v60, v68, v72
	v_fma_f32 v61, v61, v69, v73
	v_fma_f32 v58, v58, v76, v80
	v_fma_f32 v59, v59, v77, v81
	v_cvt_pk_bf16_f32 v62, v62, v63
	v_cvt_pk_bf16_f32 v63, v64, v65
	v_cvt_pk_bf16_f32 v64, v58, v59
	v_cvt_pk_bf16_f32 v61, v60, v61
	ds_bpermute_b32 v58, v139, v62
	ds_bpermute_b32 v59, v139, v63
	ds_bpermute_b32 v60, v139, v64
	ds_bpermute_b32 v61, v139, v61
	v_add_co_u32_e32 v62, vcc, s15, v122
	v_or_b32_e32 v64, 0x3000, v148
	s_nop 0
	v_addc_co_u32_e32 v63, vcc, 0, v123, vcc
	v_mov_b32_e32 v65, v149
	v_lshl_add_u64 v[66:67], s[56:57], 0, v[64:65]
	s_waitcnt lgkmcnt(0)
	global_store_dwordx4 v[62:63], v[58:61], off
	v_lshl_add_u64 v[62:63], s[24:25], 0, v[64:65]
	global_load_dwordx4 v[58:61], v[66:67], off
	s_mov_b32 s15, 0x90000
	global_load_dwordx4 v[62:65], v[62:63], off
	s_waitcnt vmcnt(1)
	v_lshlrev_b32_e32 v66, 16, v58
	v_and_b32_e32 v67, 0xffff0000, v58
	v_lshlrev_b32_e32 v58, 16, v59
	v_and_b32_e32 v59, 0xffff0000, v59
	v_lshlrev_b32_e32 v68, 16, v60
	v_and_b32_e32 v69, 0xffff0000, v60
	v_lshlrev_b32_e32 v60, 16, v61
	v_and_b32_e32 v61, 0xffff0000, v61
	s_waitcnt vmcnt(0)
	v_lshlrev_b32_e32 v70, 16, v62
	v_and_b32_e32 v71, 0xffff0000, v62
	v_lshlrev_b32_e32 v62, 16, v63
	v_and_b32_e32 v63, 0xffff0000, v63
	v_lshlrev_b32_e32 v72, 16, v64
	v_and_b32_e32 v73, 0xffff0000, v64
	v_lshlrev_b32_e32 v64, 16, v65
	v_and_b32_e32 v65, 0xffff0000, v65
	v_fma_f32 v56, v56, v58, v62
	v_fma_f32 v57, v57, v59, v63
	v_fma_f32 v54, v54, v66, v70
	v_fma_f32 v55, v55, v67, v71
	v_fma_f32 v52, v52, v60, v64
	v_fma_f32 v53, v53, v61, v65
	v_fma_f32 v50, v50, v68, v72
	v_fma_f32 v51, v51, v69, v73
	v_cvt_pk_bf16_f32 v54, v54, v55
	v_cvt_pk_bf16_f32 v55, v56, v57
	v_cvt_pk_bf16_f32 v56, v50, v51
	v_cvt_pk_bf16_f32 v53, v52, v53
	ds_bpermute_b32 v50, v139, v54
	ds_bpermute_b32 v51, v139, v55
	ds_bpermute_b32 v52, v139, v56
	ds_bpermute_b32 v53, v139, v53
	v_lshl_add_u64 v[54:55], v[122:123], 0, s[22:23]
	v_or_b32_e32 v56, 0x2400, v148
	v_mov_b32_e32 v57, v149
	v_lshl_add_u64 v[58:59], s[56:57], 0, v[56:57]
	s_waitcnt lgkmcnt(0)
	global_store_dwordx4 v[54:55], v[50:53], off offset:256
	v_lshl_add_u64 v[54:55], s[24:25], 0, v[56:57]
	global_load_dwordx4 v[50:53], v[58:59], off
	s_mov_b64 s[22:23], 0x90000
	global_load_dwordx4 v[54:57], v[54:55], off
	s_waitcnt vmcnt(1)
	v_lshlrev_b32_e32 v58, 16, v50
	v_and_b32_e32 v59, 0xffff0000, v50
	v_lshlrev_b32_e32 v50, 16, v51
	v_and_b32_e32 v51, 0xffff0000, v51
	v_lshlrev_b32_e32 v60, 16, v52
	v_and_b32_e32 v61, 0xffff0000, v52
	v_lshlrev_b32_e32 v52, 16, v53
	v_and_b32_e32 v53, 0xffff0000, v53
	s_waitcnt vmcnt(0)
	v_lshlrev_b32_e32 v62, 16, v54
	v_and_b32_e32 v63, 0xffff0000, v54
	v_lshlrev_b32_e32 v54, 16, v55
	v_and_b32_e32 v55, 0xffff0000, v55
	v_lshlrev_b32_e32 v64, 16, v56
	v_and_b32_e32 v65, 0xffff0000, v56
	v_lshlrev_b32_e32 v56, 16, v57
	v_and_b32_e32 v57, 0xffff0000, v57
	v_fma_f32 v48, v48, v50, v54
	v_fma_f32 v49, v49, v51, v55
	v_fma_f32 v46, v46, v58, v62
	v_fma_f32 v47, v47, v59, v63
	v_fma_f32 v44, v44, v52, v56
	v_fma_f32 v45, v45, v53, v57
	v_fma_f32 v42, v42, v60, v64
	v_fma_f32 v43, v43, v61, v65
	v_cvt_pk_bf16_f32 v46, v46, v47
	v_cvt_pk_bf16_f32 v47, v48, v49
	v_cvt_pk_bf16_f32 v48, v42, v43
	v_cvt_pk_bf16_f32 v45, v44, v45
	ds_bpermute_b32 v42, v139, v46
	ds_bpermute_b32 v43, v139, v47
	ds_bpermute_b32 v44, v139, v48
	ds_bpermute_b32 v45, v139, v45
	v_add_co_u32_e32 v46, vcc, s15, v122
	v_or_b32_e32 v48, 0x3400, v148
	s_nop 0
	v_addc_co_u32_e32 v47, vcc, 0, v123, vcc
	v_mov_b32_e32 v49, v149
	v_lshl_add_u64 v[50:51], s[56:57], 0, v[48:49]
	s_waitcnt lgkmcnt(0)
; __device__ __forceinline__ float bflo(unsigned w) { return __uint_as_float(w << 16); }
; __device__ __forceinline__ float bfhi(unsigned w) { return __uint_as_float(w & 0xffff0000u); }
; __device__ __forceinline__ u32x4 pack8(const f32x4 a, const f32x4 b) { u32x4 o; o.x = pk2(a.x, a.y); o.y = pk2(a.z, a.w); o.z = pk2(b.x, b.y); o.w = pk2(b.z, b.w); return o; }
; __device__ __forceinline__ size_t tile_native(int pm, int pt, int wr, int wc, int fr, int fq) { return ((size_t)((pm * 8 + pt) * 8 + wr * 4 + wc)) * 8192 + (size_t)(fr + 16 * fq) * 8; }
;     __device__ __forceinline__ void operator()(const pg8::f32x4 (&acc)[2][2][4][2], const pg8::Unit& u, int wr, int wc, int fr, int fq) const {
;         EPI_REMAP(); const int row0 = u.pm * 256 + wr * 64 + fr2, col0 = u.pn * 256 + wc * 32 + 8 * fq2; const size_t nat = tile_native(u.pm, u.pn, wr, wc, fr, fq);
; #pragma unroll
;         for (int ai = 0; ai < 2; ++ai)
; #pragma unroll
;             for (int m = 0; m < 4; ++m) { const size_t off = (size_t)(row0 + ai * 128 + m * 16) * D + col0;
; #pragma unroll
;                 for (int bj = 0; bj < 2; ++bj) { const size_t no = nat + (size_t)(((ai * 2 + bj) * 4 + m) * 512); const u32x4 gw = *(const u32x4*)(GATE + no);
;                     f32x4 a = acc[ai][bj][m][0] * (f32x4){bflo(gw.x), bfhi(gw.x), bflo(gw.y), bfhi(gw.y)}, b = acc[ai][bj][m][1] * (f32x4){bflo(gw.z), bfhi(gw.z), bflo(gw.w), bfhi(gw.w)};
;                     if (STAGE == 0) *(u32x4*)(PART + no) = pack8(a, b);
;                     else { const u32x4 pw = *(const u32x4*)(PART + no); a += (f32x4){bflo(pw.x), bfhi(pw.x), bflo(pw.y), bfhi(pw.y)}; b += (f32x4){bflo(pw.z), bfhi(pw.z), bflo(pw.w), bfhi(pw.w)};
;                         *(u32x4*)(MRG + off + bj * 128) = epi_perm(pack8(a, b), src4); } } }
	global_store_dwordx4 v[46:47], v[42:45], off
	v_lshl_add_u64 v[46:47], s[24:25], 0, v[48:49]
	global_load_dwordx4 v[42:45], v[50:51], off
	s_mov_b32 s15, 0xa0000
	global_load_dwordx4 v[46:49], v[46:47], off
	s_waitcnt vmcnt(1)
	v_lshlrev_b32_e32 v50, 16, v42
	v_and_b32_e32 v51, 0xffff0000, v42
	v_lshlrev_b32_e32 v42, 16, v43
	v_and_b32_e32 v43, 0xffff0000, v43
	v_lshlrev_b32_e32 v52, 16, v44
	v_and_b32_e32 v53, 0xffff0000, v44
	v_lshlrev_b32_e32 v44, 16, v45
	v_and_b32_e32 v45, 0xffff0000, v45
	s_waitcnt vmcnt(0)
	v_lshlrev_b32_e32 v54, 16, v46
	v_and_b32_e32 v55, 0xffff0000, v46
	v_lshlrev_b32_e32 v46, 16, v47
	v_and_b32_e32 v47, 0xffff0000, v47
	v_lshlrev_b32_e32 v56, 16, v48
	v_and_b32_e32 v57, 0xffff0000, v48
	v_lshlrev_b32_e32 v48, 16, v49
	v_and_b32_e32 v49, 0xffff0000, v49
	v_fma_f32 v40, v40, v42, v46
	v_fma_f32 v41, v41, v43, v47
	v_fma_f32 v38, v38, v50, v54
	v_fma_f32 v39, v39, v51, v55
	v_fma_f32 v36, v36, v44, v48
	v_fma_f32 v37, v37, v45, v49
	v_fma_f32 v34, v34, v52, v56
	v_fma_f32 v35, v35, v53, v57
	v_cvt_pk_bf16_f32 v38, v38, v39
	v_cvt_pk_bf16_f32 v39, v40, v41
	v_cvt_pk_bf16_f32 v40, v34, v35
	v_cvt_pk_bf16_f32 v37, v36, v37
	ds_bpermute_b32 v34, v139, v38
	ds_bpermute_b32 v35, v139, v39
	ds_bpermute_b32 v36, v139, v40
	ds_bpermute_b32 v37, v139, v37
	v_lshl_add_u64 v[38:39], v[122:123], 0, s[22:23]
	v_or_b32_e32 v40, 0x2800, v148
	v_mov_b32_e32 v41, v149
	v_lshl_add_u64 v[42:43], s[56:57], 0, v[40:41]
	s_waitcnt lgkmcnt(0)
	global_store_dwordx4 v[38:39], v[34:37], off offset:256
	v_lshl_add_u64 v[38:39], s[24:25], 0, v[40:41]
	global_load_dwordx4 v[34:37], v[42:43], off
	s_mov_b64 s[22:23], 0xa0000
	global_load_dwordx4 v[38:41], v[38:39], off
	s_waitcnt vmcnt(1)
	v_lshlrev_b32_e32 v42, 16, v34
	v_and_b32_e32 v43, 0xffff0000, v34
	v_lshlrev_b32_e32 v34, 16, v35
	v_and_b32_e32 v35, 0xffff0000, v35
	v_lshlrev_b32_e32 v44, 16, v36
	v_and_b32_e32 v45, 0xffff0000, v36
	v_lshlrev_b32_e32 v36, 16, v37
	v_and_b32_e32 v37, 0xffff0000, v37
	s_waitcnt vmcnt(0)
	v_lshlrev_b32_e32 v46, 16, v38
	v_and_b32_e32 v47, 0xffff0000, v38
	v_lshlrev_b32_e32 v38, 16, v39
	v_and_b32_e32 v39, 0xffff0000, v39
	v_lshlrev_b32_e32 v48, 16, v40
	v_and_b32_e32 v49, 0xffff0000, v40
	v_lshlrev_b32_e32 v40, 16, v41
	v_and_b32_e32 v41, 0xffff0000, v41
	v_fma_f32 v32, v32, v34, v38
	v_fma_f32 v33, v33, v35, v39
	v_fma_f32 v30, v30, v42, v46
	v_fma_f32 v31, v31, v43, v47
	v_fma_f32 v28, v28, v36, v40
	v_fma_f32 v29, v29, v37, v41
	v_fma_f32 v26, v26, v44, v48
	v_fma_f32 v27, v27, v45, v49
	v_cvt_pk_bf16_f32 v30, v30, v31
	v_cvt_pk_bf16_f32 v31, v32, v33
	v_cvt_pk_bf16_f32 v32, v26, v27
	v_cvt_pk_bf16_f32 v29, v28, v29
	ds_bpermute_b32 v26, v139, v30
	ds_bpermute_b32 v27, v139, v31
	ds_bpermute_b32 v28, v139, v32
	ds_bpermute_b32 v29, v139, v29
	v_add_co_u32_e32 v30, vcc, s15, v122
	v_or_b32_e32 v32, 0x3800, v148
	s_nop 0
	v_addc_co_u32_e32 v31, vcc, 0, v123, vcc
	v_mov_b32_e32 v33, v149
	v_lshl_add_u64 v[34:35], s[56:57], 0, v[32:33]
	s_waitcnt lgkmcnt(0)
	global_store_dwordx4 v[30:31], v[26:29], off
	v_lshl_add_u64 v[30:31], s[24:25], 0, v[32:33]
	global_load_dwordx4 v[26:29], v[34:35], off
	s_mov_b32 s15, 0xb0000
	global_load_dwordx4 v[30:33], v[30:31], off
	s_waitcnt vmcnt(1)
	v_lshlrev_b32_e32 v34, 16, v26
	v_and_b32_e32 v35, 0xffff0000, v26
	v_lshlrev_b32_e32 v26, 16, v27
	v_and_b32_e32 v27, 0xffff0000, v27
	v_lshlrev_b32_e32 v36, 16, v28
	v_and_b32_e32 v37, 0xffff0000, v28
	v_lshlrev_b32_e32 v28, 16, v29
	v_and_b32_e32 v29, 0xffff0000, v29
	s_waitcnt vmcnt(0)
; #define PG8_BAR __builtin_amdgcn_s_barrier()
; __device__ __forceinline__ float bflo(unsigned w) { return __uint_as_float(w << 16); }
; __device__ __forceinline__ float bfhi(unsigned w) { return __uint_as_float(w & 0xffff0000u); }
; template <class Epi, class Sched, bool ALIGN_EPI = false, bool SP2 = false>
; __device__ __forceinline__ void gemm_phase(PG8_LAS unsigned char* lds, const Gemm g, const Sched& S, const Epi& E) {
;     ...
;         if constexpr (ALIGN_EPI) { if (wr == 0) PG8_BAR; }
;         if constexpr (!Epi::AFTER_DRAIN) { E(acc, cur, wr, wc, fr, fq); S.done(cur); }
;         if (!has_next) break;
; #pragma unroll
;         for (int a = 0; a < 2; ++a)
; #pragma unroll
;             for (int b = 0; b < 2; ++b)
; #pragma unroll
;                 for (int m = 0; m < 4; ++m)
; #pragma unroll
;                     for (int n = 0; n < 2; ++n) acc[a][b][m][n] = (f32x4){0.f, 0.f, 0.f, 0.f};
;         cur = nxt; cA = nA; cB = nB; ++ui;
;         if constexpr (ALIGN_EPI) { if (wr == 1) PG8_BAR; }
;     __device__ __forceinline__ void operator()(const pg8::f32x4 (&acc)[2][2][4][2], const pg8::Unit& u, int wr, int wc, int fr, int fq) const {
;         EPI_REMAP(); const int row0 = u.pm * 256 + wr * 64 + fr2, col0 = u.pn * 256 + wc * 32 + 8 * fq2; const size_t nat = tile_native(u.pm, u.pn, wr, wc, fr, fq);
; #pragma unroll
;         for (int ai = 0; ai < 2; ++ai)
; #pragma unroll
;             for (int m = 0; m < 4; ++m) { const size_t off = (size_t)(row0 + ai * 128 + m * 16) * D + col0;
; #pragma unroll
;                 for (int bj = 0; bj < 2; ++bj) { const size_t no = nat + (size_t)(((ai * 2 + bj) * 4 + m) * 512); const u32x4 gw = *(const u32x4*)(GATE + no);
;                     f32x4 a = acc[ai][bj][m][0] * (f32x4){bflo(gw.x), bfhi(gw.x), bflo(gw.y), bfhi(gw.y)}, b = acc[ai][bj][m][1] * (f32x4){bflo(gw.z), bfhi(gw.z), bflo(gw.w), bfhi(gw.w)};
;                     if (STAGE == 0) *(u32x4*)(PART + no) = pack8(a, b);
;                     else { const u32x4 pw = *(const u32x4*)(PART + no); a += (f32x4){bflo(pw.x), bfhi(pw.x), bflo(pw.y), bfhi(pw.y)}; b += (f32x4){bflo(pw.z), bfhi(pw.z), bflo(pw.w), bfhi(pw.w)};
;                         *(u32x4*)(MRG + off + bj * 128) = epi_perm(pack8(a, b), src4); } } }
	v_lshlrev_b32_e32 v38, 16, v30
	v_and_b32_e32 v39, 0xffff0000, v30
	v_lshlrev_b32_e32 v30, 16, v31
	v_and_b32_e32 v31, 0xffff0000, v31
	v_lshlrev_b32_e32 v40, 16, v32
	v_and_b32_e32 v41, 0xffff0000, v32
	v_lshlrev_b32_e32 v32, 16, v33
	v_and_b32_e32 v33, 0xffff0000, v33
	v_fma_f32 v24, v24, v26, v30
	v_fma_f32 v25, v25, v27, v31
	v_fma_f32 v22, v22, v34, v38
	v_fma_f32 v23, v23, v35, v39
	v_fma_f32 v20, v20, v28, v32
	v_fma_f32 v21, v21, v29, v33
	v_fma_f32 v18, v18, v36, v40
	v_fma_f32 v19, v19, v37, v41
	v_cvt_pk_bf16_f32 v22, v22, v23
	v_cvt_pk_bf16_f32 v23, v24, v25
	v_cvt_pk_bf16_f32 v24, v18, v19
	v_cvt_pk_bf16_f32 v21, v20, v21
	ds_bpermute_b32 v18, v139, v22
	ds_bpermute_b32 v19, v139, v23
	ds_bpermute_b32 v20, v139, v24
	ds_bpermute_b32 v21, v139, v21
	v_lshl_add_u64 v[22:23], v[122:123], 0, s[22:23]
	v_or_b32_e32 v24, 0x2c00, v148
	v_mov_b32_e32 v25, v149
	v_lshl_add_u64 v[26:27], s[56:57], 0, v[24:25]
	s_waitcnt lgkmcnt(0)
	global_store_dwordx4 v[22:23], v[18:21], off offset:256
	v_lshl_add_u64 v[22:23], s[24:25], 0, v[24:25]
	global_load_dwordx4 v[18:21], v[26:27], off
	v_or_b32_e32 v148, 0x3c00, v148
	global_load_dwordx4 v[22:25], v[22:23], off
	s_mov_b64 s[22:23], 0xb0000
	s_waitcnt vmcnt(1)
	v_lshlrev_b32_e32 v26, 16, v18
	v_and_b32_e32 v27, 0xffff0000, v18
	v_lshlrev_b32_e32 v18, 16, v19
	v_and_b32_e32 v19, 0xffff0000, v19
	v_lshlrev_b32_e32 v28, 16, v20
	v_and_b32_e32 v29, 0xffff0000, v20
	v_lshlrev_b32_e32 v20, 16, v21
	v_and_b32_e32 v21, 0xffff0000, v21
	s_waitcnt vmcnt(0)
	v_lshlrev_b32_e32 v30, 16, v22
	v_and_b32_e32 v31, 0xffff0000, v22
	v_lshlrev_b32_e32 v22, 16, v23
	v_and_b32_e32 v23, 0xffff0000, v23
	v_lshlrev_b32_e32 v32, 16, v24
	v_and_b32_e32 v33, 0xffff0000, v24
	v_lshlrev_b32_e32 v24, 16, v25
	v_and_b32_e32 v25, 0xffff0000, v25
	v_fma_f32 v16, v16, v18, v22
	v_fma_f32 v17, v17, v19, v23
	v_fma_f32 v14, v14, v26, v30
	v_fma_f32 v15, v15, v27, v31
	v_fma_f32 v12, v12, v20, v24
	v_fma_f32 v13, v13, v21, v25
	v_fma_f32 v10, v10, v28, v32
	v_fma_f32 v11, v11, v29, v33
	v_cvt_pk_bf16_f32 v14, v14, v15
	v_cvt_pk_bf16_f32 v15, v16, v17
	v_cvt_pk_bf16_f32 v16, v10, v11
	v_cvt_pk_bf16_f32 v13, v12, v13
	ds_bpermute_b32 v10, v139, v14
	ds_bpermute_b32 v11, v139, v15
	ds_bpermute_b32 v12, v139, v16
	ds_bpermute_b32 v13, v139, v13
	v_add_co_u32_e32 v14, vcc, s15, v122
	v_lshl_add_u64 v[16:17], s[56:57], 0, v[148:149]
	s_nop 0
	v_addc_co_u32_e32 v15, vcc, 0, v123, vcc
	s_waitcnt lgkmcnt(0)
	global_store_dwordx4 v[14:15], v[10:13], off
	v_lshl_add_u64 v[14:15], s[24:25], 0, v[148:149]
	global_load_dwordx4 v[10:13], v[16:17], off
	s_andn2_b64 vcc, exec, s[0:1]
	global_load_dwordx4 v[14:17], v[14:15], off
	s_mov_b64 s[0:1], -1
	s_waitcnt vmcnt(1)
	v_lshlrev_b32_e32 v18, 16, v10
	v_and_b32_e32 v19, 0xffff0000, v10
	v_lshlrev_b32_e32 v10, 16, v11
	v_and_b32_e32 v11, 0xffff0000, v11
	v_lshlrev_b32_e32 v20, 16, v12
	v_and_b32_e32 v21, 0xffff0000, v12
	v_lshlrev_b32_e32 v12, 16, v13
	v_and_b32_e32 v13, 0xffff0000, v13
	s_waitcnt vmcnt(0)
	v_lshlrev_b32_e32 v22, 16, v14
	v_and_b32_e32 v23, 0xffff0000, v14
	v_lshlrev_b32_e32 v14, 16, v15
	v_and_b32_e32 v15, 0xffff0000, v15
	v_lshlrev_b32_e32 v24, 16, v16
	v_and_b32_e32 v25, 0xffff0000, v16
	v_lshlrev_b32_e32 v16, 16, v17
	v_and_b32_e32 v17, 0xffff0000, v17
	v_fma_f32 v8, v8, v10, v14
	v_fma_f32 v9, v9, v11, v15
	v_fma_f32 v6, v6, v18, v22
	v_fma_f32 v7, v7, v19, v23
	v_fma_f32 v4, v4, v12, v16
	v_fma_f32 v5, v5, v13, v17
	v_fma_f32 v2, v2, v20, v24
	v_fma_f32 v3, v3, v21, v25
	v_cvt_pk_bf16_f32 v6, v6, v7
	v_cvt_pk_bf16_f32 v7, v8, v9
	v_cvt_pk_bf16_f32 v8, v2, v3
	v_cvt_pk_bf16_f32 v5, v4, v5
	ds_bpermute_b32 v2, v139, v6
	ds_bpermute_b32 v3, v139, v7
	ds_bpermute_b32 v4, v139, v8
	ds_bpermute_b32 v5, v139, v5
	v_lshl_add_u64 v[6:7], v[122:123], 0, s[22:23]
	s_waitcnt lgkmcnt(0)
	global_store_dwordx4 v[6:7], v[2:5], off offset:256
	s_cbranch_vccnz .LBB0_2551
	s_andn2_b64 vcc, exec, s[8:9]
	s_cbranch_vccnz .LBB0_2550
	s_barrier
	s_branch .LBB0_2550

; __device__ __forceinline__ unsigned pk2(float lo, float hi) { const bfx2 b = __builtin_convertvector((f32x2){lo, hi}, bfx2); return __builtin_bit_cast(unsigned, b); }
; __device__ __forceinline__ float bflo(unsigned w) { return __uint_as_float(w << 16); }
; __device__ __forceinline__ float bfhi(unsigned w) { return __uint_as_float(w & 0xffff0000u); }
; template <int NS, class Epi>
; __device__ __forceinline__ void skinny_gemm2d(Frame& F, const bf16* A, int K, const bf16* Bt, const Epi& E) {
;     ...
;         if (ks == 1) red[(mt * 2 + nt) * 64 + lane] = acc;
;         __syncthreads();
;         if (ks == 0) { acc += red[(mt * 2 + nt) * 64 + lane]; E(r0 + lr, c0 + 4 * lq, acc, acc); }
;     __device__ __forceinline__ void operator()(int r, int c, const pg8::f32x4 a, const pg8::f32x4) const {
;         const size_t off = (size_t)(MP + r) * D + c; const u32x2 gw = *(const u32x2*)(GATE + off);
;         f32x4 v = a * (f32x4){bflo(gw.x), bfhi(gw.x), bflo(gw.y), bfhi(gw.y)};
;         if (STAGE == 1) { const u32x2 pw = *(const u32x2*)(MRG + off); v += (f32x4){bflo(pw.x), bfhi(pw.x), bflo(pw.y), bfhi(pw.y)}; }
;         u32x2 w; w.x = pk2(v.x, v.y); w.y = pk2(v.z, v.w); *(u32x2*)(MRG + off) = w; }
.LBB0_2571:
	s_and_b64 vcc, exec, s[8:9]
	s_waitcnt lgkmcnt(0)
	s_barrier
	s_cbranch_vccnz .LBB0_2568
	v_or_b32_e32 v6, s14, v1
	v_or_b32_e32 v18, s15, v14
	v_lshl_or_b32 v6, v6, 11, v17
	v_ashrrev_i32_e32 v19, 31, v18
	v_lshl_add_u64 v[18:19], v[6:7], 0, v[18:19]
	v_lshlrev_b64 v[18:19], 1, v[18:19]
	v_lshl_add_u64 v[20:21], s[56:57], 0, v[18:19]
	v_lshl_add_u64 v[24:25], s[4:5], 0, v[18:19]
	global_load_dwordx2 v[22:23], v[20:21], off
	global_load_dwordx2 v[26:27], v[24:25], off
	ds_read_b128 v[18:21], v13
	s_waitcnt lgkmcnt(0)
	v_add_f32_e32 v4, v4, v20
	v_add_f32_e32 v5, v5, v21
	v_add_f32_e32 v2, v2, v18
	v_add_f32_e32 v3, v3, v19
	s_waitcnt vmcnt(1)
	v_lshlrev_b32_e32 v18, 16, v22
	v_and_b32_e32 v19, 0xffff0000, v22
	v_lshlrev_b32_e32 v20, 16, v23
	v_and_b32_e32 v21, 0xffff0000, v23
	s_waitcnt vmcnt(0)
	v_lshlrev_b32_e32 v22, 16, v26
	v_and_b32_e32 v23, 0xffff0000, v26
	v_lshlrev_b32_e32 v26, 16, v27
	v_and_b32_e32 v27, 0xffff0000, v27
	v_fma_f32 v4, v4, v20, v26
	v_fma_f32 v5, v5, v21, v27
	v_fma_f32 v2, v2, v18, v22
	v_fma_f32 v3, v3, v19, v23
	s_nop 0
	v_cvt_pk_bf16_f32 v2, v2, v3
	v_cvt_pk_bf16_f32 v3, v4, v5
	global_store_dwordx2 v[24:25], v[2:3], off
	s_branch .LBB0_2568

; __device__ __forceinline__ unsigned pk2(float lo, float hi) { const bfx2 b = __builtin_convertvector((f32x2){lo, hi}, bfx2); return __builtin_bit_cast(unsigned, b); }
; template <int NS, class Epi>
; __device__ __forceinline__ void skinny_gemm2d(Frame& F, const bf16* A, int K, const bf16* Bt, const Epi& E) {
;     ...
;         if (ks == 1) red[(mt * 2 + nt) * 64 + lane] = acc;
;         __syncthreads();
;         if (ks == 0) { acc += red[(mt * 2 + nt) * 64 + lane]; E(r0 + lr, c0 + 4 * lq, acc, acc); }
;     __device__ __forceinline__ void operator()(int r, int c, const pg8::f32x4 a, const pg8::f32x4) const {
;         u32x2 w; w.x = pk2(a.x, a.y); w.y = pk2(a.z, a.w); *(u32x2*)(O + (size_t)(MP + r) * ldc + c) = w; }
.LBB0_2654:
	s_and_b64 vcc, exec, s[8:9]
	s_waitcnt lgkmcnt(0)
	s_barrier
	s_cbranch_vccnz .LBB0_2651
	ds_read_b128 v[18:21], v12
	v_or_b32_e32 v6, s12, v14
	v_or_b32_e32 v22, s13, v13
	v_lshlrev_b32_e32 v6, 12, v6
	v_ashrrev_i32_e32 v23, 31, v22
	s_waitcnt lgkmcnt(0)
	v_add_f32_e32 v4, v4, v20
	v_add_f32_e32 v5, v5, v21
	v_add_f32_e32 v2, v2, v18
	v_add_f32_e32 v3, v3, v19
	s_nop 0
	v_cvt_pk_bf16_f32 v2, v2, v3
	v_cvt_pk_bf16_f32 v3, v4, v5
	v_lshl_add_u64 v[4:5], s[72:73], 0, v[6:7]
	v_lshl_add_u64 v[4:5], v[22:23], 1, v[4:5]
	global_store_dwordx2 v[4:5], v[2:3], off
	s_branch .LBB0_2651

; __device__ __forceinline__ float bflo(unsigned w) { return __uint_as_float(w << 16); }
; __device__ __forceinline__ float bfhi(unsigned w) { return __uint_as_float(w & 0xffff0000u); }
; template <bool INB, bool OUTB>
; __device__ __forceinline__ void thin_phase(Frame& F, const bf16* Fb, const void* xin_p, const void* xin_s, const float* post_g, float half, void* xout, const float* next_g, bf16* H) {
;     ...
;     for (int m0 = 2 * gw; m0 < MT; m0 += 2 * NGW) {
;         f32x4 f[2][8], x[2][8]; float s[2] = {0.f, 0.f};
; #pragma unroll
;         for (int r = 0; r < 2; ++r) { const int m = m0 + r;
; #pragma unroll
;             for (int j = 0; j < 4; ++j) { const int c = (j * 64 + lane) * 8; const u32x4 w = *(const u32x4*)(Fb + (size_t)m * D + c);
;                 f[r][2 * j] = (f32x4){bflo(w.x), bfhi(w.x), bflo(w.y), bfhi(w.y)}; f[r][2 * j + 1] = (f32x4){bflo(w.z), bfhi(w.z), bflo(w.w), bfhi(w.w)};
;                 if (INB) { const bf16* xr = m < MP ? (const bf16*)xin_p + (size_t)m * D : (const bf16*)xin_s + (size_t)(m - MP) * D; const u32x4 xw = *(const u32x4*)(xr + c);
;                     x[r][2 * j] = (f32x4){bflo(xw.x), bfhi(xw.x), bflo(xw.y), bfhi(xw.y)}; x[r][2 * j + 1] = (f32x4){bflo(xw.z), bfhi(xw.z), bflo(xw.w), bfhi(xw.w)}; }
;                 else { const float* xr = m < MP ? (const float*)xin_p + (size_t)m * D : (const float*)xin_s + (size_t)(m - MP) * D; x[r][2 * j] = *(const f32x4*)(xr + c); x[r][2 * j + 1] = *(const f32x4*)(xr + c + 4); } } }
; #pragma unroll
;         for (int r = 0; r < 2; ++r)
; #pragma unroll
;             for (int q = 0; q < 8; ++q) s[r] += (f[r][q].x * f[r][q].x + f[r][q].y * f[r][q].y) + (f[r][q].z * f[r][q].z + f[r][q].w * f[r][q].w);
;         const float r0 = half / sqrtf(wave_sum(s[0]) * (1.0f / D) + RMS_EPS), r1 = half / sqrtf(wave_sum(s[1]) * (1.0f / D) + RMS_EPS);
.LBB0_2711:
	v_lshl_add_u64 v[48:49], s[12:13], 0, v[34:35]
	v_add_co_u32_e32 v2, vcc, s2, v48
	s_add_u32 s20, s12, 0x1f788000
	s_nop 0
	v_addc_co_u32_e32 v3, vcc, 0, v49, vcc
	v_add_co_u32_e32 v4, vcc, s3, v48
	global_load_dwordx4 v[86:89], v[2:3], off offset:1024
	global_load_dwordx4 v[90:93], v[2:3], off offset:2048
	v_addc_co_u32_e32 v5, vcc, 0, v49, vcc
	global_load_dwordx4 v[94:97], v[2:3], off offset:3072
	global_load_dwordx4 v[100:103], v[4:5], off offset:1024
	global_load_dwordx4 v[26:29], v[4:5], off offset:2048
	global_load_dwordx4 v[30:33], v[4:5], off offset:3072
	global_load_dwordx4 v[60:63], v[4:5], off offset:-4096
	s_addc_u32 s21, s13, 0
	s_add_i32 s16, s4, 0xffffc000
	s_lshl_b64 s[8:9], s[16:17], 12
	s_add_u32 s8, s33, s8
	s_addc_u32 s9, s50, s9
	s_cmpk_lt_i32 s4, 0x4000
	s_cselect_b32 s9, s21, s9
	s_cselect_b32 s8, s20, s8
	global_load_dwordx4 v[108:111], v1, s[8:9]
	s_add_i32 s22, s4, 1
	s_add_u32 s23, s12, 0x1f789000
	s_addc_u32 s24, s13, 0
	s_add_i32 s16, s4, 0xffffc001
	s_lshl_b64 s[20:21], s[16:17], 12
	s_add_u32 s16, s33, s20
	s_addc_u32 s20, s50, s21
	s_cmpk_lt_i32 s22, 0x4000
	s_cselect_b32 s21, s24, s20
	s_cselect_b32 s20, s23, s16
	global_load_dwordx4 v[122:125], v1, s[20:21]
	global_load_dwordx4 v[132:135], v[4:5], off
	global_load_dwordx4 v[22:25], v1, s[8:9] offset:1024
	global_load_dwordx4 v[14:17], v1, s[8:9] offset:2048
	global_load_dwordx4 v[6:9], v1, s[8:9] offset:3072
	global_load_dwordx4 v[18:21], v1, s[20:21] offset:1024
	global_load_dwordx4 v[10:13], v1, s[20:21] offset:2048
	global_load_dwordx4 v[2:5], v1, s[20:21] offset:3072
	s_waitcnt vmcnt(15)
	v_lshlrev_b32_e32 v70, 16, v88
	v_and_b32_e32 v71, 0xffff0000, v88
	s_waitcnt vmcnt(14)
	v_lshlrev_b32_e32 v83, 16, v90
	v_and_b32_e32 v79, 0xffff0000, v87
	v_and_b32_e32 v78, 0xffff0000, v86
	s_waitcnt vmcnt(9)
	v_and_b32_e32 v55, 0xffff0000, v62
	v_and_b32_e32 v54, 0xffff0000, v60
	v_and_b32_e32 v105, 0xffff0000, v63
	v_and_b32_e32 v104, 0xffff0000, v61
	v_lshlrev_b32_e32 v59, 16, v62
	v_lshlrev_b32_e32 v58, 16, v60
	v_lshlrev_b32_e32 v107, 16, v63
	v_lshlrev_b32_e32 v106, 16, v61
	v_mul_f32_e32 v56, v54, v54
	v_mul_f32_e32 v57, v55, v55
	v_mul_f32_e32 v60, v104, v104
	v_mul_f32_e32 v61, v105, v105
	v_fma_f32 v56, v58, v58, v56
	v_fma_f32 v57, v59, v59, v57
	v_fma_f32 v60, v106, v106, v60
	v_fma_f32 v61, v107, v107, v61
	v_lshlrev_b32_e32 v75, 16, v87
	v_lshlrev_b32_e32 v74, 16, v86
	v_mul_f32_e32 v86, v78, v78
	v_mul_f32_e32 v87, v79, v79
	v_mul_f32_e32 v82, v70, v70
	v_mul_f32_e32 v88, v71, v71
	v_lshlrev_b32_e32 v98, 16, v89
	v_and_b32_e32 v99, 0xffff0000, v89
	v_mov_b32_e32 v89, v83
	v_and_b32_e32 v81, 0xffff0000, v90
	v_lshlrev_b32_e32 v84, 16, v91
	v_and_b32_e32 v85, 0xffff0000, v91
	v_lshlrev_b32_e32 v50, 16, v96
	v_and_b32_e32 v51, 0xffff0000, v96
	v_lshlrev_b32_e32 v52, 16, v97
	v_and_b32_e32 v53, 0xffff0000, v97
	v_and_b32_e32 v67, 0xffff0000, v26
	v_add_f32_e32 v90, v56, v60
	v_add_f32_e32 v91, v57, v61
	v_fma_f32 v86, v74, v74, v86
	v_fma_f32 v87, v75, v75, v87
	v_add_f32_e32 v88, v82, v88
	v_add_f32_e32 v89, v83, v89
	v_mul_f32_e32 v96, v82, v82
	v_mul_f32_e32 v97, v83, v83
	v_mul_f32_e32 v66, v99, v99
	v_lshlrev_b32_e32 v76, 16, v102
	v_and_b32_e32 v77, 0xffff0000, v102
	v_mul_f32_e32 v68, v81, v81
	v_mul_f32_e32 v80, v84, v84
	v_mul_f32_e32 v102, v85, v85
	v_mov_b32_e32 v89, v97
	v_fma_f32 v96, v98, v98, v66
	v_fma_f32 v97, v99, v99, v66
	v_pk_add_f32 v[90:91], v[90:91], v[90:91] op_sel:[0,1] op_sel_hi:[1,0]
	v_pk_add_f32 v[86:87], v[86:87], v[86:87] op_sel:[0,1] op_sel_hi:[1,0]
	v_mov_b32_e32 v97, v68
	v_mov_b32_e32 v91, v80
	v_mov_b32_e32 v87, v102
	v_add_f32_e32 v88, v88, v96
	v_add_f32_e32 v89, v89, v97
	v_add_f32_e32 v86, v90, v86
	v_add_f32_e32 v87, v91, v87
	v_lshlrev_b32_e32 v90, 16, v92
	v_add_f32_e32 v86, v88, v86
	v_add_f32_e32 v87, v89, v87
	v_and_b32_e32 v91, 0xffff0000, v92
	v_mul_f32_e32 v66, v90, v90
	v_lshlrev_b32_e32 v92, 16, v93
	s_waitcnt vmcnt(8)
	v_lshlrev_b32_e32 v118, 16, v108
	v_and_b32_e32 v119, 0xffff0000, v108
	v_lshlrev_b32_e32 v120, 16, v109
	v_and_b32_e32 v121, 0xffff0000, v109
	v_add_f32_e32 v96, v86, v86
	v_add_f32_e32 v97, v86, v87
	v_fma_f32 v108, v90, v90, v66
	v_fma_f32 v109, v91, v91, v66
	v_and_b32_e32 v93, 0xffff0000, v93
	v_mul_f32_e32 v66, v92, v92
	v_lshlrev_b32_e32 v86, 16, v94
	v_lshlrev_b32_e32 v114, 16, v110
	v_and_b32_e32 v115, 0xffff0000, v110
	v_lshlrev_b32_e32 v116, 16, v111
	v_and_b32_e32 v117, 0xffff0000, v111
	v_fma_f32 v110, v92, v92, v66
	v_fma_f32 v111, v93, v93, v66
	v_and_b32_e32 v87, 0xffff0000, v94
	v_mul_f32_e32 v66, v86, v86
	v_lshlrev_b32_e32 v88, 16, v95
	v_fma_f32 v112, v86, v86, v66
	v_fma_f32 v113, v87, v87, v66
	v_and_b32_e32 v89, 0xffff0000, v95
	v_mul_f32_e32 v66, v88, v88
	v_fma_f32 v94, v88, v88, v66
	v_fma_f32 v95, v89, v89, v66
	v_add_f32_e32 v108, v108, v110
	v_add_f32_e32 v109, v109, v111
	s_waitcnt vmcnt(7)
	v_lshlrev_b32_e32 v60, 16, v122
	v_and_b32_e32 v61, 0xffff0000, v122
	v_lshlrev_b32_e32 v56, 16, v123
	v_and_b32_e32 v57, 0xffff0000, v123
	v_mul_f32_e32 v96, v51, v51
	v_mul_f32_e32 v112, v52, v52
	v_mul_f32_e32 v94, v53, v53
	v_mul_f32_e32 v122, v50, v50
	v_mov_b32_e32 v123, v109
	v_add_f32_e32 v96, v122, v96
	v_add_f32_e32 v97, v123, v97
	v_add_f32_e32 v94, v112, v94
	v_add_f32_e32 v95, v113, v95
	s_waitcnt vmcnt(6)
; #define NT_ST4(ptr_, val_) __builtin_nontemporal_store((val_), (f32x4*)(ptr_))
; __device__ __forceinline__ u32x4 pack8(const f32x4 a, const f32x4 b) { u32x4 o; o.x = pk2(a.x, a.y); o.y = pk2(a.z, a.w); o.z = pk2(b.x, b.y); o.w = pk2(b.z, b.w); return o; }
; template <bool INB, bool OUTB>
; __device__ __forceinline__ void thin_phase(Frame& F, const bf16* Fb, const void* xin_p, const void* xin_s, const float* post_g, float half, void* xout, const float* next_g, bf16* H) {
;     ...
;             for (int q = 0; q < 8; ++q) s[r] += (f[r][q].x * f[r][q].x + f[r][q].y * f[r][q].y) + (f[r][q].z * f[r][q].z + f[r][q].w * f[r][q].w);
;         const float r0 = half / sqrtf(wave_sum(s[0]) * (1.0f / D) + RMS_EPS), r1 = half / sqrtf(wave_sum(s[1]) * (1.0f / D) + RMS_EPS);
;         float s2[2] = {0.f, 0.f};
; #pragma unroll
;         for (int j = 0; j < 4; ++j) { const int c = (j * 64 + lane) * 8; const f32x4 g0 = *(const f32x4*)(post_g + c), g1 = *(const f32x4*)(post_g + c + 4);
; #pragma unroll
;             for (int r = 0; r < 2; ++r) { const f32x4 o0 = x[r][2 * j] + f[r][2 * j] * (r == 0 ? r0 : r1) * g0, o1 = x[r][2 * j + 1] + f[r][2 * j + 1] * (r == 0 ? r0 : r1) * g1; f[r][2 * j] = o0; f[r][2 * j + 1] = o1;
;                 if (OUTB) __builtin_nontemporal_store(pack8(o0, o1), (u32x4*)((bf16*)xout + (size_t)(m0 + r) * D + c));
;                 else { NT_ST4((float*)xout + (size_t)(m0 + r) * D + c, o0); NT_ST4((float*)xout + (size_t)(m0 + r) * D + c + 4, o1); }
;                 s2[r] += ((o0.x * o0.x + o0.y * o0.y) + (o0.z * o0.z + o0.w * o0.w)) + ((o1.x * o1.x + o1.y * o1.y) + (o1.z * o1.z + o1.w * o1.w)); } }
	v_and_b32_e32 v123, 0xffff0000, v134
	v_add_f32_e32 v94, v96, v94
	v_add_f32_e32 v95, v97, v95
	v_and_b32_e32 v122, 0xffff0000, v132
	v_and_b32_e32 v127, 0xffff0000, v135
	v_and_b32_e32 v126, 0xffff0000, v133
	v_lshlrev_b32_e32 v64, 16, v124
	v_and_b32_e32 v65, 0xffff0000, v124
	v_lshlrev_b32_e32 v62, 16, v125
	v_and_b32_e32 v63, 0xffff0000, v125
	v_add_f32_e32 v80, v94, v95
	v_lshlrev_b32_e32 v125, 16, v134
	v_lshlrev_b32_e32 v124, 16, v132
	v_lshlrev_b32_e32 v129, 16, v135
	v_lshlrev_b32_e32 v128, 16, v133
	v_mul_f32_e32 v94, v122, v122
	v_mul_f32_e32 v95, v123, v123
	v_mul_f32_e32 v96, v126, v126
	v_mul_f32_e32 v97, v127, v127
	v_lshlrev_b32_e32 v69, 16, v26
	v_fma_f32 v94, v124, v124, v94
	v_fma_f32 v95, v125, v125, v95
	v_fma_f32 v96, v128, v128, v96
	v_fma_f32 v97, v129, v129, v97
	v_and_b32_e32 v111, 0xffff0000, v101
	v_and_b32_e32 v110, 0xffff0000, v100
	v_add_f32_e32 v94, v94, v96
	v_add_f32_e32 v95, v95, v97
	v_lshlrev_b32_e32 v109, 16, v101
	v_lshlrev_b32_e32 v108, 16, v100
	v_mul_f32_e32 v96, v110, v110
	v_mul_f32_e32 v97, v111, v111
	v_mul_f32_e32 v68, v76, v76
	v_mul_f32_e32 v100, v77, v77
	v_and_b32_e32 v113, 0xffff0000, v103
	v_mov_b32_e32 v101, v69
	v_lshlrev_b32_e32 v72, 16, v27
	v_and_b32_e32 v73, 0xffff0000, v27
	v_fma_f32 v96, v108, v108, v96
	v_fma_f32 v97, v109, v109, v97
	v_lshlrev_b32_e32 v112, 16, v103
	v_add_f32_e32 v100, v68, v100
	v_add_f32_e32 v101, v69, v101
	v_mul_f32_e32 v102, v68, v68
	v_mul_f32_e32 v103, v69, v69
	v_mul_f32_e32 v66, v113, v113
	v_mul_f32_e32 v82, v67, v67
	v_mul_f32_e32 v132, v72, v72
	v_mul_f32_e32 v133, v73, v73
	v_mov_b32_e32 v101, v103
	v_fma_f32 v102, v112, v112, v66
	v_fma_f32 v103, v113, v113, v66
	v_pk_add_f32 v[94:95], v[94:95], v[94:95] op_sel:[0,1] op_sel_hi:[1,0]
	v_pk_add_f32 v[96:97], v[96:97], v[96:97] op_sel:[0,1] op_sel_hi:[1,0]
	v_mov_b32_e32 v103, v82
	v_mov_b32_e32 v95, v132
	v_mov_b32_e32 v97, v133
	v_add_f32_e32 v100, v100, v102
	v_add_f32_e32 v101, v101, v103
	v_add_f32_e32 v94, v94, v96
	v_add_f32_e32 v95, v95, v97
	v_lshlrev_b32_e32 v102, 16, v29
	v_add_f32_e32 v94, v100, v94
	v_add_f32_e32 v95, v101, v95
	v_lshlrev_b32_e32 v100, 16, v28
	v_and_b32_e32 v101, 0xffff0000, v28
	v_mul_f32_e32 v28, v100, v100
	v_fma_f32 v134, v100, v100, v28
	v_fma_f32 v135, v101, v101, v28
	v_and_b32_e32 v103, 0xffff0000, v29
	v_mul_f32_e32 v28, v102, v102
	v_fma_f32 v29, v103, v103, v28
	v_fma_f32 v28, v102, v102, v28
	v_lshlrev_b32_e32 v26, 16, v32
	v_and_b32_e32 v27, 0xffff0000, v32
	v_add_f32_e32 v132, v94, v94
	v_add_f32_e32 v133, v94, v95
	v_add_f32_e32 v28, v134, v28
	v_add_f32_e32 v29, v135, v29
	v_mul_f32_e32 v132, v27, v27
	v_mul_f32_e32 v136, v26, v26
	v_mov_b32_e32 v137, v29
	v_add_f32_e32 v28, v136, v132
	v_add_f32_e32 v29, v137, v133
	s_nop 0
	s_nop 0
	v_add_f32_dpp v66, v80, v80 quad_perm:[1,0,3,2] row_mask:0xf bank_mask:0xf bound_ctrl:1
	v_lshlrev_b32_e32 v94, 16, v30
	v_and_b32_e32 v95, 0xffff0000, v30
	v_add_f32_dpp v66, v66, v66 quad_perm:[2,3,0,1] row_mask:0xf bank_mask:0xf bound_ctrl:1
	v_mul_f32_e32 v30, v94, v94
	v_lshlrev_b32_e32 v96, 16, v31
	v_add_f32_dpp v66, v66, v66 row_half_mirror row_mask:0xf bank_mask:0xf bound_ctrl:1
	v_fma_f32 v140, v94, v94, v30
	v_fma_f32 v141, v95, v95, v30
	v_and_b32_e32 v97, 0xffff0000, v31
	v_add_f32_dpp v66, v66, v66 row_mirror row_mask:0xf bank_mask:0xf bound_ctrl:1
	v_mul_f32_e32 v30, v96, v96
	v_readlane_b32 s16, v66, 16
	v_readlane_b32 s20, v66, 48
	v_readlane_b32 s8, v66, 0
	v_readlane_b32 s9, v66, 32
	v_mov_b32_e32 v142, s16
	v_mov_b32_e32 v143, s20
	v_add_f32_e32 v142, s8, v142
	v_add_f32_e32 v143, s9, v143
	v_lshlrev_b32_e32 v32, 16, v33
	v_add_f32_e32 v66, v142, v143
	v_fmamk_f32 v66, v66, 0x3a000000, v130
	v_mul_f32_e32 v68, 0x4f800000, v66
	v_cmp_gt_f32_e32 vcc, s5, v66
	v_and_b32_e32 v33, 0xffff0000, v33
	v_fma_f32 v31, v97, v97, v30
	v_fma_f32 v30, v96, v96, v30
	v_cndmask_b32_e32 v66, v66, v68, vcc
	v_mul_f32_e32 v140, v32, v32
	v_mul_f32_e32 v30, v33, v33
	v_sqrt_f32_e32 v68, v66
	v_add_f32_e32 v30, v140, v30
	v_add_f32_e32 v31, v141, v31
	s_nop 0
	v_add_f32_e32 v28, v28, v30
	v_add_f32_e32 v29, v29, v31
	s_nop 0
	v_add_f32_e32 v28, v28, v29
	v_add_u32_e32 v29, -1, v68
	v_fma_f32 v30, -v29, v68, v66
	v_add_f32_dpp v28, v28, v28 quad_perm:[1,0,3,2] row_mask:0xf bank_mask:0xf bound_ctrl:1
	v_cmp_ge_f32_e64 s[8:9], 0, v30
	v_add_u32_e32 v30, 1, v68
	v_add_f32_dpp v28, v28, v28 quad_perm:[2,3,0,1] row_mask:0xf bank_mask:0xf bound_ctrl:1
	v_fma_f32 v31, -v30, v68, v66
	v_cndmask_b32_e64 v29, v68, v29, s[8:9]
	v_add_f32_dpp v28, v28, v28 row_half_mirror row_mask:0xf bank_mask:0xf bound_ctrl:1
	v_cmp_lt_f32_e64 s[8:9], 0, v31
	s_nop 0
	v_add_f32_dpp v28, v28, v28 row_mirror row_mask:0xf bank_mask:0xf bound_ctrl:1
	v_cndmask_b32_e64 v30, v29, v30, s[8:9]
	v_readlane_b32 s16, v28, 16
	v_readlane_b32 s20, v28, 48
	v_readlane_b32 s8, v28, 0
	v_readlane_b32 s9, v28, 32
	v_mov_b32_e32 v28, s16
	v_mov_b32_e32 v29, s20
	v_add_f32_e32 v28, s8, v28
	v_add_f32_e32 v29, s9, v29
	v_mul_f32_e32 v31, 0x37800000, v30
	v_add_f32_e32 v28, v28, v29
	v_fmamk_f32 v28, v28, 0x3a000000, v130
	v_mul_f32_e32 v29, 0x4f800000, v28
	v_cmp_gt_f32_e64 s[8:9], s5, v28
	v_cndmask_b32_e32 v30, v30, v31, vcc
	v_cmp_class_f32_e32 vcc, v66, v131
	v_cndmask_b32_e64 v28, v28, v29, s[8:9]
	v_sqrt_f32_e32 v29, v28
	v_cndmask_b32_e32 v30, v30, v66, vcc
	v_add_u32_e32 v31, -1, v29
	v_fma_f32 v66, -v31, v29, v28
	v_cmp_ge_f32_e32 vcc, 0, v66
	v_add_u32_e32 v66, 1, v29
	s_nop 0
	v_cndmask_b32_e32 v31, v29, v31, vcc
	v_fma_f32 v29, -v66, v29, v28
	v_cmp_lt_f32_e32 vcc, 0, v29
	s_nop 1
	v_cndmask_b32_e32 v29, v31, v66, vcc
	v_div_scale_f32 v66, s[20:21], v30, v30, 1.0
	v_rcp_f32_e32 v68, v66
	v_mul_f32_e32 v31, 0x37800000, v29
	v_cndmask_b32_e64 v29, v29, v31, s[8:9]
	v_cmp_class_f32_e32 vcc, v28, v131
	s_nop 1
	v_cndmask_b32_e32 v80, v29, v28, vcc
	v_fma_f32 v28, -v66, v68, 1.0
	v_fmac_f32_e32 v68, v28, v68
	v_div_scale_f32 v28, vcc, 1.0, v30, 1.0
	v_mul_f32_e32 v29, v28, v68
	v_fma_f32 v31, -v66, v29, v28
	v_fmac_f32_e32 v29, v31, v68
	v_fma_f32 v28, -v66, v29, v28
	v_div_scale_f32 v66, s[8:9], v80, v80, 1.0
	v_div_fmas_f32 v28, v28, v68, v29
	v_rcp_f32_e32 v68, v66
	v_div_fixup_f32 v82, v28, v30, 1.0
	v_mov_b32_e32 v28, v58
	v_mov_b32_e32 v29, v54
	v_mul_f32_e32 v30, v82, v28
	v_mul_f32_e32 v31, v82, v29
	v_mov_b32_e32 v29, v104
	v_mov_b32_e32 v54, v59
	v_mov_b32_e32 v104, v107
	v_mov_b32_e32 v28, v106
	v_mul_f32_e32 v58, v82, v54
	v_mul_f32_e32 v59, v82, v55
	v_mul_f32_e32 v54, v82, v104
	v_mul_f32_e32 v55, v82, v105
	v_add_co_u32_e32 v104, vcc, 0x1f788000, v48
	v_mul_f32_e32 v28, v82, v28
	v_mul_f32_e32 v29, v82, v29
	s_nop 0
	v_addc_co_u32_e32 v105, vcc, 0, v49, vcc
	v_fma_f32 v106, -v66, v68, 1.0
	s_waitcnt vmcnt(0)
; #define NT_ST4(ptr_, val_) __builtin_nontemporal_store((val_), (f32x4*)(ptr_))
; __device__ __forceinline__ u32x4 pack8(const f32x4 a, const f32x4 b) { u32x4 o; o.x = pk2(a.x, a.y); o.y = pk2(a.z, a.w); o.z = pk2(b.x, b.y); o.w = pk2(b.z, b.w); return o; }
; template <bool INB, bool OUTB>
; __device__ __forceinline__ void thin_phase(Frame& F, const bf16* Fb, const void* xin_p, const void* xin_s, const float* post_g, float half, void* xout, const float* next_g, bf16* H) {
;     ...
;         for (int j = 0; j < 4; ++j) { const int c = (j * 64 + lane) * 8; const f32x4 g0 = *(const f32x4*)(post_g + c), g1 = *(const f32x4*)(post_g + c + 4);
; #pragma unroll
;             for (int r = 0; r < 2; ++r) { const f32x4 o0 = x[r][2 * j] + f[r][2 * j] * (r == 0 ? r0 : r1) * g0, o1 = x[r][2 * j + 1] + f[r][2 * j + 1] * (r == 0 ? r0 : r1) * g1; f[r][2 * j] = o0; f[r][2 * j + 1] = o1;
;                 if (OUTB) __builtin_nontemporal_store(pack8(o0, o1), (u32x4*)((bf16*)xout + (size_t)(m0 + r) * D + c));
;                 else { NT_ST4((float*)xout + (size_t)(m0 + r) * D + c, o0); NT_ST4((float*)xout + (size_t)(m0 + r) * D + c + 4, o1); }
;                 s2[r] += ((o0.x * o0.x + o0.y * o0.y) + (o0.z * o0.z + o0.w * o0.w)) + ((o1.x * o1.x + o1.y * o1.y) + (o1.z * o1.z + o1.w * o1.w)); } }
	s_nop 1
	v_mov_b64_e32 v[132:133], v[144:145]
	v_mov_b64_e32 v[134:135], v[146:147]
	v_mov_b64_e32 v[136:137], v[148:149]
	v_mov_b64_e32 v[138:139], v[150:151]
	v_fma_f32 v28, v138, v28, v120
	v_fma_f32 v29, v139, v29, v121
	v_fma_f32 v30, v136, v30, v118
	v_fma_f32 v31, v137, v31, v119
	v_fma_f32 v54, v134, v54, v116
	v_fma_f32 v55, v135, v55, v117
	v_fma_f32 v58, v132, v58, v114
	v_fma_f32 v59, v133, v59, v115
	v_fmac_f32_e32 v68, v106, v68
	v_div_scale_f32 v106, vcc, 1.0, v80, 1.0
	v_cvt_pk_bf16_f32 v114, v30, v31
	v_cvt_pk_bf16_f32 v115, v28, v29
	v_cvt_pk_bf16_f32 v116, v58, v59
	v_cvt_pk_bf16_f32 v117, v54, v55
	v_mul_f32_e32 v107, v106, v68
	global_store_dwordx4 v[104:105], v[114:117], off nt
	v_mul_f32_e32 v52, v82, v52
	v_mul_f32_e32 v53, v82, v53
	s_nop 0
	v_fma_f32 v114, -v66, v107, v106
	v_fmac_f32_e32 v107, v114, v68
	v_fma_f32 v66, -v66, v107, v106
	v_div_fmas_f32 v66, v66, v68, v107
	v_div_fixup_f32 v106, v66, v80, 1.0
	v_mov_b32_e32 v114, v124
	v_mov_b32_e32 v115, v122
	v_mov_b32_e32 v116, v128
	v_mov_b32_e32 v117, v126
	v_mul_f32_e32 v114, v106, v114
	v_mul_f32_e32 v115, v106, v115
	v_mul_f32_e32 v116, v106, v116
	v_mul_f32_e32 v117, v106, v117
	v_mov_b32_e32 v122, v125
	v_mov_b32_e32 v126, v129
	v_fma_f32 v56, v138, v116, v56
	v_fma_f32 v57, v139, v117, v57
	v_fma_f32 v60, v136, v114, v60
	v_fma_f32 v61, v137, v115, v61
	v_mul_f32_e32 v114, v106, v122
	v_mul_f32_e32 v115, v106, v123
	v_mul_f32_e32 v116, v106, v126
	v_mul_f32_e32 v117, v106, v127
	v_fma_f32 v62, v134, v116, v62
	v_fma_f32 v63, v135, v117, v63
	v_fma_f32 v64, v132, v114, v64
	v_fma_f32 v65, v133, v115, v65
	v_add_co_u32_e32 v114, vcc, s11, v48
	v_cvt_pk_bf16_f32 v116, v60, v61
	v_cvt_pk_bf16_f32 v117, v56, v57
	v_cvt_pk_bf16_f32 v118, v64, v65
	v_cvt_pk_bf16_f32 v119, v62, v63
	v_addc_co_u32_e32 v115, vcc, 0, v49, vcc
	global_store_dwordx4 v[114:115], v[116:119], off nt
	s_nop 0
	s_nop 0
	s_nop 0
	v_lshlrev_b32_e32 v128, 16, v18
	v_and_b32_e32 v129, 0xffff0000, v18
	v_lshlrev_b32_e32 v132, 16, v19
	v_and_b32_e32 v133, 0xffff0000, v19
	v_mov_b32_e32 v18, v75
	v_mov_b32_e32 v19, v79
	v_lshlrev_b32_e32 v124, 16, v22
	v_and_b32_e32 v125, 0xffff0000, v22
	v_lshlrev_b32_e32 v22, 16, v23
	v_and_b32_e32 v23, 0xffff0000, v23
	v_lshlrev_b32_e32 v134, 16, v20
	v_and_b32_e32 v135, 0xffff0000, v20
	v_lshlrev_b32_e32 v136, 16, v21
	v_and_b32_e32 v137, 0xffff0000, v21
	v_mul_f32_e32 v20, v82, v18
	v_mul_f32_e32 v21, v82, v19
	v_mov_b32_e32 v75, v78
	v_lshlrev_b32_e32 v126, 16, v24
	v_and_b32_e32 v127, 0xffff0000, v24
	v_lshlrev_b32_e32 v24, 16, v25
	v_and_b32_e32 v25, 0xffff0000, v25
	v_mul_f32_e32 v18, v82, v74
	v_mul_f32_e32 v19, v82, v75
	v_mul_f32_e32 v74, v82, v98
	v_mul_f32_e32 v75, v82, v99
	v_mul_f32_e32 v78, v106, v112
	v_mul_f32_e32 v79, v106, v113
	v_mul_f32_e32 v76, v106, v76
	v_mul_f32_e32 v77, v106, v77
	v_lshlrev_b32_e32 v98, 16, v14
	v_and_b32_e32 v99, 0xffff0000, v14
	v_lshlrev_b32_e32 v14, 16, v15
	v_and_b32_e32 v15, 0xffff0000, v15
	v_mov_b32_e32 v80, v83
	v_lshlrev_b32_e32 v112, 16, v16
	v_and_b32_e32 v113, 0xffff0000, v16
	v_lshlrev_b32_e32 v16, 16, v17
	v_and_b32_e32 v17, 0xffff0000, v17
	v_mul_f32_e32 v72, v106, v72
	v_mul_f32_e32 v73, v106, v73
	v_mov_b32_e32 v66, v69
	v_mul_f32_e32 v66, v106, v66
	v_mul_f32_e32 v67, v106, v67
	v_mul_f32_e32 v26, v106, v26
	v_mul_f32_e32 v27, v106, v27
	s_and_b64 vcc, exec, s[0:1]
	s_nop 1
	v_mov_b64_e32 v[116:117], v[152:153]
	v_mov_b64_e32 v[118:119], v[154:155]
	v_mov_b64_e32 v[120:121], v[156:157]
	v_mov_b64_e32 v[122:123], v[158:159]
	v_fma_f32 v20, v20, v118, v22
	v_fma_f32 v21, v21, v119, v23
	v_mul_f32_e32 v22, v82, v70
	v_mul_f32_e32 v23, v82, v71
	v_mov_b32_e32 v70, v109
	v_mov_b32_e32 v71, v111
	v_mov_b32_e32 v109, v110
	s_nop 0
	v_fma_f32 v24, v74, v122, v24
	v_fma_f32 v25, v75, v123, v25
	v_mul_f32_e32 v74, v106, v70
	v_mul_f32_e32 v75, v106, v71
	v_mul_f32_e32 v70, v106, v108
	v_mul_f32_e32 v71, v106, v109
	v_fma_f32 v18, v18, v116, v124
	v_fma_f32 v19, v19, v117, v125
	v_fma_f32 v22, v22, v120, v126
	v_fma_f32 v23, v23, v121, v127
	v_fma_f32 v70, v116, v70, v128
	v_fma_f32 v71, v117, v71, v129
	v_fma_f32 v74, v118, v74, v132
	v_fma_f32 v75, v119, v75, v133
	v_fma_f32 v76, v120, v76, v134
	v_fma_f32 v77, v121, v77, v135
	v_fma_f32 v78, v122, v78, v136
	v_fma_f32 v79, v123, v79, v137
	v_cvt_pk_bf16_f32 v124, v18, v19
	v_cvt_pk_bf16_f32 v125, v20, v21
	v_cvt_pk_bf16_f32 v126, v22, v23
	v_cvt_pk_bf16_f32 v127, v24, v25
	v_cvt_pk_bf16_f32 v108, v70, v71
	v_cvt_pk_bf16_f32 v109, v74, v75
	v_cvt_pk_bf16_f32 v110, v76, v77
	v_cvt_pk_bf16_f32 v111, v78, v79
	global_store_dwordx4 v[104:105], v[124:127], off offset:1024 nt
	global_store_dwordx4 v[114:115], v[108:111], off offset:1024 nt
	s_nop 0
	s_nop 0
	s_nop 0
	v_lshlrev_b32_e32 v124, 16, v12
	v_and_b32_e32 v125, 0xffff0000, v12
	v_lshlrev_b32_e32 v126, 16, v13
	v_and_b32_e32 v127, 0xffff0000, v13
	v_mul_f32_e32 v12, v82, v84
	v_mul_f32_e32 v13, v82, v85
	v_lshlrev_b32_e32 v120, 16, v10
	v_and_b32_e32 v121, 0xffff0000, v10
	v_lshlrev_b32_e32 v122, 16, v11
	v_and_b32_e32 v123, 0xffff0000, v11
	v_mul_f32_e32 v10, v82, v80
	v_mul_f32_e32 v11, v82, v81
	v_mul_f32_e32 v80, v82, v92
	v_mul_f32_e32 v81, v82, v93
	v_lshlrev_b32_e32 v84, 16, v6
	v_and_b32_e32 v85, 0xffff0000, v6
	v_lshlrev_b32_e32 v6, 16, v7
	v_and_b32_e32 v7, 0xffff0000, v7
	s_nop 1
	v_mov_b64_e32 v[108:109], v[160:161]
	v_mov_b64_e32 v[110:111], v[162:163]
	v_mov_b64_e32 v[116:117], v[164:165]
	v_mov_b64_e32 v[118:119], v[166:167]
	v_fma_f32 v12, v12, v110, v14
	v_fma_f32 v13, v13, v111, v15
	v_mul_f32_e32 v14, v82, v90
	v_mul_f32_e32 v15, v82, v91
	v_fma_f32 v10, v10, v108, v98
; #define NT_ST4(ptr_, val_) __builtin_nontemporal_store((val_), (f32x4*)(ptr_))
; __device__ __forceinline__ u32x4 pack8(const f32x4 a, const f32x4 b) { u32x4 o; o.x = pk2(a.x, a.y); o.y = pk2(a.z, a.w); o.z = pk2(b.x, b.y); o.w = pk2(b.z, b.w); return o; }
; template <bool INB, bool OUTB>
; __device__ __forceinline__ void thin_phase(Frame& F, const bf16* Fb, const void* xin_p, const void* xin_s, const float* post_g, float half, void* xout, const float* next_g, bf16* H) {
;     ...
;         for (int j = 0; j < 4; ++j) { const int c = (j * 64 + lane) * 8; const f32x4 g0 = *(const f32x4*)(post_g + c), g1 = *(const f32x4*)(post_g + c + 4);
; #pragma unroll
;             for (int r = 0; r < 2; ++r) { const f32x4 o0 = x[r][2 * j] + f[r][2 * j] * (r == 0 ? r0 : r1) * g0, o1 = x[r][2 * j + 1] + f[r][2 * j + 1] * (r == 0 ? r0 : r1) * g1; f[r][2 * j] = o0; f[r][2 * j + 1] = o1;
;                 if (OUTB) __builtin_nontemporal_store(pack8(o0, o1), (u32x4*)((bf16*)xout + (size_t)(m0 + r) * D + c));
;                 else { NT_ST4((float*)xout + (size_t)(m0 + r) * D + c, o0); NT_ST4((float*)xout + (size_t)(m0 + r) * D + c + 4, o1); }
;                 s2[r] += ((o0.x * o0.x + o0.y * o0.y) + (o0.z * o0.z + o0.w * o0.w)) + ((o1.x * o1.x + o1.y * o1.y) + (o1.z * o1.z + o1.w * o1.w)); } }
;         if (next_g) { const float q0 = 1.0f / sqrtf(wave_sum(s2[0]) * (1.0f / D) + RMS_EPS), q1 = 1.0f / sqrtf(wave_sum(s2[1]) * (1.0f / D) + RMS_EPS);
; #pragma unroll
;             for (int j = 0; j < 4; ++j) { const int c = (j * 64 + lane) * 8; const f32x4 g0 = *(const f32x4*)(next_g + c), g1 = *(const f32x4*)(next_g + c + 4);
; #pragma unroll
;                 for (int r = 0; r < 2; ++r) *(u32x4*)(H + (size_t)(m0 + r) * D + c) = pack8(f[r][2 * j] * (r == 0 ? q0 : q1) * g0, f[r][2 * j + 1] * (r == 0 ? q0 : q1) * g1); } }
	v_fma_f32 v11, v11, v109, v99
	s_nop 0
	v_fma_f32 v14, v14, v116, v112
	v_fma_f32 v15, v15, v117, v113
	v_fma_f32 v16, v80, v118, v16
	v_fma_f32 v17, v81, v119, v17
	v_fma_f32 v68, v110, v72, v122
	v_fma_f32 v69, v111, v73, v123
	v_mul_f32_e32 v80, v106, v102
	v_mul_f32_e32 v81, v106, v103
	v_mul_f32_e32 v72, v106, v100
	v_mul_f32_e32 v73, v106, v101
	v_cvt_pk_bf16_f32 v90, v10, v11
	v_cvt_pk_bf16_f32 v91, v12, v13
	v_cvt_pk_bf16_f32 v92, v14, v15
	v_cvt_pk_bf16_f32 v93, v16, v17
	v_fma_f32 v66, v108, v66, v120
	v_fma_f32 v67, v109, v67, v121
	v_fma_f32 v72, v116, v72, v124
	v_fma_f32 v73, v117, v73, v125
	v_fma_f32 v80, v118, v80, v126
	v_fma_f32 v81, v119, v81, v127
	global_store_dwordx4 v[104:105], v[90:93], off offset:2048 nt
	v_lshlrev_b32_e32 v112, 16, v4
	v_and_b32_e32 v113, 0xffff0000, v4
	v_cvt_pk_bf16_f32 v90, v66, v67
	v_cvt_pk_bf16_f32 v91, v68, v69
	v_cvt_pk_bf16_f32 v92, v72, v73
	v_cvt_pk_bf16_f32 v93, v80, v81
	global_store_dwordx4 v[114:115], v[90:93], off offset:2048 nt
	s_nop 0
	s_nop 0
	s_nop 0
	v_lshlrev_b32_e32 v116, 16, v5
	v_and_b32_e32 v117, 0xffff0000, v5
	v_mul_f32_e32 v4, v82, v88
	v_mul_f32_e32 v5, v82, v89
	v_lshlrev_b32_e32 v102, 16, v8
	v_and_b32_e32 v103, 0xffff0000, v8
	v_lshlrev_b32_e32 v8, 16, v9
	v_and_b32_e32 v9, 0xffff0000, v9
	v_lshlrev_b32_e32 v108, 16, v2
	v_and_b32_e32 v109, 0xffff0000, v2
	v_lshlrev_b32_e32 v110, 16, v3
	v_and_b32_e32 v111, 0xffff0000, v3
	v_mul_f32_e32 v2, v82, v86
	v_mul_f32_e32 v3, v82, v87
	s_nop 1
	v_mov_b64_e32 v[90:91], v[168:169]
	v_mov_b64_e32 v[92:93], v[170:171]
	v_mov_b64_e32 v[98:99], v[172:173]
	v_mov_b64_e32 v[100:101], v[174:175]
	v_fma_f32 v4, v4, v92, v6
	v_fma_f32 v5, v5, v93, v7
	v_mul_f32_e32 v6, v82, v50
	v_mul_f32_e32 v7, v82, v51
	v_fma_f32 v2, v2, v90, v84
	v_fma_f32 v3, v3, v91, v85
	s_nop 0
	v_fma_f32 v6, v6, v98, v102
	v_fma_f32 v7, v7, v99, v103
	v_fma_f32 v50, v52, v100, v8
	v_fma_f32 v51, v53, v101, v9
	v_cvt_pk_bf16_f32 v82, v2, v3
	v_cvt_pk_bf16_f32 v83, v4, v5
	v_cvt_pk_bf16_f32 v84, v6, v7
	v_cvt_pk_bf16_f32 v85, v50, v51
	global_store_dwordx4 v[104:105], v[82:85], off offset:3072 nt
	v_mul_f32_e32 v8, v106, v96
	v_mul_f32_e32 v9, v106, v97
	v_mul_f32_e32 v52, v106, v94
	v_mul_f32_e32 v53, v106, v95
	v_mul_f32_e32 v82, v106, v32
	v_mul_f32_e32 v83, v106, v33
	v_fma_f32 v52, v52, v90, v108
	v_fma_f32 v53, v53, v91, v109
	v_fma_f32 v8, v8, v92, v110
	v_fma_f32 v9, v9, v93, v111
	v_fma_f32 v32, v26, v98, v112
	v_fma_f32 v33, v27, v99, v113
	v_fma_f32 v26, v82, v100, v116
	v_fma_f32 v27, v83, v101, v117
	v_cvt_pk_bf16_f32 v82, v52, v53
	v_cvt_pk_bf16_f32 v83, v8, v9
	v_cvt_pk_bf16_f32 v84, v32, v33
	v_cvt_pk_bf16_f32 v85, v26, v27
	global_store_dwordx4 v[114:115], v[82:85], off offset:3072 nt
	s_cbranch_vccnz .LBB0_2710
	s_nop 0
	v_mul_f32_e32 v82, v56, v56
	v_mul_f32_e32 v83, v57, v57
	v_mul_f32_e32 v84, v60, v60
	v_mul_f32_e32 v85, v61, v61
	v_mul_f32_e32 v94, v53, v53
	v_pk_mov_b32 v[86:87], v[84:85], v[82:83] op_sel:[1,0]
	v_mov_b32_e32 v85, v83
	v_add_f32_e32 v82, v86, v84
	v_add_f32_e32 v83, v87, v85
	v_mul_f32_e32 v84, v62, v62
	v_mul_f32_e32 v85, v63, v63
	v_mul_f32_e32 v86, v64, v64
	v_mul_f32_e32 v87, v65, v65
	v_mul_f32_e32 v95, v8, v8
	v_pk_mov_b32 v[88:89], v[86:87], v[84:85] op_sel:[1,0]
	v_mov_b32_e32 v87, v85
	v_add_f32_e32 v84, v88, v86
	v_add_f32_e32 v85, v89, v87
	v_mul_f32_e32 v86, v74, v74
	v_mul_f32_e32 v87, v75, v75
	v_mul_f32_e32 v88, v70, v70
	v_mul_f32_e32 v89, v71, v71
	v_mul_f32_e32 v96, v9, v9
	v_pk_mov_b32 v[90:91], v[88:89], v[86:87] op_sel:[1,0]
	v_mov_b32_e32 v89, v87
	v_add_f32_e32 v86, v90, v88
	v_add_f32_e32 v87, v91, v89
	v_mul_f32_e32 v88, v78, v78
	v_mul_f32_e32 v89, v79, v79
	v_mul_f32_e32 v90, v76, v76
	v_mul_f32_e32 v91, v77, v77
	v_mul_f32_e32 v97, v32, v32
	v_pk_mov_b32 v[92:93], v[90:91], v[88:89] op_sel:[1,0]
	v_mov_b32_e32 v91, v89
	v_add_f32_e32 v88, v92, v90
	v_add_f32_e32 v89, v93, v91
	v_mul_f32_e32 v90, v67, v67
	v_mul_f32_e32 v92, v52, v52
	v_fma_f32 v91, v67, v67, v90
	v_fma_f32 v90, v66, v66, v90
	v_mul_f32_e32 v98, v33, v33
	v_mov_b32_e32 v91, v92
	v_mul_f32_e32 v92, v69, v69
	v_fma_f32 v93, v69, v69, v92
	v_fma_f32 v92, v68, v68, v92
	v_pk_add_f32 v[82:83], v[82:83], v[82:83] op_sel:[0,1] op_sel_hi:[1,0]
	v_mov_b32_e32 v93, v94
	v_add_f32_e32 v90, v90, v92
	v_add_f32_e32 v91, v91, v93
	v_mul_f32_e32 v92, v73, v73
	v_fma_f32 v93, v73, v73, v92
	v_fma_f32 v92, v72, v72, v92
	v_mul_f32_e32 v94, v81, v81
	v_mov_b32_e32 v93, v95
	v_fma_f32 v95, v81, v81, v94
	v_fma_f32 v94, v80, v80, v94
	v_pk_add_f32 v[84:85], v[84:85], v[84:85] op_sel:[0,1] op_sel_hi:[1,0]
	v_mov_b32_e32 v95, v96
	v_add_f32_e32 v92, v92, v94
	v_add_f32_e32 v93, v93, v95
	v_mov_b32_e32 v83, v97
	v_mov_b32_e32 v85, v98
	v_mul_f32_e32 v99, v26, v26
	v_mul_f32_e32 v100, v27, v27
	v_add_f32_e32 v90, v90, v92
	v_add_f32_e32 v91, v91, v93
	v_add_f32_e32 v92, v82, v84
	v_add_f32_e32 v93, v83, v85
	v_add_f32_e32 v82, v86, v87
	v_add_f32_e32 v83, v87, v86
	v_add_f32_e32 v84, v88, v89
	v_add_f32_e32 v85, v89, v88
	v_mov_b32_e32 v83, v99
	v_mov_b32_e32 v85, v100
	v_add_f32_e32 v94, v82, v84
	v_add_f32_e32 v95, v83, v85
	v_mul_f32_e32 v82, v28, v28
	v_mul_f32_e32 v83, v29, v29
	v_mul_f32_e32 v84, v30, v30
	v_mul_f32_e32 v85, v31, v31
	v_mul_f32_e32 v100, v6, v6
	v_pk_mov_b32 v[86:87], v[84:85], v[82:83] op_sel:[1,0]
	v_mov_b32_e32 v85, v83
	v_add_f32_e32 v82, v86, v84
	v_add_f32_e32 v83, v87, v85
	v_mul_f32_e32 v84, v54, v54
	v_mul_f32_e32 v85, v55, v55
	v_mul_f32_e32 v86, v58, v58
	v_mul_f32_e32 v87, v59, v59
	v_pk_add_f32 v[82:83], v[82:83], v[82:83] op_sel:[0,1] op_sel_hi:[1,0]
	v_pk_mov_b32 v[88:89], v[86:87], v[84:85] op_sel:[1,0]
; __device__ __forceinline__ u32x4 pack8(const f32x4 a, const f32x4 b) { u32x4 o; o.x = pk2(a.x, a.y); o.y = pk2(a.z, a.w); o.z = pk2(b.x, b.y); o.w = pk2(b.z, b.w); return o; }
; template <bool INB, bool OUTB>
; __device__ __forceinline__ void thin_phase(Frame& F, const bf16* Fb, const void* xin_p, const void* xin_s, const float* post_g, float half, void* xout, const float* next_g, bf16* H) {
;     ...
;                 s2[r] += ((o0.x * o0.x + o0.y * o0.y) + (o0.z * o0.z + o0.w * o0.w)) + ((o1.x * o1.x + o1.y * o1.y) + (o1.z * o1.z + o1.w * o1.w)); } }
;         if (next_g) { const float q0 = 1.0f / sqrtf(wave_sum(s2[0]) * (1.0f / D) + RMS_EPS), q1 = 1.0f / sqrtf(wave_sum(s2[1]) * (1.0f / D) + RMS_EPS);
; #pragma unroll
;             for (int j = 0; j < 4; ++j) { const int c = (j * 64 + lane) * 8; const f32x4 g0 = *(const f32x4*)(next_g + c), g1 = *(const f32x4*)(next_g + c + 4);
; #pragma unroll
;                 for (int r = 0; r < 2; ++r) *(u32x4*)(H + (size_t)(m0 + r) * D + c) = pack8(f[r][2 * j] * (r == 0 ? q0 : q1) * g0, f[r][2 * j + 1] * (r == 0 ? q0 : q1) * g1); } }
	v_mov_b32_e32 v87, v85
	v_add_f32_e32 v84, v88, v86
	v_add_f32_e32 v85, v89, v87
	v_mul_f32_e32 v86, v20, v20
	v_mul_f32_e32 v87, v21, v21
	v_mul_f32_e32 v88, v18, v18
	v_mul_f32_e32 v89, v19, v19
	v_pk_add_f32 v[84:85], v[84:85], v[84:85] op_sel:[0,1] op_sel_hi:[1,0]
	v_pk_mov_b32 v[96:97], v[88:89], v[86:87] op_sel:[1,0]
	v_mov_b32_e32 v89, v87
	v_add_f32_e32 v86, v96, v88
	v_add_f32_e32 v87, v97, v89
	v_mul_f32_e32 v88, v24, v24
	v_mul_f32_e32 v89, v25, v25
	v_mul_f32_e32 v96, v22, v22
	v_mul_f32_e32 v97, v23, v23
	v_mul_f32_e32 v101, v7, v7
	v_pk_mov_b32 v[98:99], v[96:97], v[88:89] op_sel:[1,0]
	v_mov_b32_e32 v97, v89
	v_add_f32_e32 v88, v98, v96
	v_add_f32_e32 v89, v99, v97
	v_mul_f32_e32 v96, v2, v2
	v_mul_f32_e32 v97, v3, v3
	v_mov_b32_e32 v83, v96
	v_mov_b32_e32 v85, v97
	v_mul_f32_e32 v98, v4, v4
	v_mul_f32_e32 v99, v5, v5
	v_add_f32_e32 v82, v82, v84
	v_add_f32_e32 v83, v83, v85
	v_add_f32_e32 v84, v86, v87
	v_add_f32_e32 v85, v87, v86
	v_add_f32_e32 v86, v88, v89
	v_add_f32_e32 v87, v89, v88
	v_mov_b32_e32 v85, v98
	v_mov_b32_e32 v87, v99
	v_add_f32_e32 v84, v84, v86
	v_add_f32_e32 v85, v85, v87
	v_mul_f32_e32 v86, v17, v17
	v_add_f32_e32 v96, v82, v84
	v_add_f32_e32 v97, v83, v85
	v_mul_f32_e32 v82, v11, v11
	v_mul_f32_e32 v84, v13, v13
	v_fma_f32 v83, v11, v11, v82
	v_fma_f32 v82, v10, v10, v82
	v_fma_f32 v85, v13, v13, v84
	v_fma_f32 v84, v12, v12, v84
	v_mov_b32_e32 v83, v100
	v_mov_b32_e32 v85, v101
	v_add_f32_e32 v82, v82, v84
	v_add_f32_e32 v83, v83, v85
	v_mul_f32_e32 v84, v15, v15
	v_mul_f32_e32 v102, v50, v50
	v_mul_f32_e32 v103, v51, v51
	v_fma_f32 v85, v15, v15, v84
	v_fma_f32 v84, v14, v14, v84
	v_fma_f32 v87, v17, v17, v86
	v_fma_f32 v86, v16, v16, v86
	v_mov_b32_e32 v85, v102
	v_mov_b32_e32 v87, v103
	v_add_f32_e32 v84, v84, v86
	v_add_f32_e32 v85, v85, v87
	v_add_f32_e32 v92, v92, v94
	v_add_f32_e32 v93, v93, v95
	v_add_f32_e32 v98, v82, v84
	v_add_f32_e32 v99, v83, v85
	s_nop 0
	s_nop 0
	v_add_f32_e32 v96, v96, v98
	v_add_f32_e32 v97, v97, v99
	v_add_f32_e32 v90, v90, v92
	v_add_f32_e32 v91, v91, v93
	v_add_f32_e32 v96, v96, v97
	v_add_f32_e32 v90, v90, v91
	s_nop 0
	v_add_f32_dpp v96, v96, v96 quad_perm:[1,0,3,2] row_mask:0xf bank_mask:0xf bound_ctrl:1
	v_add_f32_dpp v90, v90, v90 quad_perm:[1,0,3,2] row_mask:0xf bank_mask:0xf bound_ctrl:1
	s_nop 0
	v_add_f32_dpp v96, v96, v96 quad_perm:[2,3,0,1] row_mask:0xf bank_mask:0xf bound_ctrl:1
	v_add_f32_dpp v90, v90, v90 quad_perm:[2,3,0,1] row_mask:0xf bank_mask:0xf bound_ctrl:1
	s_nop 0
	v_add_f32_dpp v96, v96, v96 row_half_mirror row_mask:0xf bank_mask:0xf bound_ctrl:1
	v_add_f32_dpp v90, v90, v90 row_half_mirror row_mask:0xf bank_mask:0xf bound_ctrl:1
	s_nop 0
	v_add_f32_dpp v96, v96, v96 row_mirror row_mask:0xf bank_mask:0xf bound_ctrl:1
	v_add_f32_dpp v90, v90, v90 row_mirror row_mask:0xf bank_mask:0xf bound_ctrl:1
	v_readlane_b32 s16, v96, 16
	v_readlane_b32 s20, v96, 48
	v_readlane_b32 s8, v96, 0
	v_readlane_b32 s9, v96, 32
	v_mov_b32_e32 v96, s16
	v_mov_b32_e32 v97, s20
	v_add_f32_e32 v96, s8, v96
	v_add_f32_e32 v97, s9, v97
	v_readlane_b32 s16, v90, 16
	v_add_f32_e32 v96, v96, v97
	v_fmamk_f32 v96, v96, 0x3a000000, v130
	v_mul_f32_e32 v97, 0x4f800000, v96
	v_cmp_gt_f32_e32 vcc, s5, v96
	v_readlane_b32 s20, v90, 48
	s_nop 0
	v_cndmask_b32_e32 v96, v96, v97, vcc
	v_sqrt_f32_e32 v97, v96
	s_nop 0
	v_add_u32_e32 v91, -1, v97
	v_fma_f32 v92, -v91, v97, v96
	v_cmp_ge_f32_e64 s[8:9], 0, v92
	v_add_u32_e32 v92, 1, v97
	v_fma_f32 v93, -v92, v97, v96
	v_cndmask_b32_e64 v91, v97, v91, s[8:9]
	v_cmp_lt_f32_e64 s[8:9], 0, v93
	s_nop 1
	v_cndmask_b32_e64 v92, v91, v92, s[8:9]
	v_readlane_b32 s8, v90, 0
	v_readlane_b32 s9, v90, 32
	v_mov_b32_e32 v90, s16
	v_mov_b32_e32 v91, s20
	v_add_f32_e32 v90, s8, v90
	v_add_f32_e32 v91, s9, v91
	v_mul_f32_e32 v93, 0x37800000, v92
	v_add_f32_e32 v90, v90, v91
	v_fmamk_f32 v90, v90, 0x3a000000, v130
	v_mul_f32_e32 v91, 0x4f800000, v90
	v_cmp_gt_f32_e64 s[8:9], s5, v90
	v_cndmask_b32_e32 v92, v92, v93, vcc
	v_cmp_class_f32_e32 vcc, v96, v131
	v_cndmask_b32_e64 v90, v90, v91, s[8:9]
	v_sqrt_f32_e32 v91, v90
	v_cndmask_b32_e32 v92, v92, v96, vcc
	v_add_u32_e32 v93, -1, v91
	v_fma_f32 v94, -v93, v91, v90
	v_cmp_ge_f32_e32 vcc, 0, v94
	v_add_u32_e32 v94, 1, v91
	s_nop 0
	v_cndmask_b32_e32 v93, v91, v93, vcc
	v_fma_f32 v91, -v94, v91, v90
	v_cmp_lt_f32_e32 vcc, 0, v91
	s_nop 1
	v_cndmask_b32_e32 v91, v93, v94, vcc
	v_div_scale_f32 v94, s[20:21], v92, v92, 1.0
	v_rcp_f32_e32 v95, v94
	v_mul_f32_e32 v93, 0x37800000, v91
	v_cndmask_b32_e64 v91, v91, v93, s[8:9]
	v_cmp_class_f32_e32 vcc, v90, v131
	s_nop 1
	v_cndmask_b32_e32 v91, v91, v90, vcc
	v_fma_f32 v90, -v94, v95, 1.0
	v_fmac_f32_e32 v95, v90, v95
	v_div_scale_f32 v90, vcc, 1.0, v92, 1.0
	v_mul_f32_e32 v93, v90, v95
	v_fma_f32 v96, -v94, v93, v90
	v_fmac_f32_e32 v93, v96, v95
	v_fma_f32 v90, -v94, v93, v90
	v_div_fmas_f32 v90, v90, v95, v93
	v_div_fixup_f32 v90, v90, v92, 1.0
	v_mul_f32_e32 v30, v30, v90
	v_mul_f32_e32 v31, v31, v90
	v_mul_f32_e32 v28, v28, v90
	v_mul_f32_e32 v29, v29, v90
	v_mul_f32_e32 v54, v54, v90
	v_mul_f32_e32 v55, v55, v90
	s_nop 1
	v_mov_b64_e32 v[82:83], v[176:177]
	v_mov_b64_e32 v[84:85], v[178:179]
	v_mov_b64_e32 v[86:87], v[180:181]
	v_mov_b64_e32 v[88:89], v[182:183]
	v_mul_f32_e32 v92, v88, v28
	v_mul_f32_e32 v93, v89, v29
	v_mul_f32_e32 v28, v86, v30
	v_mul_f32_e32 v29, v87, v31
	v_mul_f32_e32 v30, v58, v90
	v_mul_f32_e32 v31, v59, v90
	v_mul_f32_e32 v54, v84, v54
	v_mul_f32_e32 v55, v85, v55
	v_mul_f32_e32 v30, v82, v30
	v_mul_f32_e32 v31, v83, v31
	v_add_co_u32_e32 v58, vcc, s19, v48
	v_cvt_pk_bf16_f32 v30, v30, v31
	v_cvt_pk_bf16_f32 v31, v54, v55
; __device__ __forceinline__ u32x4 pack8(const f32x4 a, const f32x4 b) { u32x4 o; o.x = pk2(a.x, a.y); o.y = pk2(a.z, a.w); o.z = pk2(b.x, b.y); o.w = pk2(b.z, b.w); return o; }
; template <bool INB, bool OUTB>
; __device__ __forceinline__ void thin_phase(Frame& F, const bf16* Fb, const void* xin_p, const void* xin_s, const float* post_g, float half, void* xout, const float* next_g, bf16* H) {
;     ...
;         if (next_g) { const float q0 = 1.0f / sqrtf(wave_sum(s2[0]) * (1.0f / D) + RMS_EPS), q1 = 1.0f / sqrtf(wave_sum(s2[1]) * (1.0f / D) + RMS_EPS);
; #pragma unroll
;             for (int j = 0; j < 4; ++j) { const int c = (j * 64 + lane) * 8; const f32x4 g0 = *(const f32x4*)(next_g + c), g1 = *(const f32x4*)(next_g + c + 4);
; #pragma unroll
;                 for (int r = 0; r < 2; ++r) *(u32x4*)(H + (size_t)(m0 + r) * D + c) = pack8(f[r][2 * j] * (r == 0 ? q0 : q1) * g0, f[r][2 * j + 1] * (r == 0 ? q0 : q1) * g1); } }
	v_div_scale_f32 v54, s[8:9], v91, v91, 1.0
	v_rcp_f32_e32 v55, v54
	v_cvt_pk_bf16_f32 v28, v28, v29
	v_cvt_pk_bf16_f32 v29, v92, v93
	v_addc_co_u32_e32 v59, vcc, 0, v49, vcc
	global_store_dwordx4 v[58:59], v[28:31], off offset:-4096
	v_mul_f32_e32 v18, v18, v90
	v_mul_f32_e32 v19, v19, v90
	v_mul_f32_e32 v20, v20, v90
	v_mul_f32_e32 v21, v21, v90
	v_fma_f32 v28, -v54, v55, 1.0
	v_fmac_f32_e32 v55, v28, v55
	v_div_scale_f32 v28, vcc, 1.0, v91, 1.0
	v_mul_f32_e32 v29, v28, v55
	v_fma_f32 v30, -v54, v29, v28
	v_fmac_f32_e32 v29, v30, v55
	v_fma_f32 v28, -v54, v29, v28
	v_div_fmas_f32 v28, v28, v55, v29
	v_div_fixup_f32 v92, v28, v91, 1.0
	v_mul_f32_e32 v28, v60, v92
	v_mul_f32_e32 v29, v61, v92
	v_mul_f32_e32 v30, v56, v92
	v_mul_f32_e32 v31, v57, v92
	v_mul_f32_e32 v54, v64, v92
	v_mul_f32_e32 v55, v65, v92
	v_mul_f32_e32 v56, v62, v92
	v_mul_f32_e32 v57, v63, v92
	v_mul_f32_e32 v30, v88, v30
	v_mul_f32_e32 v31, v89, v31
	v_mul_f32_e32 v28, v86, v28
	v_mul_f32_e32 v29, v87, v29
	v_mul_f32_e32 v56, v84, v56
	v_mul_f32_e32 v57, v85, v57
	v_mul_f32_e32 v54, v82, v54
	v_mul_f32_e32 v55, v83, v55
	v_cvt_pk_bf16_f32 v28, v28, v29
	v_cvt_pk_bf16_f32 v29, v30, v31
	v_cvt_pk_bf16_f32 v30, v54, v55
	v_cvt_pk_bf16_f32 v31, v56, v57
	global_store_dwordx4 v[58:59], v[28:31], off
	s_nop 0
	s_nop 0
	s_nop 0
	v_mul_f32_e32 v22, v22, v90
	v_mul_f32_e32 v23, v23, v90
	v_mul_f32_e32 v24, v24, v90
	v_mul_f32_e32 v25, v25, v90
	v_add_co_u32_e32 v48, vcc, s18, v48
	v_mul_f32_e32 v10, v10, v90
	v_mul_f32_e32 v11, v11, v90
	s_nop 0
	v_addc_co_u32_e32 v49, vcc, 0, v49, vcc
	v_mul_f32_e32 v12, v12, v90
	v_mul_f32_e32 v13, v13, v90
	v_mul_f32_e32 v14, v14, v90
	v_mul_f32_e32 v15, v15, v90
	v_mul_f32_e32 v16, v16, v90
	v_mul_f32_e32 v17, v17, v90
	v_mul_f32_e32 v2, v2, v90
	v_mul_f32_e32 v3, v3, v90
	v_mul_f32_e32 v4, v4, v90
	v_mul_f32_e32 v5, v5, v90
	v_mul_f32_e32 v6, v6, v90
	v_mul_f32_e32 v7, v7, v90
	v_mul_f32_e32 v8, v8, v92
	v_mul_f32_e32 v9, v9, v92
	s_nop 1
	v_mov_b64_e32 v[28:29], v[184:185]
	v_mov_b64_e32 v[30:31], v[186:187]
	v_mov_b64_e32 v[54:55], v[188:189]
	v_mov_b64_e32 v[56:57], v[190:191]
	v_mul_f32_e32 v20, v20, v30
	v_mul_f32_e32 v21, v21, v31
	v_mul_f32_e32 v18, v18, v28
	v_mul_f32_e32 v19, v19, v29
	s_nop 0
	v_mul_f32_e32 v24, v24, v56
	v_mul_f32_e32 v25, v25, v57
	v_mul_f32_e32 v22, v22, v54
	v_mul_f32_e32 v23, v23, v55
	v_cvt_pk_bf16_f32 v18, v18, v19
	v_cvt_pk_bf16_f32 v19, v20, v21
	v_cvt_pk_bf16_f32 v20, v22, v23
	v_cvt_pk_bf16_f32 v21, v24, v25
	global_store_dwordx4 v[48:49], v[18:21], off offset:1024
	v_mul_f32_e32 v22, v76, v92
	v_mul_f32_e32 v23, v77, v92
	v_mul_f32_e32 v24, v78, v92
	v_mul_f32_e32 v25, v79, v92
	v_mul_f32_e32 v18, v70, v92
	v_mul_f32_e32 v19, v71, v92
	v_mul_f32_e32 v20, v74, v92
	v_mul_f32_e32 v21, v75, v92
	v_mul_f32_e32 v18, v28, v18
	v_mul_f32_e32 v19, v29, v19
	v_mul_f32_e32 v20, v30, v20
	v_mul_f32_e32 v21, v31, v21
	v_mul_f32_e32 v24, v56, v24
	v_mul_f32_e32 v25, v57, v25
	v_mul_f32_e32 v22, v54, v22
	v_mul_f32_e32 v23, v55, v23
	v_cvt_pk_bf16_f32 v18, v18, v19
	v_cvt_pk_bf16_f32 v19, v20, v21
	v_cvt_pk_bf16_f32 v20, v22, v23
	v_cvt_pk_bf16_f32 v21, v24, v25
	global_store_dwordx4 v[58:59], v[18:21], off offset:1024
	s_nop 0
	s_nop 0
	s_nop 0
	s_nop 1
	v_mov_b64_e32 v[18:19], v[192:193]
	v_mov_b64_e32 v[20:21], v[194:195]
	v_mov_b64_e32 v[22:23], v[196:197]
	v_mov_b64_e32 v[24:25], v[198:199]
	v_mul_f32_e32 v12, v12, v20
	v_mul_f32_e32 v13, v13, v21
	v_mul_f32_e32 v10, v10, v18
	v_mul_f32_e32 v11, v11, v19
	s_nop 0
	v_mul_f32_e32 v16, v16, v24
	v_mul_f32_e32 v17, v17, v25
	v_mul_f32_e32 v14, v14, v22
	v_mul_f32_e32 v15, v15, v23
	v_cvt_pk_bf16_f32 v10, v10, v11
	v_cvt_pk_bf16_f32 v11, v12, v13
	v_cvt_pk_bf16_f32 v12, v14, v15
	v_cvt_pk_bf16_f32 v13, v16, v17
	global_store_dwordx4 v[48:49], v[10:13], off offset:2048
	v_mul_f32_e32 v14, v72, v92
	v_mul_f32_e32 v15, v73, v92
	v_mul_f32_e32 v16, v80, v92
	v_mul_f32_e32 v17, v81, v92
	v_mul_f32_e32 v10, v66, v92
	v_mul_f32_e32 v11, v67, v92
	v_mul_f32_e32 v12, v68, v92
	v_mul_f32_e32 v13, v69, v92
	v_mul_f32_e32 v10, v18, v10
	v_mul_f32_e32 v11, v19, v11
	v_mul_f32_e32 v12, v20, v12
	v_mul_f32_e32 v13, v21, v13
	v_mul_f32_e32 v16, v24, v16
	v_mul_f32_e32 v17, v25, v17
	v_mul_f32_e32 v14, v22, v14
	v_mul_f32_e32 v15, v23, v15
	v_cvt_pk_bf16_f32 v10, v10, v11
	v_cvt_pk_bf16_f32 v11, v12, v13
	v_cvt_pk_bf16_f32 v12, v14, v15
	v_cvt_pk_bf16_f32 v13, v16, v17
	global_store_dwordx4 v[58:59], v[10:13], off offset:2048
	s_nop 0
	s_nop 0
	s_nop 0
	v_mul_f32_e32 v18, v50, v90
	v_mul_f32_e32 v19, v51, v90
	v_mul_f32_e32 v20, v52, v92
	v_mul_f32_e32 v21, v53, v92
	v_mul_f32_e32 v22, v32, v92
	v_mul_f32_e32 v23, v33, v92
	v_mul_f32_e32 v24, v26, v92
	v_mul_f32_e32 v25, v27, v92
	s_nop 1
	v_mov_b64_e32 v[10:11], v[200:201]
	v_mov_b64_e32 v[12:13], v[202:203]
	v_mov_b64_e32 v[14:15], v[204:205]
	v_mov_b64_e32 v[16:17], v[206:207]
	v_mul_f32_e32 v4, v4, v12
	v_mul_f32_e32 v5, v5, v13
	v_mul_f32_e32 v2, v2, v10
	v_mul_f32_e32 v3, v3, v11
	s_nop 0
	v_mul_f32_e32 v18, v18, v16
	v_mul_f32_e32 v19, v19, v17
	v_mul_f32_e32 v6, v6, v14
	v_mul_f32_e32 v7, v7, v15
	v_mul_f32_e32 v8, v8, v12
	v_mul_f32_e32 v9, v9, v13
	v_mul_f32_e32 v10, v20, v10
	v_mul_f32_e32 v11, v21, v11
	v_mul_f32_e32 v12, v24, v16
	v_mul_f32_e32 v13, v25, v17
	v_mul_f32_e32 v14, v22, v14
	v_mul_f32_e32 v15, v23, v15
	v_cvt_pk_bf16_f32 v2, v2, v3
	v_cvt_pk_bf16_f32 v3, v4, v5
	v_cvt_pk_bf16_f32 v4, v6, v7
	v_cvt_pk_bf16_f32 v5, v18, v19
	v_cvt_pk_bf16_f32 v6, v10, v11
	v_cvt_pk_bf16_f32 v7, v8, v9
	v_cvt_pk_bf16_f32 v8, v14, v15
	v_cvt_pk_bf16_f32 v9, v12, v13
	global_store_dwordx4 v[48:49], v[2:5], off offset:3072
	global_store_dwordx4 v[58:59], v[6:9], off offset:3072
	s_branch .LBB0_2710

; __device__ __forceinline__ u32x4 pack8(const f32x4 a, const f32x4 b) { u32x4 o; o.x = pk2(a.x, a.y); o.y = pk2(a.z, a.w); o.z = pk2(b.x, b.y); o.w = pk2(b.z, b.w); return o; }
; __device__ __forceinline__ f32x4 sig4(const f32x4 v) { f32x4 r; r.x = sigmoidf_(v.x); r.y = sigmoidf_(v.y); r.z = sigmoidf_(v.z); r.w = sigmoidf_(v.w); return r; }
;     __device__ __forceinline__ void operator()(const pg8::f32x4 (&acc)[2][2][4][2], const pg8::Unit& u, int wr, int wc, int fr, int fq) const {
;         EPI_REMAP(); const int row0 = u.pm * 256 + wr * 64 + fr2, col0 = u.pn * 128 + wc * 32 + 8 * fq2;
; #pragma unroll
;         for (int ai = 0; ai < 2; ++ai)
; #pragma unroll
;             for (int m = 0; m < 4; ++m) { bf16* rowp = O + (size_t)(row0 + ai * 128 + m * 16) * DFF + col0;
;                 const f32x4 a0 = acc[ai][0][m][0], a1 = acc[ai][0][m][1], b0 = acc[ai][1][m][0], b1 = acc[ai][1][m][1];
;                 *(u32x4*)rowp = epi_perm(pack8(a0 * sig4(a0) * b0, a1 * sig4(a1) * b1), src4); }
;     }
.LBB0_2777:
	v_mul_f32_e32 v157, 0xbfb8aa3b, v126
	v_exp_f32_e32 v157, v157
	v_mul_f32_e32 v160, 0xbfb8aa3b, v127
	v_exp_f32_e32 v161, v160
	v_lshl_or_b32 v148, s39, 7, v152
	v_add_f32_e32 v157, 1.0, v157
	v_rcp_f32_e32 v160, v157
	v_add_f32_e32 v157, 1.0, v161
	v_mul_f32_e32 v161, 0xbfb8aa3b, v128
	v_exp_f32_e32 v162, v161
	v_mul_f32_e32 v161, 0xbfb8aa3b, v129
	v_exp_f32_e32 v163, v161
	v_rcp_f32_e32 v161, v157
	v_add_f32_e32 v157, 1.0, v162
	v_rcp_f32_e32 v162, v157
	v_add_f32_e32 v157, 1.0, v163
	v_rcp_f32_e32 v163, v157
	v_mul_f32_e32 v157, 0xbfb8aa3b, v122
	v_mul_f32_e32 v126, v126, v160
	v_mul_f32_e32 v127, v127, v161
	v_exp_f32_e32 v157, v157
	v_mul_f32_e32 v160, 0xbfb8aa3b, v123
	v_exp_f32_e32 v161, v160
	v_mul_f32_e32 v128, v128, v162
	v_mul_f32_e32 v129, v129, v163
	v_add_f32_e32 v157, 1.0, v157
	v_rcp_f32_e32 v160, v157
	v_add_f32_e32 v157, 1.0, v161
	v_mul_f32_e32 v161, 0xbfb8aa3b, v124
	v_exp_f32_e32 v162, v161
	v_mul_f32_e32 v161, 0xbfb8aa3b, v125
	v_exp_f32_e32 v163, v161
	v_rcp_f32_e32 v161, v157
	v_add_f32_e32 v157, 1.0, v162
	v_rcp_f32_e32 v162, v157
	v_add_f32_e32 v157, 1.0, v163
	v_rcp_f32_e32 v163, v157
	v_mul_f32_e32 v122, v122, v160
	v_mul_f32_e32 v123, v123, v161
	v_mul_f32_e32 v120, v128, v120
	v_mul_f32_e32 v121, v129, v121
	v_mul_f32_e32 v118, v126, v118
	v_mul_f32_e32 v119, v127, v119
	v_mul_f32_e32 v124, v124, v162
	v_mul_f32_e32 v125, v125, v163
	v_mul_f32_e32 v114, v122, v114
	v_mul_f32_e32 v115, v123, v115
	v_mul_f32_e32 v116, v124, v116
	v_mul_f32_e32 v117, v125, v117
	v_cvt_pk_bf16_f32 v118, v118, v119
	v_cvt_pk_bf16_f32 v119, v120, v121
	v_cvt_pk_bf16_f32 v120, v114, v115
	v_cvt_pk_bf16_f32 v117, v116, v117
	ds_bpermute_b32 v114, v150, v118
	ds_bpermute_b32 v115, v150, v119
	ds_bpermute_b32 v116, v150, v120
	ds_bpermute_b32 v117, v150, v117
	v_lshl_add_u32 v156, s20, 8, v151
	v_ashrrev_i32_e32 v149, 31, v148
	v_mov_b64_e32 v[146:147], s[70:71]
	v_mad_i64_i32 v[158:159], s[22:23], v156, s38, v[146:147]
	v_lshlrev_b64 v[148:149], 1, v[148:149]
	v_lshl_add_u64 v[158:159], v[158:159], 0, v[148:149]
	v_mul_f32_e32 v118, 0xbfb8aa3b, v110
	v_mul_f32_e32 v119, 0xbfb8aa3b, v111
	s_waitcnt lgkmcnt(0)
	global_store_dwordx4 v[158:159], v[114:117], off
	v_exp_f32_e32 v118, v118
	v_exp_f32_e32 v119, v119
	v_mul_f32_e32 v116, 0xbfb8aa3b, v112
	v_mul_f32_e32 v117, 0xbfb8aa3b, v113
	v_exp_f32_e32 v116, v116
	v_exp_f32_e32 v117, v117
	v_add_f32_e32 v114, 1.0, v118
	v_add_f32_e32 v115, 1.0, v119
	v_add_f32_e32 v116, 1.0, v116
	v_add_f32_e32 v117, 1.0, v117
	v_rcp_f32_e32 v114, v114
	v_rcp_f32_e32 v115, v115
	v_rcp_f32_e32 v116, v116
	v_rcp_f32_e32 v117, v117
	s_andn2_b64 vcc, exec, s[0:1]
	v_mul_f32_e32 v110, v110, v114
	v_mul_f32_e32 v111, v111, v115
	v_mul_f32_e32 v114, 0xbfb8aa3b, v106
	v_mul_f32_e32 v115, 0xbfb8aa3b, v107
	v_mul_f32_e32 v112, v112, v116
	v_mul_f32_e32 v113, v113, v117
	v_mul_f32_e32 v116, 0xbfb8aa3b, v108
	v_mul_f32_e32 v117, 0xbfb8aa3b, v109
	v_exp_f32_e32 v114, v114
	v_exp_f32_e32 v115, v115
	v_exp_f32_e32 v116, v116
	v_exp_f32_e32 v117, v117
	v_add_f32_e32 v114, 1.0, v114
	v_add_f32_e32 v115, 1.0, v115
	v_add_f32_e32 v116, 1.0, v116
	v_add_f32_e32 v117, 1.0, v117
	v_rcp_f32_e32 v114, v114
	v_rcp_f32_e32 v115, v115
	v_rcp_f32_e32 v116, v116
	v_rcp_f32_e32 v117, v117
	v_mul_f32_e32 v104, v112, v104
	v_mul_f32_e32 v105, v113, v105
	v_mul_f32_e32 v106, v106, v114
	v_mul_f32_e32 v107, v107, v115
	v_mul_f32_e32 v102, v110, v102
	v_mul_f32_e32 v103, v111, v103
	v_mul_f32_e32 v108, v108, v116
	v_mul_f32_e32 v109, v109, v117
	v_mul_f32_e32 v98, v106, v98
	v_mul_f32_e32 v99, v107, v99
	v_mul_f32_e32 v100, v108, v100
	v_mul_f32_e32 v101, v109, v101
	v_cvt_pk_bf16_f32 v102, v102, v103
	v_cvt_pk_bf16_f32 v103, v104, v105
	v_cvt_pk_bf16_f32 v104, v98, v99
	v_cvt_pk_bf16_f32 v101, v100, v101
	ds_bpermute_b32 v98, v150, v102
	ds_bpermute_b32 v99, v150, v103
	ds_bpermute_b32 v100, v150, v104
	ds_bpermute_b32 v101, v150, v101
	v_or_b32_e32 v102, 16, v156
	v_mad_i64_i32 v[102:103], s[22:23], v102, s38, v[146:147]
	v_lshl_add_u64 v[102:103], v[102:103], 0, v[148:149]
	s_waitcnt lgkmcnt(0)
	global_store_dwordx4 v[102:103], v[98:101], off
	v_mul_f32_e32 v102, 0xbfb8aa3b, v96
	v_mul_f32_e32 v103, 0xbfb8aa3b, v97
	v_mul_f32_e32 v100, 0xbfb8aa3b, v94
	v_mul_f32_e32 v101, 0xbfb8aa3b, v95
	v_exp_f32_e32 v100, v100
	v_exp_f32_e32 v101, v101
	v_exp_f32_e32 v102, v102
	v_exp_f32_e32 v103, v103
	v_add_f32_e32 v100, 1.0, v100
	v_add_f32_e32 v101, 1.0, v101
	v_add_f32_e32 v102, 1.0, v102
	v_add_f32_e32 v103, 1.0, v103
	v_rcp_f32_e32 v100, v100
	v_rcp_f32_e32 v101, v101
	v_rcp_f32_e32 v102, v102
	v_rcp_f32_e32 v103, v103
	v_or_b32_e32 v98, 32, v156
	v_mul_f32_e32 v94, v94, v100
	v_mul_f32_e32 v95, v95, v101
	v_mul_f32_e32 v100, 0xbfb8aa3b, v90
	v_mul_f32_e32 v101, 0xbfb8aa3b, v91
	v_mul_f32_e32 v96, v96, v102
	v_mul_f32_e32 v97, v97, v103
	v_mul_f32_e32 v102, 0xbfb8aa3b, v92
	v_mul_f32_e32 v103, 0xbfb8aa3b, v93
	v_exp_f32_e32 v100, v100
	v_exp_f32_e32 v101, v101
	v_exp_f32_e32 v102, v102
	v_exp_f32_e32 v103, v103
	v_add_f32_e32 v100, 1.0, v100
	v_add_f32_e32 v101, 1.0, v101
	v_add_f32_e32 v102, 1.0, v102
	v_add_f32_e32 v103, 1.0, v103
	v_rcp_f32_e32 v100, v100
	v_rcp_f32_e32 v101, v101
	v_rcp_f32_e32 v102, v102
	v_rcp_f32_e32 v103, v103
	v_mul_f32_e32 v88, v96, v88
	v_mul_f32_e32 v89, v97, v89
	v_mul_f32_e32 v90, v90, v100
	v_mul_f32_e32 v91, v91, v101
	v_mul_f32_e32 v86, v94, v86
	v_mul_f32_e32 v87, v95, v87
	v_mul_f32_e32 v92, v92, v102
	v_mul_f32_e32 v93, v93, v103
	v_mul_f32_e32 v82, v90, v82
	v_mul_f32_e32 v83, v91, v83
	v_mul_f32_e32 v84, v92, v84
	v_mul_f32_e32 v85, v93, v85
	v_cvt_pk_bf16_f32 v86, v86, v87
	v_cvt_pk_bf16_f32 v87, v88, v89
	v_cvt_pk_bf16_f32 v88, v82, v83
	v_cvt_pk_bf16_f32 v85, v84, v85
	ds_bpermute_b32 v82, v150, v86
	ds_bpermute_b32 v83, v150, v87
	ds_bpermute_b32 v84, v150, v88
	ds_bpermute_b32 v85, v150, v85
	v_mad_i64_i32 v[98:99], s[22:23], v98, s38, v[146:147]
	v_lshl_add_u64 v[98:99], v[98:99], 0, v[148:149]
	v_mul_f32_e32 v86, 0xbfb8aa3b, v78
	v_mul_f32_e32 v87, 0xbfb8aa3b, v79
	s_waitcnt lgkmcnt(0)
; __device__ __forceinline__ u32x4 pack8(const f32x4 a, const f32x4 b) { u32x4 o; o.x = pk2(a.x, a.y); o.y = pk2(a.z, a.w); o.z = pk2(b.x, b.y); o.w = pk2(b.z, b.w); return o; }
; __device__ __forceinline__ f32x4 sig4(const f32x4 v) { f32x4 r; r.x = sigmoidf_(v.x); r.y = sigmoidf_(v.y); r.z = sigmoidf_(v.z); r.w = sigmoidf_(v.w); return r; }
;     __device__ __forceinline__ void operator()(const pg8::f32x4 (&acc)[2][2][4][2], const pg8::Unit& u, int wr, int wc, int fr, int fq) const {
;         EPI_REMAP(); const int row0 = u.pm * 256 + wr * 64 + fr2, col0 = u.pn * 128 + wc * 32 + 8 * fq2;
; #pragma unroll
;         for (int ai = 0; ai < 2; ++ai)
; #pragma unroll
;             for (int m = 0; m < 4; ++m) { bf16* rowp = O + (size_t)(row0 + ai * 128 + m * 16) * DFF + col0;
;                 const f32x4 a0 = acc[ai][0][m][0], a1 = acc[ai][0][m][1], b0 = acc[ai][1][m][0], b1 = acc[ai][1][m][1];
;                 *(u32x4*)rowp = epi_perm(pack8(a0 * sig4(a0) * b0, a1 * sig4(a1) * b1), src4); }
;     }
	global_store_dwordx4 v[98:99], v[82:85], off
	v_exp_f32_e32 v86, v86
	v_exp_f32_e32 v87, v87
	v_mul_f32_e32 v84, 0xbfb8aa3b, v80
	v_mul_f32_e32 v85, 0xbfb8aa3b, v81
	v_exp_f32_e32 v84, v84
	v_exp_f32_e32 v85, v85
	v_add_f32_e32 v82, 1.0, v86
	v_add_f32_e32 v83, 1.0, v87
	v_add_f32_e32 v84, 1.0, v84
	v_add_f32_e32 v85, 1.0, v85
	v_rcp_f32_e32 v82, v82
	v_rcp_f32_e32 v83, v83
	v_rcp_f32_e32 v84, v84
	v_rcp_f32_e32 v85, v85
	s_mov_b64 s[0:1], -1
	v_mul_f32_e32 v78, v78, v82
	v_mul_f32_e32 v79, v79, v83
	v_mul_f32_e32 v82, 0xbfb8aa3b, v74
	v_mul_f32_e32 v83, 0xbfb8aa3b, v75
	v_mul_f32_e32 v80, v80, v84
	v_mul_f32_e32 v81, v81, v85
	v_mul_f32_e32 v84, 0xbfb8aa3b, v76
	v_mul_f32_e32 v85, 0xbfb8aa3b, v77
	v_exp_f32_e32 v82, v82
	v_exp_f32_e32 v83, v83
	v_exp_f32_e32 v84, v84
	v_exp_f32_e32 v85, v85
	v_add_f32_e32 v82, 1.0, v82
	v_add_f32_e32 v83, 1.0, v83
	v_add_f32_e32 v84, 1.0, v84
	v_add_f32_e32 v85, 1.0, v85
	v_rcp_f32_e32 v82, v82
	v_rcp_f32_e32 v83, v83
	v_rcp_f32_e32 v84, v84
	v_rcp_f32_e32 v85, v85
	v_mul_f32_e32 v72, v80, v72
	v_mul_f32_e32 v73, v81, v73
	v_mul_f32_e32 v74, v74, v82
	v_mul_f32_e32 v75, v75, v83
	v_mul_f32_e32 v70, v78, v70
	v_mul_f32_e32 v71, v79, v71
	v_mul_f32_e32 v76, v76, v84
	v_mul_f32_e32 v77, v77, v85
	v_mul_f32_e32 v66, v74, v66
	v_mul_f32_e32 v67, v75, v67
	v_mul_f32_e32 v68, v76, v68
	v_mul_f32_e32 v69, v77, v69
	v_cvt_pk_bf16_f32 v70, v70, v71
	v_cvt_pk_bf16_f32 v71, v72, v73
	v_cvt_pk_bf16_f32 v72, v66, v67
	v_cvt_pk_bf16_f32 v69, v68, v69
	ds_bpermute_b32 v66, v150, v70
	ds_bpermute_b32 v67, v150, v71
	ds_bpermute_b32 v68, v150, v72
	ds_bpermute_b32 v69, v150, v69
	v_or_b32_e32 v70, 48, v156
	v_mad_i64_i32 v[70:71], s[22:23], v70, s38, v[146:147]
	v_lshl_add_u64 v[70:71], v[70:71], 0, v[148:149]
	s_waitcnt lgkmcnt(0)
	global_store_dwordx4 v[70:71], v[66:69], off
	v_mul_f32_e32 v70, 0xbfb8aa3b, v64
	v_mul_f32_e32 v71, 0xbfb8aa3b, v65
	v_mul_f32_e32 v68, 0xbfb8aa3b, v62
	v_mul_f32_e32 v69, 0xbfb8aa3b, v63
	v_exp_f32_e32 v68, v68
	v_exp_f32_e32 v69, v69
	v_exp_f32_e32 v70, v70
	v_exp_f32_e32 v71, v71
	v_add_f32_e32 v68, 1.0, v68
	v_add_f32_e32 v69, 1.0, v69
	v_add_f32_e32 v70, 1.0, v70
	v_add_f32_e32 v71, 1.0, v71
	v_rcp_f32_e32 v68, v68
	v_rcp_f32_e32 v69, v69
	v_rcp_f32_e32 v70, v70
	v_rcp_f32_e32 v71, v71
	v_add_u32_e32 v66, 0x80, v156
	v_mul_f32_e32 v62, v62, v68
	v_mul_f32_e32 v63, v63, v69
	v_mul_f32_e32 v68, 0xbfb8aa3b, v58
	v_mul_f32_e32 v69, 0xbfb8aa3b, v59
	v_mul_f32_e32 v64, v64, v70
	v_mul_f32_e32 v65, v65, v71
	v_mul_f32_e32 v70, 0xbfb8aa3b, v60
	v_mul_f32_e32 v71, 0xbfb8aa3b, v61
	v_exp_f32_e32 v68, v68
	v_exp_f32_e32 v69, v69
	v_exp_f32_e32 v70, v70
	v_exp_f32_e32 v71, v71
	v_add_f32_e32 v68, 1.0, v68
	v_add_f32_e32 v69, 1.0, v69
	v_add_f32_e32 v70, 1.0, v70
	v_add_f32_e32 v71, 1.0, v71
	v_rcp_f32_e32 v68, v68
	v_rcp_f32_e32 v69, v69
	v_rcp_f32_e32 v70, v70
	v_rcp_f32_e32 v71, v71
	v_mul_f32_e32 v56, v64, v56
	v_mul_f32_e32 v57, v65, v57
	v_mul_f32_e32 v58, v58, v68
	v_mul_f32_e32 v59, v59, v69
	v_mul_f32_e32 v54, v62, v54
	v_mul_f32_e32 v55, v63, v55
	v_mul_f32_e32 v60, v60, v70
	v_mul_f32_e32 v61, v61, v71
	v_mul_f32_e32 v50, v58, v50
	v_mul_f32_e32 v51, v59, v51
	v_mul_f32_e32 v52, v60, v52
	v_mul_f32_e32 v53, v61, v53
	v_cvt_pk_bf16_f32 v54, v54, v55
	v_cvt_pk_bf16_f32 v55, v56, v57
	v_cvt_pk_bf16_f32 v56, v50, v51
	v_cvt_pk_bf16_f32 v53, v52, v53
	ds_bpermute_b32 v50, v150, v54
	ds_bpermute_b32 v51, v150, v55
	ds_bpermute_b32 v52, v150, v56
	ds_bpermute_b32 v53, v150, v53
	v_mad_i64_i32 v[66:67], s[22:23], v66, s38, v[146:147]
	v_lshl_add_u64 v[66:67], v[66:67], 0, v[148:149]
	v_mul_f32_e32 v54, 0xbfb8aa3b, v46
	v_mul_f32_e32 v55, 0xbfb8aa3b, v47
	s_waitcnt lgkmcnt(0)
	global_store_dwordx4 v[66:67], v[50:53], off
	v_exp_f32_e32 v54, v54
	v_exp_f32_e32 v55, v55
	v_mul_f32_e32 v52, 0xbfb8aa3b, v48
	v_mul_f32_e32 v53, 0xbfb8aa3b, v49
	v_exp_f32_e32 v52, v52
	v_exp_f32_e32 v53, v53
	v_add_f32_e32 v50, 1.0, v54
	v_add_f32_e32 v51, 1.0, v55
	v_add_f32_e32 v52, 1.0, v52
	v_add_f32_e32 v53, 1.0, v53
	v_rcp_f32_e32 v50, v50
	v_rcp_f32_e32 v51, v51
	v_rcp_f32_e32 v52, v52
	v_rcp_f32_e32 v53, v53
	v_mul_f32_e32 v46, v46, v50
	v_mul_f32_e32 v47, v47, v51
	v_mul_f32_e32 v50, 0xbfb8aa3b, v42
	v_mul_f32_e32 v51, 0xbfb8aa3b, v43
	v_mul_f32_e32 v48, v48, v52
	v_mul_f32_e32 v49, v49, v53
	v_mul_f32_e32 v52, 0xbfb8aa3b, v44
	v_mul_f32_e32 v53, 0xbfb8aa3b, v45
	v_exp_f32_e32 v50, v50
	v_exp_f32_e32 v51, v51
	v_exp_f32_e32 v52, v52
	v_exp_f32_e32 v53, v53
	v_add_f32_e32 v50, 1.0, v50
	v_add_f32_e32 v51, 1.0, v51
	v_add_f32_e32 v52, 1.0, v52
	v_add_f32_e32 v53, 1.0, v53
	v_rcp_f32_e32 v50, v50
	v_rcp_f32_e32 v51, v51
	v_rcp_f32_e32 v52, v52
	v_rcp_f32_e32 v53, v53
	v_mul_f32_e32 v40, v48, v40
	v_mul_f32_e32 v41, v49, v41
	v_mul_f32_e32 v42, v42, v50
	v_mul_f32_e32 v43, v43, v51
	v_mul_f32_e32 v38, v46, v38
	v_mul_f32_e32 v39, v47, v39
	v_mul_f32_e32 v44, v44, v52
	v_mul_f32_e32 v45, v45, v53
	v_mul_f32_e32 v34, v42, v34
	v_mul_f32_e32 v35, v43, v35
	v_mul_f32_e32 v36, v44, v36
	v_mul_f32_e32 v37, v45, v37
	v_cvt_pk_bf16_f32 v38, v38, v39
	v_cvt_pk_bf16_f32 v39, v40, v41
	v_cvt_pk_bf16_f32 v40, v34, v35
	v_cvt_pk_bf16_f32 v37, v36, v37
	ds_bpermute_b32 v34, v150, v38
	ds_bpermute_b32 v35, v150, v39
	ds_bpermute_b32 v36, v150, v40
	ds_bpermute_b32 v37, v150, v37
	v_add_u32_e32 v38, 0x90, v156
	v_mad_i64_i32 v[38:39], s[22:23], v38, s38, v[146:147]
	v_lshl_add_u64 v[38:39], v[38:39], 0, v[148:149]
	s_waitcnt lgkmcnt(0)
; #define PG8_BAR __builtin_amdgcn_s_barrier()
; __device__ __forceinline__ u32x4 pack8(const f32x4 a, const f32x4 b) { u32x4 o; o.x = pk2(a.x, a.y); o.y = pk2(a.z, a.w); o.z = pk2(b.x, b.y); o.w = pk2(b.z, b.w); return o; }
; __device__ __forceinline__ f32x4 sig4(const f32x4 v) { f32x4 r; r.x = sigmoidf_(v.x); r.y = sigmoidf_(v.y); r.z = sigmoidf_(v.z); r.w = sigmoidf_(v.w); return r; }
; template <class Epi, class Sched, bool ALIGN_EPI = false, bool SP2 = false>
; __device__ __forceinline__ void gemm_phase(PG8_LAS unsigned char* lds, const Gemm g, const Sched& S, const Epi& E) {
;     ...
;         if constexpr (ALIGN_EPI) { if (wr == 0) PG8_BAR; }
;         if constexpr (!Epi::AFTER_DRAIN) { E(acc, cur, wr, wc, fr, fq); S.done(cur); }
;         if (!has_next) break;
; #pragma unroll
;         for (int a = 0; a < 2; ++a)
; #pragma unroll
;             for (int b = 0; b < 2; ++b)
; #pragma unroll
;                 for (int m = 0; m < 4; ++m)
; #pragma unroll
;                     for (int n = 0; n < 2; ++n) acc[a][b][m][n] = (f32x4){0.f, 0.f, 0.f, 0.f};
;         cur = nxt; cA = nA; cB = nB; ++ui;
;         if constexpr (ALIGN_EPI) { if (wr == 1) PG8_BAR; }
;     __device__ __forceinline__ void operator()(const pg8::f32x4 (&acc)[2][2][4][2], const pg8::Unit& u, int wr, int wc, int fr, int fq) const {
;         EPI_REMAP(); const int row0 = u.pm * 256 + wr * 64 + fr2, col0 = u.pn * 128 + wc * 32 + 8 * fq2;
; #pragma unroll
;         for (int ai = 0; ai < 2; ++ai)
; #pragma unroll
;             for (int m = 0; m < 4; ++m) { bf16* rowp = O + (size_t)(row0 + ai * 128 + m * 16) * DFF + col0;
;                 const f32x4 a0 = acc[ai][0][m][0], a1 = acc[ai][0][m][1], b0 = acc[ai][1][m][0], b1 = acc[ai][1][m][1];
;                 *(u32x4*)rowp = epi_perm(pack8(a0 * sig4(a0) * b0, a1 * sig4(a1) * b1), src4); }
;     }
	global_store_dwordx4 v[38:39], v[34:37], off
	v_mul_f32_e32 v38, 0xbfb8aa3b, v32
	v_mul_f32_e32 v39, 0xbfb8aa3b, v33
	v_mul_f32_e32 v36, 0xbfb8aa3b, v30
	v_mul_f32_e32 v37, 0xbfb8aa3b, v31
	v_exp_f32_e32 v36, v36
	v_exp_f32_e32 v37, v37
	v_exp_f32_e32 v38, v38
	v_exp_f32_e32 v39, v39
	v_add_f32_e32 v36, 1.0, v36
	v_add_f32_e32 v37, 1.0, v37
	v_add_f32_e32 v38, 1.0, v38
	v_add_f32_e32 v39, 1.0, v39
	v_rcp_f32_e32 v36, v36
	v_rcp_f32_e32 v37, v37
	v_rcp_f32_e32 v38, v38
	v_rcp_f32_e32 v39, v39
	v_add_u32_e32 v34, 0xa0, v156
	v_mul_f32_e32 v30, v30, v36
	v_mul_f32_e32 v31, v31, v37
	v_mul_f32_e32 v36, 0xbfb8aa3b, v26
	v_mul_f32_e32 v37, 0xbfb8aa3b, v27
	v_mul_f32_e32 v32, v32, v38
	v_mul_f32_e32 v33, v33, v39
	v_mul_f32_e32 v38, 0xbfb8aa3b, v28
	v_mul_f32_e32 v39, 0xbfb8aa3b, v29
	v_exp_f32_e32 v36, v36
	v_exp_f32_e32 v37, v37
	v_exp_f32_e32 v38, v38
	v_exp_f32_e32 v39, v39
	v_add_f32_e32 v36, 1.0, v36
	v_add_f32_e32 v37, 1.0, v37
	v_add_f32_e32 v38, 1.0, v38
	v_add_f32_e32 v39, 1.0, v39
	v_rcp_f32_e32 v36, v36
	v_rcp_f32_e32 v37, v37
	v_rcp_f32_e32 v38, v38
	v_rcp_f32_e32 v39, v39
	v_mul_f32_e32 v24, v32, v24
	v_mul_f32_e32 v25, v33, v25
	v_mul_f32_e32 v26, v26, v36
	v_mul_f32_e32 v27, v27, v37
	v_mul_f32_e32 v22, v30, v22
	v_mul_f32_e32 v23, v31, v23
	v_mul_f32_e32 v28, v28, v38
	v_mul_f32_e32 v29, v29, v39
	v_mul_f32_e32 v18, v26, v18
	v_mul_f32_e32 v19, v27, v19
	v_mul_f32_e32 v20, v28, v20
	v_mul_f32_e32 v21, v29, v21
	v_cvt_pk_bf16_f32 v22, v22, v23
	v_cvt_pk_bf16_f32 v23, v24, v25
	v_cvt_pk_bf16_f32 v24, v18, v19
	v_cvt_pk_bf16_f32 v21, v20, v21
	ds_bpermute_b32 v18, v150, v22
	ds_bpermute_b32 v19, v150, v23
	ds_bpermute_b32 v20, v150, v24
	ds_bpermute_b32 v21, v150, v21
	v_mad_i64_i32 v[34:35], s[22:23], v34, s38, v[146:147]
	v_lshl_add_u64 v[34:35], v[34:35], 0, v[148:149]
	v_mul_f32_e32 v22, 0xbfb8aa3b, v14
	v_mul_f32_e32 v23, 0xbfb8aa3b, v15
	s_waitcnt lgkmcnt(0)
	global_store_dwordx4 v[34:35], v[18:21], off
	v_exp_f32_e32 v22, v22
	v_exp_f32_e32 v23, v23
	v_mul_f32_e32 v20, 0xbfb8aa3b, v16
	v_mul_f32_e32 v21, 0xbfb8aa3b, v17
	v_exp_f32_e32 v20, v20
	v_exp_f32_e32 v21, v21
	v_add_f32_e32 v18, 1.0, v22
	v_add_f32_e32 v19, 1.0, v23
	v_add_f32_e32 v20, 1.0, v20
	v_add_f32_e32 v21, 1.0, v21
	v_rcp_f32_e32 v18, v18
	v_rcp_f32_e32 v19, v19
	v_rcp_f32_e32 v20, v20
	v_rcp_f32_e32 v21, v21
	v_mul_f32_e32 v14, v14, v18
	v_mul_f32_e32 v15, v15, v19
	v_mul_f32_e32 v18, 0xbfb8aa3b, v10
	v_mul_f32_e32 v19, 0xbfb8aa3b, v11
	v_mul_f32_e32 v16, v16, v20
	v_mul_f32_e32 v17, v17, v21
	v_mul_f32_e32 v20, 0xbfb8aa3b, v12
	v_mul_f32_e32 v21, 0xbfb8aa3b, v13
	v_exp_f32_e32 v18, v18
	v_exp_f32_e32 v19, v19
	v_exp_f32_e32 v20, v20
	v_exp_f32_e32 v21, v21
	v_add_f32_e32 v18, 1.0, v18
	v_add_f32_e32 v19, 1.0, v19
	v_add_f32_e32 v20, 1.0, v20
	v_add_f32_e32 v21, 1.0, v21
	v_rcp_f32_e32 v18, v18
	v_rcp_f32_e32 v19, v19
	v_rcp_f32_e32 v20, v20
	v_rcp_f32_e32 v21, v21
	v_mul_f32_e32 v8, v16, v8
	v_mul_f32_e32 v9, v17, v9
	v_mul_f32_e32 v10, v10, v18
	v_mul_f32_e32 v11, v11, v19
	v_mul_f32_e32 v6, v14, v6
	v_mul_f32_e32 v7, v15, v7
	v_mul_f32_e32 v12, v12, v20
	v_mul_f32_e32 v13, v13, v21
	v_mul_f32_e32 v2, v10, v2
	v_mul_f32_e32 v3, v11, v3
	v_mul_f32_e32 v4, v12, v4
	v_mul_f32_e32 v5, v13, v5
	v_cvt_pk_bf16_f32 v6, v6, v7
	v_cvt_pk_bf16_f32 v7, v8, v9
	v_cvt_pk_bf16_f32 v8, v2, v3
	v_cvt_pk_bf16_f32 v5, v4, v5
	ds_bpermute_b32 v2, v150, v6
	ds_bpermute_b32 v3, v150, v7
	ds_bpermute_b32 v4, v150, v8
	ds_bpermute_b32 v5, v150, v5
	v_add_u32_e32 v6, 0xb0, v156
	v_mad_i64_i32 v[6:7], s[22:23], v6, s38, v[146:147]
	v_lshl_add_u64 v[6:7], v[6:7], 0, v[148:149]
	s_waitcnt lgkmcnt(0)
	global_store_dwordx4 v[6:7], v[2:5], off
	s_cbranch_vccnz .LBB0_2770
	s_andn2_b64 vcc, exec, s[4:5]
	s_cbranch_vccnz .LBB0_2769
	s_barrier
	s_branch .LBB0_2769

; __device__ __forceinline__ unsigned pk2(float lo, float hi) { const bfx2 b = __builtin_convertvector((f32x2){lo, hi}, bfx2); return __builtin_bit_cast(unsigned, b); }
; __device__ __forceinline__ f32x4 sig4(const f32x4 v) { f32x4 r; r.x = sigmoidf_(v.x); r.y = sigmoidf_(v.y); r.z = sigmoidf_(v.z); r.w = sigmoidf_(v.w); return r; }
; template <int CW, int NB, int NS, class Epi>
; __device__ __forceinline__ void skinny_gemm(Frame& F, const bf16* A, int K, const bf16* Bt, int nchunks, const Epi& E) {
;     ...
;         if (ks == 0) {
; #pragma unroll
;             for (int i = 0; i < 2; ++i)
; #pragma unroll
;                 for (int j = 0; j < NT; ++j) {
; #pragma unroll
;                     for (int nb = 0; nb < NB; ++nb) acc[i][j][nb] += red[((i * NT + j) * NB + nb) * 256 + rg * 64 + lane];
;                     if (16 * j + 4 * lq < CW) E(32 * rg + 16 * i + lr, c0 + 16 * j + 4 * lq, acc[i][j][0], acc[i][j][NB - 1]); }
;     __device__ __forceinline__ void operator()(int r, int c, const pg8::f32x4 a, const pg8::f32x4 b) const {
;         const f32x4 v = a * sig4(a) * b; u32x2 w; w.x = pk2(v.x, v.y); w.y = pk2(v.z, v.w); *(u32x2*)(ACT + (size_t)(MP + r) * DFF + c) = w; }
.LBB0_2796:
	s_andn2_b64 vcc, exec, s[4:5]
	s_waitcnt lgkmcnt(0)
	s_barrier
	s_cbranch_vccnz .LBB0_2783
	s_waitcnt vmcnt(10)
	ds_read_b128 v[82:85], v161
	ds_read_b128 v[86:89], v161 offset:4096
	s_waitcnt vmcnt(8)
	v_or_b32_e32 v90, s24, v146
	v_ashrrev_i32_e32 v91, 31, v90
	s_waitcnt lgkmcnt(1)
	v_add_f32_e32 v78, v78, v82
	v_add_f32_e32 v79, v79, v83
	v_add_f32_e32 v80, v80, v84
	v_add_f32_e32 v81, v81, v85
	v_mul_f32_e32 v82, 0xbfb8aa3b, v78
	v_mul_f32_e32 v83, 0xbfb8aa3b, v79
	v_exp_f32_e32 v82, v82
	v_mul_f32_e32 v84, 0xbfb8aa3b, v80
	v_exp_f32_e32 v83, v83
	v_mul_f32_e32 v85, 0xbfb8aa3b, v81
	v_exp_f32_e32 v84, v84
	v_exp_f32_e32 v85, v85
	v_add_f32_e32 v82, 1.0, v82
	v_add_f32_e32 v83, 1.0, v83
	v_rcp_f32_e32 v82, v82
	v_add_f32_e32 v84, 1.0, v84
	v_add_f32_e32 v85, 1.0, v85
	v_rcp_f32_e32 v83, v83
	v_rcp_f32_e32 v84, v84
	v_rcp_f32_e32 v85, v85
	s_waitcnt lgkmcnt(0)
	v_add_f32_e32 v74, v74, v86
	v_add_f32_e32 v75, v75, v87
	v_mul_f32_e32 v78, v78, v82
	v_mul_f32_e32 v79, v79, v83
	v_add_f32_e32 v76, v76, v88
	v_add_f32_e32 v77, v77, v89
	v_mul_f32_e32 v80, v80, v84
	v_mul_f32_e32 v81, v81, v85
	v_mul_f32_e32 v74, v74, v78
	v_mul_f32_e32 v75, v75, v79
	v_mul_f32_e32 v80, v76, v80
	v_mul_f32_e32 v81, v77, v81
	v_cvt_pk_bf16_f32 v82, v74, v75
	ds_read_b128 v[74:77], v161 offset:8192
	v_cvt_pk_bf16_f32 v83, v80, v81
	ds_read_b128 v[78:81], v161 offset:12288
	v_lshlrev_b64 v[84:85], 1, v[90:91]
	s_waitcnt lgkmcnt(1)
	v_add_f32_e32 v70, v70, v74
	v_add_f32_e32 v71, v71, v75
	s_nop 0
	v_mul_f32_e32 v74, 0xbfb8aa3b, v70
	v_exp_f32_e32 v86, v74
	v_lshl_add_u64 v[74:75], v[140:141], 0, v[84:85]
	v_add_f32_e32 v72, v72, v76
	v_add_f32_e32 v73, v73, v77
	v_mul_f32_e32 v77, 0xbfb8aa3b, v71
	global_store_dwordx2 v[74:75], v[82:83], off
	v_exp_f32_e32 v77, v77
	v_mul_f32_e32 v82, 0xbfb8aa3b, v72
	v_mul_f32_e32 v83, 0xbfb8aa3b, v73
	v_exp_f32_e32 v82, v82
	v_exp_f32_e32 v83, v83
	v_add_f32_e32 v76, 1.0, v86
	v_add_f32_e32 v77, 1.0, v77
	v_rcp_f32_e32 v76, v76
	v_add_f32_e32 v82, 1.0, v82
	v_add_f32_e32 v83, 1.0, v83
	v_rcp_f32_e32 v77, v77
	v_rcp_f32_e32 v82, v82
	v_rcp_f32_e32 v83, v83
	s_waitcnt lgkmcnt(0)
	v_add_f32_e32 v80, v68, v80
	v_add_f32_e32 v81, v69, v81
	v_add_f32_e32 v78, v66, v78
	v_add_f32_e32 v79, v67, v79
	ds_read_b128 v[66:69], v161 offset:16384
	v_mul_f32_e32 v70, v70, v76
	v_mul_f32_e32 v71, v71, v77
	v_mul_f32_e32 v72, v72, v82
	v_mul_f32_e32 v73, v73, v83
	v_mul_f32_e32 v70, v78, v70
	v_mul_f32_e32 v71, v79, v71
	v_mul_f32_e32 v76, v80, v72
	v_mul_f32_e32 v77, v81, v73
	v_cvt_pk_bf16_f32 v78, v70, v71
	ds_read_b128 v[70:73], v161 offset:20480
	s_waitcnt lgkmcnt(1)
	v_add_f32_e32 v64, v64, v68
	v_add_f32_e32 v65, v65, v69
	v_add_f32_e32 v62, v62, v66
	v_add_f32_e32 v63, v63, v67
	v_mul_f32_e32 v68, 0xbfb8aa3b, v64
	v_mul_f32_e32 v69, 0xbfb8aa3b, v65
	v_exp_f32_e32 v68, v68
	v_exp_f32_e32 v69, v69
	v_mul_f32_e32 v66, 0xbfb8aa3b, v62
	v_mul_f32_e32 v67, 0xbfb8aa3b, v63
	v_exp_f32_e32 v66, v66
	v_exp_f32_e32 v67, v67
	v_add_f32_e32 v68, 1.0, v68
	v_add_f32_e32 v69, 1.0, v69
	v_rcp_f32_e32 v68, v68
	v_rcp_f32_e32 v69, v69
	v_add_f32_e32 v66, 1.0, v66
	v_add_f32_e32 v67, 1.0, v67
	v_rcp_f32_e32 v66, v66
	v_rcp_f32_e32 v67, v67
	s_waitcnt lgkmcnt(0)
	v_add_f32_e32 v60, v60, v72
	v_add_f32_e32 v61, v61, v73
	v_add_f32_e32 v70, v58, v70
	v_add_f32_e32 v71, v59, v71
	v_mul_f32_e32 v58, v64, v68
	v_mul_f32_e32 v59, v65, v69
	v_mul_f32_e32 v62, v62, v66
	v_mul_f32_e32 v63, v63, v67
	v_mul_f32_e32 v64, v60, v58
	v_mul_f32_e32 v65, v61, v59
	ds_read_b128 v[58:61], v161 offset:24576
	v_mul_f32_e32 v62, v70, v62
	v_mul_f32_e32 v63, v71, v63
	v_cvt_pk_bf16_f32 v67, v64, v65
	v_cvt_pk_bf16_f32 v66, v62, v63
	ds_read_b128 v[62:65], v161 offset:28672
	s_waitcnt lgkmcnt(1)
	v_add_f32_e32 v54, v54, v58
	v_add_f32_e32 v55, v55, v59
	v_add_f32_e32 v56, v56, v60
	v_add_f32_e32 v57, v57, v61
	v_mul_f32_e32 v58, 0xbfb8aa3b, v54
	v_exp_f32_e32 v68, v58
	v_lshl_add_u64 v[58:59], v[142:143], 0, v[84:85]
	global_store_dwordx2 v[58:59], v[66:67], off
	v_mul_f32_e32 v61, 0xbfb8aa3b, v55
	v_mul_f32_e32 v66, 0xbfb8aa3b, v56
	v_mul_f32_e32 v67, 0xbfb8aa3b, v57
	v_exp_f32_e32 v61, v61
	v_exp_f32_e32 v66, v66
	v_exp_f32_e32 v67, v67
	v_add_f32_e32 v60, 1.0, v68
	v_add_f32_e32 v61, 1.0, v61
	v_add_f32_e32 v66, 1.0, v66
	v_add_f32_e32 v67, 1.0, v67
	v_rcp_f32_e32 v60, v60
	v_rcp_f32_e32 v66, v66
	v_rcp_f32_e32 v67, v67
	v_rcp_f32_e32 v61, v61
	s_waitcnt lgkmcnt(0)
	v_add_f32_e32 v52, v52, v64
	v_add_f32_e32 v53, v53, v65
	v_add_f32_e32 v50, v50, v62
	v_add_f32_e32 v51, v51, v63
	v_mul_f32_e32 v56, v56, v66
	v_mul_f32_e32 v57, v57, v67
	v_mul_f32_e32 v54, v54, v60
	v_mul_f32_e32 v55, v55, v61
	v_mul_f32_e32 v52, v52, v56
	v_mul_f32_e32 v53, v53, v57
	v_mul_f32_e32 v50, v50, v54
	v_mul_f32_e32 v51, v51, v55
	v_cvt_pk_bf16_f32 v79, v76, v77
	v_cvt_pk_bf16_f32 v50, v50, v51
	v_cvt_pk_bf16_f32 v51, v52, v53
	global_store_dwordx2 v[74:75], v[78:79], off offset:32
	global_store_dwordx2 v[58:59], v[50:51], off offset:32
	s_branch .LBB0_2783

; __device__ __forceinline__ unsigned pk2(float lo, float hi) { const bfx2 b = __builtin_convertvector((f32x2){lo, hi}, bfx2); return __builtin_bit_cast(unsigned, b); }
; template <int NS, class Epi>
; __device__ __forceinline__ void skinny_gemm2d(Frame& F, const bf16* A, int K, const bf16* Bt, const Epi& E) {
;     ...
;         if (ks == 1) red[(mt * 2 + nt) * 64 + lane] = acc;
;         __syncthreads();
;         if (ks == 0) { acc += red[(mt * 2 + nt) * 64 + lane]; E(r0 + lr, c0 + 4 * lq, acc, acc); }
;     __device__ __forceinline__ void operator()(int r, int c, const pg8::f32x4 a, const pg8::f32x4) const {
;         u32x2 w; w.x = pk2(a.x, a.y); w.y = pk2(a.z, a.w); *(u32x2*)(O + (size_t)(MP + r) * ldc + c) = w; }
.LBB0_2883:
	s_and_b64 vcc, exec, s[4:5]
	s_waitcnt lgkmcnt(0)
	s_barrier
	s_cbranch_vccnz .LBB0_2880
	ds_read_b128 v[12:15], v18
	v_or_b32_e32 v6, s12, v22
	v_or_b32_e32 v16, s13, v19
	v_lshlrev_b32_e32 v6, 12, v6
	v_ashrrev_i32_e32 v17, 31, v16
	s_waitcnt lgkmcnt(0)
	v_add_f32_e32 v4, v4, v14
	v_add_f32_e32 v5, v5, v15
	v_add_f32_e32 v2, v2, v12
	v_add_f32_e32 v3, v3, v13
	s_nop 0
	v_cvt_pk_bf16_f32 v2, v2, v3
	v_cvt_pk_bf16_f32 v3, v4, v5
	v_lshl_add_u64 v[4:5], s[72:73], 0, v[6:7]
	v_lshl_add_u64 v[4:5], v[16:17], 1, v[4:5]
	global_store_dwordx2 v[4:5], v[2:3], off
	s_branch .LBB0_2880

; __device__ __forceinline__ float bflo(unsigned w) { return __uint_as_float(w << 16); }
; __device__ __forceinline__ float bfhi(unsigned w) { return __uint_as_float(w & 0xffff0000u); }
; template <bool INB, bool OUTB>
; __device__ __forceinline__ void thin_phase(Frame& F, const bf16* Fb, const void* xin_p, const void* xin_s, const float* post_g, float half, void* xout, const float* next_g, bf16* H) {
;     ...
;     for (int m0 = 2 * gw; m0 < MT; m0 += 2 * NGW) {
;         f32x4 f[2][8], x[2][8]; float s[2] = {0.f, 0.f};
; #pragma unroll
;         for (int r = 0; r < 2; ++r) { const int m = m0 + r;
; #pragma unroll
;             for (int j = 0; j < 4; ++j) { const int c = (j * 64 + lane) * 8; const u32x4 w = *(const u32x4*)(Fb + (size_t)m * D + c);
;                 f[r][2 * j] = (f32x4){bflo(w.x), bfhi(w.x), bflo(w.y), bfhi(w.y)}; f[r][2 * j + 1] = (f32x4){bflo(w.z), bfhi(w.z), bflo(w.w), bfhi(w.w)};
;                 if (INB) { const bf16* xr = m < MP ? (const bf16*)xin_p + (size_t)m * D : (const bf16*)xin_s + (size_t)(m - MP) * D; const u32x4 xw = *(const u32x4*)(xr + c);
;                     x[r][2 * j] = (f32x4){bflo(xw.x), bfhi(xw.x), bflo(xw.y), bfhi(xw.y)}; x[r][2 * j + 1] = (f32x4){bflo(xw.z), bfhi(xw.z), bflo(xw.w), bfhi(xw.w)}; }
;                 else { const float* xr = m < MP ? (const float*)xin_p + (size_t)m * D : (const float*)xin_s + (size_t)(m - MP) * D; x[r][2 * j] = *(const f32x4*)(xr + c); x[r][2 * j + 1] = *(const f32x4*)(xr + c + 4); } } }
; #pragma unroll
;         for (int r = 0; r < 2; ++r)
; #pragma unroll
;             for (int q = 0; q < 8; ++q) s[r] += (f[r][q].x * f[r][q].x + f[r][q].y * f[r][q].y) + (f[r][q].z * f[r][q].z + f[r][q].w * f[r][q].w);
.LBB0_2939:
	v_lshl_add_u64 v[0:1], s[12:13], 0, v[36:37]
	v_add_co_u32_e32 v2, vcc, s7, v0
	v_add_co_u32_e64 v4, s[0:1], s9, v0
	s_nop 0
	v_addc_co_u32_e32 v3, vcc, -1, v1, vcc
	v_addc_co_u32_e64 v5, s[0:1], -1, v1, s[0:1]
	s_add_u32 s2, s12, 0xfffff000
	s_nop 0
	s_nop 0
	global_load_dwordx4 v[46:49], v[4:5], off offset:-3072
	global_load_dwordx4 v[50:53], v[4:5], off offset:-2048
	global_load_dwordx4 v[54:57], v[2:3], off offset:-3072
	global_load_dwordx4 v[58:61], v[2:3], off offset:-2048
	global_load_dwordx4 v[102:105], v[2:3], off offset:-1024
	global_load_dwordx4 v[110:113], v[4:5], off offset:-1024
	global_load_dwordx4 v[78:81], v[2:3], off offset:-4096
	global_load_dwordx4 v[114:117], v[2:3], off
	s_addc_u32 s3, s13, -1
	s_add_i32 s16, s6, 0xffffc000
	s_lshl_b64 s[0:1], s[16:17], 12
	s_add_u32 s0, s33, s0
	s_addc_u32 s1, s50, s1
	s_cmpk_lt_i32 s6, 0x4000
	s_cselect_b32 s1, s3, s1
	s_cselect_b32 s0, s2, s0
	s_add_i32 s16, s6, 0xffffc001
	s_add_i32 s2, s6, 1
	global_load_dwordx4 v[118:121], v106, s[0:1]
	global_load_dwordx4 v[16:19], v106, s[0:1] offset:1024
	global_load_dwordx4 v[8:11], v106, s[0:1] offset:2048
	global_load_dwordx4 v[0:3], v106, s[0:1] offset:3072
	s_lshl_b64 s[0:1], s[16:17], 12
	s_add_u32 s0, s33, s0
	s_addc_u32 s1, s50, s1
	s_cmpk_lt_i32 s2, 0x4000
	s_cselect_b32 s1, s13, s1
	s_cselect_b32 s0, s12, s0
	global_load_dwordx4 v[32:35], v106, s[0:1]
	global_load_dwordx4 v[20:23], v106, s[0:1] offset:1024
	global_load_dwordx4 v[12:15], v106, s[0:1] offset:2048
	global_load_dwordx4 v[4:7], v106, s[0:1] offset:3072
	s_add_i32 s6, s6, s8
	s_add_u32 s12, s12, s14
	s_addc_u32 s13, s13, s15
	s_cmpk_lt_i32 s6, 0x4080
	s_waitcnt vmcnt(13)
	v_lshlrev_b32_e32 v88, 16, v56
	v_and_b32_e32 v89, 0xffff0000, v56
	s_waitcnt vmcnt(12)
	v_lshlrev_b32_e32 v77, 16, v58
	v_lshlrev_b32_e32 v82, 16, v48
	s_waitcnt vmcnt(9)
	v_and_b32_e32 v99, 0xffff0000, v80
	v_and_b32_e32 v98, 0xffff0000, v78
	v_and_b32_e32 v101, 0xffff0000, v81
	v_and_b32_e32 v100, 0xffff0000, v79
	v_and_b32_e32 v83, 0xffff0000, v48
	v_lshlrev_b32_e32 v75, 16, v50
	v_and_b32_e32 v63, 0xffff0000, v50
	v_lshlrev_b32_e32 v64, 16, v51
	v_and_b32_e32 v65, 0xffff0000, v51
	v_lshlrev_b32_e32 v87, 16, v47
	v_lshlrev_b32_e32 v86, 16, v46
	v_and_b32_e32 v91, 0xffff0000, v47
	v_and_b32_e32 v90, 0xffff0000, v46
	v_lshlrev_b32_e32 v84, 16, v49
	v_and_b32_e32 v85, 0xffff0000, v49
	v_lshlrev_b32_e32 v66, 16, v52
	v_and_b32_e32 v67, 0xffff0000, v52
	v_lshlrev_b32_e32 v68, 16, v53
	v_and_b32_e32 v69, 0xffff0000, v53
	v_and_b32_e32 v71, 0xffff0000, v58
	v_lshlrev_b32_e32 v72, 16, v59
	v_and_b32_e32 v73, 0xffff0000, v59
	v_lshlrev_b32_e32 v48, 16, v104
	v_and_b32_e32 v49, 0xffff0000, v104
	v_lshlrev_b32_e32 v52, 16, v105
	v_and_b32_e32 v53, 0xffff0000, v105
	v_lshlrev_b32_e32 v46, 16, v112
	v_and_b32_e32 v47, 0xffff0000, v112
	v_lshlrev_b32_e32 v50, 16, v113
	v_and_b32_e32 v51, 0xffff0000, v113
	v_lshlrev_b32_e32 v113, 16, v80
	v_lshlrev_b32_e32 v112, 16, v78
	v_lshlrev_b32_e32 v123, 16, v81
	v_lshlrev_b32_e32 v122, 16, v79
	v_lshlrev_b32_e32 v93, 16, v55
	v_lshlrev_b32_e32 v92, 16, v54
	v_and_b32_e32 v97, 0xffff0000, v55
	v_and_b32_e32 v96, 0xffff0000, v54
	v_lshlrev_b32_e32 v94, 16, v57
	v_and_b32_e32 v95, 0xffff0000, v57
	v_lshlrev_b32_e32 v78, 16, v60
	v_and_b32_e32 v79, 0xffff0000, v60
	v_lshlrev_b32_e32 v80, 16, v61
	v_and_b32_e32 v81, 0xffff0000, v61
	v_lshlrev_b32_e32 v54, 16, v102
	v_and_b32_e32 v55, 0xffff0000, v102
	v_lshlrev_b32_e32 v56, 16, v103
	v_and_b32_e32 v57, 0xffff0000, v103
	s_waitcnt vmcnt(8)
	v_and_b32_e32 v103, 0xffff0000, v116
	v_and_b32_e32 v102, 0xffff0000, v114
	v_and_b32_e32 v105, 0xffff0000, v117
	v_and_b32_e32 v104, 0xffff0000, v115
	v_lshlrev_b32_e32 v58, 16, v110
	v_and_b32_e32 v59, 0xffff0000, v110
	v_lshlrev_b32_e32 v60, 16, v111
	v_and_b32_e32 v61, 0xffff0000, v111
	v_mul_f32_e32 v110, v98, v98
	v_mul_f32_e32 v111, v99, v99
	v_mul_f32_e32 v130, v100, v100
	v_mul_f32_e32 v131, v101, v101
	v_lshlrev_b32_e32 v125, 16, v116
	v_lshlrev_b32_e32 v124, 16, v114
	v_lshlrev_b32_e32 v127, 16, v117
	v_lshlrev_b32_e32 v126, 16, v115
	v_mul_f32_e32 v132, v96, v96
	v_mul_f32_e32 v133, v97, v97
	v_mul_f32_e32 v148, v102, v102
	v_mul_f32_e32 v149, v103, v103
	v_mul_f32_e32 v150, v104, v104
	v_mul_f32_e32 v151, v105, v105
	v_mov_b32_e32 v158, v112
	v_mov_b32_e32 v159, v98
	v_mov_b32_e32 v98, v113
	v_fma_f32 v110, v112, v112, v110
	v_fma_f32 v111, v113, v113, v111
	v_fma_f32 v112, v122, v122, v130
	v_fma_f32 v113, v123, v123, v131
	v_mul_f32_e32 v114, v90, v90
	v_mul_f32_e32 v115, v91, v91
	v_mul_f32_e32 v76, v88, v88
	v_mul_f32_e32 v134, v89, v89
	v_mov_b32_e32 v135, v77
	v_mul_f32_e32 v136, v95, v95
	v_mov_b32_e32 v160, v122
	v_mov_b32_e32 v161, v100
	v_mov_b32_e32 v100, v123
	v_mov_b32_e32 v162, v124
	v_mov_b32_e32 v163, v102
	v_mov_b32_e32 v164, v126
	v_mov_b32_e32 v165, v104
	v_mov_b32_e32 v102, v125
	v_mov_b32_e32 v104, v127
	v_fma_f32 v122, v92, v92, v132
	v_fma_f32 v123, v93, v93, v133
	v_fma_f32 v124, v124, v124, v148
	v_fma_f32 v125, v125, v125, v149
	v_fma_f32 v126, v126, v126, v150
	v_fma_f32 v127, v127, v127, v151
	v_add_f32_e32 v110, v110, v112
	v_add_f32_e32 v111, v111, v113
	v_mul_f32_e32 v74, v82, v82
	v_mul_f32_e32 v116, v83, v83
	v_mov_b32_e32 v117, v75
	v_mul_f32_e32 v62, v85, v85
	v_mul_f32_e32 v167, v71, v71
	v_mul_f32_e32 v168, v72, v72
	v_mul_f32_e32 v169, v73, v73
	v_fma_f32 v114, v86, v86, v114
	v_fma_f32 v115, v87, v87, v115
	v_add_f32_e32 v130, v76, v134
	v_add_f32_e32 v131, v77, v135
	v_mul_f32_e32 v132, v76, v76
	v_mul_f32_e32 v133, v77, v77
	v_fma_f32 v134, v94, v94, v136
	v_fma_f32 v135, v95, v95, v136
	v_add_f32_e32 v112, v122, v123
; template <bool INB, bool OUTB>
; __device__ __forceinline__ void thin_phase(Frame& F, const bf16* Fb, const void* xin_p, const void* xin_s, const float* post_g, float half, void* xout, const float* next_g, bf16* H) {
;     ...
; #pragma unroll
;         for (int r = 0; r < 2; ++r)
; #pragma unroll
;             for (int q = 0; q < 8; ++q) s[r] += (f[r][q].x * f[r][q].x + f[r][q].y * f[r][q].y) + (f[r][q].z * f[r][q].z + f[r][q].w * f[r][q].w);
;         const float r0 = half / sqrtf(wave_sum(s[0]) * (1.0f / D) + RMS_EPS), r1 = half / sqrtf(wave_sum(s[1]) * (1.0f / D) + RMS_EPS);
	v_add_f32_e32 v113, v123, v122
	v_add_f32_e32 v124, v124, v126
	v_add_f32_e32 v125, v125, v127
	v_pk_add_f32 v[110:111], v[110:111], v[110:111] op_sel:[0,1] op_sel_hi:[1,0]
	v_mul_f32_e32 v109, v63, v63
	v_mul_f32_e32 v166, v64, v64
	v_mul_f32_e32 v147, v65, v65
	v_add_f32_e32 v116, v74, v116
	v_add_f32_e32 v117, v75, v117
	v_mul_f32_e32 v152, v74, v74
	v_mul_f32_e32 v153, v75, v75
	v_fma_f32 v154, v84, v84, v62
	v_fma_f32 v155, v85, v85, v62
	v_pk_add_f32 v[114:115], v[114:115], v[114:115] op_sel:[0,1] op_sel_hi:[1,0]
	v_mov_b32_e32 v131, v133
	v_mov_b32_e32 v135, v167
	v_mov_b32_e32 v113, v169
	v_pk_add_f32 v[124:125], v[124:125], v[124:125] op_sel:[0,1] op_sel_hi:[1,0]
	v_mov_b32_e32 v111, v168
	v_mul_f32_e32 v138, v78, v78
	v_mul_f32_e32 v140, v80, v80
	v_mov_b32_e32 v117, v153
	v_mov_b32_e32 v155, v109
	v_mov_b32_e32 v115, v147
	v_add_f32_e32 v130, v130, v134
	v_add_f32_e32 v131, v131, v135
	v_mov_b32_e32 v125, v166
	v_add_f32_e32 v110, v110, v112
	v_add_f32_e32 v111, v111, v113
	v_mul_f32_e32 v70, v66, v66
	v_mul_f32_e32 v128, v68, v68
	v_mul_f32_e32 v142, v54, v54
	v_mul_f32_e32 v144, v56, v56
	v_fma_f32 v136, v78, v78, v138
	v_fma_f32 v137, v79, v79, v138
	v_fma_f32 v138, v80, v80, v140
	v_fma_f32 v139, v81, v81, v140
	v_add_f32_e32 v116, v116, v154
	v_add_f32_e32 v117, v117, v155
	v_add_f32_e32 v112, v124, v114
	v_add_f32_e32 v113, v125, v115
	v_add_f32_e32 v110, v130, v110
	v_add_f32_e32 v111, v131, v111
	v_fma_f32 v156, v66, v66, v70
	v_fma_f32 v157, v67, v67, v70
	v_fma_f32 v129, v69, v69, v128
	v_fma_f32 v128, v68, v68, v128
	v_mul_f32_e32 v62, v58, v58
	v_mul_f32_e32 v70, v60, v60
	v_fma_f32 v140, v54, v54, v142
	v_fma_f32 v141, v55, v55, v142
	v_fma_f32 v142, v56, v56, v144
	v_fma_f32 v143, v57, v57, v144
	v_add_f32_e32 v122, v136, v138
	v_add_f32_e32 v123, v137, v139
	v_add_f32_e32 v112, v116, v112
	v_add_f32_e32 v113, v117, v113
	v_add_f32_e32 v111, v110, v111
	v_add_f32_e32 v110, v110, v110
	v_mul_f32_e32 v146, v48, v48
	v_fma_f32 v144, v58, v58, v62
	v_fma_f32 v145, v59, v59, v62
	v_fma_f32 v148, v60, v60, v70
	v_fma_f32 v149, v61, v61, v70
	v_add_f32_e32 v128, v156, v128
	v_add_f32_e32 v129, v157, v129
	v_mul_f32_e32 v140, v52, v52
	v_mul_f32_e32 v142, v53, v53
	v_mov_b32_e32 v147, v123
	v_add_f32_e32 v113, v112, v113
	v_add_f32_e32 v112, v112, v112
	v_mul_f32_e32 v110, v49, v49
	v_mul_f32_e32 v152, v46, v46
	v_mul_f32_e32 v144, v50, v50
	v_mul_f32_e32 v148, v51, v51
	v_mov_b32_e32 v153, v129
	v_add_f32_e32 v122, v140, v142
	v_add_f32_e32 v123, v141, v143
	s_waitcnt vmcnt(3)
	s_nop 1
	v_mov_b64_e32 v[24:25], v[170:171]
	v_mov_b64_e32 v[26:27], v[172:173]
	v_mov_b64_e32 v[28:29], v[174:175]
	v_mov_b64_e32 v[30:31], v[176:177]
	v_lshlrev_b32_e32 v114, 16, v32
	v_and_b32_e32 v115, 0xffff0000, v32
	v_lshlrev_b32_e32 v116, 16, v33
	v_and_b32_e32 v117, 0xffff0000, v33
	v_mul_f32_e32 v112, v47, v47
	v_add_f32_e32 v32, v146, v110
	v_add_f32_e32 v33, v147, v111
	v_add_f32_e32 v132, v144, v148
	v_add_f32_e32 v133, v145, v149
	v_lshlrev_b32_e32 v124, 16, v34
	v_and_b32_e32 v125, 0xffff0000, v34
	v_lshlrev_b32_e32 v130, 16, v35
	v_and_b32_e32 v131, 0xffff0000, v35
	v_add_f32_e32 v34, v152, v112
	v_add_f32_e32 v35, v153, v113
	v_add_f32_e32 v32, v32, v122
	v_add_f32_e32 v33, v33, v123
	v_add_f32_e32 v34, v34, v132
	v_add_f32_e32 v35, v35, v133
	v_add_f32_e32 v32, v32, v33
	v_add_f32_e32 v33, v34, v35
	v_lshlrev_b32_e32 v126, 16, v118
	v_add_f32_dpp v32, v32, v32 quad_perm:[1,0,3,2] row_mask:0xf bank_mask:0xf bound_ctrl:1
	v_add_f32_dpp v33, v33, v33 quad_perm:[1,0,3,2] row_mask:0xf bank_mask:0xf bound_ctrl:1
	v_and_b32_e32 v127, 0xffff0000, v118
	v_add_f32_dpp v32, v32, v32 quad_perm:[2,3,0,1] row_mask:0xf bank_mask:0xf bound_ctrl:1
	v_add_f32_dpp v33, v33, v33 quad_perm:[2,3,0,1] row_mask:0xf bank_mask:0xf bound_ctrl:1
	v_lshlrev_b32_e32 v118, 16, v119
	v_add_f32_dpp v32, v32, v32 row_half_mirror row_mask:0xf bank_mask:0xf bound_ctrl:1
	v_add_f32_dpp v33, v33, v33 row_half_mirror row_mask:0xf bank_mask:0xf bound_ctrl:1
	v_and_b32_e32 v119, 0xffff0000, v119
	v_add_f32_dpp v32, v32, v32 row_mirror row_mask:0xf bank_mask:0xf bound_ctrl:1
	v_add_f32_dpp v33, v33, v33 row_mirror row_mask:0xf bank_mask:0xf bound_ctrl:1
	v_readlane_b32 s4, v32, 16
	v_readlane_b32 s5, v32, 48
	v_readlane_b32 s0, v32, 0
	v_readlane_b32 s1, v32, 32
	v_readlane_b32 s2, v33, 0
	v_readlane_b32 s16, v33, 16
	v_readlane_b32 s3, v33, 32
	v_readlane_b32 s21, v33, 48
	v_mov_b32_e32 v32, s4
	v_mov_b32_e32 v33, s5
	v_add_f32_e32 v32, s0, v32
	v_add_f32_e32 v33, s1, v33
	v_mov_b32_e32 v34, s16
	v_mov_b32_e32 v35, s21
	v_add_f32_e32 v32, v32, v33
	v_add_f32_e32 v34, s2, v34
	v_add_f32_e32 v35, s3, v35
	v_fmamk_f32 v32, v32, 0x3a000000, v107
	v_add_f32_e32 v33, v34, v35
	v_mul_f32_e32 v34, 0x4f800000, v32
	v_cmp_gt_f32_e64 s[0:1], s19, v32
	v_fmamk_f32 v33, v33, 0x3a000000, v107
	v_mul_f32_e32 v35, 0x4f800000, v33
	v_cndmask_b32_e64 v32, v32, v34, s[0:1]
	v_cmp_gt_f32_e32 vcc, s19, v33
	v_sqrt_f32_e32 v34, v32
	v_lshlrev_b32_e32 v128, 16, v120
	v_cndmask_b32_e32 v33, v33, v35, vcc
	v_sqrt_f32_e32 v35, v33
	v_add_u32_e32 v62, -1, v34
	v_add_u32_e32 v70, 1, v34
	v_fma_f32 v109, -v62, v34, v32
	v_add_u32_e32 v74, -1, v35
	v_fma_f32 v110, -v70, v34, v32
	v_cmp_ge_f32_e64 s[2:3], 0, v109
	v_add_u32_e32 v76, 1, v35
	v_fma_f32 v111, -v74, v35, v33
	v_cndmask_b32_e64 v34, v34, v62, s[2:3]
	v_cmp_lt_f32_e64 s[4:5], 0, v110
	v_fma_f32 v112, -v76, v35, v33
	v_cmp_ge_f32_e64 s[2:3], 0, v111
	v_cndmask_b32_e64 v34, v34, v70, s[4:5]
	v_mul_f32_e32 v62, 0x37800000, v34
	v_cndmask_b32_e64 v35, v35, v74, s[2:3]
	v_cmp_lt_f32_e64 s[2:3], 0, v112
	v_cndmask_b32_e64 v34, v34, v62, s[0:1]
; #define NT_ST4(ptr_, val_) __builtin_nontemporal_store((val_), (f32x4*)(ptr_))
; __device__ __forceinline__ u32x4 pack8(const f32x4 a, const f32x4 b) { u32x4 o; o.x = pk2(a.x, a.y); o.y = pk2(a.z, a.w); o.z = pk2(b.x, b.y); o.w = pk2(b.z, b.w); return o; }
; template <bool INB, bool OUTB>
; __device__ __forceinline__ void thin_phase(Frame& F, const bf16* Fb, const void* xin_p, const void* xin_s, const float* post_g, float half, void* xout, const float* next_g, bf16* H) {
;     ...
;         const float r0 = half / sqrtf(wave_sum(s[0]) * (1.0f / D) + RMS_EPS), r1 = half / sqrtf(wave_sum(s[1]) * (1.0f / D) + RMS_EPS);
;         float s2[2] = {0.f, 0.f};
; #pragma unroll
;         for (int j = 0; j < 4; ++j) { const int c = (j * 64 + lane) * 8; const f32x4 g0 = *(const f32x4*)(post_g + c), g1 = *(const f32x4*)(post_g + c + 4);
; #pragma unroll
;             for (int r = 0; r < 2; ++r) { const f32x4 o0 = x[r][2 * j] + f[r][2 * j] * (r == 0 ? r0 : r1) * g0, o1 = x[r][2 * j + 1] + f[r][2 * j + 1] * (r == 0 ? r0 : r1) * g1; f[r][2 * j] = o0; f[r][2 * j + 1] = o1;
;                 if (OUTB) __builtin_nontemporal_store(pack8(o0, o1), (u32x4*)((bf16*)xout + (size_t)(m0 + r) * D + c));
;                 else { NT_ST4((float*)xout + (size_t)(m0 + r) * D + c, o0); NT_ST4((float*)xout + (size_t)(m0 + r) * D + c + 4, o1); }
;                 s2[r] += ((o0.x * o0.x + o0.y * o0.y) + (o0.z * o0.z + o0.w * o0.w)) + ((o1.x * o1.x + o1.y * o1.y) + (o1.z * o1.z + o1.w * o1.w)); } }
	v_cmp_class_f32_e64 s[0:1], v32, v108
	v_cndmask_b32_e64 v35, v35, v76, s[2:3]
	v_mul_f32_e32 v70, 0x37800000, v35
	v_cndmask_b32_e64 v32, v34, v32, s[0:1]
	v_cndmask_b32_e32 v35, v35, v70, vcc
	v_cmp_class_f32_e32 vcc, v33, v108
	v_div_scale_f32 v34, s[0:1], v32, v32, 0.5
	s_nop 0
	v_cndmask_b32_e32 v33, v35, v33, vcc
	v_rcp_f32_e32 v74, v34
	v_div_scale_f32 v62, s[0:1], v33, v33, 0.5
	v_rcp_f32_e32 v76, v62
	v_fma_f32 v109, -v34, v74, 1.0
	v_div_scale_f32 v35, vcc, 0.5, v32, 0.5
	v_fmac_f32_e32 v74, v109, v74
	v_fma_f32 v110, -v62, v76, 1.0
	v_mul_f32_e32 v109, v35, v74
	v_fmac_f32_e32 v76, v110, v76
	v_fma_f32 v110, -v34, v109, v35
	v_fmac_f32_e32 v109, v110, v74
	v_fma_f32 v34, -v34, v109, v35
	v_div_scale_f32 v70, s[0:1], 0.5, v33, 0.5
	v_div_fmas_f32 v35, v34, v74, v109
	v_add_co_u32_e32 v34, vcc, s20, v44
	v_mul_f32_e32 v136, v70, v76
	v_div_fixup_f32 v32, v35, v32, 0.5
	v_addc_co_u32_e32 v35, vcc, -1, v45, vcc
	v_fma_f32 v111, -v62, v136, v70
	v_add_co_u32_e32 v122, vcc, 0xfffff000, v44
	v_fmac_f32_e32 v136, v111, v76
	s_nop 0
	v_addc_co_u32_e32 v123, vcc, -1, v45, vcc
	v_fma_f32 v62, -v62, v136, v70
	v_mul_f32_e32 v110, v32, v158
	v_mul_f32_e32 v111, v32, v159
	v_mul_f32_e32 v112, v32, v160
	v_mul_f32_e32 v113, v32, v161
	s_mov_b64 vcc, s[0:1]
	v_and_b32_e32 v129, 0xffff0000, v120
	v_lshlrev_b32_e32 v120, 16, v121
	v_and_b32_e32 v121, 0xffff0000, v121
	v_mul_f32_e32 v132, v32, v98
	v_mul_f32_e32 v133, v32, v99
	v_mul_f32_e32 v134, v32, v100
	v_mul_f32_e32 v135, v32, v101
	v_fma_f32 v100, v30, v112, v118
	v_fma_f32 v101, v31, v113, v119
	v_fma_f32 v98, v28, v110, v126
	v_fma_f32 v99, v29, v111, v127
	v_div_fmas_f32 v62, v62, v76, v136
	v_fma_f32 v112, v26, v134, v120
	v_fma_f32 v113, v27, v135, v121
	v_fma_f32 v110, v24, v132, v128
	v_fma_f32 v111, v25, v133, v129
	global_store_dwordx4 v[34:35], v[98:101], off nt
	global_store_dwordx4 v[122:123], v[110:113], off offset:-4080 nt
	v_div_fixup_f32 v34, v62, v33, 0.5
	v_mul_f32_e32 v98, v34, v162
	v_mul_f32_e32 v99, v34, v163
	v_mul_f32_e32 v100, v34, v164
	v_mul_f32_e32 v101, v34, v165
	v_mul_f32_e32 v102, v34, v102
	v_mul_f32_e32 v103, v34, v103
	v_mul_f32_e32 v104, v34, v104
	v_mul_f32_e32 v105, v34, v105
	v_fma_f32 v30, v30, v100, v116
	v_fma_f32 v31, v31, v101, v117
	v_fma_f32 v28, v28, v98, v114
	v_fma_f32 v29, v29, v99, v115
	v_fma_f32 v26, v26, v104, v130
	v_fma_f32 v27, v27, v105, v131
	v_fma_f32 v24, v24, v102, v124
	v_fma_f32 v25, v25, v103, v125
	global_store_dwordx4 v[44:45], v[28:31], off nt
	global_store_dwordx4 v[44:45], v[24:27], off offset:16 nt
	s_nop 0
	s_nop 0
	s_nop 0
	v_mov_b32_e32 v100, v93
	v_mov_b32_e32 v101, v97
	v_mov_b32_e32 v93, v96
	v_mov_b32_e32 v98, v87
	v_mov_b32_e32 v99, v91
	v_mov_b32_e32 v87, v90
	v_lshlrev_b32_e32 v90, 16, v16
	v_and_b32_e32 v91, 0xffff0000, v16
	v_lshlrev_b32_e32 v96, 16, v17
	v_and_b32_e32 v97, 0xffff0000, v17
	v_lshlrev_b32_e32 v102, 16, v18
	v_and_b32_e32 v103, 0xffff0000, v18
	v_lshlrev_b32_e32 v104, 16, v19
	v_and_b32_e32 v105, 0xffff0000, v19
	v_mul_f32_e32 v18, v32, v100
	v_mul_f32_e32 v19, v32, v101
	v_mul_f32_e32 v16, v32, v92
	v_mul_f32_e32 v17, v32, v93
	s_waitcnt vmcnt(6)
	v_lshlrev_b32_e32 v110, 16, v20
	v_and_b32_e32 v111, 0xffff0000, v20
	v_lshlrev_b32_e32 v112, 16, v21
	v_and_b32_e32 v113, 0xffff0000, v21
	v_lshlrev_b32_e32 v114, 16, v22
	v_and_b32_e32 v115, 0xffff0000, v22
	v_lshlrev_b32_e32 v116, 16, v23
	v_and_b32_e32 v117, 0xffff0000, v23
	v_mul_f32_e32 v22, v32, v94
	v_mul_f32_e32 v23, v32, v95
	v_mul_f32_e32 v20, v32, v88
	v_mul_f32_e32 v21, v32, v89
	v_mul_f32_e32 v88, v34, v98
	v_mul_f32_e32 v89, v34, v99
	v_mul_f32_e32 v86, v34, v86
	v_mul_f32_e32 v87, v34, v87
	v_mul_f32_e32 v84, v34, v84
	v_mul_f32_e32 v85, v34, v85
	v_mul_f32_e32 v82, v34, v82
	v_mul_f32_e32 v83, v34, v83
	v_mov_b32_e32 v70, v77
	v_mov_b32_e32 v62, v75
	v_lshlrev_b32_e32 v74, 16, v11
	v_and_b32_e32 v75, 0xffff0000, v11
	s_waitcnt vmcnt(5)
	v_lshlrev_b32_e32 v76, 16, v12
	v_and_b32_e32 v77, 0xffff0000, v12
	v_mul_f32_e32 v64, v34, v64
	v_mul_f32_e32 v65, v34, v65
	v_mul_f32_e32 v62, v34, v62
	v_mul_f32_e32 v63, v34, v63
	v_mul_f32_e32 v68, v34, v68
	v_mul_f32_e32 v69, v34, v69
	v_mul_f32_e32 v66, v34, v66
	v_mul_f32_e32 v67, v34, v67
	v_mul_f32_e32 v50, v34, v50
	v_mul_f32_e32 v51, v34, v51
	s_waitcnt vmcnt(4)
; #define NT_ST4(ptr_, val_) __builtin_nontemporal_store((val_), (f32x4*)(ptr_))
; __device__ __forceinline__ u32x4 pack8(const f32x4 a, const f32x4 b) { u32x4 o; o.x = pk2(a.x, a.y); o.y = pk2(a.z, a.w); o.z = pk2(b.x, b.y); o.w = pk2(b.z, b.w); return o; }
; template <bool INB, bool OUTB>
; __device__ __forceinline__ void thin_phase(Frame& F, const bf16* Fb, const void* xin_p, const void* xin_s, const float* post_g, float half, void* xout, const float* next_g, bf16* H) {
;     ...
;         for (int j = 0; j < 4; ++j) { const int c = (j * 64 + lane) * 8; const f32x4 g0 = *(const f32x4*)(post_g + c), g1 = *(const f32x4*)(post_g + c + 4);
; #pragma unroll
;             for (int r = 0; r < 2; ++r) { const f32x4 o0 = x[r][2 * j] + f[r][2 * j] * (r == 0 ? r0 : r1) * g0, o1 = x[r][2 * j + 1] + f[r][2 * j + 1] * (r == 0 ? r0 : r1) * g1; f[r][2 * j] = o0; f[r][2 * j + 1] = o1;
;                 if (OUTB) __builtin_nontemporal_store(pack8(o0, o1), (u32x4*)((bf16*)xout + (size_t)(m0 + r) * D + c));
;                 else { NT_ST4((float*)xout + (size_t)(m0 + r) * D + c, o0); NT_ST4((float*)xout + (size_t)(m0 + r) * D + c + 4, o1); }
;                 s2[r] += ((o0.x * o0.x + o0.y * o0.y) + (o0.z * o0.z + o0.w * o0.w)) + ((o1.x * o1.x + o1.y * o1.y) + (o1.z * o1.z + o1.w * o1.w)); } }
	s_nop 1
	v_mov_b64_e32 v[24:25], v[178:179]
	v_mov_b64_e32 v[26:27], v[180:181]
	v_mov_b64_e32 v[28:29], v[182:183]
	v_mov_b64_e32 v[30:31], v[184:185]
	v_fma_f32 v16, v16, v24, v90
	v_fma_f32 v17, v17, v25, v91
	v_fma_f32 v18, v18, v26, v96
	v_fma_f32 v19, v19, v27, v97
	s_nop 0
	v_fma_f32 v20, v20, v28, v102
	v_fma_f32 v21, v21, v29, v103
	v_fma_f32 v22, v22, v30, v104
	v_fma_f32 v23, v23, v31, v105
	v_fma_f32 v24, v24, v86, v110
	v_fma_f32 v25, v25, v87, v111
	v_fma_f32 v26, v26, v88, v112
	v_fma_f32 v27, v27, v89, v113
	v_fma_f32 v28, v28, v82, v114
	v_fma_f32 v29, v29, v83, v115
	v_fma_f32 v30, v30, v84, v116
	v_fma_f32 v31, v31, v85, v117
	global_store_dwordx4 v[122:123], v[16:19], off offset:-2048 nt
	global_store_dwordx4 v[122:123], v[20:23], off offset:-2032 nt
	global_store_dwordx4 v[44:45], v[24:27], off offset:2048 nt
	global_store_dwordx4 v[44:45], v[28:31], off offset:2064 nt
	s_nop 0
	s_nop 0
	s_nop 0
	v_lshlrev_b32_e32 v26, 16, v8
	v_and_b32_e32 v27, 0xffff0000, v8
	v_lshlrev_b32_e32 v28, 16, v9
	v_and_b32_e32 v29, 0xffff0000, v9
	v_lshlrev_b32_e32 v30, 16, v10
	v_and_b32_e32 v31, 0xffff0000, v10
	v_mul_f32_e32 v10, v32, v72
	v_mul_f32_e32 v11, v32, v73
	v_mul_f32_e32 v8, v32, v70
	v_mul_f32_e32 v9, v32, v71
	v_add_co_u32_e32 v24, vcc, s18, v44
	v_lshlrev_b32_e32 v82, 16, v13
	v_and_b32_e32 v83, 0xffff0000, v13
	v_lshlrev_b32_e32 v84, 16, v14
	v_and_b32_e32 v85, 0xffff0000, v14
	v_lshlrev_b32_e32 v86, 16, v15
	v_and_b32_e32 v87, 0xffff0000, v15
	v_mul_f32_e32 v14, v32, v80
	v_mul_f32_e32 v15, v32, v81
	v_mul_f32_e32 v12, v32, v78
	v_mul_f32_e32 v13, v32, v79
	v_addc_co_u32_e32 v25, vcc, 0, v45, vcc
	s_nop 1
	v_mov_b64_e32 v[16:17], v[186:187]
	v_mov_b64_e32 v[18:19], v[188:189]
	v_mov_b64_e32 v[20:21], v[190:191]
	v_mov_b64_e32 v[22:23], v[192:193]
	v_fma_f32 v8, v8, v16, v26
	v_fma_f32 v9, v9, v17, v27
	v_fma_f32 v10, v10, v18, v28
	v_fma_f32 v11, v11, v19, v29
	s_nop 0
	v_fma_f32 v12, v12, v20, v30
	v_fma_f32 v13, v13, v21, v31
	v_fma_f32 v14, v14, v22, v74
	v_fma_f32 v15, v15, v23, v75
	v_fma_f32 v16, v62, v16, v76
	v_fma_f32 v17, v63, v17, v77
	v_fma_f32 v18, v64, v18, v82
	v_fma_f32 v19, v65, v19, v83
	v_fma_f32 v20, v66, v20, v84
	v_fma_f32 v21, v67, v21, v85
	v_fma_f32 v22, v68, v22, v86
	v_fma_f32 v23, v69, v23, v87
	global_store_dwordx4 v[44:45], v[8:11], off offset:-4096 nt
	global_store_dwordx4 v[44:45], v[12:15], off offset:-4080 nt
	global_store_dwordx4 v[24:25], v[16:19], off nt
	global_store_dwordx4 v[24:25], v[20:23], off offset:16 nt
	s_nop 0
	s_nop 0
	s_nop 0
	v_lshlrev_b32_e32 v16, 16, v0
	v_and_b32_e32 v17, 0xffff0000, v0
	v_lshlrev_b32_e32 v18, 16, v1
	v_and_b32_e32 v19, 0xffff0000, v1
	v_lshlrev_b32_e32 v20, 16, v2
	v_and_b32_e32 v21, 0xffff0000, v2
	v_lshlrev_b32_e32 v22, 16, v3
	v_and_b32_e32 v23, 0xffff0000, v3
	v_mul_f32_e32 v2, v32, v56
	v_mul_f32_e32 v3, v32, v57
	v_mul_f32_e32 v0, v32, v54
	v_mul_f32_e32 v1, v32, v55
	v_lshlrev_b32_e32 v26, 16, v4
	v_and_b32_e32 v27, 0xffff0000, v4
	v_lshlrev_b32_e32 v28, 16, v5
	v_and_b32_e32 v29, 0xffff0000, v5
	v_lshlrev_b32_e32 v30, 16, v6
	v_and_b32_e32 v31, 0xffff0000, v6
	v_lshlrev_b32_e32 v62, 16, v7
	v_and_b32_e32 v63, 0xffff0000, v7
	v_mul_f32_e32 v6, v32, v52
	v_mul_f32_e32 v7, v32, v53
	v_mul_f32_e32 v4, v32, v48
	v_mul_f32_e32 v5, v32, v49
	v_mul_f32_e32 v32, v34, v60
	v_mul_f32_e32 v33, v34, v61
	v_mul_f32_e32 v48, v34, v58
	v_mul_f32_e32 v49, v34, v59
	v_mul_f32_e32 v35, v34, v47
	v_mul_f32_e32 v34, v34, v46
	s_nop 1
	v_mov_b64_e32 v[8:9], v[194:195]
	v_mov_b64_e32 v[10:11], v[196:197]
	v_mov_b64_e32 v[12:13], v[198:199]
	v_mov_b64_e32 v[14:15], v[200:201]
	v_fma_f32 v0, v0, v8, v16
	v_fma_f32 v1, v1, v9, v17
	v_fma_f32 v2, v2, v10, v18
	v_fma_f32 v3, v3, v11, v19
	s_nop 0
	v_fma_f32 v4, v4, v12, v20
	v_fma_f32 v5, v5, v13, v21
	v_fma_f32 v6, v6, v14, v22
	v_fma_f32 v7, v7, v15, v23
	v_fma_f32 v8, v48, v8, v26
	v_fma_f32 v9, v49, v9, v27
	v_fma_f32 v10, v32, v10, v28
	v_fma_f32 v11, v33, v11, v29
	v_fma_f32 v12, v34, v12, v30
	v_fma_f32 v13, v35, v13, v31
	v_fma_f32 v14, v50, v14, v62
	v_fma_f32 v15, v51, v15, v63
	global_store_dwordx4 v[44:45], v[0:3], off offset:-2048 nt
	global_store_dwordx4 v[44:45], v[4:7], off offset:-2032 nt
	global_store_dwordx4 v[24:25], v[8:11], off offset:2048 nt
	global_store_dwordx4 v[24:25], v[12:15], off offset:2064 nt
	v_lshl_add_u64 v[44:45], v[44:45], 0, s[10:11]
	s_cbranch_scc1 .LBB0_2939
